# hand-written phase C1 (merge-gate GEMM): 256x128 tiles x4 per block, LDS-DMA 3-stage ring, half-step fragment read-ahead, sigmoid epilogue under next tile's MFMAs; plus hand-written C2
# speedup vs baseline: 1.1577x; 1.0236x over previous
.LBB0_810:
	s_or_b64 exec, exec, s[4:5]
	v_readlane_b32 s0, v253, 59
	v_mov_b32_e32 v1, v0
	v_readlane_b32 s1, v253, 60
	v_readlane_b32 s62, v254, 36
	v_readlane_b32 s70, v254, 38
	v_readlane_b32 s76, v254, 40
	v_readlane_b32 s86, v254, 42
	v_readlane_b32 s94, v254, 44
	s_andn2_b64 vcc, exec, s[0:1]
	v_readfirstlane_b32 s50, v1
	v_readlane_b32 s63, v254, 37
	v_readlane_b32 s71, v254, 39
	v_readlane_b32 s77, v254, 41
	v_readlane_b32 s87, v254, 43
	v_readlane_b32 s95, v254, 45
	s_mov_b64 s[52:53], 0x18000
	s_cbranch_vccnz .LBB0_826
	s_branch .Lc1_start
.Lisl_142:
	s_branch .LBB0_142

.Lc1_start:
	v_mov_b32_e32 v238, 0x200f0
	ds_read_b64 v[236:237], v238
	s_waitcnt lgkmcnt(0)
	v_readfirstlane_b32 s20, v236
	v_readfirstlane_b32 s21, v237
	s_barrier
	v_and_b32_e32 v236, 63, v0
	v_lshrrev_b32_e32 v237, 6, v0
	v_lshrrev_b32_e32 v238, 3, v236
	v_lshrrev_b32_e32 v239, 4, v236
	s_nop 0
	v_readfirstlane_b32 s0, v237
	v_add_u32_e32 v200, 0, v239
	v_xor_b32_e32 v200, v200, v236
	v_and_b32_e32 v200, 7, v200
	v_lshlrev_b32_e32 v200, 4, v200
	v_lshl_add_u32 v130, v237, 5, v238
	v_add_u32_e32 v130, 0, v130
	v_mul_u32_u24_e32 v130, 0x800, v130
	v_add_u32_e32 v200, v200, v130
	v_add_u32_e32 v201, 4, v239
	v_xor_b32_e32 v201, v201, v236
	v_and_b32_e32 v201, 7, v201
	v_lshlrev_b32_e32 v201, 4, v201
	v_lshl_add_u32 v130, v237, 5, v238
	v_add_u32_e32 v130, 8, v130
	v_mul_u32_u24_e32 v130, 0x800, v130
	v_add_u32_e32 v201, v201, v130
	v_add_u32_e32 v202, 8, v239
	v_xor_b32_e32 v202, v202, v236
	v_and_b32_e32 v202, 7, v202
	v_lshlrev_b32_e32 v202, 4, v202
	v_lshl_add_u32 v130, v237, 5, v238
	v_add_u32_e32 v130, 16, v130
	v_mul_u32_u24_e32 v130, 0x800, v130
	v_add_u32_e32 v202, v202, v130
	v_add_u32_e32 v203, 12, v239
	v_xor_b32_e32 v203, v203, v236
	v_and_b32_e32 v203, 7, v203
	v_lshlrev_b32_e32 v203, 4, v203
	v_lshl_add_u32 v130, v237, 5, v238
	v_add_u32_e32 v130, 24, v130
	v_mul_u32_u24_e32 v130, 0x800, v130
	v_add_u32_e32 v203, v203, v130
	v_add_u32_e32 v204, 0, v239
	v_xor_b32_e32 v204, v204, v236
	v_and_b32_e32 v204, 7, v204
	v_lshlrev_b32_e32 v204, 4, v204
	v_lshl_add_u32 v130, v237, 4, v238
	v_add_u32_e32 v130, 0, v130
	v_mul_u32_u24_e32 v130, 0x800, v130
	v_add_u32_e32 v204, v204, v130
	v_add_u32_e32 v205, 4, v239
	v_xor_b32_e32 v205, v205, v236
	v_and_b32_e32 v205, 7, v205
	v_lshlrev_b32_e32 v205, 4, v205
	v_lshl_add_u32 v130, v237, 4, v238
	v_add_u32_e32 v130, 8, v130
	v_mul_u32_u24_e32 v130, 0x800, v130
	v_add_u32_e32 v205, v205, v130
	v_and_b32_e32 v238, 15, v236
	v_lshrrev_b32_e32 v130, 1, v238
	v_xor_b32_e32 v130, v130, v239
	v_lshlrev_b32_e32 v130, 4, v130
	v_lshrrev_b32_e32 v236, 1, v237
	v_lshl_add_u32 v236, v236, 6, v238
	v_lshl_add_u32 v236, v236, 7, v130
	v_and_b32_e32 v237, 1, v237
	v_lshl_add_u32 v237, v237, 6, v238
	v_lshl_add_u32 v237, v237, 7, v130
	v_add_u32_e32 v218, 0x100, v236
	v_xor_b32_e32 v225, 64, v218
	v_add_u32_e32 v230, 0x8100, v237
	v_xor_b32_e32 v233, 64, v230
	v_add_u32_e32 v219, 0xc100, v236
	v_xor_b32_e32 v228, 64, v219
	v_add_u32_e32 v231, 0x14100, v237
	v_xor_b32_e32 v234, 64, v231
	v_add_u32_e32 v224, 0x18100, v236
	v_xor_b32_e32 v229, 64, v224
	v_add_u32_e32 v232, 0x20100, v237
	v_xor_b32_e32 v235, 64, v232
	s_lshl_b32 s1, s0, 12
	s_add_u32 s8, s1, 0x100
	s_lshl_b32 s1, s0, 11
	s_add_u32 s9, s1, 0x8100
	v_and_b32_e32 v236, 63, v0
	v_lshrrev_b32_e32 v237, 6, v0
	v_and_b32_e32 v238, 15, v236
	v_lshrrev_b32_e32 v239, 4, v236
	v_lshlrev_b32_e32 v240, 13, v237
	v_lshl_add_u32 v240, v238, 7, v240
	v_lshl_add_u32 v240, v239, 5, v240
	v_add_u32_e32 v241, 0x1000, v240
	s_and_b32 s1, s2, 7
	s_lshr_b32 s22, s2, 3
	s_and_b32 s23, s22, 3
	s_lshl_b32 s1, s1, 2
	s_add_u32 s1, s1, s23
	s_lshr_b32 s22, s22, 2
	s_lshl_b32 s23, s1, 19
	s_add_u32 s4, s26, s23
	s_addc_u32 s5, s27, 0
	v_readlane_b32 s6, v254, 57
	v_readlane_b32 s7, v254, 58
	s_lshl_b32 s23, s22, 20
	s_add_u32 s23, s23, 0x640000
	s_nop 0
	s_add_u32 s6, s6, s23
	s_addc_u32 s7, s7, 0
	s_lshr_b32 s23, s22, 1
	s_lshl_b32 s23, s23, 5
	s_add_u32 s23, s23, s1
	s_lshl_b32 s23, s23, 3
	s_and_b32 s24, s22, 1
	s_lshl_b32 s24, s24, 2
	s_add_u32 s23, s23, s24
	s_lshl_b32 s13, s23, 16
	s_mov_b32 s12, 0xbfb8aa3b
	s_mov_b32 m0, s8
	s_nop 0
	global_load_lds_dwordx4 v200, s[4:5]
	s_add_u32 m0, s8, 0x400
	s_nop 0
	global_load_lds_dwordx4 v201, s[4:5]
	s_add_u32 m0, s8, 0x800
	s_nop 0
	global_load_lds_dwordx4 v202, s[4:5]
	s_add_u32 m0, s8, 0xc00
	s_nop 0
	global_load_lds_dwordx4 v203, s[4:5]
	s_mov_b32 m0, s9
	s_nop 0
	global_load_lds_dwordx4 v204, s[6:7]
	s_add_u32 m0, s9, 0x400
	s_nop 0
	global_load_lds_dwordx4 v205, s[6:7]
	s_add_u32 s4, s4, 0x80
	s_addc_u32 s5, s5, 0
	s_add_u32 s6, s6, 0x80
	s_addc_u32 s7, s7, 0
	s_add_u32 m0, s8, 0xc000
	s_nop 0
	global_load_lds_dwordx4 v200, s[4:5]
	s_add_u32 m0, s8, 0xc400
	s_nop 0
	global_load_lds_dwordx4 v201, s[4:5]
	s_add_u32 m0, s8, 0xc800
	s_nop 0
	global_load_lds_dwordx4 v202, s[4:5]
	s_add_u32 m0, s8, 0xcc00
	s_nop 0
	global_load_lds_dwordx4 v203, s[4:5]
	s_add_u32 m0, s9, 0xc000
	s_nop 0
	global_load_lds_dwordx4 v204, s[6:7]
	s_add_u32 m0, s9, 0xc400
	s_nop 0
	global_load_lds_dwordx4 v205, s[6:7]
	s_add_u32 s4, s4, 0x80
	s_addc_u32 s5, s5, 0
	s_add_u32 s6, s6, 0x80
	s_addc_u32 s7, s7, 0
	s_add_u32 m0, s8, 0x18000
	s_nop 0
	global_load_lds_dwordx4 v200, s[4:5]
	s_add_u32 m0, s8, 0x18400
	s_nop 0
	global_load_lds_dwordx4 v201, s[4:5]
	s_add_u32 m0, s8, 0x18800
	s_nop 0
	global_load_lds_dwordx4 v202, s[4:5]
	s_add_u32 m0, s8, 0x18c00
	s_nop 0
	global_load_lds_dwordx4 v203, s[4:5]
	s_add_u32 m0, s9, 0x18000
	s_nop 0
	global_load_lds_dwordx4 v204, s[6:7]
	s_add_u32 m0, s9, 0x18400
	s_nop 0
	global_load_lds_dwordx4 v205, s[6:7]
	s_add_u32 s4, s4, 0x80
	s_addc_u32 s5, s5, 0
	s_add_u32 s6, s6, 0x80
	s_addc_u32 s7, s7, 0
	s_waitcnt vmcnt(12)
	s_barrier
	ds_read_b128 v[136:139], v218 offset:0
	ds_read_b128 v[140:143], v218 offset:2048
	ds_read_b128 v[144:147], v218 offset:4096
	ds_read_b128 v[148:151], v218 offset:6144
	ds_read_b128 v[152:155], v230 offset:0
	ds_read_b128 v[156:159], v230 offset:2048
	ds_read_b128 v[160:163], v230 offset:4096
	ds_read_b128 v[164:167], v230 offset:6144
	s_waitcnt lgkmcnt(0)
	v_mfma_f32_16x16x32_bf16 v[2:5], v[152:155], v[136:139], 0
	ds_read_b128 v[168:171], v225 offset:0
	v_mfma_f32_16x16x32_bf16 v[6:9], v[156:159], v[136:139], 0
	ds_read_b128 v[172:175], v225 offset:2048
	v_mfma_f32_16x16x32_bf16 v[10:13], v[160:163], v[136:139], 0
	ds_read_b128 v[176:179], v225 offset:4096
	v_mfma_f32_16x16x32_bf16 v[14:17], v[164:167], v[136:139], 0
	ds_read_b128 v[180:183], v225 offset:6144
	v_mfma_f32_16x16x32_bf16 v[18:21], v[152:155], v[140:143], 0
	ds_read_b128 v[184:187], v233 offset:0
	v_mfma_f32_16x16x32_bf16 v[22:25], v[156:159], v[140:143], 0
	ds_read_b128 v[188:191], v233 offset:2048
	v_mfma_f32_16x16x32_bf16 v[26:29], v[160:163], v[140:143], 0
	ds_read_b128 v[192:195], v233 offset:4096
	v_mfma_f32_16x16x32_bf16 v[30:33], v[164:167], v[140:143], 0
	ds_read_b128 v[196:199], v233 offset:6144
	v_mfma_f32_16x16x32_bf16 v[34:37], v[152:155], v[144:147], 0
	v_mfma_f32_16x16x32_bf16 v[38:41], v[156:159], v[144:147], 0
	v_mfma_f32_16x16x32_bf16 v[42:45], v[160:163], v[144:147], 0
	v_mfma_f32_16x16x32_bf16 v[46:49], v[164:167], v[144:147], 0
	v_mfma_f32_16x16x32_bf16 v[50:53], v[152:155], v[148:151], 0
	v_mfma_f32_16x16x32_bf16 v[54:57], v[156:159], v[148:151], 0
	v_mfma_f32_16x16x32_bf16 v[58:61], v[160:163], v[148:151], 0
	v_mfma_f32_16x16x32_bf16 v[62:65], v[164:167], v[148:151], 0
	s_waitcnt vmcnt(6) lgkmcnt(0)
	s_barrier
	v_mfma_f32_16x16x32_bf16 v[2:5], v[184:187], v[168:171], v[2:5]
	ds_read_b128 v[136:139], v219 offset:0
	v_mfma_f32_16x16x32_bf16 v[6:9], v[188:191], v[168:171], v[6:9]
	ds_read_b128 v[140:143], v219 offset:2048
	v_mfma_f32_16x16x32_bf16 v[10:13], v[192:195], v[168:171], v[10:13]
	ds_read_b128 v[144:147], v219 offset:4096
	v_mfma_f32_16x16x32_bf16 v[14:17], v[196:199], v[168:171], v[14:17]
	ds_read_b128 v[148:151], v219 offset:6144
	v_mfma_f32_16x16x32_bf16 v[18:21], v[184:187], v[172:175], v[18:21]
	ds_read_b128 v[152:155], v231 offset:0
	v_mfma_f32_16x16x32_bf16 v[22:25], v[188:191], v[172:175], v[22:25]
	ds_read_b128 v[156:159], v231 offset:2048
	v_mfma_f32_16x16x32_bf16 v[26:29], v[192:195], v[172:175], v[26:29]
	ds_read_b128 v[160:163], v231 offset:4096
	v_mfma_f32_16x16x32_bf16 v[30:33], v[196:199], v[172:175], v[30:33]
	ds_read_b128 v[164:167], v231 offset:6144
	s_mov_b32 m0, s8
	v_mfma_f32_16x16x32_bf16 v[34:37], v[184:187], v[176:179], v[34:37]
	global_load_lds_dwordx4 v200, s[4:5]
	s_add_u32 m0, s8, 0x400
	v_mfma_f32_16x16x32_bf16 v[38:41], v[188:191], v[176:179], v[38:41]
	global_load_lds_dwordx4 v201, s[4:5]
	s_add_u32 m0, s8, 0x800
	v_mfma_f32_16x16x32_bf16 v[42:45], v[192:195], v[176:179], v[42:45]
	global_load_lds_dwordx4 v202, s[4:5]
	s_add_u32 m0, s8, 0xc00
	v_mfma_f32_16x16x32_bf16 v[46:49], v[196:199], v[176:179], v[46:49]
	global_load_lds_dwordx4 v203, s[4:5]
	s_mov_b32 m0, s9
	v_mfma_f32_16x16x32_bf16 v[50:53], v[184:187], v[180:183], v[50:53]
	global_load_lds_dwordx4 v204, s[6:7]
	s_add_u32 m0, s9, 0x400
	v_mfma_f32_16x16x32_bf16 v[54:57], v[188:191], v[180:183], v[54:57]
	global_load_lds_dwordx4 v205, s[6:7]
	v_mfma_f32_16x16x32_bf16 v[58:61], v[192:195], v[180:183], v[58:61]
	s_add_u32 s4, s4, 0x80
	s_addc_u32 s5, s5, 0
	v_mfma_f32_16x16x32_bf16 v[62:65], v[196:199], v[180:183], v[62:65]
	s_add_u32 s6, s6, 0x80
	s_addc_u32 s7, s7, 0
	s_waitcnt lgkmcnt(0)
	v_mfma_f32_16x16x32_bf16 v[2:5], v[152:155], v[136:139], v[2:5]
	ds_read_b128 v[168:171], v228 offset:0
	v_mfma_f32_16x16x32_bf16 v[6:9], v[156:159], v[136:139], v[6:9]
	ds_read_b128 v[172:175], v228 offset:2048
	v_mfma_f32_16x16x32_bf16 v[10:13], v[160:163], v[136:139], v[10:13]
	ds_read_b128 v[176:179], v228 offset:4096
	v_mfma_f32_16x16x32_bf16 v[14:17], v[164:167], v[136:139], v[14:17]
	ds_read_b128 v[180:183], v228 offset:6144
	v_mfma_f32_16x16x32_bf16 v[18:21], v[152:155], v[140:143], v[18:21]
	ds_read_b128 v[184:187], v234 offset:0
	v_mfma_f32_16x16x32_bf16 v[22:25], v[156:159], v[140:143], v[22:25]
	ds_read_b128 v[188:191], v234 offset:2048
	v_mfma_f32_16x16x32_bf16 v[26:29], v[160:163], v[140:143], v[26:29]
	ds_read_b128 v[192:195], v234 offset:4096
	v_mfma_f32_16x16x32_bf16 v[30:33], v[164:167], v[140:143], v[30:33]
	ds_read_b128 v[196:199], v234 offset:6144
	v_mfma_f32_16x16x32_bf16 v[34:37], v[152:155], v[144:147], v[34:37]
	v_mfma_f32_16x16x32_bf16 v[38:41], v[156:159], v[144:147], v[38:41]
	v_mfma_f32_16x16x32_bf16 v[42:45], v[160:163], v[144:147], v[42:45]
	v_mfma_f32_16x16x32_bf16 v[46:49], v[164:167], v[144:147], v[46:49]
	v_mfma_f32_16x16x32_bf16 v[50:53], v[152:155], v[148:151], v[50:53]
	v_mfma_f32_16x16x32_bf16 v[54:57], v[156:159], v[148:151], v[54:57]
	v_mfma_f32_16x16x32_bf16 v[58:61], v[160:163], v[148:151], v[58:61]
	v_mfma_f32_16x16x32_bf16 v[62:65], v[164:167], v[148:151], v[62:65]
	s_waitcnt vmcnt(6) lgkmcnt(0)
	s_barrier
	v_mfma_f32_16x16x32_bf16 v[2:5], v[184:187], v[168:171], v[2:5]
	ds_read_b128 v[136:139], v224 offset:0
	v_mfma_f32_16x16x32_bf16 v[6:9], v[188:191], v[168:171], v[6:9]
	ds_read_b128 v[140:143], v224 offset:2048
	v_mfma_f32_16x16x32_bf16 v[10:13], v[192:195], v[168:171], v[10:13]
	ds_read_b128 v[144:147], v224 offset:4096
	v_mfma_f32_16x16x32_bf16 v[14:17], v[196:199], v[168:171], v[14:17]
	ds_read_b128 v[148:151], v224 offset:6144
	v_mfma_f32_16x16x32_bf16 v[18:21], v[184:187], v[172:175], v[18:21]
	ds_read_b128 v[152:155], v232 offset:0
	v_mfma_f32_16x16x32_bf16 v[22:25], v[188:191], v[172:175], v[22:25]
	ds_read_b128 v[156:159], v232 offset:2048
	v_mfma_f32_16x16x32_bf16 v[26:29], v[192:195], v[172:175], v[26:29]
	ds_read_b128 v[160:163], v232 offset:4096
	v_mfma_f32_16x16x32_bf16 v[30:33], v[196:199], v[172:175], v[30:33]
	ds_read_b128 v[164:167], v232 offset:6144
	s_add_u32 m0, s8, 0xc000
	v_mfma_f32_16x16x32_bf16 v[34:37], v[184:187], v[176:179], v[34:37]
	global_load_lds_dwordx4 v200, s[4:5]
	s_add_u32 m0, s8, 0xc400
	v_mfma_f32_16x16x32_bf16 v[38:41], v[188:191], v[176:179], v[38:41]
	global_load_lds_dwordx4 v201, s[4:5]
	s_add_u32 m0, s8, 0xc800
	v_mfma_f32_16x16x32_bf16 v[42:45], v[192:195], v[176:179], v[42:45]
	global_load_lds_dwordx4 v202, s[4:5]
	s_add_u32 m0, s8, 0xcc00
	v_mfma_f32_16x16x32_bf16 v[46:49], v[196:199], v[176:179], v[46:49]
	global_load_lds_dwordx4 v203, s[4:5]
	s_add_u32 m0, s9, 0xc000
	v_mfma_f32_16x16x32_bf16 v[50:53], v[184:187], v[180:183], v[50:53]
	global_load_lds_dwordx4 v204, s[6:7]
	s_add_u32 m0, s9, 0xc400
	v_mfma_f32_16x16x32_bf16 v[54:57], v[188:191], v[180:183], v[54:57]
	global_load_lds_dwordx4 v205, s[6:7]
	v_mfma_f32_16x16x32_bf16 v[58:61], v[192:195], v[180:183], v[58:61]
	s_add_u32 s4, s4, 0x80
	s_addc_u32 s5, s5, 0
	v_mfma_f32_16x16x32_bf16 v[62:65], v[196:199], v[180:183], v[62:65]
	s_add_u32 s6, s6, 0x80
	s_addc_u32 s7, s7, 0
	s_waitcnt lgkmcnt(0)
	v_mfma_f32_16x16x32_bf16 v[2:5], v[152:155], v[136:139], v[2:5]
	ds_read_b128 v[168:171], v229 offset:0
	v_mfma_f32_16x16x32_bf16 v[6:9], v[156:159], v[136:139], v[6:9]
	ds_read_b128 v[172:175], v229 offset:2048
	v_mfma_f32_16x16x32_bf16 v[10:13], v[160:163], v[136:139], v[10:13]
	ds_read_b128 v[176:179], v229 offset:4096
	v_mfma_f32_16x16x32_bf16 v[14:17], v[164:167], v[136:139], v[14:17]
	ds_read_b128 v[180:183], v229 offset:6144
	v_mfma_f32_16x16x32_bf16 v[18:21], v[152:155], v[140:143], v[18:21]
	ds_read_b128 v[184:187], v235 offset:0
	v_mfma_f32_16x16x32_bf16 v[22:25], v[156:159], v[140:143], v[22:25]
	ds_read_b128 v[188:191], v235 offset:2048
	v_mfma_f32_16x16x32_bf16 v[26:29], v[160:163], v[140:143], v[26:29]
	ds_read_b128 v[192:195], v235 offset:4096
	v_mfma_f32_16x16x32_bf16 v[30:33], v[164:167], v[140:143], v[30:33]
	ds_read_b128 v[196:199], v235 offset:6144
	v_mfma_f32_16x16x32_bf16 v[34:37], v[152:155], v[144:147], v[34:37]
	v_mfma_f32_16x16x32_bf16 v[38:41], v[156:159], v[144:147], v[38:41]
	v_mfma_f32_16x16x32_bf16 v[42:45], v[160:163], v[144:147], v[42:45]
	v_mfma_f32_16x16x32_bf16 v[46:49], v[164:167], v[144:147], v[46:49]
	v_mfma_f32_16x16x32_bf16 v[50:53], v[152:155], v[148:151], v[50:53]
	v_mfma_f32_16x16x32_bf16 v[54:57], v[156:159], v[148:151], v[54:57]
	v_mfma_f32_16x16x32_bf16 v[58:61], v[160:163], v[148:151], v[58:61]
	v_mfma_f32_16x16x32_bf16 v[62:65], v[164:167], v[148:151], v[62:65]
	s_waitcnt vmcnt(6) lgkmcnt(0)
	s_barrier
	v_mfma_f32_16x16x32_bf16 v[2:5], v[184:187], v[168:171], v[2:5]
	ds_read_b128 v[136:139], v218 offset:0
	v_mfma_f32_16x16x32_bf16 v[6:9], v[188:191], v[168:171], v[6:9]
	ds_read_b128 v[140:143], v218 offset:2048
	v_mfma_f32_16x16x32_bf16 v[10:13], v[192:195], v[168:171], v[10:13]
	ds_read_b128 v[144:147], v218 offset:4096
	v_mfma_f32_16x16x32_bf16 v[14:17], v[196:199], v[168:171], v[14:17]
	ds_read_b128 v[148:151], v218 offset:6144
	v_mfma_f32_16x16x32_bf16 v[18:21], v[184:187], v[172:175], v[18:21]
	ds_read_b128 v[152:155], v230 offset:0
	v_mfma_f32_16x16x32_bf16 v[22:25], v[188:191], v[172:175], v[22:25]
	ds_read_b128 v[156:159], v230 offset:2048
	v_mfma_f32_16x16x32_bf16 v[26:29], v[192:195], v[172:175], v[26:29]
	ds_read_b128 v[160:163], v230 offset:4096
	v_mfma_f32_16x16x32_bf16 v[30:33], v[196:199], v[172:175], v[30:33]
	ds_read_b128 v[164:167], v230 offset:6144
	s_add_u32 m0, s8, 0x18000
	v_mfma_f32_16x16x32_bf16 v[34:37], v[184:187], v[176:179], v[34:37]
	global_load_lds_dwordx4 v200, s[4:5]
	s_add_u32 m0, s8, 0x18400
	v_mfma_f32_16x16x32_bf16 v[38:41], v[188:191], v[176:179], v[38:41]
	global_load_lds_dwordx4 v201, s[4:5]
	s_add_u32 m0, s8, 0x18800
	v_mfma_f32_16x16x32_bf16 v[42:45], v[192:195], v[176:179], v[42:45]
	global_load_lds_dwordx4 v202, s[4:5]
	s_add_u32 m0, s8, 0x18c00
	v_mfma_f32_16x16x32_bf16 v[46:49], v[196:199], v[176:179], v[46:49]
	global_load_lds_dwordx4 v203, s[4:5]
	s_add_u32 m0, s9, 0x18000
	v_mfma_f32_16x16x32_bf16 v[50:53], v[184:187], v[180:183], v[50:53]
	global_load_lds_dwordx4 v204, s[6:7]
	s_add_u32 m0, s9, 0x18400
	v_mfma_f32_16x16x32_bf16 v[54:57], v[188:191], v[180:183], v[54:57]
	global_load_lds_dwordx4 v205, s[6:7]
	v_mfma_f32_16x16x32_bf16 v[58:61], v[192:195], v[180:183], v[58:61]
	s_add_u32 s4, s4, 0x80
	s_addc_u32 s5, s5, 0
	v_mfma_f32_16x16x32_bf16 v[62:65], v[196:199], v[180:183], v[62:65]
	s_add_u32 s6, s6, 0x80
	s_addc_u32 s7, s7, 0
	s_waitcnt lgkmcnt(0)
	v_mfma_f32_16x16x32_bf16 v[2:5], v[152:155], v[136:139], v[2:5]
	ds_read_b128 v[168:171], v225 offset:0
	v_mfma_f32_16x16x32_bf16 v[6:9], v[156:159], v[136:139], v[6:9]
	ds_read_b128 v[172:175], v225 offset:2048
	v_mfma_f32_16x16x32_bf16 v[10:13], v[160:163], v[136:139], v[10:13]
	ds_read_b128 v[176:179], v225 offset:4096
	v_mfma_f32_16x16x32_bf16 v[14:17], v[164:167], v[136:139], v[14:17]
	ds_read_b128 v[180:183], v225 offset:6144
	v_mfma_f32_16x16x32_bf16 v[18:21], v[152:155], v[140:143], v[18:21]
	ds_read_b128 v[184:187], v233 offset:0
	v_mfma_f32_16x16x32_bf16 v[22:25], v[156:159], v[140:143], v[22:25]
	ds_read_b128 v[188:191], v233 offset:2048
	v_mfma_f32_16x16x32_bf16 v[26:29], v[160:163], v[140:143], v[26:29]
	ds_read_b128 v[192:195], v233 offset:4096
	v_mfma_f32_16x16x32_bf16 v[30:33], v[164:167], v[140:143], v[30:33]
	ds_read_b128 v[196:199], v233 offset:6144
	v_mfma_f32_16x16x32_bf16 v[34:37], v[152:155], v[144:147], v[34:37]
	v_mfma_f32_16x16x32_bf16 v[38:41], v[156:159], v[144:147], v[38:41]
	v_mfma_f32_16x16x32_bf16 v[42:45], v[160:163], v[144:147], v[42:45]
	v_mfma_f32_16x16x32_bf16 v[46:49], v[164:167], v[144:147], v[46:49]
	v_mfma_f32_16x16x32_bf16 v[50:53], v[152:155], v[148:151], v[50:53]
	v_mfma_f32_16x16x32_bf16 v[54:57], v[156:159], v[148:151], v[54:57]
	v_mfma_f32_16x16x32_bf16 v[58:61], v[160:163], v[148:151], v[58:61]
	v_mfma_f32_16x16x32_bf16 v[62:65], v[164:167], v[148:151], v[62:65]
	s_waitcnt vmcnt(6) lgkmcnt(0)
	s_barrier
	v_mfma_f32_16x16x32_bf16 v[2:5], v[184:187], v[168:171], v[2:5]
	ds_read_b128 v[136:139], v219 offset:0
	v_mfma_f32_16x16x32_bf16 v[6:9], v[188:191], v[168:171], v[6:9]
	ds_read_b128 v[140:143], v219 offset:2048
	v_mfma_f32_16x16x32_bf16 v[10:13], v[192:195], v[168:171], v[10:13]
	ds_read_b128 v[144:147], v219 offset:4096
	v_mfma_f32_16x16x32_bf16 v[14:17], v[196:199], v[168:171], v[14:17]
	ds_read_b128 v[148:151], v219 offset:6144
	v_mfma_f32_16x16x32_bf16 v[18:21], v[184:187], v[172:175], v[18:21]
	ds_read_b128 v[152:155], v231 offset:0
	v_mfma_f32_16x16x32_bf16 v[22:25], v[188:191], v[172:175], v[22:25]
	ds_read_b128 v[156:159], v231 offset:2048
	v_mfma_f32_16x16x32_bf16 v[26:29], v[192:195], v[172:175], v[26:29]
	ds_read_b128 v[160:163], v231 offset:4096
	v_mfma_f32_16x16x32_bf16 v[30:33], v[196:199], v[172:175], v[30:33]
	ds_read_b128 v[164:167], v231 offset:6144
	s_mov_b32 m0, s8
	v_mfma_f32_16x16x32_bf16 v[34:37], v[184:187], v[176:179], v[34:37]
	global_load_lds_dwordx4 v200, s[4:5]
	s_add_u32 m0, s8, 0x400
	v_mfma_f32_16x16x32_bf16 v[38:41], v[188:191], v[176:179], v[38:41]
	global_load_lds_dwordx4 v201, s[4:5]
	s_add_u32 m0, s8, 0x800
	v_mfma_f32_16x16x32_bf16 v[42:45], v[192:195], v[176:179], v[42:45]
	global_load_lds_dwordx4 v202, s[4:5]
	s_add_u32 m0, s8, 0xc00
	v_mfma_f32_16x16x32_bf16 v[46:49], v[196:199], v[176:179], v[46:49]
	global_load_lds_dwordx4 v203, s[4:5]
	s_mov_b32 m0, s9
	v_mfma_f32_16x16x32_bf16 v[50:53], v[184:187], v[180:183], v[50:53]
	global_load_lds_dwordx4 v204, s[6:7]
	s_add_u32 m0, s9, 0x400
	v_mfma_f32_16x16x32_bf16 v[54:57], v[188:191], v[180:183], v[54:57]
	global_load_lds_dwordx4 v205, s[6:7]
	v_mfma_f32_16x16x32_bf16 v[58:61], v[192:195], v[180:183], v[58:61]
	s_add_u32 s4, s4, 0x80
	s_addc_u32 s5, s5, 0
	v_mfma_f32_16x16x32_bf16 v[62:65], v[196:199], v[180:183], v[62:65]
	s_add_u32 s6, s6, 0x80
	s_addc_u32 s7, s7, 0
	s_waitcnt lgkmcnt(0)
	v_mfma_f32_16x16x32_bf16 v[2:5], v[152:155], v[136:139], v[2:5]
	ds_read_b128 v[168:171], v228 offset:0
	v_mfma_f32_16x16x32_bf16 v[6:9], v[156:159], v[136:139], v[6:9]
	ds_read_b128 v[172:175], v228 offset:2048
	v_mfma_f32_16x16x32_bf16 v[10:13], v[160:163], v[136:139], v[10:13]
	ds_read_b128 v[176:179], v228 offset:4096
	v_mfma_f32_16x16x32_bf16 v[14:17], v[164:167], v[136:139], v[14:17]
	ds_read_b128 v[180:183], v228 offset:6144
	v_mfma_f32_16x16x32_bf16 v[18:21], v[152:155], v[140:143], v[18:21]
	ds_read_b128 v[184:187], v234 offset:0
	v_mfma_f32_16x16x32_bf16 v[22:25], v[156:159], v[140:143], v[22:25]
	ds_read_b128 v[188:191], v234 offset:2048
	v_mfma_f32_16x16x32_bf16 v[26:29], v[160:163], v[140:143], v[26:29]
	ds_read_b128 v[192:195], v234 offset:4096
	v_mfma_f32_16x16x32_bf16 v[30:33], v[164:167], v[140:143], v[30:33]
	ds_read_b128 v[196:199], v234 offset:6144
	v_mfma_f32_16x16x32_bf16 v[34:37], v[152:155], v[144:147], v[34:37]
	v_mfma_f32_16x16x32_bf16 v[38:41], v[156:159], v[144:147], v[38:41]
	v_mfma_f32_16x16x32_bf16 v[42:45], v[160:163], v[144:147], v[42:45]
	v_mfma_f32_16x16x32_bf16 v[46:49], v[164:167], v[144:147], v[46:49]
	v_mfma_f32_16x16x32_bf16 v[50:53], v[152:155], v[148:151], v[50:53]
	v_mfma_f32_16x16x32_bf16 v[54:57], v[156:159], v[148:151], v[54:57]
	v_mfma_f32_16x16x32_bf16 v[58:61], v[160:163], v[148:151], v[58:61]
	v_mfma_f32_16x16x32_bf16 v[62:65], v[164:167], v[148:151], v[62:65]
	s_waitcnt vmcnt(6) lgkmcnt(0)
	s_barrier
	v_mfma_f32_16x16x32_bf16 v[2:5], v[184:187], v[168:171], v[2:5]
	ds_read_b128 v[136:139], v224 offset:0
	v_mfma_f32_16x16x32_bf16 v[6:9], v[188:191], v[168:171], v[6:9]
	ds_read_b128 v[140:143], v224 offset:2048
	v_mfma_f32_16x16x32_bf16 v[10:13], v[192:195], v[168:171], v[10:13]
	ds_read_b128 v[144:147], v224 offset:4096
	v_mfma_f32_16x16x32_bf16 v[14:17], v[196:199], v[168:171], v[14:17]
	ds_read_b128 v[148:151], v224 offset:6144
	v_mfma_f32_16x16x32_bf16 v[18:21], v[184:187], v[172:175], v[18:21]
	ds_read_b128 v[152:155], v232 offset:0
	v_mfma_f32_16x16x32_bf16 v[22:25], v[188:191], v[172:175], v[22:25]
	ds_read_b128 v[156:159], v232 offset:2048
	v_mfma_f32_16x16x32_bf16 v[26:29], v[192:195], v[172:175], v[26:29]
	ds_read_b128 v[160:163], v232 offset:4096
	v_mfma_f32_16x16x32_bf16 v[30:33], v[196:199], v[172:175], v[30:33]
	ds_read_b128 v[164:167], v232 offset:6144
	s_add_u32 m0, s8, 0xc000
	v_mfma_f32_16x16x32_bf16 v[34:37], v[184:187], v[176:179], v[34:37]
	global_load_lds_dwordx4 v200, s[4:5]
	s_add_u32 m0, s8, 0xc400
	v_mfma_f32_16x16x32_bf16 v[38:41], v[188:191], v[176:179], v[38:41]
	global_load_lds_dwordx4 v201, s[4:5]
	s_add_u32 m0, s8, 0xc800
	v_mfma_f32_16x16x32_bf16 v[42:45], v[192:195], v[176:179], v[42:45]
	global_load_lds_dwordx4 v202, s[4:5]
	s_add_u32 m0, s8, 0xcc00
	v_mfma_f32_16x16x32_bf16 v[46:49], v[196:199], v[176:179], v[46:49]
	global_load_lds_dwordx4 v203, s[4:5]
	s_add_u32 m0, s9, 0xc000
	v_mfma_f32_16x16x32_bf16 v[50:53], v[184:187], v[180:183], v[50:53]
	global_load_lds_dwordx4 v204, s[6:7]
	s_add_u32 m0, s9, 0xc400
	v_mfma_f32_16x16x32_bf16 v[54:57], v[188:191], v[180:183], v[54:57]
	global_load_lds_dwordx4 v205, s[6:7]
	v_mfma_f32_16x16x32_bf16 v[58:61], v[192:195], v[180:183], v[58:61]
	s_add_u32 s4, s4, 0x80
	s_addc_u32 s5, s5, 0
	v_mfma_f32_16x16x32_bf16 v[62:65], v[196:199], v[180:183], v[62:65]
	s_add_u32 s6, s6, 0x80
	s_addc_u32 s7, s7, 0
	s_waitcnt lgkmcnt(0)
	v_mfma_f32_16x16x32_bf16 v[2:5], v[152:155], v[136:139], v[2:5]
	ds_read_b128 v[168:171], v229 offset:0
	v_mfma_f32_16x16x32_bf16 v[6:9], v[156:159], v[136:139], v[6:9]
	ds_read_b128 v[172:175], v229 offset:2048
	v_mfma_f32_16x16x32_bf16 v[10:13], v[160:163], v[136:139], v[10:13]
	ds_read_b128 v[176:179], v229 offset:4096
	v_mfma_f32_16x16x32_bf16 v[14:17], v[164:167], v[136:139], v[14:17]
	ds_read_b128 v[180:183], v229 offset:6144
	v_mfma_f32_16x16x32_bf16 v[18:21], v[152:155], v[140:143], v[18:21]
	ds_read_b128 v[184:187], v235 offset:0
	v_mfma_f32_16x16x32_bf16 v[22:25], v[156:159], v[140:143], v[22:25]
	ds_read_b128 v[188:191], v235 offset:2048
	v_mfma_f32_16x16x32_bf16 v[26:29], v[160:163], v[140:143], v[26:29]
	ds_read_b128 v[192:195], v235 offset:4096
	v_mfma_f32_16x16x32_bf16 v[30:33], v[164:167], v[140:143], v[30:33]
	ds_read_b128 v[196:199], v235 offset:6144
	v_mfma_f32_16x16x32_bf16 v[34:37], v[152:155], v[144:147], v[34:37]
	v_mfma_f32_16x16x32_bf16 v[38:41], v[156:159], v[144:147], v[38:41]
	v_mfma_f32_16x16x32_bf16 v[42:45], v[160:163], v[144:147], v[42:45]
	v_mfma_f32_16x16x32_bf16 v[46:49], v[164:167], v[144:147], v[46:49]
	v_mfma_f32_16x16x32_bf16 v[50:53], v[152:155], v[148:151], v[50:53]
	v_mfma_f32_16x16x32_bf16 v[54:57], v[156:159], v[148:151], v[54:57]
	v_mfma_f32_16x16x32_bf16 v[58:61], v[160:163], v[148:151], v[58:61]
	v_mfma_f32_16x16x32_bf16 v[62:65], v[164:167], v[148:151], v[62:65]
	s_waitcnt vmcnt(6) lgkmcnt(0)
	s_barrier
	v_mfma_f32_16x16x32_bf16 v[2:5], v[184:187], v[168:171], v[2:5]
	ds_read_b128 v[136:139], v218 offset:0
	v_mfma_f32_16x16x32_bf16 v[6:9], v[188:191], v[168:171], v[6:9]
	ds_read_b128 v[140:143], v218 offset:2048
	v_mfma_f32_16x16x32_bf16 v[10:13], v[192:195], v[168:171], v[10:13]
	ds_read_b128 v[144:147], v218 offset:4096
	v_mfma_f32_16x16x32_bf16 v[14:17], v[196:199], v[168:171], v[14:17]
	ds_read_b128 v[148:151], v218 offset:6144
	v_mfma_f32_16x16x32_bf16 v[18:21], v[184:187], v[172:175], v[18:21]
	ds_read_b128 v[152:155], v230 offset:0
	v_mfma_f32_16x16x32_bf16 v[22:25], v[188:191], v[172:175], v[22:25]
	ds_read_b128 v[156:159], v230 offset:2048
	v_mfma_f32_16x16x32_bf16 v[26:29], v[192:195], v[172:175], v[26:29]
	ds_read_b128 v[160:163], v230 offset:4096
	v_mfma_f32_16x16x32_bf16 v[30:33], v[196:199], v[172:175], v[30:33]
	ds_read_b128 v[164:167], v230 offset:6144
	s_add_u32 m0, s8, 0x18000
	v_mfma_f32_16x16x32_bf16 v[34:37], v[184:187], v[176:179], v[34:37]
	global_load_lds_dwordx4 v200, s[4:5]
	s_add_u32 m0, s8, 0x18400
	v_mfma_f32_16x16x32_bf16 v[38:41], v[188:191], v[176:179], v[38:41]
	global_load_lds_dwordx4 v201, s[4:5]
	s_add_u32 m0, s8, 0x18800
	v_mfma_f32_16x16x32_bf16 v[42:45], v[192:195], v[176:179], v[42:45]
	global_load_lds_dwordx4 v202, s[4:5]
	s_add_u32 m0, s8, 0x18c00
	v_mfma_f32_16x16x32_bf16 v[46:49], v[196:199], v[176:179], v[46:49]
	global_load_lds_dwordx4 v203, s[4:5]
	s_add_u32 m0, s9, 0x18000
	v_mfma_f32_16x16x32_bf16 v[50:53], v[184:187], v[180:183], v[50:53]
	global_load_lds_dwordx4 v204, s[6:7]
	s_add_u32 m0, s9, 0x18400
	v_mfma_f32_16x16x32_bf16 v[54:57], v[188:191], v[180:183], v[54:57]
	global_load_lds_dwordx4 v205, s[6:7]
	v_mfma_f32_16x16x32_bf16 v[58:61], v[192:195], v[180:183], v[58:61]
	s_add_u32 s4, s4, 0x80
	s_addc_u32 s5, s5, 0
	v_mfma_f32_16x16x32_bf16 v[62:65], v[196:199], v[180:183], v[62:65]
	s_add_u32 s6, s6, 0x80
	s_addc_u32 s7, s7, 0
	s_waitcnt lgkmcnt(0)
	v_mfma_f32_16x16x32_bf16 v[2:5], v[152:155], v[136:139], v[2:5]
	ds_read_b128 v[168:171], v225 offset:0
	v_mfma_f32_16x16x32_bf16 v[6:9], v[156:159], v[136:139], v[6:9]
	ds_read_b128 v[172:175], v225 offset:2048
	v_mfma_f32_16x16x32_bf16 v[10:13], v[160:163], v[136:139], v[10:13]
	ds_read_b128 v[176:179], v225 offset:4096
	v_mfma_f32_16x16x32_bf16 v[14:17], v[164:167], v[136:139], v[14:17]
	ds_read_b128 v[180:183], v225 offset:6144
	v_mfma_f32_16x16x32_bf16 v[18:21], v[152:155], v[140:143], v[18:21]
	ds_read_b128 v[184:187], v233 offset:0
	v_mfma_f32_16x16x32_bf16 v[22:25], v[156:159], v[140:143], v[22:25]
	ds_read_b128 v[188:191], v233 offset:2048
	v_mfma_f32_16x16x32_bf16 v[26:29], v[160:163], v[140:143], v[26:29]
	ds_read_b128 v[192:195], v233 offset:4096
	v_mfma_f32_16x16x32_bf16 v[30:33], v[164:167], v[140:143], v[30:33]
	ds_read_b128 v[196:199], v233 offset:6144
	v_mfma_f32_16x16x32_bf16 v[34:37], v[152:155], v[144:147], v[34:37]
	v_mfma_f32_16x16x32_bf16 v[38:41], v[156:159], v[144:147], v[38:41]
	v_mfma_f32_16x16x32_bf16 v[42:45], v[160:163], v[144:147], v[42:45]
	v_mfma_f32_16x16x32_bf16 v[46:49], v[164:167], v[144:147], v[46:49]
	v_mfma_f32_16x16x32_bf16 v[50:53], v[152:155], v[148:151], v[50:53]
	v_mfma_f32_16x16x32_bf16 v[54:57], v[156:159], v[148:151], v[54:57]
	v_mfma_f32_16x16x32_bf16 v[58:61], v[160:163], v[148:151], v[58:61]
	v_mfma_f32_16x16x32_bf16 v[62:65], v[164:167], v[148:151], v[62:65]
	s_waitcnt vmcnt(6) lgkmcnt(0)
	s_barrier
	v_mfma_f32_16x16x32_bf16 v[2:5], v[184:187], v[168:171], v[2:5]
	ds_read_b128 v[136:139], v219 offset:0
	v_mfma_f32_16x16x32_bf16 v[6:9], v[188:191], v[168:171], v[6:9]
	ds_read_b128 v[140:143], v219 offset:2048
	v_mfma_f32_16x16x32_bf16 v[10:13], v[192:195], v[168:171], v[10:13]
	ds_read_b128 v[144:147], v219 offset:4096
	v_mfma_f32_16x16x32_bf16 v[14:17], v[196:199], v[168:171], v[14:17]
	ds_read_b128 v[148:151], v219 offset:6144
	v_mfma_f32_16x16x32_bf16 v[18:21], v[184:187], v[172:175], v[18:21]
	ds_read_b128 v[152:155], v231 offset:0
	v_mfma_f32_16x16x32_bf16 v[22:25], v[188:191], v[172:175], v[22:25]
	ds_read_b128 v[156:159], v231 offset:2048
	v_mfma_f32_16x16x32_bf16 v[26:29], v[192:195], v[172:175], v[26:29]
	ds_read_b128 v[160:163], v231 offset:4096
	v_mfma_f32_16x16x32_bf16 v[30:33], v[196:199], v[172:175], v[30:33]
	ds_read_b128 v[164:167], v231 offset:6144
	s_mov_b32 m0, s8
	v_mfma_f32_16x16x32_bf16 v[34:37], v[184:187], v[176:179], v[34:37]
	global_load_lds_dwordx4 v200, s[4:5]
	s_add_u32 m0, s8, 0x400
	v_mfma_f32_16x16x32_bf16 v[38:41], v[188:191], v[176:179], v[38:41]
	global_load_lds_dwordx4 v201, s[4:5]
	s_add_u32 m0, s8, 0x800
	v_mfma_f32_16x16x32_bf16 v[42:45], v[192:195], v[176:179], v[42:45]
	global_load_lds_dwordx4 v202, s[4:5]
	s_add_u32 m0, s8, 0xc00
	v_mfma_f32_16x16x32_bf16 v[46:49], v[196:199], v[176:179], v[46:49]
	global_load_lds_dwordx4 v203, s[4:5]
	s_mov_b32 m0, s9
	v_mfma_f32_16x16x32_bf16 v[50:53], v[184:187], v[180:183], v[50:53]
	global_load_lds_dwordx4 v204, s[6:7]
	s_add_u32 m0, s9, 0x400
	v_mfma_f32_16x16x32_bf16 v[54:57], v[188:191], v[180:183], v[54:57]
	global_load_lds_dwordx4 v205, s[6:7]
	v_mfma_f32_16x16x32_bf16 v[58:61], v[192:195], v[180:183], v[58:61]
	s_add_u32 s4, s4, 0x80
	s_addc_u32 s5, s5, 0
	v_mfma_f32_16x16x32_bf16 v[62:65], v[196:199], v[180:183], v[62:65]
	s_add_u32 s6, s6, 0x80
	s_addc_u32 s7, s7, 0
	s_waitcnt lgkmcnt(0)
	v_mfma_f32_16x16x32_bf16 v[2:5], v[152:155], v[136:139], v[2:5]
	ds_read_b128 v[168:171], v228 offset:0
	v_mfma_f32_16x16x32_bf16 v[6:9], v[156:159], v[136:139], v[6:9]
	ds_read_b128 v[172:175], v228 offset:2048
	v_mfma_f32_16x16x32_bf16 v[10:13], v[160:163], v[136:139], v[10:13]
	ds_read_b128 v[176:179], v228 offset:4096
	v_mfma_f32_16x16x32_bf16 v[14:17], v[164:167], v[136:139], v[14:17]
	ds_read_b128 v[180:183], v228 offset:6144
	v_mfma_f32_16x16x32_bf16 v[18:21], v[152:155], v[140:143], v[18:21]
	ds_read_b128 v[184:187], v234 offset:0
	v_mfma_f32_16x16x32_bf16 v[22:25], v[156:159], v[140:143], v[22:25]
	ds_read_b128 v[188:191], v234 offset:2048
	v_mfma_f32_16x16x32_bf16 v[26:29], v[160:163], v[140:143], v[26:29]
	ds_read_b128 v[192:195], v234 offset:4096
	v_mfma_f32_16x16x32_bf16 v[30:33], v[164:167], v[140:143], v[30:33]
	ds_read_b128 v[196:199], v234 offset:6144
	v_mfma_f32_16x16x32_bf16 v[34:37], v[152:155], v[144:147], v[34:37]
	v_mfma_f32_16x16x32_bf16 v[38:41], v[156:159], v[144:147], v[38:41]
	v_mfma_f32_16x16x32_bf16 v[42:45], v[160:163], v[144:147], v[42:45]
	v_mfma_f32_16x16x32_bf16 v[46:49], v[164:167], v[144:147], v[46:49]
	v_mfma_f32_16x16x32_bf16 v[50:53], v[152:155], v[148:151], v[50:53]
	v_mfma_f32_16x16x32_bf16 v[54:57], v[156:159], v[148:151], v[54:57]
	v_mfma_f32_16x16x32_bf16 v[58:61], v[160:163], v[148:151], v[58:61]
	v_mfma_f32_16x16x32_bf16 v[62:65], v[164:167], v[148:151], v[62:65]
	s_waitcnt vmcnt(6) lgkmcnt(0)
	s_barrier
	v_mfma_f32_16x16x32_bf16 v[2:5], v[184:187], v[168:171], v[2:5]
	ds_read_b128 v[136:139], v224 offset:0
	v_mfma_f32_16x16x32_bf16 v[6:9], v[188:191], v[168:171], v[6:9]
	ds_read_b128 v[140:143], v224 offset:2048
	v_mfma_f32_16x16x32_bf16 v[10:13], v[192:195], v[168:171], v[10:13]
	ds_read_b128 v[144:147], v224 offset:4096
	v_mfma_f32_16x16x32_bf16 v[14:17], v[196:199], v[168:171], v[14:17]
	ds_read_b128 v[148:151], v224 offset:6144
	v_mfma_f32_16x16x32_bf16 v[18:21], v[184:187], v[172:175], v[18:21]
	ds_read_b128 v[152:155], v232 offset:0
	v_mfma_f32_16x16x32_bf16 v[22:25], v[188:191], v[172:175], v[22:25]
	ds_read_b128 v[156:159], v232 offset:2048
	v_mfma_f32_16x16x32_bf16 v[26:29], v[192:195], v[172:175], v[26:29]
	ds_read_b128 v[160:163], v232 offset:4096
	v_mfma_f32_16x16x32_bf16 v[30:33], v[196:199], v[172:175], v[30:33]
	ds_read_b128 v[164:167], v232 offset:6144
	s_add_u32 m0, s8, 0xc000
	v_mfma_f32_16x16x32_bf16 v[34:37], v[184:187], v[176:179], v[34:37]
	global_load_lds_dwordx4 v200, s[4:5]
	s_add_u32 m0, s8, 0xc400
	v_mfma_f32_16x16x32_bf16 v[38:41], v[188:191], v[176:179], v[38:41]
	global_load_lds_dwordx4 v201, s[4:5]
	s_add_u32 m0, s8, 0xc800
	v_mfma_f32_16x16x32_bf16 v[42:45], v[192:195], v[176:179], v[42:45]
	global_load_lds_dwordx4 v202, s[4:5]
	s_add_u32 m0, s8, 0xcc00
	v_mfma_f32_16x16x32_bf16 v[46:49], v[196:199], v[176:179], v[46:49]
	global_load_lds_dwordx4 v203, s[4:5]
	s_add_u32 m0, s9, 0xc000
	v_mfma_f32_16x16x32_bf16 v[50:53], v[184:187], v[180:183], v[50:53]
	global_load_lds_dwordx4 v204, s[6:7]
	s_add_u32 m0, s9, 0xc400
	v_mfma_f32_16x16x32_bf16 v[54:57], v[188:191], v[180:183], v[54:57]
	global_load_lds_dwordx4 v205, s[6:7]
	v_mfma_f32_16x16x32_bf16 v[58:61], v[192:195], v[180:183], v[58:61]
	s_add_u32 s4, s4, 0x80
	s_addc_u32 s5, s5, 0
	v_mfma_f32_16x16x32_bf16 v[62:65], v[196:199], v[180:183], v[62:65]
	s_add_u32 s6, s6, 0x80
	s_addc_u32 s7, s7, 0
	s_waitcnt lgkmcnt(0)
	v_mfma_f32_16x16x32_bf16 v[2:5], v[152:155], v[136:139], v[2:5]
	ds_read_b128 v[168:171], v229 offset:0
	v_mfma_f32_16x16x32_bf16 v[6:9], v[156:159], v[136:139], v[6:9]
	ds_read_b128 v[172:175], v229 offset:2048
	v_mfma_f32_16x16x32_bf16 v[10:13], v[160:163], v[136:139], v[10:13]
	ds_read_b128 v[176:179], v229 offset:4096
	v_mfma_f32_16x16x32_bf16 v[14:17], v[164:167], v[136:139], v[14:17]
	ds_read_b128 v[180:183], v229 offset:6144
	v_mfma_f32_16x16x32_bf16 v[18:21], v[152:155], v[140:143], v[18:21]
	ds_read_b128 v[184:187], v235 offset:0
	v_mfma_f32_16x16x32_bf16 v[22:25], v[156:159], v[140:143], v[22:25]
	ds_read_b128 v[188:191], v235 offset:2048
	v_mfma_f32_16x16x32_bf16 v[26:29], v[160:163], v[140:143], v[26:29]
	ds_read_b128 v[192:195], v235 offset:4096
	v_mfma_f32_16x16x32_bf16 v[30:33], v[164:167], v[140:143], v[30:33]
	ds_read_b128 v[196:199], v235 offset:6144
	v_mfma_f32_16x16x32_bf16 v[34:37], v[152:155], v[144:147], v[34:37]
	v_mfma_f32_16x16x32_bf16 v[38:41], v[156:159], v[144:147], v[38:41]
	v_mfma_f32_16x16x32_bf16 v[42:45], v[160:163], v[144:147], v[42:45]
	v_mfma_f32_16x16x32_bf16 v[46:49], v[164:167], v[144:147], v[46:49]
	v_mfma_f32_16x16x32_bf16 v[50:53], v[152:155], v[148:151], v[50:53]
	v_mfma_f32_16x16x32_bf16 v[54:57], v[156:159], v[148:151], v[54:57]
	v_mfma_f32_16x16x32_bf16 v[58:61], v[160:163], v[148:151], v[58:61]
	v_mfma_f32_16x16x32_bf16 v[62:65], v[164:167], v[148:151], v[62:65]
	s_waitcnt vmcnt(6) lgkmcnt(0)
	s_barrier
	v_mfma_f32_16x16x32_bf16 v[2:5], v[184:187], v[168:171], v[2:5]
	ds_read_b128 v[136:139], v218 offset:0
	v_mfma_f32_16x16x32_bf16 v[6:9], v[188:191], v[168:171], v[6:9]
	ds_read_b128 v[140:143], v218 offset:2048
	v_mfma_f32_16x16x32_bf16 v[10:13], v[192:195], v[168:171], v[10:13]
	ds_read_b128 v[144:147], v218 offset:4096
	v_mfma_f32_16x16x32_bf16 v[14:17], v[196:199], v[168:171], v[14:17]
	ds_read_b128 v[148:151], v218 offset:6144
	v_mfma_f32_16x16x32_bf16 v[18:21], v[184:187], v[172:175], v[18:21]
	ds_read_b128 v[152:155], v230 offset:0
	v_mfma_f32_16x16x32_bf16 v[22:25], v[188:191], v[172:175], v[22:25]
	ds_read_b128 v[156:159], v230 offset:2048
	v_mfma_f32_16x16x32_bf16 v[26:29], v[192:195], v[172:175], v[26:29]
	ds_read_b128 v[160:163], v230 offset:4096
	v_mfma_f32_16x16x32_bf16 v[30:33], v[196:199], v[172:175], v[30:33]
	ds_read_b128 v[164:167], v230 offset:6144
	s_add_u32 m0, s8, 0x18000
	v_mfma_f32_16x16x32_bf16 v[34:37], v[184:187], v[176:179], v[34:37]
	global_load_lds_dwordx4 v200, s[4:5]
	s_add_u32 m0, s8, 0x18400
	v_mfma_f32_16x16x32_bf16 v[38:41], v[188:191], v[176:179], v[38:41]
	global_load_lds_dwordx4 v201, s[4:5]
	s_add_u32 m0, s8, 0x18800
	v_mfma_f32_16x16x32_bf16 v[42:45], v[192:195], v[176:179], v[42:45]
	global_load_lds_dwordx4 v202, s[4:5]
	s_add_u32 m0, s8, 0x18c00
	v_mfma_f32_16x16x32_bf16 v[46:49], v[196:199], v[176:179], v[46:49]
	global_load_lds_dwordx4 v203, s[4:5]
	s_add_u32 m0, s9, 0x18000
	v_mfma_f32_16x16x32_bf16 v[50:53], v[184:187], v[180:183], v[50:53]
	global_load_lds_dwordx4 v204, s[6:7]
	s_add_u32 m0, s9, 0x18400
	v_mfma_f32_16x16x32_bf16 v[54:57], v[188:191], v[180:183], v[54:57]
	global_load_lds_dwordx4 v205, s[6:7]
	v_mfma_f32_16x16x32_bf16 v[58:61], v[192:195], v[180:183], v[58:61]
	s_add_u32 s4, s4, 0x80
	s_addc_u32 s5, s5, 0
	v_mfma_f32_16x16x32_bf16 v[62:65], v[196:199], v[180:183], v[62:65]
	s_add_u32 s6, s6, 0x80
	s_addc_u32 s7, s7, 0
	s_waitcnt lgkmcnt(0)
	v_mfma_f32_16x16x32_bf16 v[2:5], v[152:155], v[136:139], v[2:5]
	ds_read_b128 v[168:171], v225 offset:0
	v_mfma_f32_16x16x32_bf16 v[6:9], v[156:159], v[136:139], v[6:9]
	ds_read_b128 v[172:175], v225 offset:2048
	v_mfma_f32_16x16x32_bf16 v[10:13], v[160:163], v[136:139], v[10:13]
	ds_read_b128 v[176:179], v225 offset:4096
	v_mfma_f32_16x16x32_bf16 v[14:17], v[164:167], v[136:139], v[14:17]
	ds_read_b128 v[180:183], v225 offset:6144
	v_mfma_f32_16x16x32_bf16 v[18:21], v[152:155], v[140:143], v[18:21]
	ds_read_b128 v[184:187], v233 offset:0
	v_mfma_f32_16x16x32_bf16 v[22:25], v[156:159], v[140:143], v[22:25]
	ds_read_b128 v[188:191], v233 offset:2048
	v_mfma_f32_16x16x32_bf16 v[26:29], v[160:163], v[140:143], v[26:29]
	ds_read_b128 v[192:195], v233 offset:4096
	v_mfma_f32_16x16x32_bf16 v[30:33], v[164:167], v[140:143], v[30:33]
	ds_read_b128 v[196:199], v233 offset:6144
	v_mfma_f32_16x16x32_bf16 v[34:37], v[152:155], v[144:147], v[34:37]
	v_mfma_f32_16x16x32_bf16 v[38:41], v[156:159], v[144:147], v[38:41]
	v_mfma_f32_16x16x32_bf16 v[42:45], v[160:163], v[144:147], v[42:45]
	v_mfma_f32_16x16x32_bf16 v[46:49], v[164:167], v[144:147], v[46:49]
	v_mfma_f32_16x16x32_bf16 v[50:53], v[152:155], v[148:151], v[50:53]
	v_mfma_f32_16x16x32_bf16 v[54:57], v[156:159], v[148:151], v[54:57]
	v_mfma_f32_16x16x32_bf16 v[58:61], v[160:163], v[148:151], v[58:61]
	v_mfma_f32_16x16x32_bf16 v[62:65], v[164:167], v[148:151], v[62:65]
	s_waitcnt vmcnt(6) lgkmcnt(0)
	s_barrier
	v_mfma_f32_16x16x32_bf16 v[2:5], v[184:187], v[168:171], v[2:5]
	ds_read_b128 v[136:139], v219 offset:0
	v_mfma_f32_16x16x32_bf16 v[6:9], v[188:191], v[168:171], v[6:9]
	ds_read_b128 v[140:143], v219 offset:2048
	v_mfma_f32_16x16x32_bf16 v[10:13], v[192:195], v[168:171], v[10:13]
	ds_read_b128 v[144:147], v219 offset:4096
	v_mfma_f32_16x16x32_bf16 v[14:17], v[196:199], v[168:171], v[14:17]
	ds_read_b128 v[148:151], v219 offset:6144
	v_mfma_f32_16x16x32_bf16 v[18:21], v[184:187], v[172:175], v[18:21]
	ds_read_b128 v[152:155], v231 offset:0
	v_mfma_f32_16x16x32_bf16 v[22:25], v[188:191], v[172:175], v[22:25]
	ds_read_b128 v[156:159], v231 offset:2048
	v_mfma_f32_16x16x32_bf16 v[26:29], v[192:195], v[172:175], v[26:29]
	ds_read_b128 v[160:163], v231 offset:4096
	v_mfma_f32_16x16x32_bf16 v[30:33], v[196:199], v[172:175], v[30:33]
	ds_read_b128 v[164:167], v231 offset:6144
	s_mov_b32 m0, s8
	v_mfma_f32_16x16x32_bf16 v[34:37], v[184:187], v[176:179], v[34:37]
	global_load_lds_dwordx4 v200, s[4:5]
	s_add_u32 m0, s8, 0x400
	v_mfma_f32_16x16x32_bf16 v[38:41], v[188:191], v[176:179], v[38:41]
	global_load_lds_dwordx4 v201, s[4:5]
	s_add_u32 m0, s8, 0x800
	v_mfma_f32_16x16x32_bf16 v[42:45], v[192:195], v[176:179], v[42:45]
	global_load_lds_dwordx4 v202, s[4:5]
	s_add_u32 m0, s8, 0xc00
	v_mfma_f32_16x16x32_bf16 v[46:49], v[196:199], v[176:179], v[46:49]
	global_load_lds_dwordx4 v203, s[4:5]
	s_mov_b32 m0, s9
	v_mfma_f32_16x16x32_bf16 v[50:53], v[184:187], v[180:183], v[50:53]
	global_load_lds_dwordx4 v204, s[6:7]
	s_add_u32 m0, s9, 0x400
	v_mfma_f32_16x16x32_bf16 v[54:57], v[188:191], v[180:183], v[54:57]
	global_load_lds_dwordx4 v205, s[6:7]
	v_mfma_f32_16x16x32_bf16 v[58:61], v[192:195], v[180:183], v[58:61]
	s_add_u32 s4, s4, 0x80
	s_addc_u32 s5, s5, 0
	v_mfma_f32_16x16x32_bf16 v[62:65], v[196:199], v[180:183], v[62:65]
	s_add_u32 s6, s6, 0x80
	s_addc_u32 s7, s7, 0
	s_waitcnt lgkmcnt(0)
	v_mfma_f32_16x16x32_bf16 v[2:5], v[152:155], v[136:139], v[2:5]
	ds_read_b128 v[168:171], v228 offset:0
	v_mfma_f32_16x16x32_bf16 v[6:9], v[156:159], v[136:139], v[6:9]
	ds_read_b128 v[172:175], v228 offset:2048
	v_mfma_f32_16x16x32_bf16 v[10:13], v[160:163], v[136:139], v[10:13]
	ds_read_b128 v[176:179], v228 offset:4096
	v_mfma_f32_16x16x32_bf16 v[14:17], v[164:167], v[136:139], v[14:17]
	ds_read_b128 v[180:183], v228 offset:6144
	v_mfma_f32_16x16x32_bf16 v[18:21], v[152:155], v[140:143], v[18:21]
	ds_read_b128 v[184:187], v234 offset:0
	v_mfma_f32_16x16x32_bf16 v[22:25], v[156:159], v[140:143], v[22:25]
	ds_read_b128 v[188:191], v234 offset:2048
	v_mfma_f32_16x16x32_bf16 v[26:29], v[160:163], v[140:143], v[26:29]
	ds_read_b128 v[192:195], v234 offset:4096
	v_mfma_f32_16x16x32_bf16 v[30:33], v[164:167], v[140:143], v[30:33]
	ds_read_b128 v[196:199], v234 offset:6144
	v_mfma_f32_16x16x32_bf16 v[34:37], v[152:155], v[144:147], v[34:37]
	v_mfma_f32_16x16x32_bf16 v[38:41], v[156:159], v[144:147], v[38:41]
	v_mfma_f32_16x16x32_bf16 v[42:45], v[160:163], v[144:147], v[42:45]
	v_mfma_f32_16x16x32_bf16 v[46:49], v[164:167], v[144:147], v[46:49]
	v_mfma_f32_16x16x32_bf16 v[50:53], v[152:155], v[148:151], v[50:53]
	v_mfma_f32_16x16x32_bf16 v[54:57], v[156:159], v[148:151], v[54:57]
	v_mfma_f32_16x16x32_bf16 v[58:61], v[160:163], v[148:151], v[58:61]
	v_mfma_f32_16x16x32_bf16 v[62:65], v[164:167], v[148:151], v[62:65]
	s_waitcnt vmcnt(6) lgkmcnt(0)
	s_barrier
	v_mfma_f32_16x16x32_bf16 v[2:5], v[184:187], v[168:171], v[2:5]
	ds_read_b128 v[136:139], v224 offset:0
	v_mfma_f32_16x16x32_bf16 v[6:9], v[188:191], v[168:171], v[6:9]
	ds_read_b128 v[140:143], v224 offset:2048
	v_mfma_f32_16x16x32_bf16 v[10:13], v[192:195], v[168:171], v[10:13]
	ds_read_b128 v[144:147], v224 offset:4096
	v_mfma_f32_16x16x32_bf16 v[14:17], v[196:199], v[168:171], v[14:17]
	ds_read_b128 v[148:151], v224 offset:6144
	v_mfma_f32_16x16x32_bf16 v[18:21], v[184:187], v[172:175], v[18:21]
	ds_read_b128 v[152:155], v232 offset:0
	v_mfma_f32_16x16x32_bf16 v[22:25], v[188:191], v[172:175], v[22:25]
	ds_read_b128 v[156:159], v232 offset:2048
	v_mfma_f32_16x16x32_bf16 v[26:29], v[192:195], v[172:175], v[26:29]
	ds_read_b128 v[160:163], v232 offset:4096
	v_mfma_f32_16x16x32_bf16 v[30:33], v[196:199], v[172:175], v[30:33]
	ds_read_b128 v[164:167], v232 offset:6144
	s_add_u32 m0, s8, 0xc000
	v_mfma_f32_16x16x32_bf16 v[34:37], v[184:187], v[176:179], v[34:37]
	global_load_lds_dwordx4 v200, s[4:5]
	s_add_u32 m0, s8, 0xc400
	v_mfma_f32_16x16x32_bf16 v[38:41], v[188:191], v[176:179], v[38:41]
	global_load_lds_dwordx4 v201, s[4:5]
	s_add_u32 m0, s8, 0xc800
	v_mfma_f32_16x16x32_bf16 v[42:45], v[192:195], v[176:179], v[42:45]
	global_load_lds_dwordx4 v202, s[4:5]
	s_add_u32 m0, s8, 0xcc00
	v_mfma_f32_16x16x32_bf16 v[46:49], v[196:199], v[176:179], v[46:49]
	global_load_lds_dwordx4 v203, s[4:5]
	s_add_u32 m0, s9, 0xc000
	v_mfma_f32_16x16x32_bf16 v[50:53], v[184:187], v[180:183], v[50:53]
	global_load_lds_dwordx4 v204, s[6:7]
	s_add_u32 m0, s9, 0xc400
	v_mfma_f32_16x16x32_bf16 v[54:57], v[188:191], v[180:183], v[54:57]
	global_load_lds_dwordx4 v205, s[6:7]
	v_mfma_f32_16x16x32_bf16 v[58:61], v[192:195], v[180:183], v[58:61]
	s_add_u32 s4, s4, 0x80
	s_addc_u32 s5, s5, 0
	v_mfma_f32_16x16x32_bf16 v[62:65], v[196:199], v[180:183], v[62:65]
	s_add_u32 s6, s6, 0x80
	s_addc_u32 s7, s7, 0
	s_waitcnt lgkmcnt(0)
	v_mfma_f32_16x16x32_bf16 v[2:5], v[152:155], v[136:139], v[2:5]
	ds_read_b128 v[168:171], v229 offset:0
	v_mfma_f32_16x16x32_bf16 v[6:9], v[156:159], v[136:139], v[6:9]
	ds_read_b128 v[172:175], v229 offset:2048
	v_mfma_f32_16x16x32_bf16 v[10:13], v[160:163], v[136:139], v[10:13]
	ds_read_b128 v[176:179], v229 offset:4096
	v_mfma_f32_16x16x32_bf16 v[14:17], v[164:167], v[136:139], v[14:17]
	ds_read_b128 v[180:183], v229 offset:6144
	v_mfma_f32_16x16x32_bf16 v[18:21], v[152:155], v[140:143], v[18:21]
	ds_read_b128 v[184:187], v235 offset:0
	v_mfma_f32_16x16x32_bf16 v[22:25], v[156:159], v[140:143], v[22:25]
	ds_read_b128 v[188:191], v235 offset:2048
	v_mfma_f32_16x16x32_bf16 v[26:29], v[160:163], v[140:143], v[26:29]
	ds_read_b128 v[192:195], v235 offset:4096
	v_mfma_f32_16x16x32_bf16 v[30:33], v[164:167], v[140:143], v[30:33]
	ds_read_b128 v[196:199], v235 offset:6144
	v_mfma_f32_16x16x32_bf16 v[34:37], v[152:155], v[144:147], v[34:37]
	v_mfma_f32_16x16x32_bf16 v[38:41], v[156:159], v[144:147], v[38:41]
	v_mfma_f32_16x16x32_bf16 v[42:45], v[160:163], v[144:147], v[42:45]
	v_mfma_f32_16x16x32_bf16 v[46:49], v[164:167], v[144:147], v[46:49]
	v_mfma_f32_16x16x32_bf16 v[50:53], v[152:155], v[148:151], v[50:53]
	v_mfma_f32_16x16x32_bf16 v[54:57], v[156:159], v[148:151], v[54:57]
	v_mfma_f32_16x16x32_bf16 v[58:61], v[160:163], v[148:151], v[58:61]
	v_mfma_f32_16x16x32_bf16 v[62:65], v[164:167], v[148:151], v[62:65]
	s_waitcnt vmcnt(6) lgkmcnt(0)
	s_barrier
	v_mfma_f32_16x16x32_bf16 v[2:5], v[184:187], v[168:171], v[2:5]
	ds_read_b128 v[136:139], v218 offset:0
	v_mfma_f32_16x16x32_bf16 v[6:9], v[188:191], v[168:171], v[6:9]
	ds_read_b128 v[140:143], v218 offset:2048
	v_mfma_f32_16x16x32_bf16 v[10:13], v[192:195], v[168:171], v[10:13]
	ds_read_b128 v[144:147], v218 offset:4096
	v_mfma_f32_16x16x32_bf16 v[14:17], v[196:199], v[168:171], v[14:17]
	ds_read_b128 v[148:151], v218 offset:6144
	v_mfma_f32_16x16x32_bf16 v[18:21], v[184:187], v[172:175], v[18:21]
	ds_read_b128 v[152:155], v230 offset:0
	v_mfma_f32_16x16x32_bf16 v[22:25], v[188:191], v[172:175], v[22:25]
	ds_read_b128 v[156:159], v230 offset:2048
	v_mfma_f32_16x16x32_bf16 v[26:29], v[192:195], v[172:175], v[26:29]
	ds_read_b128 v[160:163], v230 offset:4096
	v_mfma_f32_16x16x32_bf16 v[30:33], v[196:199], v[172:175], v[30:33]
	ds_read_b128 v[164:167], v230 offset:6144
	s_add_u32 m0, s8, 0x18000
	v_mfma_f32_16x16x32_bf16 v[34:37], v[184:187], v[176:179], v[34:37]
	global_load_lds_dwordx4 v200, s[4:5]
	s_add_u32 m0, s8, 0x18400
	v_mfma_f32_16x16x32_bf16 v[38:41], v[188:191], v[176:179], v[38:41]
	global_load_lds_dwordx4 v201, s[4:5]
	s_add_u32 m0, s8, 0x18800
	v_mfma_f32_16x16x32_bf16 v[42:45], v[192:195], v[176:179], v[42:45]
	global_load_lds_dwordx4 v202, s[4:5]
	s_add_u32 m0, s8, 0x18c00
	v_mfma_f32_16x16x32_bf16 v[46:49], v[196:199], v[176:179], v[46:49]
	global_load_lds_dwordx4 v203, s[4:5]
	s_add_u32 m0, s9, 0x18000
	v_mfma_f32_16x16x32_bf16 v[50:53], v[184:187], v[180:183], v[50:53]
	global_load_lds_dwordx4 v204, s[6:7]
	s_add_u32 m0, s9, 0x18400
	v_mfma_f32_16x16x32_bf16 v[54:57], v[188:191], v[180:183], v[54:57]
	global_load_lds_dwordx4 v205, s[6:7]
	v_mfma_f32_16x16x32_bf16 v[58:61], v[192:195], v[180:183], v[58:61]
	s_add_u32 s4, s4, 0x80
	s_addc_u32 s5, s5, 0
	v_mfma_f32_16x16x32_bf16 v[62:65], v[196:199], v[180:183], v[62:65]
	s_add_u32 s6, s6, 0x80
	s_addc_u32 s7, s7, 0
	s_waitcnt lgkmcnt(0)
	v_mfma_f32_16x16x32_bf16 v[2:5], v[152:155], v[136:139], v[2:5]
	ds_read_b128 v[168:171], v225 offset:0
	v_mfma_f32_16x16x32_bf16 v[6:9], v[156:159], v[136:139], v[6:9]
	ds_read_b128 v[172:175], v225 offset:2048
	v_mfma_f32_16x16x32_bf16 v[10:13], v[160:163], v[136:139], v[10:13]
	ds_read_b128 v[176:179], v225 offset:4096
	v_mfma_f32_16x16x32_bf16 v[14:17], v[164:167], v[136:139], v[14:17]
	ds_read_b128 v[180:183], v225 offset:6144
	v_mfma_f32_16x16x32_bf16 v[18:21], v[152:155], v[140:143], v[18:21]
	ds_read_b128 v[184:187], v233 offset:0
	v_mfma_f32_16x16x32_bf16 v[22:25], v[156:159], v[140:143], v[22:25]
	ds_read_b128 v[188:191], v233 offset:2048
	v_mfma_f32_16x16x32_bf16 v[26:29], v[160:163], v[140:143], v[26:29]
	ds_read_b128 v[192:195], v233 offset:4096
	v_mfma_f32_16x16x32_bf16 v[30:33], v[164:167], v[140:143], v[30:33]
	ds_read_b128 v[196:199], v233 offset:6144
	v_mfma_f32_16x16x32_bf16 v[34:37], v[152:155], v[144:147], v[34:37]
	v_mfma_f32_16x16x32_bf16 v[38:41], v[156:159], v[144:147], v[38:41]
	v_mfma_f32_16x16x32_bf16 v[42:45], v[160:163], v[144:147], v[42:45]
	v_mfma_f32_16x16x32_bf16 v[46:49], v[164:167], v[144:147], v[46:49]
	v_mfma_f32_16x16x32_bf16 v[50:53], v[152:155], v[148:151], v[50:53]
	v_mfma_f32_16x16x32_bf16 v[54:57], v[156:159], v[148:151], v[54:57]
	v_mfma_f32_16x16x32_bf16 v[58:61], v[160:163], v[148:151], v[58:61]
	v_mfma_f32_16x16x32_bf16 v[62:65], v[164:167], v[148:151], v[62:65]
	s_waitcnt vmcnt(6) lgkmcnt(0)
	s_barrier
	v_mfma_f32_16x16x32_bf16 v[2:5], v[184:187], v[168:171], v[2:5]
	ds_read_b128 v[136:139], v219 offset:0
	v_mfma_f32_16x16x32_bf16 v[6:9], v[188:191], v[168:171], v[6:9]
	ds_read_b128 v[140:143], v219 offset:2048
	v_mfma_f32_16x16x32_bf16 v[10:13], v[192:195], v[168:171], v[10:13]
	ds_read_b128 v[144:147], v219 offset:4096
	v_mfma_f32_16x16x32_bf16 v[14:17], v[196:199], v[168:171], v[14:17]
	ds_read_b128 v[148:151], v219 offset:6144
	v_mfma_f32_16x16x32_bf16 v[18:21], v[184:187], v[172:175], v[18:21]
	ds_read_b128 v[152:155], v231 offset:0
	v_mfma_f32_16x16x32_bf16 v[22:25], v[188:191], v[172:175], v[22:25]
	ds_read_b128 v[156:159], v231 offset:2048
	v_mfma_f32_16x16x32_bf16 v[26:29], v[192:195], v[172:175], v[26:29]
	ds_read_b128 v[160:163], v231 offset:4096
	v_mfma_f32_16x16x32_bf16 v[30:33], v[196:199], v[172:175], v[30:33]
	ds_read_b128 v[164:167], v231 offset:6144
	s_mov_b32 m0, s8
	v_mfma_f32_16x16x32_bf16 v[34:37], v[184:187], v[176:179], v[34:37]
	global_load_lds_dwordx4 v200, s[4:5]
	s_add_u32 m0, s8, 0x400
	v_mfma_f32_16x16x32_bf16 v[38:41], v[188:191], v[176:179], v[38:41]
	global_load_lds_dwordx4 v201, s[4:5]
	s_add_u32 m0, s8, 0x800
	v_mfma_f32_16x16x32_bf16 v[42:45], v[192:195], v[176:179], v[42:45]
	global_load_lds_dwordx4 v202, s[4:5]
	s_add_u32 m0, s8, 0xc00
	v_mfma_f32_16x16x32_bf16 v[46:49], v[196:199], v[176:179], v[46:49]
	global_load_lds_dwordx4 v203, s[4:5]
	s_mov_b32 m0, s9
	v_mfma_f32_16x16x32_bf16 v[50:53], v[184:187], v[180:183], v[50:53]
	global_load_lds_dwordx4 v204, s[6:7]
	s_add_u32 m0, s9, 0x400
	v_mfma_f32_16x16x32_bf16 v[54:57], v[188:191], v[180:183], v[54:57]
	global_load_lds_dwordx4 v205, s[6:7]
	v_mfma_f32_16x16x32_bf16 v[58:61], v[192:195], v[180:183], v[58:61]
	s_sub_u32 s4, s4, 0x780
	s_subb_u32 s5, s5, 0
	v_mfma_f32_16x16x32_bf16 v[62:65], v[196:199], v[180:183], v[62:65]
	s_add_u32 s6, s6, 0x3f880
	s_addc_u32 s7, s7, 0
	s_waitcnt lgkmcnt(0)
	v_mfma_f32_16x16x32_bf16 v[2:5], v[152:155], v[136:139], v[2:5]
	ds_read_b128 v[168:171], v228 offset:0
	v_mfma_f32_16x16x32_bf16 v[6:9], v[156:159], v[136:139], v[6:9]
	ds_read_b128 v[172:175], v228 offset:2048
	v_mfma_f32_16x16x32_bf16 v[10:13], v[160:163], v[136:139], v[10:13]
	ds_read_b128 v[176:179], v228 offset:4096
	v_mfma_f32_16x16x32_bf16 v[14:17], v[164:167], v[136:139], v[14:17]
	ds_read_b128 v[180:183], v228 offset:6144
	v_mfma_f32_16x16x32_bf16 v[18:21], v[152:155], v[140:143], v[18:21]
	ds_read_b128 v[184:187], v234 offset:0
	v_mfma_f32_16x16x32_bf16 v[22:25], v[156:159], v[140:143], v[22:25]
	ds_read_b128 v[188:191], v234 offset:2048
	v_mfma_f32_16x16x32_bf16 v[26:29], v[160:163], v[140:143], v[26:29]
	ds_read_b128 v[192:195], v234 offset:4096
	v_mfma_f32_16x16x32_bf16 v[30:33], v[164:167], v[140:143], v[30:33]
	ds_read_b128 v[196:199], v234 offset:6144
	v_mfma_f32_16x16x32_bf16 v[34:37], v[152:155], v[144:147], v[34:37]
	v_mfma_f32_16x16x32_bf16 v[38:41], v[156:159], v[144:147], v[38:41]
	v_mfma_f32_16x16x32_bf16 v[42:45], v[160:163], v[144:147], v[42:45]
	v_mfma_f32_16x16x32_bf16 v[46:49], v[164:167], v[144:147], v[46:49]
	v_mfma_f32_16x16x32_bf16 v[50:53], v[152:155], v[148:151], v[50:53]
	v_mfma_f32_16x16x32_bf16 v[54:57], v[156:159], v[148:151], v[54:57]
	v_mfma_f32_16x16x32_bf16 v[58:61], v[160:163], v[148:151], v[58:61]
	v_mfma_f32_16x16x32_bf16 v[62:65], v[164:167], v[148:151], v[62:65]
	s_waitcnt vmcnt(6) lgkmcnt(0)
	s_barrier
	v_mfma_f32_16x16x32_bf16 v[2:5], v[184:187], v[168:171], v[2:5]
	ds_read_b128 v[136:139], v224 offset:0
	v_mfma_f32_16x16x32_bf16 v[6:9], v[188:191], v[168:171], v[6:9]
	ds_read_b128 v[140:143], v224 offset:2048
	v_mfma_f32_16x16x32_bf16 v[10:13], v[192:195], v[168:171], v[10:13]
	ds_read_b128 v[144:147], v224 offset:4096
	v_mfma_f32_16x16x32_bf16 v[14:17], v[196:199], v[168:171], v[14:17]
	ds_read_b128 v[148:151], v224 offset:6144
	v_mfma_f32_16x16x32_bf16 v[18:21], v[184:187], v[172:175], v[18:21]
	ds_read_b128 v[152:155], v232 offset:0
	v_mfma_f32_16x16x32_bf16 v[22:25], v[188:191], v[172:175], v[22:25]
	ds_read_b128 v[156:159], v232 offset:2048
	v_mfma_f32_16x16x32_bf16 v[26:29], v[192:195], v[172:175], v[26:29]
	ds_read_b128 v[160:163], v232 offset:4096
	v_mfma_f32_16x16x32_bf16 v[30:33], v[196:199], v[172:175], v[30:33]
	ds_read_b128 v[164:167], v232 offset:6144
	s_add_u32 m0, s8, 0xc000
	v_mfma_f32_16x16x32_bf16 v[34:37], v[184:187], v[176:179], v[34:37]
	global_load_lds_dwordx4 v200, s[4:5]
	s_add_u32 m0, s8, 0xc400
	v_mfma_f32_16x16x32_bf16 v[38:41], v[188:191], v[176:179], v[38:41]
	global_load_lds_dwordx4 v201, s[4:5]
	s_add_u32 m0, s8, 0xc800
	v_mfma_f32_16x16x32_bf16 v[42:45], v[192:195], v[176:179], v[42:45]
	global_load_lds_dwordx4 v202, s[4:5]
	s_add_u32 m0, s8, 0xcc00
	v_mfma_f32_16x16x32_bf16 v[46:49], v[196:199], v[176:179], v[46:49]
	global_load_lds_dwordx4 v203, s[4:5]
	s_add_u32 m0, s9, 0xc000
	v_mfma_f32_16x16x32_bf16 v[50:53], v[184:187], v[180:183], v[50:53]
	global_load_lds_dwordx4 v204, s[6:7]
	s_add_u32 m0, s9, 0xc400
	v_mfma_f32_16x16x32_bf16 v[54:57], v[188:191], v[180:183], v[54:57]
	global_load_lds_dwordx4 v205, s[6:7]
	v_mfma_f32_16x16x32_bf16 v[58:61], v[192:195], v[180:183], v[58:61]
	s_add_u32 s4, s4, 0x80
	s_addc_u32 s5, s5, 0
	v_mfma_f32_16x16x32_bf16 v[62:65], v[196:199], v[180:183], v[62:65]
	s_add_u32 s6, s6, 0x80
	s_addc_u32 s7, s7, 0
	s_waitcnt lgkmcnt(0)
	v_mfma_f32_16x16x32_bf16 v[2:5], v[152:155], v[136:139], v[2:5]
	ds_read_b128 v[168:171], v229 offset:0
	v_mfma_f32_16x16x32_bf16 v[6:9], v[156:159], v[136:139], v[6:9]
	ds_read_b128 v[172:175], v229 offset:2048
	v_mfma_f32_16x16x32_bf16 v[10:13], v[160:163], v[136:139], v[10:13]
	ds_read_b128 v[176:179], v229 offset:4096
	v_mfma_f32_16x16x32_bf16 v[14:17], v[164:167], v[136:139], v[14:17]
	ds_read_b128 v[180:183], v229 offset:6144
	v_mfma_f32_16x16x32_bf16 v[18:21], v[152:155], v[140:143], v[18:21]
	ds_read_b128 v[184:187], v235 offset:0
	v_mfma_f32_16x16x32_bf16 v[22:25], v[156:159], v[140:143], v[22:25]
	ds_read_b128 v[188:191], v235 offset:2048
	v_mfma_f32_16x16x32_bf16 v[26:29], v[160:163], v[140:143], v[26:29]
	ds_read_b128 v[192:195], v235 offset:4096
	v_mfma_f32_16x16x32_bf16 v[30:33], v[164:167], v[140:143], v[30:33]
	ds_read_b128 v[196:199], v235 offset:6144
	v_mfma_f32_16x16x32_bf16 v[34:37], v[152:155], v[144:147], v[34:37]
	v_mfma_f32_16x16x32_bf16 v[38:41], v[156:159], v[144:147], v[38:41]
	v_mfma_f32_16x16x32_bf16 v[42:45], v[160:163], v[144:147], v[42:45]
	v_mfma_f32_16x16x32_bf16 v[46:49], v[164:167], v[144:147], v[46:49]
	v_mfma_f32_16x16x32_bf16 v[50:53], v[152:155], v[148:151], v[50:53]
	v_mfma_f32_16x16x32_bf16 v[54:57], v[156:159], v[148:151], v[54:57]
	v_mfma_f32_16x16x32_bf16 v[58:61], v[160:163], v[148:151], v[58:61]
	v_mfma_f32_16x16x32_bf16 v[62:65], v[164:167], v[148:151], v[62:65]
	s_waitcnt vmcnt(6) lgkmcnt(0)
	s_barrier
	v_mfma_f32_16x16x32_bf16 v[2:5], v[184:187], v[168:171], v[2:5]
	ds_read_b128 v[136:139], v218 offset:0
	v_mfma_f32_16x16x32_bf16 v[6:9], v[188:191], v[168:171], v[6:9]
	ds_read_b128 v[140:143], v218 offset:2048
	v_mfma_f32_16x16x32_bf16 v[10:13], v[192:195], v[168:171], v[10:13]
	ds_read_b128 v[144:147], v218 offset:4096
	v_mfma_f32_16x16x32_bf16 v[14:17], v[196:199], v[168:171], v[14:17]
	ds_read_b128 v[148:151], v218 offset:6144
	v_mfma_f32_16x16x32_bf16 v[18:21], v[184:187], v[172:175], v[18:21]
	ds_read_b128 v[152:155], v230 offset:0
	v_mfma_f32_16x16x32_bf16 v[22:25], v[188:191], v[172:175], v[22:25]
	ds_read_b128 v[156:159], v230 offset:2048
	v_mfma_f32_16x16x32_bf16 v[26:29], v[192:195], v[172:175], v[26:29]
	ds_read_b128 v[160:163], v230 offset:4096
	v_mfma_f32_16x16x32_bf16 v[30:33], v[196:199], v[172:175], v[30:33]
	ds_read_b128 v[164:167], v230 offset:6144
	s_add_u32 m0, s8, 0x18000
	v_mfma_f32_16x16x32_bf16 v[34:37], v[184:187], v[176:179], v[34:37]
	global_load_lds_dwordx4 v200, s[4:5]
	s_add_u32 m0, s8, 0x18400
	v_mfma_f32_16x16x32_bf16 v[38:41], v[188:191], v[176:179], v[38:41]
	global_load_lds_dwordx4 v201, s[4:5]
	s_add_u32 m0, s8, 0x18800
	v_mfma_f32_16x16x32_bf16 v[42:45], v[192:195], v[176:179], v[42:45]
	global_load_lds_dwordx4 v202, s[4:5]
	s_add_u32 m0, s8, 0x18c00
	v_mfma_f32_16x16x32_bf16 v[46:49], v[196:199], v[176:179], v[46:49]
	global_load_lds_dwordx4 v203, s[4:5]
	s_add_u32 m0, s9, 0x18000
	v_mfma_f32_16x16x32_bf16 v[50:53], v[184:187], v[180:183], v[50:53]
	global_load_lds_dwordx4 v204, s[6:7]
	s_add_u32 m0, s9, 0x18400
	v_mfma_f32_16x16x32_bf16 v[54:57], v[188:191], v[180:183], v[54:57]
	global_load_lds_dwordx4 v205, s[6:7]
	v_mfma_f32_16x16x32_bf16 v[58:61], v[192:195], v[180:183], v[58:61]
	s_add_u32 s4, s4, 0x80
	s_addc_u32 s5, s5, 0
	v_mfma_f32_16x16x32_bf16 v[62:65], v[196:199], v[180:183], v[62:65]
	s_add_u32 s6, s6, 0x80
	s_addc_u32 s7, s7, 0
	s_waitcnt lgkmcnt(0)
	v_mfma_f32_16x16x32_bf16 v[2:5], v[152:155], v[136:139], v[2:5]
	ds_read_b128 v[168:171], v225 offset:0
	v_mfma_f32_16x16x32_bf16 v[6:9], v[156:159], v[136:139], v[6:9]
	ds_read_b128 v[172:175], v225 offset:2048
	v_mfma_f32_16x16x32_bf16 v[10:13], v[160:163], v[136:139], v[10:13]
	ds_read_b128 v[176:179], v225 offset:4096
	v_mfma_f32_16x16x32_bf16 v[14:17], v[164:167], v[136:139], v[14:17]
	ds_read_b128 v[180:183], v225 offset:6144
	v_mfma_f32_16x16x32_bf16 v[18:21], v[152:155], v[140:143], v[18:21]
	ds_read_b128 v[184:187], v233 offset:0
	v_mfma_f32_16x16x32_bf16 v[22:25], v[156:159], v[140:143], v[22:25]
	ds_read_b128 v[188:191], v233 offset:2048
	v_mfma_f32_16x16x32_bf16 v[26:29], v[160:163], v[140:143], v[26:29]
	ds_read_b128 v[192:195], v233 offset:4096
	v_mfma_f32_16x16x32_bf16 v[30:33], v[164:167], v[140:143], v[30:33]
	ds_read_b128 v[196:199], v233 offset:6144
	v_mfma_f32_16x16x32_bf16 v[34:37], v[152:155], v[144:147], v[34:37]
	v_mfma_f32_16x16x32_bf16 v[38:41], v[156:159], v[144:147], v[38:41]
	v_mfma_f32_16x16x32_bf16 v[42:45], v[160:163], v[144:147], v[42:45]
	v_mfma_f32_16x16x32_bf16 v[46:49], v[164:167], v[144:147], v[46:49]
	v_mfma_f32_16x16x32_bf16 v[50:53], v[152:155], v[148:151], v[50:53]
	v_mfma_f32_16x16x32_bf16 v[54:57], v[156:159], v[148:151], v[54:57]
	v_mfma_f32_16x16x32_bf16 v[58:61], v[160:163], v[148:151], v[58:61]
	v_mfma_f32_16x16x32_bf16 v[62:65], v[164:167], v[148:151], v[62:65]
	s_waitcnt vmcnt(6) lgkmcnt(0)
	s_barrier
	v_mfma_f32_16x16x32_bf16 v[2:5], v[184:187], v[168:171], v[2:5]
	ds_read_b128 v[136:139], v219 offset:0
	v_mfma_f32_16x16x32_bf16 v[6:9], v[188:191], v[168:171], v[6:9]
	ds_read_b128 v[140:143], v219 offset:2048
	v_mfma_f32_16x16x32_bf16 v[10:13], v[192:195], v[168:171], v[10:13]
	ds_read_b128 v[144:147], v219 offset:4096
	v_mfma_f32_16x16x32_bf16 v[14:17], v[196:199], v[168:171], v[14:17]
	ds_read_b128 v[148:151], v219 offset:6144
	v_mfma_f32_16x16x32_bf16 v[18:21], v[184:187], v[172:175], v[18:21]
	ds_read_b128 v[152:155], v231 offset:0
	v_mfma_f32_16x16x32_bf16 v[22:25], v[188:191], v[172:175], v[22:25]
	ds_read_b128 v[156:159], v231 offset:2048
	v_mfma_f32_16x16x32_bf16 v[26:29], v[192:195], v[172:175], v[26:29]
	ds_read_b128 v[160:163], v231 offset:4096
	v_mfma_f32_16x16x32_bf16 v[30:33], v[196:199], v[172:175], v[30:33]
	ds_read_b128 v[164:167], v231 offset:6144
	s_mov_b32 m0, s8
	v_mfma_f32_16x16x32_bf16 v[34:37], v[184:187], v[176:179], v[34:37]
	global_load_lds_dwordx4 v200, s[4:5]
	s_add_u32 m0, s8, 0x400
	v_mfma_f32_16x16x32_bf16 v[38:41], v[188:191], v[176:179], v[38:41]
	global_load_lds_dwordx4 v201, s[4:5]
	s_add_u32 m0, s8, 0x800
	v_mfma_f32_16x16x32_bf16 v[42:45], v[192:195], v[176:179], v[42:45]
	global_load_lds_dwordx4 v202, s[4:5]
	s_add_u32 m0, s8, 0xc00
	v_mfma_f32_16x16x32_bf16 v[46:49], v[196:199], v[176:179], v[46:49]
	global_load_lds_dwordx4 v203, s[4:5]
	s_mov_b32 m0, s9
	v_mfma_f32_16x16x32_bf16 v[50:53], v[184:187], v[180:183], v[50:53]
	global_load_lds_dwordx4 v204, s[6:7]
	s_add_u32 m0, s9, 0x400
	v_mfma_f32_16x16x32_bf16 v[54:57], v[188:191], v[180:183], v[54:57]
	global_load_lds_dwordx4 v205, s[6:7]
	v_mfma_f32_16x16x32_bf16 v[58:61], v[192:195], v[180:183], v[58:61]
	s_add_u32 s4, s4, 0x80
	s_addc_u32 s5, s5, 0
	v_mfma_f32_16x16x32_bf16 v[62:65], v[196:199], v[180:183], v[62:65]
	s_add_u32 s6, s6, 0x80
	s_addc_u32 s7, s7, 0
	s_waitcnt lgkmcnt(0)
	v_mfma_f32_16x16x32_bf16 v[66:69], v[152:155], v[136:139], 0
	ds_read_b128 v[168:171], v228 offset:0
	v_mfma_f32_16x16x32_bf16 v[70:73], v[156:159], v[136:139], 0
	ds_read_b128 v[172:175], v228 offset:2048
	s_add_u32 s10, s28, s13
	s_addc_u32 s11, s29, 0
	v_mfma_f32_16x16x32_bf16 v[74:77], v[160:163], v[136:139], 0
	ds_read_b128 v[176:179], v228 offset:4096
	s_add_u32 s13, s13, 0x10000
	v_mfma_f32_16x16x32_bf16 v[78:81], v[164:167], v[136:139], 0
	ds_read_b128 v[180:183], v228 offset:6144
	v_mul_f32_e32 v2, s12, v2
	v_mfma_f32_16x16x32_bf16 v[82:85], v[152:155], v[140:143], 0
	ds_read_b128 v[184:187], v234 offset:0
	v_mfma_f32_16x16x32_bf16 v[86:89], v[156:159], v[140:143], 0
	ds_read_b128 v[188:191], v234 offset:2048
	v_mul_f32_e32 v3, s12, v3
	v_mfma_f32_16x16x32_bf16 v[90:93], v[160:163], v[140:143], 0
	ds_read_b128 v[192:195], v234 offset:4096
	v_mul_f32_e32 v4, s12, v4
	v_mfma_f32_16x16x32_bf16 v[94:97], v[164:167], v[140:143], 0
	ds_read_b128 v[196:199], v234 offset:6144
	v_mul_f32_e32 v5, s12, v5
	v_mfma_f32_16x16x32_bf16 v[98:101], v[152:155], v[144:147], 0
	v_mfma_f32_16x16x32_bf16 v[102:105], v[156:159], v[144:147], 0
	v_mul_f32_e32 v6, s12, v6
	v_mfma_f32_16x16x32_bf16 v[106:109], v[160:163], v[144:147], 0
	v_mul_f32_e32 v7, s12, v7
	v_mfma_f32_16x16x32_bf16 v[110:113], v[164:167], v[144:147], 0
	v_mul_f32_e32 v8, s12, v8
	v_mfma_f32_16x16x32_bf16 v[114:117], v[152:155], v[148:151], 0
	v_mfma_f32_16x16x32_bf16 v[118:121], v[156:159], v[148:151], 0
	v_mul_f32_e32 v9, s12, v9
	v_mfma_f32_16x16x32_bf16 v[122:125], v[160:163], v[148:151], 0
	v_exp_f32_e32 v2, v2
	v_mfma_f32_16x16x32_bf16 v[126:129], v[164:167], v[148:151], 0
	v_exp_f32_e32 v3, v3
	s_waitcnt vmcnt(6) lgkmcnt(0)
	s_barrier
	v_mfma_f32_16x16x32_bf16 v[66:69], v[184:187], v[168:171], v[66:69]
	ds_read_b128 v[136:139], v224 offset:0
	v_mfma_f32_16x16x32_bf16 v[70:73], v[188:191], v[168:171], v[70:73]
	ds_read_b128 v[140:143], v224 offset:2048
	v_mfma_f32_16x16x32_bf16 v[74:77], v[192:195], v[168:171], v[74:77]
	ds_read_b128 v[144:147], v224 offset:4096
	v_exp_f32_e32 v4, v4
	v_mfma_f32_16x16x32_bf16 v[78:81], v[196:199], v[168:171], v[78:81]
	ds_read_b128 v[148:151], v224 offset:6144
	v_mfma_f32_16x16x32_bf16 v[82:85], v[184:187], v[172:175], v[82:85]
	ds_read_b128 v[152:155], v232 offset:0
	v_exp_f32_e32 v5, v5
	v_mfma_f32_16x16x32_bf16 v[86:89], v[188:191], v[172:175], v[86:89]
	ds_read_b128 v[156:159], v232 offset:2048
	v_mfma_f32_16x16x32_bf16 v[90:93], v[192:195], v[172:175], v[90:93]
	ds_read_b128 v[160:163], v232 offset:4096
	v_exp_f32_e32 v6, v6
	v_mfma_f32_16x16x32_bf16 v[94:97], v[196:199], v[172:175], v[94:97]
	ds_read_b128 v[164:167], v232 offset:6144
	s_add_u32 m0, s8, 0xc000
	v_mfma_f32_16x16x32_bf16 v[98:101], v[184:187], v[176:179], v[98:101]
	global_load_lds_dwordx4 v200, s[4:5]
	s_add_u32 m0, s8, 0xc400
	v_mfma_f32_16x16x32_bf16 v[102:105], v[188:191], v[176:179], v[102:105]
	global_load_lds_dwordx4 v201, s[4:5]
	v_exp_f32_e32 v7, v7
	s_add_u32 m0, s8, 0xc800
	v_mfma_f32_16x16x32_bf16 v[106:109], v[192:195], v[176:179], v[106:109]
	global_load_lds_dwordx4 v202, s[4:5]
	s_add_u32 m0, s8, 0xcc00
	v_mfma_f32_16x16x32_bf16 v[110:113], v[196:199], v[176:179], v[110:113]
	global_load_lds_dwordx4 v203, s[4:5]
	v_exp_f32_e32 v8, v8
	s_add_u32 m0, s9, 0xc000
	v_mfma_f32_16x16x32_bf16 v[114:117], v[184:187], v[180:183], v[114:117]
	global_load_lds_dwordx4 v204, s[6:7]
	s_add_u32 m0, s9, 0xc400
	v_mfma_f32_16x16x32_bf16 v[118:121], v[188:191], v[180:183], v[118:121]
	global_load_lds_dwordx4 v205, s[6:7]
	v_exp_f32_e32 v9, v9
	v_mfma_f32_16x16x32_bf16 v[122:125], v[192:195], v[180:183], v[122:125]
	s_add_u32 s4, s4, 0x80
	s_addc_u32 s5, s5, 0
	v_mfma_f32_16x16x32_bf16 v[126:129], v[196:199], v[180:183], v[126:129]
	s_add_u32 s6, s6, 0x80
	s_addc_u32 s7, s7, 0
	v_add_f32_e32 v2, 1.0, v2
	s_waitcnt lgkmcnt(0)
	v_mfma_f32_16x16x32_bf16 v[66:69], v[152:155], v[136:139], v[66:69]
	ds_read_b128 v[168:171], v229 offset:0
	v_mfma_f32_16x16x32_bf16 v[70:73], v[156:159], v[136:139], v[70:73]
	ds_read_b128 v[172:175], v229 offset:2048
	v_add_f32_e32 v3, 1.0, v3
	v_mfma_f32_16x16x32_bf16 v[74:77], v[160:163], v[136:139], v[74:77]
	ds_read_b128 v[176:179], v229 offset:4096
	v_add_f32_e32 v4, 1.0, v4
	v_mfma_f32_16x16x32_bf16 v[78:81], v[164:167], v[136:139], v[78:81]
	ds_read_b128 v[180:183], v229 offset:6144
	v_add_f32_e32 v5, 1.0, v5
	v_mfma_f32_16x16x32_bf16 v[82:85], v[152:155], v[140:143], v[82:85]
	ds_read_b128 v[184:187], v235 offset:0
	v_mfma_f32_16x16x32_bf16 v[86:89], v[156:159], v[140:143], v[86:89]
	ds_read_b128 v[188:191], v235 offset:2048
	v_add_f32_e32 v6, 1.0, v6
	v_mfma_f32_16x16x32_bf16 v[90:93], v[160:163], v[140:143], v[90:93]
	ds_read_b128 v[192:195], v235 offset:4096
	v_add_f32_e32 v7, 1.0, v7
	v_mfma_f32_16x16x32_bf16 v[94:97], v[164:167], v[140:143], v[94:97]
	ds_read_b128 v[196:199], v235 offset:6144
	v_add_f32_e32 v8, 1.0, v8
	v_mfma_f32_16x16x32_bf16 v[98:101], v[152:155], v[144:147], v[98:101]
	v_mfma_f32_16x16x32_bf16 v[102:105], v[156:159], v[144:147], v[102:105]
	v_add_f32_e32 v9, 1.0, v9
	v_mfma_f32_16x16x32_bf16 v[106:109], v[160:163], v[144:147], v[106:109]
	v_rcp_f32_e32 v2, v2
	v_mfma_f32_16x16x32_bf16 v[110:113], v[164:167], v[144:147], v[110:113]
	v_rcp_f32_e32 v3, v3
	v_mfma_f32_16x16x32_bf16 v[114:117], v[152:155], v[148:151], v[114:117]
	v_mfma_f32_16x16x32_bf16 v[118:121], v[156:159], v[148:151], v[118:121]
	v_rcp_f32_e32 v4, v4
	v_mfma_f32_16x16x32_bf16 v[122:125], v[160:163], v[148:151], v[122:125]
	v_rcp_f32_e32 v5, v5
	v_mfma_f32_16x16x32_bf16 v[126:129], v[164:167], v[148:151], v[126:129]
	v_rcp_f32_e32 v6, v6
	s_waitcnt vmcnt(6) lgkmcnt(0)
	s_barrier
	v_mfma_f32_16x16x32_bf16 v[66:69], v[184:187], v[168:171], v[66:69]
	ds_read_b128 v[136:139], v218 offset:0
	v_mfma_f32_16x16x32_bf16 v[70:73], v[188:191], v[168:171], v[70:73]
	ds_read_b128 v[140:143], v218 offset:2048
	v_mfma_f32_16x16x32_bf16 v[74:77], v[192:195], v[168:171], v[74:77]
	ds_read_b128 v[144:147], v218 offset:4096
	v_rcp_f32_e32 v7, v7
	v_mfma_f32_16x16x32_bf16 v[78:81], v[196:199], v[168:171], v[78:81]
	ds_read_b128 v[148:151], v218 offset:6144
	v_mfma_f32_16x16x32_bf16 v[82:85], v[184:187], v[172:175], v[82:85]
	ds_read_b128 v[152:155], v230 offset:0
	v_rcp_f32_e32 v8, v8
	v_mfma_f32_16x16x32_bf16 v[86:89], v[188:191], v[172:175], v[86:89]
	ds_read_b128 v[156:159], v230 offset:2048
	v_mfma_f32_16x16x32_bf16 v[90:93], v[192:195], v[172:175], v[90:93]
	ds_read_b128 v[160:163], v230 offset:4096
	v_rcp_f32_e32 v9, v9
	v_mfma_f32_16x16x32_bf16 v[94:97], v[196:199], v[172:175], v[94:97]
	ds_read_b128 v[164:167], v230 offset:6144
	s_add_u32 m0, s8, 0x18000
	v_mfma_f32_16x16x32_bf16 v[98:101], v[184:187], v[176:179], v[98:101]
	global_load_lds_dwordx4 v200, s[4:5]
	s_add_u32 m0, s8, 0x18400
	v_mfma_f32_16x16x32_bf16 v[102:105], v[188:191], v[176:179], v[102:105]
	global_load_lds_dwordx4 v201, s[4:5]
	v_cvt_pk_bf16_f32 v2, v2, v3
	s_add_u32 m0, s8, 0x18800
	v_mfma_f32_16x16x32_bf16 v[106:109], v[192:195], v[176:179], v[106:109]
	global_load_lds_dwordx4 v202, s[4:5]
	s_add_u32 m0, s8, 0x18c00
	v_mfma_f32_16x16x32_bf16 v[110:113], v[196:199], v[176:179], v[110:113]
	global_load_lds_dwordx4 v203, s[4:5]
	v_cvt_pk_bf16_f32 v3, v4, v5
	s_add_u32 m0, s9, 0x18000
	v_mfma_f32_16x16x32_bf16 v[114:117], v[184:187], v[180:183], v[114:117]
	global_load_lds_dwordx4 v204, s[6:7]
	s_add_u32 m0, s9, 0x18400
	v_mfma_f32_16x16x32_bf16 v[118:121], v[188:191], v[180:183], v[118:121]
	global_load_lds_dwordx4 v205, s[6:7]
	v_cvt_pk_bf16_f32 v4, v6, v7
	v_mfma_f32_16x16x32_bf16 v[122:125], v[192:195], v[180:183], v[122:125]
	s_add_u32 s4, s4, 0x80
	s_addc_u32 s5, s5, 0
	v_mfma_f32_16x16x32_bf16 v[126:129], v[196:199], v[180:183], v[126:129]
	s_add_u32 s6, s6, 0x80
	s_addc_u32 s7, s7, 0
	v_cvt_pk_bf16_f32 v5, v8, v9
	s_waitcnt lgkmcnt(0)
	v_mfma_f32_16x16x32_bf16 v[66:69], v[152:155], v[136:139], v[66:69]
	ds_read_b128 v[168:171], v225 offset:0
	v_mfma_f32_16x16x32_bf16 v[70:73], v[156:159], v[136:139], v[70:73]
	ds_read_b128 v[172:175], v225 offset:2048
	global_store_dwordx4 v240, v[2:5], s[10:11] offset:0
	v_mfma_f32_16x16x32_bf16 v[74:77], v[160:163], v[136:139], v[74:77]
	ds_read_b128 v[176:179], v225 offset:4096
	v_mul_f32_e32 v10, s12, v10
	v_mfma_f32_16x16x32_bf16 v[78:81], v[164:167], v[136:139], v[78:81]
	ds_read_b128 v[180:183], v225 offset:6144
	v_mul_f32_e32 v11, s12, v11
	v_mfma_f32_16x16x32_bf16 v[82:85], v[152:155], v[140:143], v[82:85]
	ds_read_b128 v[184:187], v233 offset:0
	v_mfma_f32_16x16x32_bf16 v[86:89], v[156:159], v[140:143], v[86:89]
	ds_read_b128 v[188:191], v233 offset:2048
	v_mul_f32_e32 v12, s12, v12
	v_mfma_f32_16x16x32_bf16 v[90:93], v[160:163], v[140:143], v[90:93]
	ds_read_b128 v[192:195], v233 offset:4096
	v_mul_f32_e32 v13, s12, v13
	v_mfma_f32_16x16x32_bf16 v[94:97], v[164:167], v[140:143], v[94:97]
	ds_read_b128 v[196:199], v233 offset:6144
	v_mul_f32_e32 v14, s12, v14
	v_mfma_f32_16x16x32_bf16 v[98:101], v[152:155], v[144:147], v[98:101]
	v_mfma_f32_16x16x32_bf16 v[102:105], v[156:159], v[144:147], v[102:105]
	v_mul_f32_e32 v15, s12, v15
	v_mfma_f32_16x16x32_bf16 v[106:109], v[160:163], v[144:147], v[106:109]
	v_mul_f32_e32 v16, s12, v16
	v_mfma_f32_16x16x32_bf16 v[110:113], v[164:167], v[144:147], v[110:113]
	v_mul_f32_e32 v17, s12, v17
	v_mfma_f32_16x16x32_bf16 v[114:117], v[152:155], v[148:151], v[114:117]
	v_mfma_f32_16x16x32_bf16 v[118:121], v[156:159], v[148:151], v[118:121]
	v_exp_f32_e32 v10, v10
	v_mfma_f32_16x16x32_bf16 v[122:125], v[160:163], v[148:151], v[122:125]
	v_exp_f32_e32 v11, v11
	v_mfma_f32_16x16x32_bf16 v[126:129], v[164:167], v[148:151], v[126:129]
	v_exp_f32_e32 v12, v12
	s_waitcnt vmcnt(7) lgkmcnt(0)
	s_barrier
	v_mfma_f32_16x16x32_bf16 v[66:69], v[184:187], v[168:171], v[66:69]
	ds_read_b128 v[136:139], v219 offset:0
	v_mfma_f32_16x16x32_bf16 v[70:73], v[188:191], v[168:171], v[70:73]
	ds_read_b128 v[140:143], v219 offset:2048
	v_mfma_f32_16x16x32_bf16 v[74:77], v[192:195], v[168:171], v[74:77]
	ds_read_b128 v[144:147], v219 offset:4096
	v_exp_f32_e32 v13, v13
	v_mfma_f32_16x16x32_bf16 v[78:81], v[196:199], v[168:171], v[78:81]
	ds_read_b128 v[148:151], v219 offset:6144
	v_mfma_f32_16x16x32_bf16 v[82:85], v[184:187], v[172:175], v[82:85]
	ds_read_b128 v[152:155], v231 offset:0
	v_exp_f32_e32 v14, v14
	v_mfma_f32_16x16x32_bf16 v[86:89], v[188:191], v[172:175], v[86:89]
	ds_read_b128 v[156:159], v231 offset:2048
	v_mfma_f32_16x16x32_bf16 v[90:93], v[192:195], v[172:175], v[90:93]
	ds_read_b128 v[160:163], v231 offset:4096
	v_exp_f32_e32 v15, v15
	v_mfma_f32_16x16x32_bf16 v[94:97], v[196:199], v[172:175], v[94:97]
	ds_read_b128 v[164:167], v231 offset:6144
	s_mov_b32 m0, s8
	v_mfma_f32_16x16x32_bf16 v[98:101], v[184:187], v[176:179], v[98:101]
	global_load_lds_dwordx4 v200, s[4:5]
	s_add_u32 m0, s8, 0x400
	v_mfma_f32_16x16x32_bf16 v[102:105], v[188:191], v[176:179], v[102:105]
	global_load_lds_dwordx4 v201, s[4:5]
	v_exp_f32_e32 v16, v16
	s_add_u32 m0, s8, 0x800
	v_mfma_f32_16x16x32_bf16 v[106:109], v[192:195], v[176:179], v[106:109]
	global_load_lds_dwordx4 v202, s[4:5]
	s_add_u32 m0, s8, 0xc00
	v_mfma_f32_16x16x32_bf16 v[110:113], v[196:199], v[176:179], v[110:113]
	global_load_lds_dwordx4 v203, s[4:5]
	v_exp_f32_e32 v17, v17
	s_mov_b32 m0, s9
	v_mfma_f32_16x16x32_bf16 v[114:117], v[184:187], v[180:183], v[114:117]
	global_load_lds_dwordx4 v204, s[6:7]
	s_add_u32 m0, s9, 0x400
	v_mfma_f32_16x16x32_bf16 v[118:121], v[188:191], v[180:183], v[118:121]
	global_load_lds_dwordx4 v205, s[6:7]
	v_add_f32_e32 v10, 1.0, v10
	v_mfma_f32_16x16x32_bf16 v[122:125], v[192:195], v[180:183], v[122:125]
	s_add_u32 s4, s4, 0x80
	s_addc_u32 s5, s5, 0
	v_mfma_f32_16x16x32_bf16 v[126:129], v[196:199], v[180:183], v[126:129]
	s_add_u32 s6, s6, 0x80
	s_addc_u32 s7, s7, 0
	v_add_f32_e32 v11, 1.0, v11
	s_waitcnt lgkmcnt(0)
	v_mfma_f32_16x16x32_bf16 v[66:69], v[152:155], v[136:139], v[66:69]
	ds_read_b128 v[168:171], v228 offset:0
	v_mfma_f32_16x16x32_bf16 v[70:73], v[156:159], v[136:139], v[70:73]
	ds_read_b128 v[172:175], v228 offset:2048
	v_add_f32_e32 v12, 1.0, v12
	v_mfma_f32_16x16x32_bf16 v[74:77], v[160:163], v[136:139], v[74:77]
	ds_read_b128 v[176:179], v228 offset:4096
	v_add_f32_e32 v13, 1.0, v13
	v_mfma_f32_16x16x32_bf16 v[78:81], v[164:167], v[136:139], v[78:81]
	ds_read_b128 v[180:183], v228 offset:6144
	v_add_f32_e32 v14, 1.0, v14
	v_mfma_f32_16x16x32_bf16 v[82:85], v[152:155], v[140:143], v[82:85]
	ds_read_b128 v[184:187], v234 offset:0
	v_mfma_f32_16x16x32_bf16 v[86:89], v[156:159], v[140:143], v[86:89]
	ds_read_b128 v[188:191], v234 offset:2048
	v_add_f32_e32 v15, 1.0, v15
	v_mfma_f32_16x16x32_bf16 v[90:93], v[160:163], v[140:143], v[90:93]
	ds_read_b128 v[192:195], v234 offset:4096
	v_add_f32_e32 v16, 1.0, v16
	v_mfma_f32_16x16x32_bf16 v[94:97], v[164:167], v[140:143], v[94:97]
	ds_read_b128 v[196:199], v234 offset:6144
	v_add_f32_e32 v17, 1.0, v17
	v_mfma_f32_16x16x32_bf16 v[98:101], v[152:155], v[144:147], v[98:101]
	v_mfma_f32_16x16x32_bf16 v[102:105], v[156:159], v[144:147], v[102:105]
	v_rcp_f32_e32 v10, v10
	v_mfma_f32_16x16x32_bf16 v[106:109], v[160:163], v[144:147], v[106:109]
	v_rcp_f32_e32 v11, v11
	v_mfma_f32_16x16x32_bf16 v[110:113], v[164:167], v[144:147], v[110:113]
	v_rcp_f32_e32 v12, v12
	v_mfma_f32_16x16x32_bf16 v[114:117], v[152:155], v[148:151], v[114:117]
	v_mfma_f32_16x16x32_bf16 v[118:121], v[156:159], v[148:151], v[118:121]
	v_rcp_f32_e32 v13, v13
	v_mfma_f32_16x16x32_bf16 v[122:125], v[160:163], v[148:151], v[122:125]
	v_rcp_f32_e32 v14, v14
	v_mfma_f32_16x16x32_bf16 v[126:129], v[164:167], v[148:151], v[126:129]
	v_rcp_f32_e32 v15, v15
	s_waitcnt vmcnt(7) lgkmcnt(0)
	s_barrier
	v_mfma_f32_16x16x32_bf16 v[66:69], v[184:187], v[168:171], v[66:69]
	ds_read_b128 v[136:139], v224 offset:0
	v_mfma_f32_16x16x32_bf16 v[70:73], v[188:191], v[168:171], v[70:73]
	ds_read_b128 v[140:143], v224 offset:2048
	v_mfma_f32_16x16x32_bf16 v[74:77], v[192:195], v[168:171], v[74:77]
	ds_read_b128 v[144:147], v224 offset:4096
	v_rcp_f32_e32 v16, v16
	v_mfma_f32_16x16x32_bf16 v[78:81], v[196:199], v[168:171], v[78:81]
	ds_read_b128 v[148:151], v224 offset:6144
	v_mfma_f32_16x16x32_bf16 v[82:85], v[184:187], v[172:175], v[82:85]
	ds_read_b128 v[152:155], v232 offset:0
	v_rcp_f32_e32 v17, v17
	v_mfma_f32_16x16x32_bf16 v[86:89], v[188:191], v[172:175], v[86:89]
	ds_read_b128 v[156:159], v232 offset:2048
	v_mfma_f32_16x16x32_bf16 v[90:93], v[192:195], v[172:175], v[90:93]
	ds_read_b128 v[160:163], v232 offset:4096
	v_cvt_pk_bf16_f32 v10, v10, v11
	v_mfma_f32_16x16x32_bf16 v[94:97], v[196:199], v[172:175], v[94:97]
	ds_read_b128 v[164:167], v232 offset:6144
	s_add_u32 m0, s8, 0xc000
	v_mfma_f32_16x16x32_bf16 v[98:101], v[184:187], v[176:179], v[98:101]
	global_load_lds_dwordx4 v200, s[4:5]
	s_add_u32 m0, s8, 0xc400
	v_mfma_f32_16x16x32_bf16 v[102:105], v[188:191], v[176:179], v[102:105]
	global_load_lds_dwordx4 v201, s[4:5]
	v_cvt_pk_bf16_f32 v11, v12, v13
	s_add_u32 m0, s8, 0xc800
	v_mfma_f32_16x16x32_bf16 v[106:109], v[192:195], v[176:179], v[106:109]
	global_load_lds_dwordx4 v202, s[4:5]
	s_add_u32 m0, s8, 0xcc00
	v_mfma_f32_16x16x32_bf16 v[110:113], v[196:199], v[176:179], v[110:113]
	global_load_lds_dwordx4 v203, s[4:5]
	v_cvt_pk_bf16_f32 v12, v14, v15
	s_add_u32 m0, s9, 0xc000
	v_mfma_f32_16x16x32_bf16 v[114:117], v[184:187], v[180:183], v[114:117]
	global_load_lds_dwordx4 v204, s[6:7]
	s_add_u32 m0, s9, 0xc400
	v_mfma_f32_16x16x32_bf16 v[118:121], v[188:191], v[180:183], v[118:121]
	global_load_lds_dwordx4 v205, s[6:7]
	v_cvt_pk_bf16_f32 v13, v16, v17
	v_mfma_f32_16x16x32_bf16 v[122:125], v[192:195], v[180:183], v[122:125]
	s_add_u32 s4, s4, 0x80
	s_addc_u32 s5, s5, 0
	v_mfma_f32_16x16x32_bf16 v[126:129], v[196:199], v[180:183], v[126:129]
	s_add_u32 s6, s6, 0x80
	s_addc_u32 s7, s7, 0
	global_store_dwordx4 v240, v[10:13], s[10:11] offset:16
	s_waitcnt lgkmcnt(0)
	v_mfma_f32_16x16x32_bf16 v[66:69], v[152:155], v[136:139], v[66:69]
	ds_read_b128 v[168:171], v229 offset:0
	v_mfma_f32_16x16x32_bf16 v[70:73], v[156:159], v[136:139], v[70:73]
	ds_read_b128 v[172:175], v229 offset:2048
	v_mul_f32_e32 v18, s12, v18
	v_mfma_f32_16x16x32_bf16 v[74:77], v[160:163], v[136:139], v[74:77]
	ds_read_b128 v[176:179], v229 offset:4096
	v_mul_f32_e32 v19, s12, v19
	v_mfma_f32_16x16x32_bf16 v[78:81], v[164:167], v[136:139], v[78:81]
	ds_read_b128 v[180:183], v229 offset:6144
	v_mul_f32_e32 v20, s12, v20
	v_mfma_f32_16x16x32_bf16 v[82:85], v[152:155], v[140:143], v[82:85]
	ds_read_b128 v[184:187], v235 offset:0
	v_mfma_f32_16x16x32_bf16 v[86:89], v[156:159], v[140:143], v[86:89]
	ds_read_b128 v[188:191], v235 offset:2048
	v_mul_f32_e32 v21, s12, v21
	v_mfma_f32_16x16x32_bf16 v[90:93], v[160:163], v[140:143], v[90:93]
	ds_read_b128 v[192:195], v235 offset:4096
	v_mul_f32_e32 v22, s12, v22
	v_mfma_f32_16x16x32_bf16 v[94:97], v[164:167], v[140:143], v[94:97]
	ds_read_b128 v[196:199], v235 offset:6144
	v_mul_f32_e32 v23, s12, v23
	v_mfma_f32_16x16x32_bf16 v[98:101], v[152:155], v[144:147], v[98:101]
	v_mfma_f32_16x16x32_bf16 v[102:105], v[156:159], v[144:147], v[102:105]
	v_mul_f32_e32 v24, s12, v24
	v_mfma_f32_16x16x32_bf16 v[106:109], v[160:163], v[144:147], v[106:109]
	v_mul_f32_e32 v25, s12, v25
	v_mfma_f32_16x16x32_bf16 v[110:113], v[164:167], v[144:147], v[110:113]
	v_exp_f32_e32 v18, v18
	v_mfma_f32_16x16x32_bf16 v[114:117], v[152:155], v[148:151], v[114:117]
	v_mfma_f32_16x16x32_bf16 v[118:121], v[156:159], v[148:151], v[118:121]
	v_exp_f32_e32 v19, v19
	v_mfma_f32_16x16x32_bf16 v[122:125], v[160:163], v[148:151], v[122:125]
	v_exp_f32_e32 v20, v20
	v_mfma_f32_16x16x32_bf16 v[126:129], v[164:167], v[148:151], v[126:129]
	v_exp_f32_e32 v21, v21
	s_waitcnt vmcnt(7) lgkmcnt(0)
	s_barrier
	v_mfma_f32_16x16x32_bf16 v[66:69], v[184:187], v[168:171], v[66:69]
	ds_read_b128 v[136:139], v218 offset:0
	v_mfma_f32_16x16x32_bf16 v[70:73], v[188:191], v[168:171], v[70:73]
	ds_read_b128 v[140:143], v218 offset:2048
	v_mfma_f32_16x16x32_bf16 v[74:77], v[192:195], v[168:171], v[74:77]
	ds_read_b128 v[144:147], v218 offset:4096
	v_exp_f32_e32 v22, v22
	v_mfma_f32_16x16x32_bf16 v[78:81], v[196:199], v[168:171], v[78:81]
	ds_read_b128 v[148:151], v218 offset:6144
	v_mfma_f32_16x16x32_bf16 v[82:85], v[184:187], v[172:175], v[82:85]
	ds_read_b128 v[152:155], v230 offset:0
	v_exp_f32_e32 v23, v23
	v_mfma_f32_16x16x32_bf16 v[86:89], v[188:191], v[172:175], v[86:89]
	ds_read_b128 v[156:159], v230 offset:2048
	v_mfma_f32_16x16x32_bf16 v[90:93], v[192:195], v[172:175], v[90:93]
	ds_read_b128 v[160:163], v230 offset:4096
	v_exp_f32_e32 v24, v24
	v_mfma_f32_16x16x32_bf16 v[94:97], v[196:199], v[172:175], v[94:97]
	ds_read_b128 v[164:167], v230 offset:6144
	s_add_u32 m0, s8, 0x18000
	v_mfma_f32_16x16x32_bf16 v[98:101], v[184:187], v[176:179], v[98:101]
	global_load_lds_dwordx4 v200, s[4:5]
	s_add_u32 m0, s8, 0x18400
	v_mfma_f32_16x16x32_bf16 v[102:105], v[188:191], v[176:179], v[102:105]
	global_load_lds_dwordx4 v201, s[4:5]
	v_exp_f32_e32 v25, v25
	s_add_u32 m0, s8, 0x18800
	v_mfma_f32_16x16x32_bf16 v[106:109], v[192:195], v[176:179], v[106:109]
	global_load_lds_dwordx4 v202, s[4:5]
	s_add_u32 m0, s8, 0x18c00
	v_mfma_f32_16x16x32_bf16 v[110:113], v[196:199], v[176:179], v[110:113]
	global_load_lds_dwordx4 v203, s[4:5]
	v_add_f32_e32 v18, 1.0, v18
	s_add_u32 m0, s9, 0x18000
	v_mfma_f32_16x16x32_bf16 v[114:117], v[184:187], v[180:183], v[114:117]
	global_load_lds_dwordx4 v204, s[6:7]
	s_add_u32 m0, s9, 0x18400
	v_mfma_f32_16x16x32_bf16 v[118:121], v[188:191], v[180:183], v[118:121]
	global_load_lds_dwordx4 v205, s[6:7]
	v_add_f32_e32 v19, 1.0, v19
	v_mfma_f32_16x16x32_bf16 v[122:125], v[192:195], v[180:183], v[122:125]
	s_add_u32 s4, s4, 0x80
	s_addc_u32 s5, s5, 0
	v_mfma_f32_16x16x32_bf16 v[126:129], v[196:199], v[180:183], v[126:129]
	s_add_u32 s6, s6, 0x80
	s_addc_u32 s7, s7, 0
	v_add_f32_e32 v20, 1.0, v20
	s_waitcnt lgkmcnt(0)
	v_mfma_f32_16x16x32_bf16 v[66:69], v[152:155], v[136:139], v[66:69]
	ds_read_b128 v[168:171], v225 offset:0
	v_mfma_f32_16x16x32_bf16 v[70:73], v[156:159], v[136:139], v[70:73]
	ds_read_b128 v[172:175], v225 offset:2048
	v_add_f32_e32 v21, 1.0, v21
	v_mfma_f32_16x16x32_bf16 v[74:77], v[160:163], v[136:139], v[74:77]
	ds_read_b128 v[176:179], v225 offset:4096
	v_add_f32_e32 v22, 1.0, v22
	v_mfma_f32_16x16x32_bf16 v[78:81], v[164:167], v[136:139], v[78:81]
	ds_read_b128 v[180:183], v225 offset:6144
	v_add_f32_e32 v23, 1.0, v23
	v_mfma_f32_16x16x32_bf16 v[82:85], v[152:155], v[140:143], v[82:85]
	ds_read_b128 v[184:187], v233 offset:0
	v_mfma_f32_16x16x32_bf16 v[86:89], v[156:159], v[140:143], v[86:89]
	ds_read_b128 v[188:191], v233 offset:2048
	v_add_f32_e32 v24, 1.0, v24
	v_mfma_f32_16x16x32_bf16 v[90:93], v[160:163], v[140:143], v[90:93]
	ds_read_b128 v[192:195], v233 offset:4096
	v_add_f32_e32 v25, 1.0, v25
	v_mfma_f32_16x16x32_bf16 v[94:97], v[164:167], v[140:143], v[94:97]
	ds_read_b128 v[196:199], v233 offset:6144
	v_rcp_f32_e32 v18, v18
	v_mfma_f32_16x16x32_bf16 v[98:101], v[152:155], v[144:147], v[98:101]
	v_mfma_f32_16x16x32_bf16 v[102:105], v[156:159], v[144:147], v[102:105]
	v_rcp_f32_e32 v19, v19
	v_mfma_f32_16x16x32_bf16 v[106:109], v[160:163], v[144:147], v[106:109]
	v_rcp_f32_e32 v20, v20
	v_mfma_f32_16x16x32_bf16 v[110:113], v[164:167], v[144:147], v[110:113]
	v_rcp_f32_e32 v21, v21
	v_mfma_f32_16x16x32_bf16 v[114:117], v[152:155], v[148:151], v[114:117]
	v_mfma_f32_16x16x32_bf16 v[118:121], v[156:159], v[148:151], v[118:121]
	v_rcp_f32_e32 v22, v22
	v_mfma_f32_16x16x32_bf16 v[122:125], v[160:163], v[148:151], v[122:125]
	v_rcp_f32_e32 v23, v23
	v_mfma_f32_16x16x32_bf16 v[126:129], v[164:167], v[148:151], v[126:129]
	v_rcp_f32_e32 v24, v24
	s_waitcnt vmcnt(7) lgkmcnt(0)
	s_barrier
	v_mfma_f32_16x16x32_bf16 v[66:69], v[184:187], v[168:171], v[66:69]
	ds_read_b128 v[136:139], v219 offset:0
	v_mfma_f32_16x16x32_bf16 v[70:73], v[188:191], v[168:171], v[70:73]
	ds_read_b128 v[140:143], v219 offset:2048
	v_mfma_f32_16x16x32_bf16 v[74:77], v[192:195], v[168:171], v[74:77]
	ds_read_b128 v[144:147], v219 offset:4096
	v_rcp_f32_e32 v25, v25
	v_mfma_f32_16x16x32_bf16 v[78:81], v[196:199], v[168:171], v[78:81]
	ds_read_b128 v[148:151], v219 offset:6144
	v_mfma_f32_16x16x32_bf16 v[82:85], v[184:187], v[172:175], v[82:85]
	ds_read_b128 v[152:155], v231 offset:0
	v_cvt_pk_bf16_f32 v18, v18, v19
	v_mfma_f32_16x16x32_bf16 v[86:89], v[188:191], v[172:175], v[86:89]
	ds_read_b128 v[156:159], v231 offset:2048
	v_mfma_f32_16x16x32_bf16 v[90:93], v[192:195], v[172:175], v[90:93]
	ds_read_b128 v[160:163], v231 offset:4096
	v_cvt_pk_bf16_f32 v19, v20, v21
	v_mfma_f32_16x16x32_bf16 v[94:97], v[196:199], v[172:175], v[94:97]
	ds_read_b128 v[164:167], v231 offset:6144
	s_mov_b32 m0, s8
	v_mfma_f32_16x16x32_bf16 v[98:101], v[184:187], v[176:179], v[98:101]
	global_load_lds_dwordx4 v200, s[4:5]
	s_add_u32 m0, s8, 0x400
	v_mfma_f32_16x16x32_bf16 v[102:105], v[188:191], v[176:179], v[102:105]
	global_load_lds_dwordx4 v201, s[4:5]
	v_cvt_pk_bf16_f32 v20, v22, v23
	s_add_u32 m0, s8, 0x800
	v_mfma_f32_16x16x32_bf16 v[106:109], v[192:195], v[176:179], v[106:109]
	global_load_lds_dwordx4 v202, s[4:5]
	s_add_u32 m0, s8, 0xc00
	v_mfma_f32_16x16x32_bf16 v[110:113], v[196:199], v[176:179], v[110:113]
	global_load_lds_dwordx4 v203, s[4:5]
	v_cvt_pk_bf16_f32 v21, v24, v25
	s_mov_b32 m0, s9
	v_mfma_f32_16x16x32_bf16 v[114:117], v[184:187], v[180:183], v[114:117]
	global_load_lds_dwordx4 v204, s[6:7]
	s_add_u32 m0, s9, 0x400
	v_mfma_f32_16x16x32_bf16 v[118:121], v[188:191], v[180:183], v[118:121]
	global_load_lds_dwordx4 v205, s[6:7]
	global_store_dwordx4 v240, v[18:21], s[10:11] offset:2048
	v_mfma_f32_16x16x32_bf16 v[122:125], v[192:195], v[180:183], v[122:125]
	s_add_u32 s4, s4, 0x80
	s_addc_u32 s5, s5, 0
	v_mfma_f32_16x16x32_bf16 v[126:129], v[196:199], v[180:183], v[126:129]
	s_add_u32 s6, s6, 0x80
	s_addc_u32 s7, s7, 0
	v_mul_f32_e32 v26, s12, v26
	s_waitcnt lgkmcnt(0)
	v_mfma_f32_16x16x32_bf16 v[66:69], v[152:155], v[136:139], v[66:69]
	ds_read_b128 v[168:171], v228 offset:0
	v_mfma_f32_16x16x32_bf16 v[70:73], v[156:159], v[136:139], v[70:73]
	ds_read_b128 v[172:175], v228 offset:2048
	v_mul_f32_e32 v27, s12, v27
	v_mfma_f32_16x16x32_bf16 v[74:77], v[160:163], v[136:139], v[74:77]
	ds_read_b128 v[176:179], v228 offset:4096
	v_mul_f32_e32 v28, s12, v28
	v_mfma_f32_16x16x32_bf16 v[78:81], v[164:167], v[136:139], v[78:81]
	ds_read_b128 v[180:183], v228 offset:6144
	v_mul_f32_e32 v29, s12, v29
	v_mfma_f32_16x16x32_bf16 v[82:85], v[152:155], v[140:143], v[82:85]
	ds_read_b128 v[184:187], v234 offset:0
	v_mfma_f32_16x16x32_bf16 v[86:89], v[156:159], v[140:143], v[86:89]
	ds_read_b128 v[188:191], v234 offset:2048
	v_mul_f32_e32 v30, s12, v30
	v_mfma_f32_16x16x32_bf16 v[90:93], v[160:163], v[140:143], v[90:93]
	ds_read_b128 v[192:195], v234 offset:4096
	v_mul_f32_e32 v31, s12, v31
	v_mfma_f32_16x16x32_bf16 v[94:97], v[164:167], v[140:143], v[94:97]
	ds_read_b128 v[196:199], v234 offset:6144
	v_mul_f32_e32 v32, s12, v32
	v_mfma_f32_16x16x32_bf16 v[98:101], v[152:155], v[144:147], v[98:101]
	v_mfma_f32_16x16x32_bf16 v[102:105], v[156:159], v[144:147], v[102:105]
	v_mul_f32_e32 v33, s12, v33
	v_mfma_f32_16x16x32_bf16 v[106:109], v[160:163], v[144:147], v[106:109]
	v_exp_f32_e32 v26, v26
	v_mfma_f32_16x16x32_bf16 v[110:113], v[164:167], v[144:147], v[110:113]
	v_exp_f32_e32 v27, v27
	v_mfma_f32_16x16x32_bf16 v[114:117], v[152:155], v[148:151], v[114:117]
	v_mfma_f32_16x16x32_bf16 v[118:121], v[156:159], v[148:151], v[118:121]
	v_exp_f32_e32 v28, v28
	v_mfma_f32_16x16x32_bf16 v[122:125], v[160:163], v[148:151], v[122:125]
	v_exp_f32_e32 v29, v29
	v_mfma_f32_16x16x32_bf16 v[126:129], v[164:167], v[148:151], v[126:129]
	v_exp_f32_e32 v30, v30
	s_waitcnt vmcnt(7) lgkmcnt(0)
	s_barrier
	v_mfma_f32_16x16x32_bf16 v[66:69], v[184:187], v[168:171], v[66:69]
	ds_read_b128 v[136:139], v224 offset:0
	v_mfma_f32_16x16x32_bf16 v[70:73], v[188:191], v[168:171], v[70:73]
	ds_read_b128 v[140:143], v224 offset:2048
	v_mfma_f32_16x16x32_bf16 v[74:77], v[192:195], v[168:171], v[74:77]
	ds_read_b128 v[144:147], v224 offset:4096
	v_exp_f32_e32 v31, v31
	v_mfma_f32_16x16x32_bf16 v[78:81], v[196:199], v[168:171], v[78:81]
	ds_read_b128 v[148:151], v224 offset:6144
	v_mfma_f32_16x16x32_bf16 v[82:85], v[184:187], v[172:175], v[82:85]
	ds_read_b128 v[152:155], v232 offset:0
	v_exp_f32_e32 v32, v32
	v_mfma_f32_16x16x32_bf16 v[86:89], v[188:191], v[172:175], v[86:89]
	ds_read_b128 v[156:159], v232 offset:2048
	v_mfma_f32_16x16x32_bf16 v[90:93], v[192:195], v[172:175], v[90:93]
	ds_read_b128 v[160:163], v232 offset:4096
	v_exp_f32_e32 v33, v33
	v_mfma_f32_16x16x32_bf16 v[94:97], v[196:199], v[172:175], v[94:97]
	ds_read_b128 v[164:167], v232 offset:6144
	s_add_u32 m0, s8, 0xc000
	v_mfma_f32_16x16x32_bf16 v[98:101], v[184:187], v[176:179], v[98:101]
	global_load_lds_dwordx4 v200, s[4:5]
	s_add_u32 m0, s8, 0xc400
	v_mfma_f32_16x16x32_bf16 v[102:105], v[188:191], v[176:179], v[102:105]
	global_load_lds_dwordx4 v201, s[4:5]
	v_add_f32_e32 v26, 1.0, v26
	s_add_u32 m0, s8, 0xc800
	v_mfma_f32_16x16x32_bf16 v[106:109], v[192:195], v[176:179], v[106:109]
	global_load_lds_dwordx4 v202, s[4:5]
	s_add_u32 m0, s8, 0xcc00
	v_mfma_f32_16x16x32_bf16 v[110:113], v[196:199], v[176:179], v[110:113]
	global_load_lds_dwordx4 v203, s[4:5]
	v_add_f32_e32 v27, 1.0, v27
	s_add_u32 m0, s9, 0xc000
	v_mfma_f32_16x16x32_bf16 v[114:117], v[184:187], v[180:183], v[114:117]
	global_load_lds_dwordx4 v204, s[6:7]
	s_add_u32 m0, s9, 0xc400
	v_mfma_f32_16x16x32_bf16 v[118:121], v[188:191], v[180:183], v[118:121]
	global_load_lds_dwordx4 v205, s[6:7]
	v_add_f32_e32 v28, 1.0, v28
	v_mfma_f32_16x16x32_bf16 v[122:125], v[192:195], v[180:183], v[122:125]
	s_add_u32 s4, s4, 0x80
	s_addc_u32 s5, s5, 0
	v_mfma_f32_16x16x32_bf16 v[126:129], v[196:199], v[180:183], v[126:129]
	s_add_u32 s6, s6, 0x80
	s_addc_u32 s7, s7, 0
	v_add_f32_e32 v29, 1.0, v29
	s_waitcnt lgkmcnt(0)
	v_mfma_f32_16x16x32_bf16 v[66:69], v[152:155], v[136:139], v[66:69]
	ds_read_b128 v[168:171], v229 offset:0
	v_mfma_f32_16x16x32_bf16 v[70:73], v[156:159], v[136:139], v[70:73]
	ds_read_b128 v[172:175], v229 offset:2048
	v_add_f32_e32 v30, 1.0, v30
	v_mfma_f32_16x16x32_bf16 v[74:77], v[160:163], v[136:139], v[74:77]
	ds_read_b128 v[176:179], v229 offset:4096
	v_add_f32_e32 v31, 1.0, v31
	v_mfma_f32_16x16x32_bf16 v[78:81], v[164:167], v[136:139], v[78:81]
	ds_read_b128 v[180:183], v229 offset:6144
	v_add_f32_e32 v32, 1.0, v32
	v_mfma_f32_16x16x32_bf16 v[82:85], v[152:155], v[140:143], v[82:85]
	ds_read_b128 v[184:187], v235 offset:0
	v_mfma_f32_16x16x32_bf16 v[86:89], v[156:159], v[140:143], v[86:89]
	ds_read_b128 v[188:191], v235 offset:2048
	v_add_f32_e32 v33, 1.0, v33
	v_mfma_f32_16x16x32_bf16 v[90:93], v[160:163], v[140:143], v[90:93]
	ds_read_b128 v[192:195], v235 offset:4096
	v_rcp_f32_e32 v26, v26
	v_mfma_f32_16x16x32_bf16 v[94:97], v[164:167], v[140:143], v[94:97]
	ds_read_b128 v[196:199], v235 offset:6144
	v_rcp_f32_e32 v27, v27
	v_mfma_f32_16x16x32_bf16 v[98:101], v[152:155], v[144:147], v[98:101]
	v_mfma_f32_16x16x32_bf16 v[102:105], v[156:159], v[144:147], v[102:105]
	v_rcp_f32_e32 v28, v28
	v_mfma_f32_16x16x32_bf16 v[106:109], v[160:163], v[144:147], v[106:109]
	v_rcp_f32_e32 v29, v29
	v_mfma_f32_16x16x32_bf16 v[110:113], v[164:167], v[144:147], v[110:113]
	v_rcp_f32_e32 v30, v30
	v_mfma_f32_16x16x32_bf16 v[114:117], v[152:155], v[148:151], v[114:117]
	v_mfma_f32_16x16x32_bf16 v[118:121], v[156:159], v[148:151], v[118:121]
	v_rcp_f32_e32 v31, v31
	v_mfma_f32_16x16x32_bf16 v[122:125], v[160:163], v[148:151], v[122:125]
	v_rcp_f32_e32 v32, v32
	v_mfma_f32_16x16x32_bf16 v[126:129], v[164:167], v[148:151], v[126:129]
	v_rcp_f32_e32 v33, v33
	s_waitcnt vmcnt(7) lgkmcnt(0)
	s_barrier
	v_mfma_f32_16x16x32_bf16 v[66:69], v[184:187], v[168:171], v[66:69]
	ds_read_b128 v[136:139], v218 offset:0
	v_mfma_f32_16x16x32_bf16 v[70:73], v[188:191], v[168:171], v[70:73]
	ds_read_b128 v[140:143], v218 offset:2048
	v_mfma_f32_16x16x32_bf16 v[74:77], v[192:195], v[168:171], v[74:77]
	ds_read_b128 v[144:147], v218 offset:4096
	v_cvt_pk_bf16_f32 v26, v26, v27
	v_mfma_f32_16x16x32_bf16 v[78:81], v[196:199], v[168:171], v[78:81]
	ds_read_b128 v[148:151], v218 offset:6144
	v_mfma_f32_16x16x32_bf16 v[82:85], v[184:187], v[172:175], v[82:85]
	ds_read_b128 v[152:155], v230 offset:0
	v_cvt_pk_bf16_f32 v27, v28, v29
	v_mfma_f32_16x16x32_bf16 v[86:89], v[188:191], v[172:175], v[86:89]
	ds_read_b128 v[156:159], v230 offset:2048
	v_mfma_f32_16x16x32_bf16 v[90:93], v[192:195], v[172:175], v[90:93]
	ds_read_b128 v[160:163], v230 offset:4096
	v_cvt_pk_bf16_f32 v28, v30, v31
	v_mfma_f32_16x16x32_bf16 v[94:97], v[196:199], v[172:175], v[94:97]
	ds_read_b128 v[164:167], v230 offset:6144
	s_add_u32 m0, s8, 0x18000
	v_mfma_f32_16x16x32_bf16 v[98:101], v[184:187], v[176:179], v[98:101]
	global_load_lds_dwordx4 v200, s[4:5]
	s_add_u32 m0, s8, 0x18400
	v_mfma_f32_16x16x32_bf16 v[102:105], v[188:191], v[176:179], v[102:105]
	global_load_lds_dwordx4 v201, s[4:5]
	v_cvt_pk_bf16_f32 v29, v32, v33
	s_add_u32 m0, s8, 0x18800
	v_mfma_f32_16x16x32_bf16 v[106:109], v[192:195], v[176:179], v[106:109]
	global_load_lds_dwordx4 v202, s[4:5]
	s_add_u32 m0, s8, 0x18c00
	v_mfma_f32_16x16x32_bf16 v[110:113], v[196:199], v[176:179], v[110:113]
	global_load_lds_dwordx4 v203, s[4:5]
	global_store_dwordx4 v240, v[26:29], s[10:11] offset:2064
	s_add_u32 m0, s9, 0x18000
	v_mfma_f32_16x16x32_bf16 v[114:117], v[184:187], v[180:183], v[114:117]
	global_load_lds_dwordx4 v204, s[6:7]
	s_add_u32 m0, s9, 0x18400
	v_mfma_f32_16x16x32_bf16 v[118:121], v[188:191], v[180:183], v[118:121]
	global_load_lds_dwordx4 v205, s[6:7]
	v_mul_f32_e32 v34, s12, v34
	v_mfma_f32_16x16x32_bf16 v[122:125], v[192:195], v[180:183], v[122:125]
	s_add_u32 s4, s4, 0x80
	s_addc_u32 s5, s5, 0
	v_mfma_f32_16x16x32_bf16 v[126:129], v[196:199], v[180:183], v[126:129]
	s_add_u32 s6, s6, 0x80
	s_addc_u32 s7, s7, 0
	v_mul_f32_e32 v35, s12, v35
	s_waitcnt lgkmcnt(0)
	v_mfma_f32_16x16x32_bf16 v[66:69], v[152:155], v[136:139], v[66:69]
	ds_read_b128 v[168:171], v225 offset:0
	v_mfma_f32_16x16x32_bf16 v[70:73], v[156:159], v[136:139], v[70:73]
	ds_read_b128 v[172:175], v225 offset:2048
	v_mul_f32_e32 v36, s12, v36
	v_mfma_f32_16x16x32_bf16 v[74:77], v[160:163], v[136:139], v[74:77]
	ds_read_b128 v[176:179], v225 offset:4096
	v_mul_f32_e32 v37, s12, v37
	v_mfma_f32_16x16x32_bf16 v[78:81], v[164:167], v[136:139], v[78:81]
	ds_read_b128 v[180:183], v225 offset:6144
	v_mul_f32_e32 v38, s12, v38
	v_mfma_f32_16x16x32_bf16 v[82:85], v[152:155], v[140:143], v[82:85]
	ds_read_b128 v[184:187], v233 offset:0
	v_mfma_f32_16x16x32_bf16 v[86:89], v[156:159], v[140:143], v[86:89]
	ds_read_b128 v[188:191], v233 offset:2048
	v_mul_f32_e32 v39, s12, v39
	v_mfma_f32_16x16x32_bf16 v[90:93], v[160:163], v[140:143], v[90:93]
	ds_read_b128 v[192:195], v233 offset:4096
	v_mul_f32_e32 v40, s12, v40
	v_mfma_f32_16x16x32_bf16 v[94:97], v[164:167], v[140:143], v[94:97]
	ds_read_b128 v[196:199], v233 offset:6144
	v_mul_f32_e32 v41, s12, v41
	v_mfma_f32_16x16x32_bf16 v[98:101], v[152:155], v[144:147], v[98:101]
	v_mfma_f32_16x16x32_bf16 v[102:105], v[156:159], v[144:147], v[102:105]
	v_exp_f32_e32 v34, v34
	v_mfma_f32_16x16x32_bf16 v[106:109], v[160:163], v[144:147], v[106:109]
	v_exp_f32_e32 v35, v35
	v_mfma_f32_16x16x32_bf16 v[110:113], v[164:167], v[144:147], v[110:113]
	v_exp_f32_e32 v36, v36
	v_mfma_f32_16x16x32_bf16 v[114:117], v[152:155], v[148:151], v[114:117]
	v_mfma_f32_16x16x32_bf16 v[118:121], v[156:159], v[148:151], v[118:121]
	v_exp_f32_e32 v37, v37
	v_mfma_f32_16x16x32_bf16 v[122:125], v[160:163], v[148:151], v[122:125]
	v_exp_f32_e32 v38, v38
	v_mfma_f32_16x16x32_bf16 v[126:129], v[164:167], v[148:151], v[126:129]
	v_exp_f32_e32 v39, v39
	s_waitcnt vmcnt(7) lgkmcnt(0)
	s_barrier
	v_mfma_f32_16x16x32_bf16 v[66:69], v[184:187], v[168:171], v[66:69]
	ds_read_b128 v[136:139], v219 offset:0
	v_mfma_f32_16x16x32_bf16 v[70:73], v[188:191], v[168:171], v[70:73]
	ds_read_b128 v[140:143], v219 offset:2048
	v_mfma_f32_16x16x32_bf16 v[74:77], v[192:195], v[168:171], v[74:77]
	ds_read_b128 v[144:147], v219 offset:4096
	v_exp_f32_e32 v40, v40
	v_mfma_f32_16x16x32_bf16 v[78:81], v[196:199], v[168:171], v[78:81]
	ds_read_b128 v[148:151], v219 offset:6144
	v_mfma_f32_16x16x32_bf16 v[82:85], v[184:187], v[172:175], v[82:85]
	ds_read_b128 v[152:155], v231 offset:0
	v_exp_f32_e32 v41, v41
	v_mfma_f32_16x16x32_bf16 v[86:89], v[188:191], v[172:175], v[86:89]
	ds_read_b128 v[156:159], v231 offset:2048
	v_mfma_f32_16x16x32_bf16 v[90:93], v[192:195], v[172:175], v[90:93]
	ds_read_b128 v[160:163], v231 offset:4096
	v_add_f32_e32 v34, 1.0, v34
	v_mfma_f32_16x16x32_bf16 v[94:97], v[196:199], v[172:175], v[94:97]
	ds_read_b128 v[164:167], v231 offset:6144
	s_mov_b32 m0, s8
	v_mfma_f32_16x16x32_bf16 v[98:101], v[184:187], v[176:179], v[98:101]
	global_load_lds_dwordx4 v200, s[4:5]
	s_add_u32 m0, s8, 0x400
	v_mfma_f32_16x16x32_bf16 v[102:105], v[188:191], v[176:179], v[102:105]
	global_load_lds_dwordx4 v201, s[4:5]
	v_add_f32_e32 v35, 1.0, v35
	s_add_u32 m0, s8, 0x800
	v_mfma_f32_16x16x32_bf16 v[106:109], v[192:195], v[176:179], v[106:109]
	global_load_lds_dwordx4 v202, s[4:5]
	s_add_u32 m0, s8, 0xc00
	v_mfma_f32_16x16x32_bf16 v[110:113], v[196:199], v[176:179], v[110:113]
	global_load_lds_dwordx4 v203, s[4:5]
	v_add_f32_e32 v36, 1.0, v36
	s_mov_b32 m0, s9
	v_mfma_f32_16x16x32_bf16 v[114:117], v[184:187], v[180:183], v[114:117]
	global_load_lds_dwordx4 v204, s[6:7]
	s_add_u32 m0, s9, 0x400
	v_mfma_f32_16x16x32_bf16 v[118:121], v[188:191], v[180:183], v[118:121]
	global_load_lds_dwordx4 v205, s[6:7]
	v_add_f32_e32 v37, 1.0, v37
	v_mfma_f32_16x16x32_bf16 v[122:125], v[192:195], v[180:183], v[122:125]
	s_add_u32 s4, s4, 0x80
	s_addc_u32 s5, s5, 0
	v_mfma_f32_16x16x32_bf16 v[126:129], v[196:199], v[180:183], v[126:129]
	s_add_u32 s6, s6, 0x80
	s_addc_u32 s7, s7, 0
	v_add_f32_e32 v38, 1.0, v38
	s_waitcnt lgkmcnt(0)
	v_mfma_f32_16x16x32_bf16 v[66:69], v[152:155], v[136:139], v[66:69]
	ds_read_b128 v[168:171], v228 offset:0
	v_mfma_f32_16x16x32_bf16 v[70:73], v[156:159], v[136:139], v[70:73]
	ds_read_b128 v[172:175], v228 offset:2048
	v_add_f32_e32 v39, 1.0, v39
	v_mfma_f32_16x16x32_bf16 v[74:77], v[160:163], v[136:139], v[74:77]
	ds_read_b128 v[176:179], v228 offset:4096
	v_add_f32_e32 v40, 1.0, v40
	v_mfma_f32_16x16x32_bf16 v[78:81], v[164:167], v[136:139], v[78:81]
	ds_read_b128 v[180:183], v228 offset:6144
	v_add_f32_e32 v41, 1.0, v41
	v_mfma_f32_16x16x32_bf16 v[82:85], v[152:155], v[140:143], v[82:85]
	ds_read_b128 v[184:187], v234 offset:0
	v_mfma_f32_16x16x32_bf16 v[86:89], v[156:159], v[140:143], v[86:89]
	ds_read_b128 v[188:191], v234 offset:2048
	v_rcp_f32_e32 v34, v34
	v_mfma_f32_16x16x32_bf16 v[90:93], v[160:163], v[140:143], v[90:93]
	ds_read_b128 v[192:195], v234 offset:4096
	v_rcp_f32_e32 v35, v35
	v_mfma_f32_16x16x32_bf16 v[94:97], v[164:167], v[140:143], v[94:97]
	ds_read_b128 v[196:199], v234 offset:6144
	v_rcp_f32_e32 v36, v36
	v_mfma_f32_16x16x32_bf16 v[98:101], v[152:155], v[144:147], v[98:101]
	v_mfma_f32_16x16x32_bf16 v[102:105], v[156:159], v[144:147], v[102:105]
	v_rcp_f32_e32 v37, v37
	v_mfma_f32_16x16x32_bf16 v[106:109], v[160:163], v[144:147], v[106:109]
	v_rcp_f32_e32 v38, v38
	v_mfma_f32_16x16x32_bf16 v[110:113], v[164:167], v[144:147], v[110:113]
	v_rcp_f32_e32 v39, v39
	v_mfma_f32_16x16x32_bf16 v[114:117], v[152:155], v[148:151], v[114:117]
	v_mfma_f32_16x16x32_bf16 v[118:121], v[156:159], v[148:151], v[118:121]
	v_rcp_f32_e32 v40, v40
	v_mfma_f32_16x16x32_bf16 v[122:125], v[160:163], v[148:151], v[122:125]
	v_rcp_f32_e32 v41, v41
	v_mfma_f32_16x16x32_bf16 v[126:129], v[164:167], v[148:151], v[126:129]
	v_cvt_pk_bf16_f32 v34, v34, v35
	s_waitcnt vmcnt(6) lgkmcnt(0)
	s_barrier
	v_mfma_f32_16x16x32_bf16 v[66:69], v[184:187], v[168:171], v[66:69]
	ds_read_b128 v[136:139], v224 offset:0
	v_mfma_f32_16x16x32_bf16 v[70:73], v[188:191], v[168:171], v[70:73]
	ds_read_b128 v[140:143], v224 offset:2048
	v_mfma_f32_16x16x32_bf16 v[74:77], v[192:195], v[168:171], v[74:77]
	ds_read_b128 v[144:147], v224 offset:4096
	v_cvt_pk_bf16_f32 v35, v36, v37
	v_mfma_f32_16x16x32_bf16 v[78:81], v[196:199], v[168:171], v[78:81]
	ds_read_b128 v[148:151], v224 offset:6144
	v_mfma_f32_16x16x32_bf16 v[82:85], v[184:187], v[172:175], v[82:85]
	ds_read_b128 v[152:155], v232 offset:0
	v_cvt_pk_bf16_f32 v36, v38, v39
	v_mfma_f32_16x16x32_bf16 v[86:89], v[188:191], v[172:175], v[86:89]
	ds_read_b128 v[156:159], v232 offset:2048
	v_mfma_f32_16x16x32_bf16 v[90:93], v[192:195], v[172:175], v[90:93]
	ds_read_b128 v[160:163], v232 offset:4096
	v_cvt_pk_bf16_f32 v37, v40, v41
	v_mfma_f32_16x16x32_bf16 v[94:97], v[196:199], v[172:175], v[94:97]
	ds_read_b128 v[164:167], v232 offset:6144
	s_add_u32 m0, s8, 0xc000
	v_mfma_f32_16x16x32_bf16 v[98:101], v[184:187], v[176:179], v[98:101]
	global_load_lds_dwordx4 v200, s[4:5]
	s_add_u32 m0, s8, 0xc400
	v_mfma_f32_16x16x32_bf16 v[102:105], v[188:191], v[176:179], v[102:105]
	global_load_lds_dwordx4 v201, s[4:5]
	global_store_dwordx4 v241, v[34:37], s[10:11] offset:0
	s_add_u32 m0, s8, 0xc800
	v_mfma_f32_16x16x32_bf16 v[106:109], v[192:195], v[176:179], v[106:109]
	global_load_lds_dwordx4 v202, s[4:5]
	s_add_u32 m0, s8, 0xcc00
	v_mfma_f32_16x16x32_bf16 v[110:113], v[196:199], v[176:179], v[110:113]
	global_load_lds_dwordx4 v203, s[4:5]
	v_mul_f32_e32 v42, s12, v42
	s_add_u32 m0, s9, 0xc000
	v_mfma_f32_16x16x32_bf16 v[114:117], v[184:187], v[180:183], v[114:117]
	global_load_lds_dwordx4 v204, s[6:7]
	s_add_u32 m0, s9, 0xc400
	v_mfma_f32_16x16x32_bf16 v[118:121], v[188:191], v[180:183], v[118:121]
	global_load_lds_dwordx4 v205, s[6:7]
	v_mul_f32_e32 v43, s12, v43
	v_mfma_f32_16x16x32_bf16 v[122:125], v[192:195], v[180:183], v[122:125]
	s_add_u32 s4, s4, 0x80
	s_addc_u32 s5, s5, 0
	v_mfma_f32_16x16x32_bf16 v[126:129], v[196:199], v[180:183], v[126:129]
	s_add_u32 s6, s6, 0x80
	s_addc_u32 s7, s7, 0
	v_mul_f32_e32 v44, s12, v44
	s_waitcnt lgkmcnt(0)
	v_mfma_f32_16x16x32_bf16 v[66:69], v[152:155], v[136:139], v[66:69]
	ds_read_b128 v[168:171], v229 offset:0
	v_mfma_f32_16x16x32_bf16 v[70:73], v[156:159], v[136:139], v[70:73]
	ds_read_b128 v[172:175], v229 offset:2048
	v_mul_f32_e32 v45, s12, v45
	v_mfma_f32_16x16x32_bf16 v[74:77], v[160:163], v[136:139], v[74:77]
	ds_read_b128 v[176:179], v229 offset:4096
	v_mul_f32_e32 v46, s12, v46
	v_mfma_f32_16x16x32_bf16 v[78:81], v[164:167], v[136:139], v[78:81]
	ds_read_b128 v[180:183], v229 offset:6144
	v_mul_f32_e32 v47, s12, v47
	v_mfma_f32_16x16x32_bf16 v[82:85], v[152:155], v[140:143], v[82:85]
	ds_read_b128 v[184:187], v235 offset:0
	v_mfma_f32_16x16x32_bf16 v[86:89], v[156:159], v[140:143], v[86:89]
	ds_read_b128 v[188:191], v235 offset:2048
	v_mul_f32_e32 v48, s12, v48
	v_mfma_f32_16x16x32_bf16 v[90:93], v[160:163], v[140:143], v[90:93]
	ds_read_b128 v[192:195], v235 offset:4096
	v_mul_f32_e32 v49, s12, v49
	v_mfma_f32_16x16x32_bf16 v[94:97], v[164:167], v[140:143], v[94:97]
	ds_read_b128 v[196:199], v235 offset:6144
	v_exp_f32_e32 v42, v42
	v_mfma_f32_16x16x32_bf16 v[98:101], v[152:155], v[144:147], v[98:101]
	v_mfma_f32_16x16x32_bf16 v[102:105], v[156:159], v[144:147], v[102:105]
	v_exp_f32_e32 v43, v43
	v_mfma_f32_16x16x32_bf16 v[106:109], v[160:163], v[144:147], v[106:109]
	v_exp_f32_e32 v44, v44
	v_mfma_f32_16x16x32_bf16 v[110:113], v[164:167], v[144:147], v[110:113]
	v_exp_f32_e32 v45, v45
	v_mfma_f32_16x16x32_bf16 v[114:117], v[152:155], v[148:151], v[114:117]
	v_mfma_f32_16x16x32_bf16 v[118:121], v[156:159], v[148:151], v[118:121]
	v_exp_f32_e32 v46, v46
	v_mfma_f32_16x16x32_bf16 v[122:125], v[160:163], v[148:151], v[122:125]
	v_exp_f32_e32 v47, v47
	v_mfma_f32_16x16x32_bf16 v[126:129], v[164:167], v[148:151], v[126:129]
	v_exp_f32_e32 v48, v48
	s_waitcnt vmcnt(7) lgkmcnt(0)
	s_barrier
	v_mfma_f32_16x16x32_bf16 v[66:69], v[184:187], v[168:171], v[66:69]
	ds_read_b128 v[136:139], v218 offset:0
	v_mfma_f32_16x16x32_bf16 v[70:73], v[188:191], v[168:171], v[70:73]
	ds_read_b128 v[140:143], v218 offset:2048
	v_mfma_f32_16x16x32_bf16 v[74:77], v[192:195], v[168:171], v[74:77]
	ds_read_b128 v[144:147], v218 offset:4096
	v_exp_f32_e32 v49, v49
	v_mfma_f32_16x16x32_bf16 v[78:81], v[196:199], v[168:171], v[78:81]
	ds_read_b128 v[148:151], v218 offset:6144
	v_mfma_f32_16x16x32_bf16 v[82:85], v[184:187], v[172:175], v[82:85]
	ds_read_b128 v[152:155], v230 offset:0
	v_add_f32_e32 v42, 1.0, v42
	v_mfma_f32_16x16x32_bf16 v[86:89], v[188:191], v[172:175], v[86:89]
	ds_read_b128 v[156:159], v230 offset:2048
	v_mfma_f32_16x16x32_bf16 v[90:93], v[192:195], v[172:175], v[90:93]
	ds_read_b128 v[160:163], v230 offset:4096
	v_add_f32_e32 v43, 1.0, v43
	v_mfma_f32_16x16x32_bf16 v[94:97], v[196:199], v[172:175], v[94:97]
	ds_read_b128 v[164:167], v230 offset:6144
	s_add_u32 m0, s8, 0x18000
	v_mfma_f32_16x16x32_bf16 v[98:101], v[184:187], v[176:179], v[98:101]
	global_load_lds_dwordx4 v200, s[4:5]
	s_add_u32 m0, s8, 0x18400
	v_mfma_f32_16x16x32_bf16 v[102:105], v[188:191], v[176:179], v[102:105]
	global_load_lds_dwordx4 v201, s[4:5]
	v_add_f32_e32 v44, 1.0, v44
	s_add_u32 m0, s8, 0x18800
	v_mfma_f32_16x16x32_bf16 v[106:109], v[192:195], v[176:179], v[106:109]
	global_load_lds_dwordx4 v202, s[4:5]
	s_add_u32 m0, s8, 0x18c00
	v_mfma_f32_16x16x32_bf16 v[110:113], v[196:199], v[176:179], v[110:113]
	global_load_lds_dwordx4 v203, s[4:5]
	v_add_f32_e32 v45, 1.0, v45
	s_add_u32 m0, s9, 0x18000
	v_mfma_f32_16x16x32_bf16 v[114:117], v[184:187], v[180:183], v[114:117]
	global_load_lds_dwordx4 v204, s[6:7]
	s_add_u32 m0, s9, 0x18400
	v_mfma_f32_16x16x32_bf16 v[118:121], v[188:191], v[180:183], v[118:121]
	global_load_lds_dwordx4 v205, s[6:7]
	v_add_f32_e32 v46, 1.0, v46
	v_mfma_f32_16x16x32_bf16 v[122:125], v[192:195], v[180:183], v[122:125]
	s_add_u32 s4, s4, 0x80
	s_addc_u32 s5, s5, 0
	v_mfma_f32_16x16x32_bf16 v[126:129], v[196:199], v[180:183], v[126:129]
	s_add_u32 s6, s6, 0x80
	s_addc_u32 s7, s7, 0
	v_add_f32_e32 v47, 1.0, v47
	s_waitcnt lgkmcnt(0)
	v_mfma_f32_16x16x32_bf16 v[66:69], v[152:155], v[136:139], v[66:69]
	ds_read_b128 v[168:171], v225 offset:0
	v_mfma_f32_16x16x32_bf16 v[70:73], v[156:159], v[136:139], v[70:73]
	ds_read_b128 v[172:175], v225 offset:2048
	v_add_f32_e32 v48, 1.0, v48
	v_mfma_f32_16x16x32_bf16 v[74:77], v[160:163], v[136:139], v[74:77]
	ds_read_b128 v[176:179], v225 offset:4096
	v_add_f32_e32 v49, 1.0, v49
	v_mfma_f32_16x16x32_bf16 v[78:81], v[164:167], v[136:139], v[78:81]
	ds_read_b128 v[180:183], v225 offset:6144
	v_rcp_f32_e32 v42, v42
	v_mfma_f32_16x16x32_bf16 v[82:85], v[152:155], v[140:143], v[82:85]
	ds_read_b128 v[184:187], v233 offset:0
	v_mfma_f32_16x16x32_bf16 v[86:89], v[156:159], v[140:143], v[86:89]
	ds_read_b128 v[188:191], v233 offset:2048
	v_rcp_f32_e32 v43, v43
	v_mfma_f32_16x16x32_bf16 v[90:93], v[160:163], v[140:143], v[90:93]
	ds_read_b128 v[192:195], v233 offset:4096
	v_rcp_f32_e32 v44, v44
	v_mfma_f32_16x16x32_bf16 v[94:97], v[164:167], v[140:143], v[94:97]
	ds_read_b128 v[196:199], v233 offset:6144
	v_rcp_f32_e32 v45, v45
	v_mfma_f32_16x16x32_bf16 v[98:101], v[152:155], v[144:147], v[98:101]
	v_mfma_f32_16x16x32_bf16 v[102:105], v[156:159], v[144:147], v[102:105]
	v_rcp_f32_e32 v46, v46
	v_mfma_f32_16x16x32_bf16 v[106:109], v[160:163], v[144:147], v[106:109]
	v_rcp_f32_e32 v47, v47
	v_mfma_f32_16x16x32_bf16 v[110:113], v[164:167], v[144:147], v[110:113]
	v_rcp_f32_e32 v48, v48
	v_mfma_f32_16x16x32_bf16 v[114:117], v[152:155], v[148:151], v[114:117]
	v_mfma_f32_16x16x32_bf16 v[118:121], v[156:159], v[148:151], v[118:121]
	v_rcp_f32_e32 v49, v49
	v_mfma_f32_16x16x32_bf16 v[122:125], v[160:163], v[148:151], v[122:125]
	v_cvt_pk_bf16_f32 v42, v42, v43
	v_mfma_f32_16x16x32_bf16 v[126:129], v[164:167], v[148:151], v[126:129]
	v_cvt_pk_bf16_f32 v43, v44, v45
	s_waitcnt vmcnt(6) lgkmcnt(0)
	s_barrier
	v_mfma_f32_16x16x32_bf16 v[66:69], v[184:187], v[168:171], v[66:69]
	ds_read_b128 v[136:139], v219 offset:0
	v_mfma_f32_16x16x32_bf16 v[70:73], v[188:191], v[168:171], v[70:73]
	ds_read_b128 v[140:143], v219 offset:2048
	v_mfma_f32_16x16x32_bf16 v[74:77], v[192:195], v[168:171], v[74:77]
	ds_read_b128 v[144:147], v219 offset:4096
	v_cvt_pk_bf16_f32 v44, v46, v47
	v_mfma_f32_16x16x32_bf16 v[78:81], v[196:199], v[168:171], v[78:81]
	ds_read_b128 v[148:151], v219 offset:6144
	v_mfma_f32_16x16x32_bf16 v[82:85], v[184:187], v[172:175], v[82:85]
	ds_read_b128 v[152:155], v231 offset:0
	v_cvt_pk_bf16_f32 v45, v48, v49
	v_mfma_f32_16x16x32_bf16 v[86:89], v[188:191], v[172:175], v[86:89]
	ds_read_b128 v[156:159], v231 offset:2048
	v_mfma_f32_16x16x32_bf16 v[90:93], v[192:195], v[172:175], v[90:93]
	ds_read_b128 v[160:163], v231 offset:4096
	global_store_dwordx4 v241, v[42:45], s[10:11] offset:16
	v_mfma_f32_16x16x32_bf16 v[94:97], v[196:199], v[172:175], v[94:97]
	ds_read_b128 v[164:167], v231 offset:6144
	s_mov_b32 m0, s8
	v_mfma_f32_16x16x32_bf16 v[98:101], v[184:187], v[176:179], v[98:101]
	global_load_lds_dwordx4 v200, s[4:5]
	s_add_u32 m0, s8, 0x400
	v_mfma_f32_16x16x32_bf16 v[102:105], v[188:191], v[176:179], v[102:105]
	global_load_lds_dwordx4 v201, s[4:5]
	v_mul_f32_e32 v50, s12, v50
	s_add_u32 m0, s8, 0x800
	v_mfma_f32_16x16x32_bf16 v[106:109], v[192:195], v[176:179], v[106:109]
	global_load_lds_dwordx4 v202, s[4:5]
	s_add_u32 m0, s8, 0xc00
	v_mfma_f32_16x16x32_bf16 v[110:113], v[196:199], v[176:179], v[110:113]
	global_load_lds_dwordx4 v203, s[4:5]
	v_mul_f32_e32 v51, s12, v51
	s_mov_b32 m0, s9
	v_mfma_f32_16x16x32_bf16 v[114:117], v[184:187], v[180:183], v[114:117]
	global_load_lds_dwordx4 v204, s[6:7]
	s_add_u32 m0, s9, 0x400
	v_mfma_f32_16x16x32_bf16 v[118:121], v[188:191], v[180:183], v[118:121]
	global_load_lds_dwordx4 v205, s[6:7]
	v_mul_f32_e32 v52, s12, v52
	v_mfma_f32_16x16x32_bf16 v[122:125], v[192:195], v[180:183], v[122:125]
	s_add_u32 s4, s4, 0x80
	s_addc_u32 s5, s5, 0
	v_mfma_f32_16x16x32_bf16 v[126:129], v[196:199], v[180:183], v[126:129]
	s_add_u32 s6, s6, 0x80
	s_addc_u32 s7, s7, 0
	v_mul_f32_e32 v53, s12, v53
	s_waitcnt lgkmcnt(0)
	v_mfma_f32_16x16x32_bf16 v[66:69], v[152:155], v[136:139], v[66:69]
	ds_read_b128 v[168:171], v228 offset:0
	v_mfma_f32_16x16x32_bf16 v[70:73], v[156:159], v[136:139], v[70:73]
	ds_read_b128 v[172:175], v228 offset:2048
	v_mul_f32_e32 v54, s12, v54
	v_mfma_f32_16x16x32_bf16 v[74:77], v[160:163], v[136:139], v[74:77]
	ds_read_b128 v[176:179], v228 offset:4096
	v_mul_f32_e32 v55, s12, v55
	v_mfma_f32_16x16x32_bf16 v[78:81], v[164:167], v[136:139], v[78:81]
	ds_read_b128 v[180:183], v228 offset:6144
	v_mul_f32_e32 v56, s12, v56
	v_mfma_f32_16x16x32_bf16 v[82:85], v[152:155], v[140:143], v[82:85]
	ds_read_b128 v[184:187], v234 offset:0
	v_mfma_f32_16x16x32_bf16 v[86:89], v[156:159], v[140:143], v[86:89]
	ds_read_b128 v[188:191], v234 offset:2048
	v_mul_f32_e32 v57, s12, v57
	v_mfma_f32_16x16x32_bf16 v[90:93], v[160:163], v[140:143], v[90:93]
	ds_read_b128 v[192:195], v234 offset:4096
	v_exp_f32_e32 v50, v50
	v_mfma_f32_16x16x32_bf16 v[94:97], v[164:167], v[140:143], v[94:97]
	ds_read_b128 v[196:199], v234 offset:6144
	v_exp_f32_e32 v51, v51
	v_mfma_f32_16x16x32_bf16 v[98:101], v[152:155], v[144:147], v[98:101]
	v_mfma_f32_16x16x32_bf16 v[102:105], v[156:159], v[144:147], v[102:105]
	v_exp_f32_e32 v52, v52
	v_mfma_f32_16x16x32_bf16 v[106:109], v[160:163], v[144:147], v[106:109]
	v_exp_f32_e32 v53, v53
	v_mfma_f32_16x16x32_bf16 v[110:113], v[164:167], v[144:147], v[110:113]
	v_exp_f32_e32 v54, v54
	v_mfma_f32_16x16x32_bf16 v[114:117], v[152:155], v[148:151], v[114:117]
	v_mfma_f32_16x16x32_bf16 v[118:121], v[156:159], v[148:151], v[118:121]
	v_exp_f32_e32 v55, v55
	v_mfma_f32_16x16x32_bf16 v[122:125], v[160:163], v[148:151], v[122:125]
	v_exp_f32_e32 v56, v56
	v_mfma_f32_16x16x32_bf16 v[126:129], v[164:167], v[148:151], v[126:129]
	v_exp_f32_e32 v57, v57
	s_waitcnt vmcnt(7) lgkmcnt(0)
	s_barrier
	v_mfma_f32_16x16x32_bf16 v[66:69], v[184:187], v[168:171], v[66:69]
	ds_read_b128 v[136:139], v224 offset:0
	v_mfma_f32_16x16x32_bf16 v[70:73], v[188:191], v[168:171], v[70:73]
	ds_read_b128 v[140:143], v224 offset:2048
	v_mfma_f32_16x16x32_bf16 v[74:77], v[192:195], v[168:171], v[74:77]
	ds_read_b128 v[144:147], v224 offset:4096
	v_add_f32_e32 v50, 1.0, v50
	v_mfma_f32_16x16x32_bf16 v[78:81], v[196:199], v[168:171], v[78:81]
	ds_read_b128 v[148:151], v224 offset:6144
	v_mfma_f32_16x16x32_bf16 v[82:85], v[184:187], v[172:175], v[82:85]
	ds_read_b128 v[152:155], v232 offset:0
	v_add_f32_e32 v51, 1.0, v51
	v_mfma_f32_16x16x32_bf16 v[86:89], v[188:191], v[172:175], v[86:89]
	ds_read_b128 v[156:159], v232 offset:2048
	v_mfma_f32_16x16x32_bf16 v[90:93], v[192:195], v[172:175], v[90:93]
	ds_read_b128 v[160:163], v232 offset:4096
	v_add_f32_e32 v52, 1.0, v52
	v_mfma_f32_16x16x32_bf16 v[94:97], v[196:199], v[172:175], v[94:97]
	ds_read_b128 v[164:167], v232 offset:6144
	s_add_u32 m0, s8, 0xc000
	v_mfma_f32_16x16x32_bf16 v[98:101], v[184:187], v[176:179], v[98:101]
	global_load_lds_dwordx4 v200, s[4:5]
	s_add_u32 m0, s8, 0xc400
	v_mfma_f32_16x16x32_bf16 v[102:105], v[188:191], v[176:179], v[102:105]
	global_load_lds_dwordx4 v201, s[4:5]
	v_add_f32_e32 v53, 1.0, v53
	s_add_u32 m0, s8, 0xc800
	v_mfma_f32_16x16x32_bf16 v[106:109], v[192:195], v[176:179], v[106:109]
	global_load_lds_dwordx4 v202, s[4:5]
	s_add_u32 m0, s8, 0xcc00
	v_mfma_f32_16x16x32_bf16 v[110:113], v[196:199], v[176:179], v[110:113]
	global_load_lds_dwordx4 v203, s[4:5]
	v_add_f32_e32 v54, 1.0, v54
	s_add_u32 m0, s9, 0xc000
	v_mfma_f32_16x16x32_bf16 v[114:117], v[184:187], v[180:183], v[114:117]
	global_load_lds_dwordx4 v204, s[6:7]
	s_add_u32 m0, s9, 0xc400
	v_mfma_f32_16x16x32_bf16 v[118:121], v[188:191], v[180:183], v[118:121]
	global_load_lds_dwordx4 v205, s[6:7]
	v_add_f32_e32 v55, 1.0, v55
	v_mfma_f32_16x16x32_bf16 v[122:125], v[192:195], v[180:183], v[122:125]
	s_sub_u32 s4, s4, 0x780
	s_subb_u32 s5, s5, 0
	v_mfma_f32_16x16x32_bf16 v[126:129], v[196:199], v[180:183], v[126:129]
	s_add_u32 s6, s6, 0x3f880
	s_addc_u32 s7, s7, 0
	v_add_f32_e32 v56, 1.0, v56
	s_waitcnt lgkmcnt(0)
	v_mfma_f32_16x16x32_bf16 v[66:69], v[152:155], v[136:139], v[66:69]
	ds_read_b128 v[168:171], v229 offset:0
	v_mfma_f32_16x16x32_bf16 v[70:73], v[156:159], v[136:139], v[70:73]
	ds_read_b128 v[172:175], v229 offset:2048
	v_add_f32_e32 v57, 1.0, v57
	v_mfma_f32_16x16x32_bf16 v[74:77], v[160:163], v[136:139], v[74:77]
	ds_read_b128 v[176:179], v229 offset:4096
	v_rcp_f32_e32 v50, v50
	v_mfma_f32_16x16x32_bf16 v[78:81], v[164:167], v[136:139], v[78:81]
	ds_read_b128 v[180:183], v229 offset:6144
	v_rcp_f32_e32 v51, v51
	v_mfma_f32_16x16x32_bf16 v[82:85], v[152:155], v[140:143], v[82:85]
	ds_read_b128 v[184:187], v235 offset:0
	v_mfma_f32_16x16x32_bf16 v[86:89], v[156:159], v[140:143], v[86:89]
	ds_read_b128 v[188:191], v235 offset:2048
	v_rcp_f32_e32 v52, v52
	v_mfma_f32_16x16x32_bf16 v[90:93], v[160:163], v[140:143], v[90:93]
	ds_read_b128 v[192:195], v235 offset:4096
	v_rcp_f32_e32 v53, v53
	v_mfma_f32_16x16x32_bf16 v[94:97], v[164:167], v[140:143], v[94:97]
	ds_read_b128 v[196:199], v235 offset:6144
	v_rcp_f32_e32 v54, v54
	v_mfma_f32_16x16x32_bf16 v[98:101], v[152:155], v[144:147], v[98:101]
	v_mfma_f32_16x16x32_bf16 v[102:105], v[156:159], v[144:147], v[102:105]
	v_rcp_f32_e32 v55, v55
	v_mfma_f32_16x16x32_bf16 v[106:109], v[160:163], v[144:147], v[106:109]
	v_rcp_f32_e32 v56, v56
	v_mfma_f32_16x16x32_bf16 v[110:113], v[164:167], v[144:147], v[110:113]
	v_rcp_f32_e32 v57, v57
	v_mfma_f32_16x16x32_bf16 v[114:117], v[152:155], v[148:151], v[114:117]
	v_mfma_f32_16x16x32_bf16 v[118:121], v[156:159], v[148:151], v[118:121]
	v_cvt_pk_bf16_f32 v50, v50, v51
	v_mfma_f32_16x16x32_bf16 v[122:125], v[160:163], v[148:151], v[122:125]
	v_cvt_pk_bf16_f32 v51, v52, v53
	v_mfma_f32_16x16x32_bf16 v[126:129], v[164:167], v[148:151], v[126:129]
	v_cvt_pk_bf16_f32 v52, v54, v55
	s_waitcnt vmcnt(6) lgkmcnt(0)
	s_barrier
	v_mfma_f32_16x16x32_bf16 v[66:69], v[184:187], v[168:171], v[66:69]
	ds_read_b128 v[136:139], v218 offset:0
	v_mfma_f32_16x16x32_bf16 v[70:73], v[188:191], v[168:171], v[70:73]
	ds_read_b128 v[140:143], v218 offset:2048
	v_mfma_f32_16x16x32_bf16 v[74:77], v[192:195], v[168:171], v[74:77]
	ds_read_b128 v[144:147], v218 offset:4096
	v_cvt_pk_bf16_f32 v53, v56, v57
	v_mfma_f32_16x16x32_bf16 v[78:81], v[196:199], v[168:171], v[78:81]
	ds_read_b128 v[148:151], v218 offset:6144
	v_mfma_f32_16x16x32_bf16 v[82:85], v[184:187], v[172:175], v[82:85]
	ds_read_b128 v[152:155], v230 offset:0
	global_store_dwordx4 v241, v[50:53], s[10:11] offset:2048
	v_mfma_f32_16x16x32_bf16 v[86:89], v[188:191], v[172:175], v[86:89]
	ds_read_b128 v[156:159], v230 offset:2048
	v_mfma_f32_16x16x32_bf16 v[90:93], v[192:195], v[172:175], v[90:93]
	ds_read_b128 v[160:163], v230 offset:4096
	v_mul_f32_e32 v58, s12, v58
	v_mfma_f32_16x16x32_bf16 v[94:97], v[196:199], v[172:175], v[94:97]
	ds_read_b128 v[164:167], v230 offset:6144
	s_add_u32 m0, s8, 0x18000
	v_mfma_f32_16x16x32_bf16 v[98:101], v[184:187], v[176:179], v[98:101]
	global_load_lds_dwordx4 v200, s[4:5]
	s_add_u32 m0, s8, 0x18400
	v_mfma_f32_16x16x32_bf16 v[102:105], v[188:191], v[176:179], v[102:105]
	global_load_lds_dwordx4 v201, s[4:5]
	v_mul_f32_e32 v59, s12, v59
	s_add_u32 m0, s8, 0x18800
	v_mfma_f32_16x16x32_bf16 v[106:109], v[192:195], v[176:179], v[106:109]
	global_load_lds_dwordx4 v202, s[4:5]
	s_add_u32 m0, s8, 0x18c00
	v_mfma_f32_16x16x32_bf16 v[110:113], v[196:199], v[176:179], v[110:113]
	global_load_lds_dwordx4 v203, s[4:5]
	v_mul_f32_e32 v60, s12, v60
	s_add_u32 m0, s9, 0x18000
	v_mfma_f32_16x16x32_bf16 v[114:117], v[184:187], v[180:183], v[114:117]
	global_load_lds_dwordx4 v204, s[6:7]
	s_add_u32 m0, s9, 0x18400
	v_mfma_f32_16x16x32_bf16 v[118:121], v[188:191], v[180:183], v[118:121]
	global_load_lds_dwordx4 v205, s[6:7]
	v_mul_f32_e32 v61, s12, v61
	v_mfma_f32_16x16x32_bf16 v[122:125], v[192:195], v[180:183], v[122:125]
	s_add_u32 s4, s4, 0x80
	s_addc_u32 s5, s5, 0
	v_mfma_f32_16x16x32_bf16 v[126:129], v[196:199], v[180:183], v[126:129]
	s_add_u32 s6, s6, 0x80
	s_addc_u32 s7, s7, 0
	v_mul_f32_e32 v62, s12, v62
	s_waitcnt lgkmcnt(0)
	v_mfma_f32_16x16x32_bf16 v[66:69], v[152:155], v[136:139], v[66:69]
	ds_read_b128 v[168:171], v225 offset:0
	v_mfma_f32_16x16x32_bf16 v[70:73], v[156:159], v[136:139], v[70:73]
	ds_read_b128 v[172:175], v225 offset:2048
	v_mul_f32_e32 v63, s12, v63
	v_mfma_f32_16x16x32_bf16 v[74:77], v[160:163], v[136:139], v[74:77]
	ds_read_b128 v[176:179], v225 offset:4096
	v_mul_f32_e32 v64, s12, v64
	v_mfma_f32_16x16x32_bf16 v[78:81], v[164:167], v[136:139], v[78:81]
	ds_read_b128 v[180:183], v225 offset:6144
	v_mul_f32_e32 v65, s12, v65
	v_mfma_f32_16x16x32_bf16 v[82:85], v[152:155], v[140:143], v[82:85]
	ds_read_b128 v[184:187], v233 offset:0
	v_mfma_f32_16x16x32_bf16 v[86:89], v[156:159], v[140:143], v[86:89]
	ds_read_b128 v[188:191], v233 offset:2048
	v_exp_f32_e32 v58, v58
	v_mfma_f32_16x16x32_bf16 v[90:93], v[160:163], v[140:143], v[90:93]
	ds_read_b128 v[192:195], v233 offset:4096
	v_exp_f32_e32 v59, v59
	v_mfma_f32_16x16x32_bf16 v[94:97], v[164:167], v[140:143], v[94:97]
	ds_read_b128 v[196:199], v233 offset:6144
	v_exp_f32_e32 v60, v60
	v_mfma_f32_16x16x32_bf16 v[98:101], v[152:155], v[144:147], v[98:101]
	v_mfma_f32_16x16x32_bf16 v[102:105], v[156:159], v[144:147], v[102:105]
	v_exp_f32_e32 v61, v61
	v_mfma_f32_16x16x32_bf16 v[106:109], v[160:163], v[144:147], v[106:109]
	v_exp_f32_e32 v62, v62
	v_mfma_f32_16x16x32_bf16 v[110:113], v[164:167], v[144:147], v[110:113]
	v_exp_f32_e32 v63, v63
	v_mfma_f32_16x16x32_bf16 v[114:117], v[152:155], v[148:151], v[114:117]
	v_mfma_f32_16x16x32_bf16 v[118:121], v[156:159], v[148:151], v[118:121]
	v_exp_f32_e32 v64, v64
	v_mfma_f32_16x16x32_bf16 v[122:125], v[160:163], v[148:151], v[122:125]
	v_exp_f32_e32 v65, v65
	v_mfma_f32_16x16x32_bf16 v[126:129], v[164:167], v[148:151], v[126:129]
	v_add_f32_e32 v58, 1.0, v58
	s_waitcnt vmcnt(7) lgkmcnt(0)
	s_barrier
	v_mfma_f32_16x16x32_bf16 v[66:69], v[184:187], v[168:171], v[66:69]
	ds_read_b128 v[136:139], v219 offset:0
	v_mfma_f32_16x16x32_bf16 v[70:73], v[188:191], v[168:171], v[70:73]
	ds_read_b128 v[140:143], v219 offset:2048
	v_mfma_f32_16x16x32_bf16 v[74:77], v[192:195], v[168:171], v[74:77]
	ds_read_b128 v[144:147], v219 offset:4096
	v_add_f32_e32 v59, 1.0, v59
	v_mfma_f32_16x16x32_bf16 v[78:81], v[196:199], v[168:171], v[78:81]
	ds_read_b128 v[148:151], v219 offset:6144
	v_mfma_f32_16x16x32_bf16 v[82:85], v[184:187], v[172:175], v[82:85]
	ds_read_b128 v[152:155], v231 offset:0
	v_add_f32_e32 v60, 1.0, v60
	v_mfma_f32_16x16x32_bf16 v[86:89], v[188:191], v[172:175], v[86:89]
	ds_read_b128 v[156:159], v231 offset:2048
	v_mfma_f32_16x16x32_bf16 v[90:93], v[192:195], v[172:175], v[90:93]
	ds_read_b128 v[160:163], v231 offset:4096
	v_add_f32_e32 v61, 1.0, v61
	v_mfma_f32_16x16x32_bf16 v[94:97], v[196:199], v[172:175], v[94:97]
	ds_read_b128 v[164:167], v231 offset:6144
	s_mov_b32 m0, s8
	v_mfma_f32_16x16x32_bf16 v[98:101], v[184:187], v[176:179], v[98:101]
	global_load_lds_dwordx4 v200, s[4:5]
	s_add_u32 m0, s8, 0x400
	v_mfma_f32_16x16x32_bf16 v[102:105], v[188:191], v[176:179], v[102:105]
	global_load_lds_dwordx4 v201, s[4:5]
	v_add_f32_e32 v62, 1.0, v62
	s_add_u32 m0, s8, 0x800
	v_mfma_f32_16x16x32_bf16 v[106:109], v[192:195], v[176:179], v[106:109]
	global_load_lds_dwordx4 v202, s[4:5]
	s_add_u32 m0, s8, 0xc00
	v_mfma_f32_16x16x32_bf16 v[110:113], v[196:199], v[176:179], v[110:113]
	global_load_lds_dwordx4 v203, s[4:5]
	v_add_f32_e32 v63, 1.0, v63
	s_mov_b32 m0, s9
	v_mfma_f32_16x16x32_bf16 v[114:117], v[184:187], v[180:183], v[114:117]
	global_load_lds_dwordx4 v204, s[6:7]
	s_add_u32 m0, s9, 0x400
	v_mfma_f32_16x16x32_bf16 v[118:121], v[188:191], v[180:183], v[118:121]
	global_load_lds_dwordx4 v205, s[6:7]
	v_add_f32_e32 v64, 1.0, v64
	v_mfma_f32_16x16x32_bf16 v[122:125], v[192:195], v[180:183], v[122:125]
	s_add_u32 s4, s4, 0x80
	s_addc_u32 s5, s5, 0
	v_mfma_f32_16x16x32_bf16 v[126:129], v[196:199], v[180:183], v[126:129]
	s_add_u32 s6, s6, 0x80
	s_addc_u32 s7, s7, 0
	v_add_f32_e32 v65, 1.0, v65
	s_waitcnt lgkmcnt(0)
	v_mfma_f32_16x16x32_bf16 v[66:69], v[152:155], v[136:139], v[66:69]
	ds_read_b128 v[168:171], v228 offset:0
	v_mfma_f32_16x16x32_bf16 v[70:73], v[156:159], v[136:139], v[70:73]
	ds_read_b128 v[172:175], v228 offset:2048
	v_rcp_f32_e32 v58, v58
	v_mfma_f32_16x16x32_bf16 v[74:77], v[160:163], v[136:139], v[74:77]
	ds_read_b128 v[176:179], v228 offset:4096
	v_rcp_f32_e32 v59, v59
	v_mfma_f32_16x16x32_bf16 v[78:81], v[164:167], v[136:139], v[78:81]
	ds_read_b128 v[180:183], v228 offset:6144
	v_rcp_f32_e32 v60, v60
	v_mfma_f32_16x16x32_bf16 v[82:85], v[152:155], v[140:143], v[82:85]
	ds_read_b128 v[184:187], v234 offset:0
	v_mfma_f32_16x16x32_bf16 v[86:89], v[156:159], v[140:143], v[86:89]
	ds_read_b128 v[188:191], v234 offset:2048
	v_rcp_f32_e32 v61, v61
	v_mfma_f32_16x16x32_bf16 v[90:93], v[160:163], v[140:143], v[90:93]
	ds_read_b128 v[192:195], v234 offset:4096
	v_rcp_f32_e32 v62, v62
	v_mfma_f32_16x16x32_bf16 v[94:97], v[164:167], v[140:143], v[94:97]
	ds_read_b128 v[196:199], v234 offset:6144
	v_rcp_f32_e32 v63, v63
	v_mfma_f32_16x16x32_bf16 v[98:101], v[152:155], v[144:147], v[98:101]
	v_mfma_f32_16x16x32_bf16 v[102:105], v[156:159], v[144:147], v[102:105]
	v_rcp_f32_e32 v64, v64
	v_mfma_f32_16x16x32_bf16 v[106:109], v[160:163], v[144:147], v[106:109]
	v_rcp_f32_e32 v65, v65
	v_mfma_f32_16x16x32_bf16 v[110:113], v[164:167], v[144:147], v[110:113]
	v_cvt_pk_bf16_f32 v58, v58, v59
	v_mfma_f32_16x16x32_bf16 v[114:117], v[152:155], v[148:151], v[114:117]
	v_mfma_f32_16x16x32_bf16 v[118:121], v[156:159], v[148:151], v[118:121]
	v_cvt_pk_bf16_f32 v59, v60, v61
	v_mfma_f32_16x16x32_bf16 v[122:125], v[160:163], v[148:151], v[122:125]
	v_cvt_pk_bf16_f32 v60, v62, v63
	v_mfma_f32_16x16x32_bf16 v[126:129], v[164:167], v[148:151], v[126:129]
	v_cvt_pk_bf16_f32 v61, v64, v65
	s_waitcnt vmcnt(6) lgkmcnt(0)
	s_barrier
	v_mfma_f32_16x16x32_bf16 v[66:69], v[184:187], v[168:171], v[66:69]
	ds_read_b128 v[136:139], v224 offset:0
	v_mfma_f32_16x16x32_bf16 v[70:73], v[188:191], v[168:171], v[70:73]
	ds_read_b128 v[140:143], v224 offset:2048
	v_mfma_f32_16x16x32_bf16 v[74:77], v[192:195], v[168:171], v[74:77]
	ds_read_b128 v[144:147], v224 offset:4096
	v_mfma_f32_16x16x32_bf16 v[78:81], v[196:199], v[168:171], v[78:81]
	ds_read_b128 v[148:151], v224 offset:6144
	v_mfma_f32_16x16x32_bf16 v[82:85], v[184:187], v[172:175], v[82:85]
	ds_read_b128 v[152:155], v232 offset:0
	v_mfma_f32_16x16x32_bf16 v[86:89], v[188:191], v[172:175], v[86:89]
	ds_read_b128 v[156:159], v232 offset:2048
	v_mfma_f32_16x16x32_bf16 v[90:93], v[192:195], v[172:175], v[90:93]
	ds_read_b128 v[160:163], v232 offset:4096
	v_mfma_f32_16x16x32_bf16 v[94:97], v[196:199], v[172:175], v[94:97]
	ds_read_b128 v[164:167], v232 offset:6144
	s_add_u32 m0, s8, 0xc000
	v_mfma_f32_16x16x32_bf16 v[98:101], v[184:187], v[176:179], v[98:101]
	global_load_lds_dwordx4 v200, s[4:5]
	s_add_u32 m0, s8, 0xc400
	v_mfma_f32_16x16x32_bf16 v[102:105], v[188:191], v[176:179], v[102:105]
	global_load_lds_dwordx4 v201, s[4:5]
	s_add_u32 m0, s8, 0xc800
	v_mfma_f32_16x16x32_bf16 v[106:109], v[192:195], v[176:179], v[106:109]
	global_load_lds_dwordx4 v202, s[4:5]
	s_add_u32 m0, s8, 0xcc00
	v_mfma_f32_16x16x32_bf16 v[110:113], v[196:199], v[176:179], v[110:113]
	global_load_lds_dwordx4 v203, s[4:5]
	s_add_u32 m0, s9, 0xc000
	v_mfma_f32_16x16x32_bf16 v[114:117], v[184:187], v[180:183], v[114:117]
	global_load_lds_dwordx4 v204, s[6:7]
	s_add_u32 m0, s9, 0xc400
	v_mfma_f32_16x16x32_bf16 v[118:121], v[188:191], v[180:183], v[118:121]
	global_load_lds_dwordx4 v205, s[6:7]
	v_mfma_f32_16x16x32_bf16 v[122:125], v[192:195], v[180:183], v[122:125]
	s_add_u32 s4, s4, 0x80
	s_addc_u32 s5, s5, 0
	v_mfma_f32_16x16x32_bf16 v[126:129], v[196:199], v[180:183], v[126:129]
	s_add_u32 s6, s6, 0x80
	s_addc_u32 s7, s7, 0
	global_store_dwordx4 v241, v[58:61], s[10:11] offset:2064
	s_waitcnt lgkmcnt(0)
	v_mfma_f32_16x16x32_bf16 v[2:5], v[152:155], v[136:139], 0
	ds_read_b128 v[168:171], v229 offset:0
	v_mfma_f32_16x16x32_bf16 v[6:9], v[156:159], v[136:139], 0
	ds_read_b128 v[172:175], v229 offset:2048
	s_add_u32 s10, s28, s13
	s_addc_u32 s11, s29, 0
	v_mfma_f32_16x16x32_bf16 v[10:13], v[160:163], v[136:139], 0
	ds_read_b128 v[176:179], v229 offset:4096
	s_add_u32 s13, s13, 0x10000
	v_mfma_f32_16x16x32_bf16 v[14:17], v[164:167], v[136:139], 0
	ds_read_b128 v[180:183], v229 offset:6144
	v_mul_f32_e32 v66, s12, v66
	v_mfma_f32_16x16x32_bf16 v[18:21], v[152:155], v[140:143], 0
	ds_read_b128 v[184:187], v235 offset:0
	v_mfma_f32_16x16x32_bf16 v[22:25], v[156:159], v[140:143], 0
	ds_read_b128 v[188:191], v235 offset:2048
	v_mul_f32_e32 v67, s12, v67
	v_mfma_f32_16x16x32_bf16 v[26:29], v[160:163], v[140:143], 0
	ds_read_b128 v[192:195], v235 offset:4096
	v_mul_f32_e32 v68, s12, v68
	v_mfma_f32_16x16x32_bf16 v[30:33], v[164:167], v[140:143], 0
	ds_read_b128 v[196:199], v235 offset:6144
	v_mul_f32_e32 v69, s12, v69
	v_mfma_f32_16x16x32_bf16 v[34:37], v[152:155], v[144:147], 0
	v_mfma_f32_16x16x32_bf16 v[38:41], v[156:159], v[144:147], 0
	v_mul_f32_e32 v70, s12, v70
	v_mfma_f32_16x16x32_bf16 v[42:45], v[160:163], v[144:147], 0
	v_mul_f32_e32 v71, s12, v71
	v_mfma_f32_16x16x32_bf16 v[46:49], v[164:167], v[144:147], 0
	v_mul_f32_e32 v72, s12, v72
	v_mfma_f32_16x16x32_bf16 v[50:53], v[152:155], v[148:151], 0
	v_mfma_f32_16x16x32_bf16 v[54:57], v[156:159], v[148:151], 0
	v_mul_f32_e32 v73, s12, v73
	v_mfma_f32_16x16x32_bf16 v[58:61], v[160:163], v[148:151], 0
	v_exp_f32_e32 v66, v66
	v_mfma_f32_16x16x32_bf16 v[62:65], v[164:167], v[148:151], 0
	v_exp_f32_e32 v67, v67
	s_waitcnt vmcnt(7) lgkmcnt(0)
	s_barrier
	v_mfma_f32_16x16x32_bf16 v[2:5], v[184:187], v[168:171], v[2:5]
	ds_read_b128 v[136:139], v218 offset:0
	v_mfma_f32_16x16x32_bf16 v[6:9], v[188:191], v[168:171], v[6:9]
	ds_read_b128 v[140:143], v218 offset:2048
	v_mfma_f32_16x16x32_bf16 v[10:13], v[192:195], v[168:171], v[10:13]
	ds_read_b128 v[144:147], v218 offset:4096
	v_exp_f32_e32 v68, v68
	v_mfma_f32_16x16x32_bf16 v[14:17], v[196:199], v[168:171], v[14:17]
	ds_read_b128 v[148:151], v218 offset:6144
	v_mfma_f32_16x16x32_bf16 v[18:21], v[184:187], v[172:175], v[18:21]
	ds_read_b128 v[152:155], v230 offset:0
	v_exp_f32_e32 v69, v69
	v_mfma_f32_16x16x32_bf16 v[22:25], v[188:191], v[172:175], v[22:25]
	ds_read_b128 v[156:159], v230 offset:2048
	v_mfma_f32_16x16x32_bf16 v[26:29], v[192:195], v[172:175], v[26:29]
	ds_read_b128 v[160:163], v230 offset:4096
	v_exp_f32_e32 v70, v70
	v_mfma_f32_16x16x32_bf16 v[30:33], v[196:199], v[172:175], v[30:33]
	ds_read_b128 v[164:167], v230 offset:6144
	s_add_u32 m0, s8, 0x18000
	v_mfma_f32_16x16x32_bf16 v[34:37], v[184:187], v[176:179], v[34:37]
	global_load_lds_dwordx4 v200, s[4:5]
	s_add_u32 m0, s8, 0x18400
	v_mfma_f32_16x16x32_bf16 v[38:41], v[188:191], v[176:179], v[38:41]
	global_load_lds_dwordx4 v201, s[4:5]
	v_exp_f32_e32 v71, v71
	s_add_u32 m0, s8, 0x18800
	v_mfma_f32_16x16x32_bf16 v[42:45], v[192:195], v[176:179], v[42:45]
	global_load_lds_dwordx4 v202, s[4:5]
	s_add_u32 m0, s8, 0x18c00
	v_mfma_f32_16x16x32_bf16 v[46:49], v[196:199], v[176:179], v[46:49]
	global_load_lds_dwordx4 v203, s[4:5]
	v_exp_f32_e32 v72, v72
	s_add_u32 m0, s9, 0x18000
	v_mfma_f32_16x16x32_bf16 v[50:53], v[184:187], v[180:183], v[50:53]
	global_load_lds_dwordx4 v204, s[6:7]
	s_add_u32 m0, s9, 0x18400
	v_mfma_f32_16x16x32_bf16 v[54:57], v[188:191], v[180:183], v[54:57]
	global_load_lds_dwordx4 v205, s[6:7]
	v_exp_f32_e32 v73, v73
	v_mfma_f32_16x16x32_bf16 v[58:61], v[192:195], v[180:183], v[58:61]
	s_add_u32 s4, s4, 0x80
	s_addc_u32 s5, s5, 0
	v_mfma_f32_16x16x32_bf16 v[62:65], v[196:199], v[180:183], v[62:65]
	s_add_u32 s6, s6, 0x80
	s_addc_u32 s7, s7, 0
	v_add_f32_e32 v66, 1.0, v66
	s_waitcnt lgkmcnt(0)
	v_mfma_f32_16x16x32_bf16 v[2:5], v[152:155], v[136:139], v[2:5]
	ds_read_b128 v[168:171], v225 offset:0
	v_mfma_f32_16x16x32_bf16 v[6:9], v[156:159], v[136:139], v[6:9]
	ds_read_b128 v[172:175], v225 offset:2048
	v_add_f32_e32 v67, 1.0, v67
	v_mfma_f32_16x16x32_bf16 v[10:13], v[160:163], v[136:139], v[10:13]
	ds_read_b128 v[176:179], v225 offset:4096
	v_add_f32_e32 v68, 1.0, v68
	v_mfma_f32_16x16x32_bf16 v[14:17], v[164:167], v[136:139], v[14:17]
	ds_read_b128 v[180:183], v225 offset:6144
	v_add_f32_e32 v69, 1.0, v69
	v_mfma_f32_16x16x32_bf16 v[18:21], v[152:155], v[140:143], v[18:21]
	ds_read_b128 v[184:187], v233 offset:0
	v_mfma_f32_16x16x32_bf16 v[22:25], v[156:159], v[140:143], v[22:25]
	ds_read_b128 v[188:191], v233 offset:2048
	v_add_f32_e32 v70, 1.0, v70
	v_mfma_f32_16x16x32_bf16 v[26:29], v[160:163], v[140:143], v[26:29]
	ds_read_b128 v[192:195], v233 offset:4096
	v_add_f32_e32 v71, 1.0, v71
	v_mfma_f32_16x16x32_bf16 v[30:33], v[164:167], v[140:143], v[30:33]
	ds_read_b128 v[196:199], v233 offset:6144
	v_add_f32_e32 v72, 1.0, v72
	v_mfma_f32_16x16x32_bf16 v[34:37], v[152:155], v[144:147], v[34:37]
	v_mfma_f32_16x16x32_bf16 v[38:41], v[156:159], v[144:147], v[38:41]
	v_add_f32_e32 v73, 1.0, v73
	v_mfma_f32_16x16x32_bf16 v[42:45], v[160:163], v[144:147], v[42:45]
	v_rcp_f32_e32 v66, v66
	v_mfma_f32_16x16x32_bf16 v[46:49], v[164:167], v[144:147], v[46:49]
	v_rcp_f32_e32 v67, v67
	v_mfma_f32_16x16x32_bf16 v[50:53], v[152:155], v[148:151], v[50:53]
	v_mfma_f32_16x16x32_bf16 v[54:57], v[156:159], v[148:151], v[54:57]
	v_rcp_f32_e32 v68, v68
	v_mfma_f32_16x16x32_bf16 v[58:61], v[160:163], v[148:151], v[58:61]
	v_rcp_f32_e32 v69, v69
	v_mfma_f32_16x16x32_bf16 v[62:65], v[164:167], v[148:151], v[62:65]
	v_rcp_f32_e32 v70, v70
	s_waitcnt vmcnt(7) lgkmcnt(0)
	s_barrier
	v_mfma_f32_16x16x32_bf16 v[2:5], v[184:187], v[168:171], v[2:5]
	ds_read_b128 v[136:139], v219 offset:0
	v_mfma_f32_16x16x32_bf16 v[6:9], v[188:191], v[168:171], v[6:9]
	ds_read_b128 v[140:143], v219 offset:2048
	v_mfma_f32_16x16x32_bf16 v[10:13], v[192:195], v[168:171], v[10:13]
	ds_read_b128 v[144:147], v219 offset:4096
	v_rcp_f32_e32 v71, v71
	v_mfma_f32_16x16x32_bf16 v[14:17], v[196:199], v[168:171], v[14:17]
	ds_read_b128 v[148:151], v219 offset:6144
	v_mfma_f32_16x16x32_bf16 v[18:21], v[184:187], v[172:175], v[18:21]
	ds_read_b128 v[152:155], v231 offset:0
	v_rcp_f32_e32 v72, v72
	v_mfma_f32_16x16x32_bf16 v[22:25], v[188:191], v[172:175], v[22:25]
	ds_read_b128 v[156:159], v231 offset:2048
	v_mfma_f32_16x16x32_bf16 v[26:29], v[192:195], v[172:175], v[26:29]
	ds_read_b128 v[160:163], v231 offset:4096
	v_rcp_f32_e32 v73, v73
	v_mfma_f32_16x16x32_bf16 v[30:33], v[196:199], v[172:175], v[30:33]
	ds_read_b128 v[164:167], v231 offset:6144
	s_mov_b32 m0, s8
	v_mfma_f32_16x16x32_bf16 v[34:37], v[184:187], v[176:179], v[34:37]
	global_load_lds_dwordx4 v200, s[4:5]
	s_add_u32 m0, s8, 0x400
	v_mfma_f32_16x16x32_bf16 v[38:41], v[188:191], v[176:179], v[38:41]
	global_load_lds_dwordx4 v201, s[4:5]
	v_cvt_pk_bf16_f32 v66, v66, v67
	s_add_u32 m0, s8, 0x800
	v_mfma_f32_16x16x32_bf16 v[42:45], v[192:195], v[176:179], v[42:45]
	global_load_lds_dwordx4 v202, s[4:5]
	s_add_u32 m0, s8, 0xc00
	v_mfma_f32_16x16x32_bf16 v[46:49], v[196:199], v[176:179], v[46:49]
	global_load_lds_dwordx4 v203, s[4:5]
	v_cvt_pk_bf16_f32 v67, v68, v69
	s_mov_b32 m0, s9
	v_mfma_f32_16x16x32_bf16 v[50:53], v[184:187], v[180:183], v[50:53]
	global_load_lds_dwordx4 v204, s[6:7]
	s_add_u32 m0, s9, 0x400
	v_mfma_f32_16x16x32_bf16 v[54:57], v[188:191], v[180:183], v[54:57]
	global_load_lds_dwordx4 v205, s[6:7]
	v_cvt_pk_bf16_f32 v68, v70, v71
	v_mfma_f32_16x16x32_bf16 v[58:61], v[192:195], v[180:183], v[58:61]
	s_add_u32 s4, s4, 0x80
	s_addc_u32 s5, s5, 0
	v_mfma_f32_16x16x32_bf16 v[62:65], v[196:199], v[180:183], v[62:65]
	s_add_u32 s6, s6, 0x80
	s_addc_u32 s7, s7, 0
	v_cvt_pk_bf16_f32 v69, v72, v73
	s_waitcnt lgkmcnt(0)
	v_mfma_f32_16x16x32_bf16 v[2:5], v[152:155], v[136:139], v[2:5]
	ds_read_b128 v[168:171], v228 offset:0
	v_mfma_f32_16x16x32_bf16 v[6:9], v[156:159], v[136:139], v[6:9]
	ds_read_b128 v[172:175], v228 offset:2048
	global_store_dwordx4 v240, v[66:69], s[10:11] offset:0
	v_mfma_f32_16x16x32_bf16 v[10:13], v[160:163], v[136:139], v[10:13]
	ds_read_b128 v[176:179], v228 offset:4096
	v_mul_f32_e32 v74, s12, v74
	v_mfma_f32_16x16x32_bf16 v[14:17], v[164:167], v[136:139], v[14:17]
	ds_read_b128 v[180:183], v228 offset:6144
	v_mul_f32_e32 v75, s12, v75
	v_mfma_f32_16x16x32_bf16 v[18:21], v[152:155], v[140:143], v[18:21]
	ds_read_b128 v[184:187], v234 offset:0
	v_mfma_f32_16x16x32_bf16 v[22:25], v[156:159], v[140:143], v[22:25]
	ds_read_b128 v[188:191], v234 offset:2048
	v_mul_f32_e32 v76, s12, v76
	v_mfma_f32_16x16x32_bf16 v[26:29], v[160:163], v[140:143], v[26:29]
	ds_read_b128 v[192:195], v234 offset:4096
	v_mul_f32_e32 v77, s12, v77
	v_mfma_f32_16x16x32_bf16 v[30:33], v[164:167], v[140:143], v[30:33]
	ds_read_b128 v[196:199], v234 offset:6144
	v_mul_f32_e32 v78, s12, v78
	v_mfma_f32_16x16x32_bf16 v[34:37], v[152:155], v[144:147], v[34:37]
	v_mfma_f32_16x16x32_bf16 v[38:41], v[156:159], v[144:147], v[38:41]
	v_mul_f32_e32 v79, s12, v79
	v_mfma_f32_16x16x32_bf16 v[42:45], v[160:163], v[144:147], v[42:45]
	v_mul_f32_e32 v80, s12, v80
	v_mfma_f32_16x16x32_bf16 v[46:49], v[164:167], v[144:147], v[46:49]
	v_mul_f32_e32 v81, s12, v81
	v_mfma_f32_16x16x32_bf16 v[50:53], v[152:155], v[148:151], v[50:53]
	v_mfma_f32_16x16x32_bf16 v[54:57], v[156:159], v[148:151], v[54:57]
	v_exp_f32_e32 v74, v74
	v_mfma_f32_16x16x32_bf16 v[58:61], v[160:163], v[148:151], v[58:61]
	v_exp_f32_e32 v75, v75
	v_mfma_f32_16x16x32_bf16 v[62:65], v[164:167], v[148:151], v[62:65]
	v_exp_f32_e32 v76, v76
	s_waitcnt vmcnt(7) lgkmcnt(0)
	s_barrier
	v_mfma_f32_16x16x32_bf16 v[2:5], v[184:187], v[168:171], v[2:5]
	ds_read_b128 v[136:139], v224 offset:0
	v_mfma_f32_16x16x32_bf16 v[6:9], v[188:191], v[168:171], v[6:9]
	ds_read_b128 v[140:143], v224 offset:2048
	v_mfma_f32_16x16x32_bf16 v[10:13], v[192:195], v[168:171], v[10:13]
	ds_read_b128 v[144:147], v224 offset:4096
	v_exp_f32_e32 v77, v77
	v_mfma_f32_16x16x32_bf16 v[14:17], v[196:199], v[168:171], v[14:17]
	ds_read_b128 v[148:151], v224 offset:6144
	v_mfma_f32_16x16x32_bf16 v[18:21], v[184:187], v[172:175], v[18:21]
	ds_read_b128 v[152:155], v232 offset:0
	v_exp_f32_e32 v78, v78
	v_mfma_f32_16x16x32_bf16 v[22:25], v[188:191], v[172:175], v[22:25]
	ds_read_b128 v[156:159], v232 offset:2048
	v_mfma_f32_16x16x32_bf16 v[26:29], v[192:195], v[172:175], v[26:29]
	ds_read_b128 v[160:163], v232 offset:4096
	v_exp_f32_e32 v79, v79
	v_mfma_f32_16x16x32_bf16 v[30:33], v[196:199], v[172:175], v[30:33]
	ds_read_b128 v[164:167], v232 offset:6144
	s_add_u32 m0, s8, 0xc000
	v_mfma_f32_16x16x32_bf16 v[34:37], v[184:187], v[176:179], v[34:37]
	global_load_lds_dwordx4 v200, s[4:5]
	s_add_u32 m0, s8, 0xc400
	v_mfma_f32_16x16x32_bf16 v[38:41], v[188:191], v[176:179], v[38:41]
	global_load_lds_dwordx4 v201, s[4:5]
	v_exp_f32_e32 v80, v80
	s_add_u32 m0, s8, 0xc800
	v_mfma_f32_16x16x32_bf16 v[42:45], v[192:195], v[176:179], v[42:45]
	global_load_lds_dwordx4 v202, s[4:5]
	s_add_u32 m0, s8, 0xcc00
	v_mfma_f32_16x16x32_bf16 v[46:49], v[196:199], v[176:179], v[46:49]
	global_load_lds_dwordx4 v203, s[4:5]
	v_exp_f32_e32 v81, v81
	s_add_u32 m0, s9, 0xc000
	v_mfma_f32_16x16x32_bf16 v[50:53], v[184:187], v[180:183], v[50:53]
	global_load_lds_dwordx4 v204, s[6:7]
	s_add_u32 m0, s9, 0xc400
	v_mfma_f32_16x16x32_bf16 v[54:57], v[188:191], v[180:183], v[54:57]
	global_load_lds_dwordx4 v205, s[6:7]
	v_add_f32_e32 v74, 1.0, v74
	v_mfma_f32_16x16x32_bf16 v[58:61], v[192:195], v[180:183], v[58:61]
	s_add_u32 s4, s4, 0x80
	s_addc_u32 s5, s5, 0
	v_mfma_f32_16x16x32_bf16 v[62:65], v[196:199], v[180:183], v[62:65]
	s_add_u32 s6, s6, 0x80
	s_addc_u32 s7, s7, 0
	v_add_f32_e32 v75, 1.0, v75
	s_waitcnt lgkmcnt(0)
	v_mfma_f32_16x16x32_bf16 v[2:5], v[152:155], v[136:139], v[2:5]
	ds_read_b128 v[168:171], v229 offset:0
	v_mfma_f32_16x16x32_bf16 v[6:9], v[156:159], v[136:139], v[6:9]
	ds_read_b128 v[172:175], v229 offset:2048
	v_add_f32_e32 v76, 1.0, v76
	v_mfma_f32_16x16x32_bf16 v[10:13], v[160:163], v[136:139], v[10:13]
	ds_read_b128 v[176:179], v229 offset:4096
	v_add_f32_e32 v77, 1.0, v77
	v_mfma_f32_16x16x32_bf16 v[14:17], v[164:167], v[136:139], v[14:17]
	ds_read_b128 v[180:183], v229 offset:6144
	v_add_f32_e32 v78, 1.0, v78
	v_mfma_f32_16x16x32_bf16 v[18:21], v[152:155], v[140:143], v[18:21]
	ds_read_b128 v[184:187], v235 offset:0
	v_mfma_f32_16x16x32_bf16 v[22:25], v[156:159], v[140:143], v[22:25]
	ds_read_b128 v[188:191], v235 offset:2048
	v_add_f32_e32 v79, 1.0, v79
	v_mfma_f32_16x16x32_bf16 v[26:29], v[160:163], v[140:143], v[26:29]
	ds_read_b128 v[192:195], v235 offset:4096
	v_add_f32_e32 v80, 1.0, v80
	v_mfma_f32_16x16x32_bf16 v[30:33], v[164:167], v[140:143], v[30:33]
	ds_read_b128 v[196:199], v235 offset:6144
	v_add_f32_e32 v81, 1.0, v81
	v_mfma_f32_16x16x32_bf16 v[34:37], v[152:155], v[144:147], v[34:37]
	v_mfma_f32_16x16x32_bf16 v[38:41], v[156:159], v[144:147], v[38:41]
	v_rcp_f32_e32 v74, v74
	v_mfma_f32_16x16x32_bf16 v[42:45], v[160:163], v[144:147], v[42:45]
	v_rcp_f32_e32 v75, v75
	v_mfma_f32_16x16x32_bf16 v[46:49], v[164:167], v[144:147], v[46:49]
	v_rcp_f32_e32 v76, v76
	v_mfma_f32_16x16x32_bf16 v[50:53], v[152:155], v[148:151], v[50:53]
	v_mfma_f32_16x16x32_bf16 v[54:57], v[156:159], v[148:151], v[54:57]
	v_rcp_f32_e32 v77, v77
	v_mfma_f32_16x16x32_bf16 v[58:61], v[160:163], v[148:151], v[58:61]
	v_rcp_f32_e32 v78, v78
	v_mfma_f32_16x16x32_bf16 v[62:65], v[164:167], v[148:151], v[62:65]
	v_rcp_f32_e32 v79, v79
	s_waitcnt vmcnt(7) lgkmcnt(0)
	s_barrier
	v_mfma_f32_16x16x32_bf16 v[2:5], v[184:187], v[168:171], v[2:5]
	ds_read_b128 v[136:139], v218 offset:0
	v_mfma_f32_16x16x32_bf16 v[6:9], v[188:191], v[168:171], v[6:9]
	ds_read_b128 v[140:143], v218 offset:2048
	v_mfma_f32_16x16x32_bf16 v[10:13], v[192:195], v[168:171], v[10:13]
	ds_read_b128 v[144:147], v218 offset:4096
	v_rcp_f32_e32 v80, v80
	v_mfma_f32_16x16x32_bf16 v[14:17], v[196:199], v[168:171], v[14:17]
	ds_read_b128 v[148:151], v218 offset:6144
	v_mfma_f32_16x16x32_bf16 v[18:21], v[184:187], v[172:175], v[18:21]
	ds_read_b128 v[152:155], v230 offset:0
	v_rcp_f32_e32 v81, v81
	v_mfma_f32_16x16x32_bf16 v[22:25], v[188:191], v[172:175], v[22:25]
	ds_read_b128 v[156:159], v230 offset:2048
	v_mfma_f32_16x16x32_bf16 v[26:29], v[192:195], v[172:175], v[26:29]
	ds_read_b128 v[160:163], v230 offset:4096
	v_cvt_pk_bf16_f32 v74, v74, v75
	v_mfma_f32_16x16x32_bf16 v[30:33], v[196:199], v[172:175], v[30:33]
	ds_read_b128 v[164:167], v230 offset:6144
	s_add_u32 m0, s8, 0x18000
	v_mfma_f32_16x16x32_bf16 v[34:37], v[184:187], v[176:179], v[34:37]
	global_load_lds_dwordx4 v200, s[4:5]
	s_add_u32 m0, s8, 0x18400
	v_mfma_f32_16x16x32_bf16 v[38:41], v[188:191], v[176:179], v[38:41]
	global_load_lds_dwordx4 v201, s[4:5]
	v_cvt_pk_bf16_f32 v75, v76, v77
	s_add_u32 m0, s8, 0x18800
	v_mfma_f32_16x16x32_bf16 v[42:45], v[192:195], v[176:179], v[42:45]
	global_load_lds_dwordx4 v202, s[4:5]
	s_add_u32 m0, s8, 0x18c00
	v_mfma_f32_16x16x32_bf16 v[46:49], v[196:199], v[176:179], v[46:49]
	global_load_lds_dwordx4 v203, s[4:5]
	v_cvt_pk_bf16_f32 v76, v78, v79
	s_add_u32 m0, s9, 0x18000
	v_mfma_f32_16x16x32_bf16 v[50:53], v[184:187], v[180:183], v[50:53]
	global_load_lds_dwordx4 v204, s[6:7]
	s_add_u32 m0, s9, 0x18400
	v_mfma_f32_16x16x32_bf16 v[54:57], v[188:191], v[180:183], v[54:57]
	global_load_lds_dwordx4 v205, s[6:7]
	v_cvt_pk_bf16_f32 v77, v80, v81
	v_mfma_f32_16x16x32_bf16 v[58:61], v[192:195], v[180:183], v[58:61]
	s_add_u32 s4, s4, 0x80
	s_addc_u32 s5, s5, 0
	v_mfma_f32_16x16x32_bf16 v[62:65], v[196:199], v[180:183], v[62:65]
	s_add_u32 s6, s6, 0x80
	s_addc_u32 s7, s7, 0
	global_store_dwordx4 v240, v[74:77], s[10:11] offset:16
	s_waitcnt lgkmcnt(0)
	v_mfma_f32_16x16x32_bf16 v[2:5], v[152:155], v[136:139], v[2:5]
	ds_read_b128 v[168:171], v225 offset:0
	v_mfma_f32_16x16x32_bf16 v[6:9], v[156:159], v[136:139], v[6:9]
	ds_read_b128 v[172:175], v225 offset:2048
	v_mul_f32_e32 v82, s12, v82
	v_mfma_f32_16x16x32_bf16 v[10:13], v[160:163], v[136:139], v[10:13]
	ds_read_b128 v[176:179], v225 offset:4096
	v_mul_f32_e32 v83, s12, v83
	v_mfma_f32_16x16x32_bf16 v[14:17], v[164:167], v[136:139], v[14:17]
	ds_read_b128 v[180:183], v225 offset:6144
	v_mul_f32_e32 v84, s12, v84
	v_mfma_f32_16x16x32_bf16 v[18:21], v[152:155], v[140:143], v[18:21]
	ds_read_b128 v[184:187], v233 offset:0
	v_mfma_f32_16x16x32_bf16 v[22:25], v[156:159], v[140:143], v[22:25]
	ds_read_b128 v[188:191], v233 offset:2048
	v_mul_f32_e32 v85, s12, v85
	v_mfma_f32_16x16x32_bf16 v[26:29], v[160:163], v[140:143], v[26:29]
	ds_read_b128 v[192:195], v233 offset:4096
	v_mul_f32_e32 v86, s12, v86
	v_mfma_f32_16x16x32_bf16 v[30:33], v[164:167], v[140:143], v[30:33]
	ds_read_b128 v[196:199], v233 offset:6144
	v_mul_f32_e32 v87, s12, v87
	v_mfma_f32_16x16x32_bf16 v[34:37], v[152:155], v[144:147], v[34:37]
	v_mfma_f32_16x16x32_bf16 v[38:41], v[156:159], v[144:147], v[38:41]
	v_mul_f32_e32 v88, s12, v88
	v_mfma_f32_16x16x32_bf16 v[42:45], v[160:163], v[144:147], v[42:45]
	v_mul_f32_e32 v89, s12, v89
	v_mfma_f32_16x16x32_bf16 v[46:49], v[164:167], v[144:147], v[46:49]
	v_exp_f32_e32 v82, v82
	v_mfma_f32_16x16x32_bf16 v[50:53], v[152:155], v[148:151], v[50:53]
	v_mfma_f32_16x16x32_bf16 v[54:57], v[156:159], v[148:151], v[54:57]
	v_exp_f32_e32 v83, v83
	v_mfma_f32_16x16x32_bf16 v[58:61], v[160:163], v[148:151], v[58:61]
	v_exp_f32_e32 v84, v84
	v_mfma_f32_16x16x32_bf16 v[62:65], v[164:167], v[148:151], v[62:65]
	v_exp_f32_e32 v85, v85
	s_waitcnt vmcnt(7) lgkmcnt(0)
	s_barrier
	v_mfma_f32_16x16x32_bf16 v[2:5], v[184:187], v[168:171], v[2:5]
	ds_read_b128 v[136:139], v219 offset:0
	v_mfma_f32_16x16x32_bf16 v[6:9], v[188:191], v[168:171], v[6:9]
	ds_read_b128 v[140:143], v219 offset:2048
	v_mfma_f32_16x16x32_bf16 v[10:13], v[192:195], v[168:171], v[10:13]
	ds_read_b128 v[144:147], v219 offset:4096
	v_exp_f32_e32 v86, v86
	v_mfma_f32_16x16x32_bf16 v[14:17], v[196:199], v[168:171], v[14:17]
	ds_read_b128 v[148:151], v219 offset:6144
	v_mfma_f32_16x16x32_bf16 v[18:21], v[184:187], v[172:175], v[18:21]
	ds_read_b128 v[152:155], v231 offset:0
	v_exp_f32_e32 v87, v87
	v_mfma_f32_16x16x32_bf16 v[22:25], v[188:191], v[172:175], v[22:25]
	ds_read_b128 v[156:159], v231 offset:2048
	v_mfma_f32_16x16x32_bf16 v[26:29], v[192:195], v[172:175], v[26:29]
	ds_read_b128 v[160:163], v231 offset:4096
	v_exp_f32_e32 v88, v88
	v_mfma_f32_16x16x32_bf16 v[30:33], v[196:199], v[172:175], v[30:33]
	ds_read_b128 v[164:167], v231 offset:6144
	s_mov_b32 m0, s8
	v_mfma_f32_16x16x32_bf16 v[34:37], v[184:187], v[176:179], v[34:37]
	global_load_lds_dwordx4 v200, s[4:5]
	s_add_u32 m0, s8, 0x400
	v_mfma_f32_16x16x32_bf16 v[38:41], v[188:191], v[176:179], v[38:41]
	global_load_lds_dwordx4 v201, s[4:5]
	v_exp_f32_e32 v89, v89
	s_add_u32 m0, s8, 0x800
	v_mfma_f32_16x16x32_bf16 v[42:45], v[192:195], v[176:179], v[42:45]
	global_load_lds_dwordx4 v202, s[4:5]
	s_add_u32 m0, s8, 0xc00
	v_mfma_f32_16x16x32_bf16 v[46:49], v[196:199], v[176:179], v[46:49]
	global_load_lds_dwordx4 v203, s[4:5]
	v_add_f32_e32 v82, 1.0, v82
	s_mov_b32 m0, s9
	v_mfma_f32_16x16x32_bf16 v[50:53], v[184:187], v[180:183], v[50:53]
	global_load_lds_dwordx4 v204, s[6:7]
	s_add_u32 m0, s9, 0x400
	v_mfma_f32_16x16x32_bf16 v[54:57], v[188:191], v[180:183], v[54:57]
	global_load_lds_dwordx4 v205, s[6:7]
	v_add_f32_e32 v83, 1.0, v83
	v_mfma_f32_16x16x32_bf16 v[58:61], v[192:195], v[180:183], v[58:61]
	s_add_u32 s4, s4, 0x80
	s_addc_u32 s5, s5, 0
	v_mfma_f32_16x16x32_bf16 v[62:65], v[196:199], v[180:183], v[62:65]
	s_add_u32 s6, s6, 0x80
	s_addc_u32 s7, s7, 0
	v_add_f32_e32 v84, 1.0, v84
	s_waitcnt lgkmcnt(0)
	v_mfma_f32_16x16x32_bf16 v[2:5], v[152:155], v[136:139], v[2:5]
	ds_read_b128 v[168:171], v228 offset:0
	v_mfma_f32_16x16x32_bf16 v[6:9], v[156:159], v[136:139], v[6:9]
	ds_read_b128 v[172:175], v228 offset:2048
	v_add_f32_e32 v85, 1.0, v85
	v_mfma_f32_16x16x32_bf16 v[10:13], v[160:163], v[136:139], v[10:13]
	ds_read_b128 v[176:179], v228 offset:4096
	v_add_f32_e32 v86, 1.0, v86
	v_mfma_f32_16x16x32_bf16 v[14:17], v[164:167], v[136:139], v[14:17]
	ds_read_b128 v[180:183], v228 offset:6144
	v_add_f32_e32 v87, 1.0, v87
	v_mfma_f32_16x16x32_bf16 v[18:21], v[152:155], v[140:143], v[18:21]
	ds_read_b128 v[184:187], v234 offset:0
	v_mfma_f32_16x16x32_bf16 v[22:25], v[156:159], v[140:143], v[22:25]
	ds_read_b128 v[188:191], v234 offset:2048
	v_add_f32_e32 v88, 1.0, v88
	v_mfma_f32_16x16x32_bf16 v[26:29], v[160:163], v[140:143], v[26:29]
	ds_read_b128 v[192:195], v234 offset:4096
	v_add_f32_e32 v89, 1.0, v89
	v_mfma_f32_16x16x32_bf16 v[30:33], v[164:167], v[140:143], v[30:33]
	ds_read_b128 v[196:199], v234 offset:6144
	v_rcp_f32_e32 v82, v82
	v_mfma_f32_16x16x32_bf16 v[34:37], v[152:155], v[144:147], v[34:37]
	v_mfma_f32_16x16x32_bf16 v[38:41], v[156:159], v[144:147], v[38:41]
	v_rcp_f32_e32 v83, v83
	v_mfma_f32_16x16x32_bf16 v[42:45], v[160:163], v[144:147], v[42:45]
	v_rcp_f32_e32 v84, v84
	v_mfma_f32_16x16x32_bf16 v[46:49], v[164:167], v[144:147], v[46:49]
	v_rcp_f32_e32 v85, v85
	v_mfma_f32_16x16x32_bf16 v[50:53], v[152:155], v[148:151], v[50:53]
	v_mfma_f32_16x16x32_bf16 v[54:57], v[156:159], v[148:151], v[54:57]
	v_rcp_f32_e32 v86, v86
	v_mfma_f32_16x16x32_bf16 v[58:61], v[160:163], v[148:151], v[58:61]
	v_rcp_f32_e32 v87, v87
	v_mfma_f32_16x16x32_bf16 v[62:65], v[164:167], v[148:151], v[62:65]
	v_rcp_f32_e32 v88, v88
	s_waitcnt vmcnt(7) lgkmcnt(0)
	s_barrier
	v_mfma_f32_16x16x32_bf16 v[2:5], v[184:187], v[168:171], v[2:5]
	ds_read_b128 v[136:139], v224 offset:0
	v_mfma_f32_16x16x32_bf16 v[6:9], v[188:191], v[168:171], v[6:9]
	ds_read_b128 v[140:143], v224 offset:2048
	v_mfma_f32_16x16x32_bf16 v[10:13], v[192:195], v[168:171], v[10:13]
	ds_read_b128 v[144:147], v224 offset:4096
	v_rcp_f32_e32 v89, v89
	v_mfma_f32_16x16x32_bf16 v[14:17], v[196:199], v[168:171], v[14:17]
	ds_read_b128 v[148:151], v224 offset:6144
	v_mfma_f32_16x16x32_bf16 v[18:21], v[184:187], v[172:175], v[18:21]
	ds_read_b128 v[152:155], v232 offset:0
	v_cvt_pk_bf16_f32 v82, v82, v83
	v_mfma_f32_16x16x32_bf16 v[22:25], v[188:191], v[172:175], v[22:25]
	ds_read_b128 v[156:159], v232 offset:2048
	v_mfma_f32_16x16x32_bf16 v[26:29], v[192:195], v[172:175], v[26:29]
	ds_read_b128 v[160:163], v232 offset:4096
	v_cvt_pk_bf16_f32 v83, v84, v85
	v_mfma_f32_16x16x32_bf16 v[30:33], v[196:199], v[172:175], v[30:33]
	ds_read_b128 v[164:167], v232 offset:6144
	s_add_u32 m0, s8, 0xc000
	v_mfma_f32_16x16x32_bf16 v[34:37], v[184:187], v[176:179], v[34:37]
	global_load_lds_dwordx4 v200, s[4:5]
	s_add_u32 m0, s8, 0xc400
	v_mfma_f32_16x16x32_bf16 v[38:41], v[188:191], v[176:179], v[38:41]
	global_load_lds_dwordx4 v201, s[4:5]
	v_cvt_pk_bf16_f32 v84, v86, v87
	s_add_u32 m0, s8, 0xc800
	v_mfma_f32_16x16x32_bf16 v[42:45], v[192:195], v[176:179], v[42:45]
	global_load_lds_dwordx4 v202, s[4:5]
	s_add_u32 m0, s8, 0xcc00
	v_mfma_f32_16x16x32_bf16 v[46:49], v[196:199], v[176:179], v[46:49]
	global_load_lds_dwordx4 v203, s[4:5]
	v_cvt_pk_bf16_f32 v85, v88, v89
	s_add_u32 m0, s9, 0xc000
	v_mfma_f32_16x16x32_bf16 v[50:53], v[184:187], v[180:183], v[50:53]
	global_load_lds_dwordx4 v204, s[6:7]
	s_add_u32 m0, s9, 0xc400
	v_mfma_f32_16x16x32_bf16 v[54:57], v[188:191], v[180:183], v[54:57]
	global_load_lds_dwordx4 v205, s[6:7]
	global_store_dwordx4 v240, v[82:85], s[10:11] offset:2048
	v_mfma_f32_16x16x32_bf16 v[58:61], v[192:195], v[180:183], v[58:61]
	s_add_u32 s4, s4, 0x80
	s_addc_u32 s5, s5, 0
	v_mfma_f32_16x16x32_bf16 v[62:65], v[196:199], v[180:183], v[62:65]
	s_add_u32 s6, s6, 0x80
	s_addc_u32 s7, s7, 0
	v_mul_f32_e32 v90, s12, v90
	s_waitcnt lgkmcnt(0)
	v_mfma_f32_16x16x32_bf16 v[2:5], v[152:155], v[136:139], v[2:5]
	ds_read_b128 v[168:171], v229 offset:0
	v_mfma_f32_16x16x32_bf16 v[6:9], v[156:159], v[136:139], v[6:9]
	ds_read_b128 v[172:175], v229 offset:2048
	v_mul_f32_e32 v91, s12, v91
	v_mfma_f32_16x16x32_bf16 v[10:13], v[160:163], v[136:139], v[10:13]
	ds_read_b128 v[176:179], v229 offset:4096
	v_mul_f32_e32 v92, s12, v92
	v_mfma_f32_16x16x32_bf16 v[14:17], v[164:167], v[136:139], v[14:17]
	ds_read_b128 v[180:183], v229 offset:6144
	v_mul_f32_e32 v93, s12, v93
	v_mfma_f32_16x16x32_bf16 v[18:21], v[152:155], v[140:143], v[18:21]
	ds_read_b128 v[184:187], v235 offset:0
	v_mfma_f32_16x16x32_bf16 v[22:25], v[156:159], v[140:143], v[22:25]
	ds_read_b128 v[188:191], v235 offset:2048
	v_mul_f32_e32 v94, s12, v94
	v_mfma_f32_16x16x32_bf16 v[26:29], v[160:163], v[140:143], v[26:29]
	ds_read_b128 v[192:195], v235 offset:4096
	v_mul_f32_e32 v95, s12, v95
	v_mfma_f32_16x16x32_bf16 v[30:33], v[164:167], v[140:143], v[30:33]
	ds_read_b128 v[196:199], v235 offset:6144
	v_mul_f32_e32 v96, s12, v96
	v_mfma_f32_16x16x32_bf16 v[34:37], v[152:155], v[144:147], v[34:37]
	v_mfma_f32_16x16x32_bf16 v[38:41], v[156:159], v[144:147], v[38:41]
	v_mul_f32_e32 v97, s12, v97
	v_mfma_f32_16x16x32_bf16 v[42:45], v[160:163], v[144:147], v[42:45]
	v_exp_f32_e32 v90, v90
	v_mfma_f32_16x16x32_bf16 v[46:49], v[164:167], v[144:147], v[46:49]
	v_exp_f32_e32 v91, v91
	v_mfma_f32_16x16x32_bf16 v[50:53], v[152:155], v[148:151], v[50:53]
	v_mfma_f32_16x16x32_bf16 v[54:57], v[156:159], v[148:151], v[54:57]
	v_exp_f32_e32 v92, v92
	v_mfma_f32_16x16x32_bf16 v[58:61], v[160:163], v[148:151], v[58:61]
	v_exp_f32_e32 v93, v93
	v_mfma_f32_16x16x32_bf16 v[62:65], v[164:167], v[148:151], v[62:65]
	v_exp_f32_e32 v94, v94
	s_waitcnt vmcnt(7) lgkmcnt(0)
	s_barrier
	v_mfma_f32_16x16x32_bf16 v[2:5], v[184:187], v[168:171], v[2:5]
	ds_read_b128 v[136:139], v218 offset:0
	v_mfma_f32_16x16x32_bf16 v[6:9], v[188:191], v[168:171], v[6:9]
	ds_read_b128 v[140:143], v218 offset:2048
	v_mfma_f32_16x16x32_bf16 v[10:13], v[192:195], v[168:171], v[10:13]
	ds_read_b128 v[144:147], v218 offset:4096
	v_exp_f32_e32 v95, v95
	v_mfma_f32_16x16x32_bf16 v[14:17], v[196:199], v[168:171], v[14:17]
	ds_read_b128 v[148:151], v218 offset:6144
	v_mfma_f32_16x16x32_bf16 v[18:21], v[184:187], v[172:175], v[18:21]
	ds_read_b128 v[152:155], v230 offset:0
	v_exp_f32_e32 v96, v96
	v_mfma_f32_16x16x32_bf16 v[22:25], v[188:191], v[172:175], v[22:25]
	ds_read_b128 v[156:159], v230 offset:2048
	v_mfma_f32_16x16x32_bf16 v[26:29], v[192:195], v[172:175], v[26:29]
	ds_read_b128 v[160:163], v230 offset:4096
	v_exp_f32_e32 v97, v97
	v_mfma_f32_16x16x32_bf16 v[30:33], v[196:199], v[172:175], v[30:33]
	ds_read_b128 v[164:167], v230 offset:6144
	s_add_u32 m0, s8, 0x18000
	v_mfma_f32_16x16x32_bf16 v[34:37], v[184:187], v[176:179], v[34:37]
	global_load_lds_dwordx4 v200, s[4:5]
	s_add_u32 m0, s8, 0x18400
	v_mfma_f32_16x16x32_bf16 v[38:41], v[188:191], v[176:179], v[38:41]
	global_load_lds_dwordx4 v201, s[4:5]
	v_add_f32_e32 v90, 1.0, v90
	s_add_u32 m0, s8, 0x18800
	v_mfma_f32_16x16x32_bf16 v[42:45], v[192:195], v[176:179], v[42:45]
	global_load_lds_dwordx4 v202, s[4:5]
	s_add_u32 m0, s8, 0x18c00
	v_mfma_f32_16x16x32_bf16 v[46:49], v[196:199], v[176:179], v[46:49]
	global_load_lds_dwordx4 v203, s[4:5]
	v_add_f32_e32 v91, 1.0, v91
	s_add_u32 m0, s9, 0x18000
	v_mfma_f32_16x16x32_bf16 v[50:53], v[184:187], v[180:183], v[50:53]
	global_load_lds_dwordx4 v204, s[6:7]
	s_add_u32 m0, s9, 0x18400
	v_mfma_f32_16x16x32_bf16 v[54:57], v[188:191], v[180:183], v[54:57]
	global_load_lds_dwordx4 v205, s[6:7]
	v_add_f32_e32 v92, 1.0, v92
	v_mfma_f32_16x16x32_bf16 v[58:61], v[192:195], v[180:183], v[58:61]
	s_add_u32 s4, s4, 0x80
	s_addc_u32 s5, s5, 0
	v_mfma_f32_16x16x32_bf16 v[62:65], v[196:199], v[180:183], v[62:65]
	s_add_u32 s6, s6, 0x80
	s_addc_u32 s7, s7, 0
	v_add_f32_e32 v93, 1.0, v93
	s_waitcnt lgkmcnt(0)
	v_mfma_f32_16x16x32_bf16 v[2:5], v[152:155], v[136:139], v[2:5]
	ds_read_b128 v[168:171], v225 offset:0
	v_mfma_f32_16x16x32_bf16 v[6:9], v[156:159], v[136:139], v[6:9]
	ds_read_b128 v[172:175], v225 offset:2048
	v_add_f32_e32 v94, 1.0, v94
	v_mfma_f32_16x16x32_bf16 v[10:13], v[160:163], v[136:139], v[10:13]
	ds_read_b128 v[176:179], v225 offset:4096
	v_add_f32_e32 v95, 1.0, v95
	v_mfma_f32_16x16x32_bf16 v[14:17], v[164:167], v[136:139], v[14:17]
	ds_read_b128 v[180:183], v225 offset:6144
	v_add_f32_e32 v96, 1.0, v96
	v_mfma_f32_16x16x32_bf16 v[18:21], v[152:155], v[140:143], v[18:21]
	ds_read_b128 v[184:187], v233 offset:0
	v_mfma_f32_16x16x32_bf16 v[22:25], v[156:159], v[140:143], v[22:25]
	ds_read_b128 v[188:191], v233 offset:2048
	v_add_f32_e32 v97, 1.0, v97
	v_mfma_f32_16x16x32_bf16 v[26:29], v[160:163], v[140:143], v[26:29]
	ds_read_b128 v[192:195], v233 offset:4096
	v_rcp_f32_e32 v90, v90
	v_mfma_f32_16x16x32_bf16 v[30:33], v[164:167], v[140:143], v[30:33]
	ds_read_b128 v[196:199], v233 offset:6144
	v_rcp_f32_e32 v91, v91
	v_mfma_f32_16x16x32_bf16 v[34:37], v[152:155], v[144:147], v[34:37]
	v_mfma_f32_16x16x32_bf16 v[38:41], v[156:159], v[144:147], v[38:41]
	v_rcp_f32_e32 v92, v92
	v_mfma_f32_16x16x32_bf16 v[42:45], v[160:163], v[144:147], v[42:45]
	v_rcp_f32_e32 v93, v93
	v_mfma_f32_16x16x32_bf16 v[46:49], v[164:167], v[144:147], v[46:49]
	v_rcp_f32_e32 v94, v94
	v_mfma_f32_16x16x32_bf16 v[50:53], v[152:155], v[148:151], v[50:53]
	v_mfma_f32_16x16x32_bf16 v[54:57], v[156:159], v[148:151], v[54:57]
	v_rcp_f32_e32 v95, v95
	v_mfma_f32_16x16x32_bf16 v[58:61], v[160:163], v[148:151], v[58:61]
	v_rcp_f32_e32 v96, v96
	v_mfma_f32_16x16x32_bf16 v[62:65], v[164:167], v[148:151], v[62:65]
	v_rcp_f32_e32 v97, v97
	s_waitcnt vmcnt(7) lgkmcnt(0)
	s_barrier
	v_mfma_f32_16x16x32_bf16 v[2:5], v[184:187], v[168:171], v[2:5]
	ds_read_b128 v[136:139], v219 offset:0
	v_mfma_f32_16x16x32_bf16 v[6:9], v[188:191], v[168:171], v[6:9]
	ds_read_b128 v[140:143], v219 offset:2048
	v_mfma_f32_16x16x32_bf16 v[10:13], v[192:195], v[168:171], v[10:13]
	ds_read_b128 v[144:147], v219 offset:4096
	v_cvt_pk_bf16_f32 v90, v90, v91
	v_mfma_f32_16x16x32_bf16 v[14:17], v[196:199], v[168:171], v[14:17]
	ds_read_b128 v[148:151], v219 offset:6144
	v_mfma_f32_16x16x32_bf16 v[18:21], v[184:187], v[172:175], v[18:21]
	ds_read_b128 v[152:155], v231 offset:0
	v_cvt_pk_bf16_f32 v91, v92, v93
	v_mfma_f32_16x16x32_bf16 v[22:25], v[188:191], v[172:175], v[22:25]
	ds_read_b128 v[156:159], v231 offset:2048
	v_mfma_f32_16x16x32_bf16 v[26:29], v[192:195], v[172:175], v[26:29]
	ds_read_b128 v[160:163], v231 offset:4096
	v_cvt_pk_bf16_f32 v92, v94, v95
	v_mfma_f32_16x16x32_bf16 v[30:33], v[196:199], v[172:175], v[30:33]
	ds_read_b128 v[164:167], v231 offset:6144
	s_mov_b32 m0, s8
	v_mfma_f32_16x16x32_bf16 v[34:37], v[184:187], v[176:179], v[34:37]
	global_load_lds_dwordx4 v200, s[4:5]
	s_add_u32 m0, s8, 0x400
	v_mfma_f32_16x16x32_bf16 v[38:41], v[188:191], v[176:179], v[38:41]
	global_load_lds_dwordx4 v201, s[4:5]
	v_cvt_pk_bf16_f32 v93, v96, v97
	s_add_u32 m0, s8, 0x800
	v_mfma_f32_16x16x32_bf16 v[42:45], v[192:195], v[176:179], v[42:45]
	global_load_lds_dwordx4 v202, s[4:5]
	s_add_u32 m0, s8, 0xc00
	v_mfma_f32_16x16x32_bf16 v[46:49], v[196:199], v[176:179], v[46:49]
	global_load_lds_dwordx4 v203, s[4:5]
	global_store_dwordx4 v240, v[90:93], s[10:11] offset:2064
	s_mov_b32 m0, s9
	v_mfma_f32_16x16x32_bf16 v[50:53], v[184:187], v[180:183], v[50:53]
	global_load_lds_dwordx4 v204, s[6:7]
	s_add_u32 m0, s9, 0x400
	v_mfma_f32_16x16x32_bf16 v[54:57], v[188:191], v[180:183], v[54:57]
	global_load_lds_dwordx4 v205, s[6:7]
	v_mul_f32_e32 v98, s12, v98
	v_mfma_f32_16x16x32_bf16 v[58:61], v[192:195], v[180:183], v[58:61]
	s_add_u32 s4, s4, 0x80
	s_addc_u32 s5, s5, 0
	v_mfma_f32_16x16x32_bf16 v[62:65], v[196:199], v[180:183], v[62:65]
	s_add_u32 s6, s6, 0x80
	s_addc_u32 s7, s7, 0
	v_mul_f32_e32 v99, s12, v99
	s_waitcnt lgkmcnt(0)
	v_mfma_f32_16x16x32_bf16 v[2:5], v[152:155], v[136:139], v[2:5]
	ds_read_b128 v[168:171], v228 offset:0
	v_mfma_f32_16x16x32_bf16 v[6:9], v[156:159], v[136:139], v[6:9]
	ds_read_b128 v[172:175], v228 offset:2048
	v_mul_f32_e32 v100, s12, v100
	v_mfma_f32_16x16x32_bf16 v[10:13], v[160:163], v[136:139], v[10:13]
	ds_read_b128 v[176:179], v228 offset:4096
	v_mul_f32_e32 v101, s12, v101
	v_mfma_f32_16x16x32_bf16 v[14:17], v[164:167], v[136:139], v[14:17]
	ds_read_b128 v[180:183], v228 offset:6144
	v_mul_f32_e32 v102, s12, v102
	v_mfma_f32_16x16x32_bf16 v[18:21], v[152:155], v[140:143], v[18:21]
	ds_read_b128 v[184:187], v234 offset:0
	v_mfma_f32_16x16x32_bf16 v[22:25], v[156:159], v[140:143], v[22:25]
	ds_read_b128 v[188:191], v234 offset:2048
	v_mul_f32_e32 v103, s12, v103
	v_mfma_f32_16x16x32_bf16 v[26:29], v[160:163], v[140:143], v[26:29]
	ds_read_b128 v[192:195], v234 offset:4096
	v_mul_f32_e32 v104, s12, v104
	v_mfma_f32_16x16x32_bf16 v[30:33], v[164:167], v[140:143], v[30:33]
	ds_read_b128 v[196:199], v234 offset:6144
	v_mul_f32_e32 v105, s12, v105
	v_mfma_f32_16x16x32_bf16 v[34:37], v[152:155], v[144:147], v[34:37]
	v_mfma_f32_16x16x32_bf16 v[38:41], v[156:159], v[144:147], v[38:41]
	v_exp_f32_e32 v98, v98
	v_mfma_f32_16x16x32_bf16 v[42:45], v[160:163], v[144:147], v[42:45]
	v_exp_f32_e32 v99, v99
	v_mfma_f32_16x16x32_bf16 v[46:49], v[164:167], v[144:147], v[46:49]
	v_exp_f32_e32 v100, v100
	v_mfma_f32_16x16x32_bf16 v[50:53], v[152:155], v[148:151], v[50:53]
	v_mfma_f32_16x16x32_bf16 v[54:57], v[156:159], v[148:151], v[54:57]
	v_exp_f32_e32 v101, v101
	v_mfma_f32_16x16x32_bf16 v[58:61], v[160:163], v[148:151], v[58:61]
	v_exp_f32_e32 v102, v102
	v_mfma_f32_16x16x32_bf16 v[62:65], v[164:167], v[148:151], v[62:65]
	v_exp_f32_e32 v103, v103
	s_waitcnt vmcnt(7) lgkmcnt(0)
	s_barrier
	v_mfma_f32_16x16x32_bf16 v[2:5], v[184:187], v[168:171], v[2:5]
	ds_read_b128 v[136:139], v224 offset:0
	v_mfma_f32_16x16x32_bf16 v[6:9], v[188:191], v[168:171], v[6:9]
	ds_read_b128 v[140:143], v224 offset:2048
	v_mfma_f32_16x16x32_bf16 v[10:13], v[192:195], v[168:171], v[10:13]
	ds_read_b128 v[144:147], v224 offset:4096
	v_exp_f32_e32 v104, v104
	v_mfma_f32_16x16x32_bf16 v[14:17], v[196:199], v[168:171], v[14:17]
	ds_read_b128 v[148:151], v224 offset:6144
	v_mfma_f32_16x16x32_bf16 v[18:21], v[184:187], v[172:175], v[18:21]
	ds_read_b128 v[152:155], v232 offset:0
	v_exp_f32_e32 v105, v105
	v_mfma_f32_16x16x32_bf16 v[22:25], v[188:191], v[172:175], v[22:25]
	ds_read_b128 v[156:159], v232 offset:2048
	v_mfma_f32_16x16x32_bf16 v[26:29], v[192:195], v[172:175], v[26:29]
	ds_read_b128 v[160:163], v232 offset:4096
	v_add_f32_e32 v98, 1.0, v98
	v_mfma_f32_16x16x32_bf16 v[30:33], v[196:199], v[172:175], v[30:33]
	ds_read_b128 v[164:167], v232 offset:6144
	s_add_u32 m0, s8, 0xc000
	v_mfma_f32_16x16x32_bf16 v[34:37], v[184:187], v[176:179], v[34:37]
	global_load_lds_dwordx4 v200, s[4:5]
	s_add_u32 m0, s8, 0xc400
	v_mfma_f32_16x16x32_bf16 v[38:41], v[188:191], v[176:179], v[38:41]
	global_load_lds_dwordx4 v201, s[4:5]
	v_add_f32_e32 v99, 1.0, v99
	s_add_u32 m0, s8, 0xc800
	v_mfma_f32_16x16x32_bf16 v[42:45], v[192:195], v[176:179], v[42:45]
	global_load_lds_dwordx4 v202, s[4:5]
	s_add_u32 m0, s8, 0xcc00
	v_mfma_f32_16x16x32_bf16 v[46:49], v[196:199], v[176:179], v[46:49]
	global_load_lds_dwordx4 v203, s[4:5]
	v_add_f32_e32 v100, 1.0, v100
	s_add_u32 m0, s9, 0xc000
	v_mfma_f32_16x16x32_bf16 v[50:53], v[184:187], v[180:183], v[50:53]
	global_load_lds_dwordx4 v204, s[6:7]
	s_add_u32 m0, s9, 0xc400
	v_mfma_f32_16x16x32_bf16 v[54:57], v[188:191], v[180:183], v[54:57]
	global_load_lds_dwordx4 v205, s[6:7]
	v_add_f32_e32 v101, 1.0, v101
	v_mfma_f32_16x16x32_bf16 v[58:61], v[192:195], v[180:183], v[58:61]
	s_add_u32 s4, s4, 0x80
	s_addc_u32 s5, s5, 0
	v_mfma_f32_16x16x32_bf16 v[62:65], v[196:199], v[180:183], v[62:65]
	s_add_u32 s6, s6, 0x80
	s_addc_u32 s7, s7, 0
	v_add_f32_e32 v102, 1.0, v102
	s_waitcnt lgkmcnt(0)
	v_mfma_f32_16x16x32_bf16 v[2:5], v[152:155], v[136:139], v[2:5]
	ds_read_b128 v[168:171], v229 offset:0
	v_mfma_f32_16x16x32_bf16 v[6:9], v[156:159], v[136:139], v[6:9]
	ds_read_b128 v[172:175], v229 offset:2048
	v_add_f32_e32 v103, 1.0, v103
	v_mfma_f32_16x16x32_bf16 v[10:13], v[160:163], v[136:139], v[10:13]
	ds_read_b128 v[176:179], v229 offset:4096
	v_add_f32_e32 v104, 1.0, v104
	v_mfma_f32_16x16x32_bf16 v[14:17], v[164:167], v[136:139], v[14:17]
	ds_read_b128 v[180:183], v229 offset:6144
	v_add_f32_e32 v105, 1.0, v105
	v_mfma_f32_16x16x32_bf16 v[18:21], v[152:155], v[140:143], v[18:21]
	ds_read_b128 v[184:187], v235 offset:0
	v_mfma_f32_16x16x32_bf16 v[22:25], v[156:159], v[140:143], v[22:25]
	ds_read_b128 v[188:191], v235 offset:2048
	v_rcp_f32_e32 v98, v98
	v_mfma_f32_16x16x32_bf16 v[26:29], v[160:163], v[140:143], v[26:29]
	ds_read_b128 v[192:195], v235 offset:4096
	v_rcp_f32_e32 v99, v99
	v_mfma_f32_16x16x32_bf16 v[30:33], v[164:167], v[140:143], v[30:33]
	ds_read_b128 v[196:199], v235 offset:6144
	v_rcp_f32_e32 v100, v100
	v_mfma_f32_16x16x32_bf16 v[34:37], v[152:155], v[144:147], v[34:37]
	v_mfma_f32_16x16x32_bf16 v[38:41], v[156:159], v[144:147], v[38:41]
	v_rcp_f32_e32 v101, v101
	v_mfma_f32_16x16x32_bf16 v[42:45], v[160:163], v[144:147], v[42:45]
	v_rcp_f32_e32 v102, v102
	v_mfma_f32_16x16x32_bf16 v[46:49], v[164:167], v[144:147], v[46:49]
	v_rcp_f32_e32 v103, v103
	v_mfma_f32_16x16x32_bf16 v[50:53], v[152:155], v[148:151], v[50:53]
	v_mfma_f32_16x16x32_bf16 v[54:57], v[156:159], v[148:151], v[54:57]
	v_rcp_f32_e32 v104, v104
	v_mfma_f32_16x16x32_bf16 v[58:61], v[160:163], v[148:151], v[58:61]
	v_rcp_f32_e32 v105, v105
	v_mfma_f32_16x16x32_bf16 v[62:65], v[164:167], v[148:151], v[62:65]
	v_cvt_pk_bf16_f32 v98, v98, v99
	s_waitcnt vmcnt(6) lgkmcnt(0)
	s_barrier
	v_mfma_f32_16x16x32_bf16 v[2:5], v[184:187], v[168:171], v[2:5]
	ds_read_b128 v[136:139], v218 offset:0
	v_mfma_f32_16x16x32_bf16 v[6:9], v[188:191], v[168:171], v[6:9]
	ds_read_b128 v[140:143], v218 offset:2048
	v_mfma_f32_16x16x32_bf16 v[10:13], v[192:195], v[168:171], v[10:13]
	ds_read_b128 v[144:147], v218 offset:4096
	v_cvt_pk_bf16_f32 v99, v100, v101
	v_mfma_f32_16x16x32_bf16 v[14:17], v[196:199], v[168:171], v[14:17]
	ds_read_b128 v[148:151], v218 offset:6144
	v_mfma_f32_16x16x32_bf16 v[18:21], v[184:187], v[172:175], v[18:21]
	ds_read_b128 v[152:155], v230 offset:0
	v_cvt_pk_bf16_f32 v100, v102, v103
	v_mfma_f32_16x16x32_bf16 v[22:25], v[188:191], v[172:175], v[22:25]
	ds_read_b128 v[156:159], v230 offset:2048
	v_mfma_f32_16x16x32_bf16 v[26:29], v[192:195], v[172:175], v[26:29]
	ds_read_b128 v[160:163], v230 offset:4096
	v_cvt_pk_bf16_f32 v101, v104, v105
	v_mfma_f32_16x16x32_bf16 v[30:33], v[196:199], v[172:175], v[30:33]
	ds_read_b128 v[164:167], v230 offset:6144
	s_add_u32 m0, s8, 0x18000
	v_mfma_f32_16x16x32_bf16 v[34:37], v[184:187], v[176:179], v[34:37]
	global_load_lds_dwordx4 v200, s[4:5]
	s_add_u32 m0, s8, 0x18400
	v_mfma_f32_16x16x32_bf16 v[38:41], v[188:191], v[176:179], v[38:41]
	global_load_lds_dwordx4 v201, s[4:5]
	global_store_dwordx4 v241, v[98:101], s[10:11] offset:0
	s_add_u32 m0, s8, 0x18800
	v_mfma_f32_16x16x32_bf16 v[42:45], v[192:195], v[176:179], v[42:45]
	global_load_lds_dwordx4 v202, s[4:5]
	s_add_u32 m0, s8, 0x18c00
	v_mfma_f32_16x16x32_bf16 v[46:49], v[196:199], v[176:179], v[46:49]
	global_load_lds_dwordx4 v203, s[4:5]
	v_mul_f32_e32 v106, s12, v106
	s_add_u32 m0, s9, 0x18000
	v_mfma_f32_16x16x32_bf16 v[50:53], v[184:187], v[180:183], v[50:53]
	global_load_lds_dwordx4 v204, s[6:7]
	s_add_u32 m0, s9, 0x18400
	v_mfma_f32_16x16x32_bf16 v[54:57], v[188:191], v[180:183], v[54:57]
	global_load_lds_dwordx4 v205, s[6:7]
	v_mul_f32_e32 v107, s12, v107
	v_mfma_f32_16x16x32_bf16 v[58:61], v[192:195], v[180:183], v[58:61]
	s_add_u32 s4, s4, 0x80
	s_addc_u32 s5, s5, 0
	v_mfma_f32_16x16x32_bf16 v[62:65], v[196:199], v[180:183], v[62:65]
	s_add_u32 s6, s6, 0x80
	s_addc_u32 s7, s7, 0
	v_mul_f32_e32 v108, s12, v108
	s_waitcnt lgkmcnt(0)
	v_mfma_f32_16x16x32_bf16 v[2:5], v[152:155], v[136:139], v[2:5]
	ds_read_b128 v[168:171], v225 offset:0
	v_mfma_f32_16x16x32_bf16 v[6:9], v[156:159], v[136:139], v[6:9]
	ds_read_b128 v[172:175], v225 offset:2048
	v_mul_f32_e32 v109, s12, v109
	v_mfma_f32_16x16x32_bf16 v[10:13], v[160:163], v[136:139], v[10:13]
	ds_read_b128 v[176:179], v225 offset:4096
	v_mul_f32_e32 v110, s12, v110
	v_mfma_f32_16x16x32_bf16 v[14:17], v[164:167], v[136:139], v[14:17]
	ds_read_b128 v[180:183], v225 offset:6144
	v_mul_f32_e32 v111, s12, v111
	v_mfma_f32_16x16x32_bf16 v[18:21], v[152:155], v[140:143], v[18:21]
	ds_read_b128 v[184:187], v233 offset:0
	v_mfma_f32_16x16x32_bf16 v[22:25], v[156:159], v[140:143], v[22:25]
	ds_read_b128 v[188:191], v233 offset:2048
	v_mul_f32_e32 v112, s12, v112
	v_mfma_f32_16x16x32_bf16 v[26:29], v[160:163], v[140:143], v[26:29]
	ds_read_b128 v[192:195], v233 offset:4096
	v_mul_f32_e32 v113, s12, v113
	v_mfma_f32_16x16x32_bf16 v[30:33], v[164:167], v[140:143], v[30:33]
	ds_read_b128 v[196:199], v233 offset:6144
	v_exp_f32_e32 v106, v106
	v_mfma_f32_16x16x32_bf16 v[34:37], v[152:155], v[144:147], v[34:37]
	v_mfma_f32_16x16x32_bf16 v[38:41], v[156:159], v[144:147], v[38:41]
	v_exp_f32_e32 v107, v107
	v_mfma_f32_16x16x32_bf16 v[42:45], v[160:163], v[144:147], v[42:45]
	v_exp_f32_e32 v108, v108
	v_mfma_f32_16x16x32_bf16 v[46:49], v[164:167], v[144:147], v[46:49]
	v_exp_f32_e32 v109, v109
	v_mfma_f32_16x16x32_bf16 v[50:53], v[152:155], v[148:151], v[50:53]
	v_mfma_f32_16x16x32_bf16 v[54:57], v[156:159], v[148:151], v[54:57]
	v_exp_f32_e32 v110, v110
	v_mfma_f32_16x16x32_bf16 v[58:61], v[160:163], v[148:151], v[58:61]
	v_exp_f32_e32 v111, v111
	v_mfma_f32_16x16x32_bf16 v[62:65], v[164:167], v[148:151], v[62:65]
	v_exp_f32_e32 v112, v112
	s_waitcnt vmcnt(7) lgkmcnt(0)
	s_barrier
	v_mfma_f32_16x16x32_bf16 v[2:5], v[184:187], v[168:171], v[2:5]
	ds_read_b128 v[136:139], v219 offset:0
	v_mfma_f32_16x16x32_bf16 v[6:9], v[188:191], v[168:171], v[6:9]
	ds_read_b128 v[140:143], v219 offset:2048
	v_mfma_f32_16x16x32_bf16 v[10:13], v[192:195], v[168:171], v[10:13]
	ds_read_b128 v[144:147], v219 offset:4096
	v_exp_f32_e32 v113, v113
	v_mfma_f32_16x16x32_bf16 v[14:17], v[196:199], v[168:171], v[14:17]
	ds_read_b128 v[148:151], v219 offset:6144
	v_mfma_f32_16x16x32_bf16 v[18:21], v[184:187], v[172:175], v[18:21]
	ds_read_b128 v[152:155], v231 offset:0
	v_add_f32_e32 v106, 1.0, v106
	v_mfma_f32_16x16x32_bf16 v[22:25], v[188:191], v[172:175], v[22:25]
	ds_read_b128 v[156:159], v231 offset:2048
	v_mfma_f32_16x16x32_bf16 v[26:29], v[192:195], v[172:175], v[26:29]
	ds_read_b128 v[160:163], v231 offset:4096
	v_add_f32_e32 v107, 1.0, v107
	v_mfma_f32_16x16x32_bf16 v[30:33], v[196:199], v[172:175], v[30:33]
	ds_read_b128 v[164:167], v231 offset:6144
	s_mov_b32 m0, s8
	v_mfma_f32_16x16x32_bf16 v[34:37], v[184:187], v[176:179], v[34:37]
	global_load_lds_dwordx4 v200, s[4:5]
	s_add_u32 m0, s8, 0x400
	v_mfma_f32_16x16x32_bf16 v[38:41], v[188:191], v[176:179], v[38:41]
	global_load_lds_dwordx4 v201, s[4:5]
	v_add_f32_e32 v108, 1.0, v108
	s_add_u32 m0, s8, 0x800
	v_mfma_f32_16x16x32_bf16 v[42:45], v[192:195], v[176:179], v[42:45]
	global_load_lds_dwordx4 v202, s[4:5]
	s_add_u32 m0, s8, 0xc00
	v_mfma_f32_16x16x32_bf16 v[46:49], v[196:199], v[176:179], v[46:49]
	global_load_lds_dwordx4 v203, s[4:5]
	v_add_f32_e32 v109, 1.0, v109
	s_mov_b32 m0, s9
	v_mfma_f32_16x16x32_bf16 v[50:53], v[184:187], v[180:183], v[50:53]
	global_load_lds_dwordx4 v204, s[6:7]
	s_add_u32 m0, s9, 0x400
	v_mfma_f32_16x16x32_bf16 v[54:57], v[188:191], v[180:183], v[54:57]
	global_load_lds_dwordx4 v205, s[6:7]
	v_add_f32_e32 v110, 1.0, v110
	v_mfma_f32_16x16x32_bf16 v[58:61], v[192:195], v[180:183], v[58:61]
	s_add_u32 s4, s4, 0x80
	s_addc_u32 s5, s5, 0
	v_mfma_f32_16x16x32_bf16 v[62:65], v[196:199], v[180:183], v[62:65]
	s_add_u32 s6, s6, 0x80
	s_addc_u32 s7, s7, 0
	v_add_f32_e32 v111, 1.0, v111
	s_waitcnt lgkmcnt(0)
	v_mfma_f32_16x16x32_bf16 v[2:5], v[152:155], v[136:139], v[2:5]
	ds_read_b128 v[168:171], v228 offset:0
	v_mfma_f32_16x16x32_bf16 v[6:9], v[156:159], v[136:139], v[6:9]
	ds_read_b128 v[172:175], v228 offset:2048
	v_add_f32_e32 v112, 1.0, v112
	v_mfma_f32_16x16x32_bf16 v[10:13], v[160:163], v[136:139], v[10:13]
	ds_read_b128 v[176:179], v228 offset:4096
	v_add_f32_e32 v113, 1.0, v113
	v_mfma_f32_16x16x32_bf16 v[14:17], v[164:167], v[136:139], v[14:17]
	ds_read_b128 v[180:183], v228 offset:6144
	v_rcp_f32_e32 v106, v106
	v_mfma_f32_16x16x32_bf16 v[18:21], v[152:155], v[140:143], v[18:21]
	ds_read_b128 v[184:187], v234 offset:0
	v_mfma_f32_16x16x32_bf16 v[22:25], v[156:159], v[140:143], v[22:25]
	ds_read_b128 v[188:191], v234 offset:2048
	v_rcp_f32_e32 v107, v107
	v_mfma_f32_16x16x32_bf16 v[26:29], v[160:163], v[140:143], v[26:29]
	ds_read_b128 v[192:195], v234 offset:4096
	v_rcp_f32_e32 v108, v108
	v_mfma_f32_16x16x32_bf16 v[30:33], v[164:167], v[140:143], v[30:33]
	ds_read_b128 v[196:199], v234 offset:6144
	v_rcp_f32_e32 v109, v109
	v_mfma_f32_16x16x32_bf16 v[34:37], v[152:155], v[144:147], v[34:37]
	v_mfma_f32_16x16x32_bf16 v[38:41], v[156:159], v[144:147], v[38:41]
	v_rcp_f32_e32 v110, v110
	v_mfma_f32_16x16x32_bf16 v[42:45], v[160:163], v[144:147], v[42:45]
	v_rcp_f32_e32 v111, v111
	v_mfma_f32_16x16x32_bf16 v[46:49], v[164:167], v[144:147], v[46:49]
	v_rcp_f32_e32 v112, v112
	v_mfma_f32_16x16x32_bf16 v[50:53], v[152:155], v[148:151], v[50:53]
	v_mfma_f32_16x16x32_bf16 v[54:57], v[156:159], v[148:151], v[54:57]
	v_rcp_f32_e32 v113, v113
	v_mfma_f32_16x16x32_bf16 v[58:61], v[160:163], v[148:151], v[58:61]
	v_cvt_pk_bf16_f32 v106, v106, v107
	v_mfma_f32_16x16x32_bf16 v[62:65], v[164:167], v[148:151], v[62:65]
	v_cvt_pk_bf16_f32 v107, v108, v109
	s_waitcnt vmcnt(6) lgkmcnt(0)
	s_barrier
	v_mfma_f32_16x16x32_bf16 v[2:5], v[184:187], v[168:171], v[2:5]
	ds_read_b128 v[136:139], v224 offset:0
	v_mfma_f32_16x16x32_bf16 v[6:9], v[188:191], v[168:171], v[6:9]
	ds_read_b128 v[140:143], v224 offset:2048
	v_mfma_f32_16x16x32_bf16 v[10:13], v[192:195], v[168:171], v[10:13]
	ds_read_b128 v[144:147], v224 offset:4096
	v_cvt_pk_bf16_f32 v108, v110, v111
	v_mfma_f32_16x16x32_bf16 v[14:17], v[196:199], v[168:171], v[14:17]
	ds_read_b128 v[148:151], v224 offset:6144
	v_mfma_f32_16x16x32_bf16 v[18:21], v[184:187], v[172:175], v[18:21]
	ds_read_b128 v[152:155], v232 offset:0
	v_cvt_pk_bf16_f32 v109, v112, v113
	v_mfma_f32_16x16x32_bf16 v[22:25], v[188:191], v[172:175], v[22:25]
	ds_read_b128 v[156:159], v232 offset:2048
	v_mfma_f32_16x16x32_bf16 v[26:29], v[192:195], v[172:175], v[26:29]
	ds_read_b128 v[160:163], v232 offset:4096
	global_store_dwordx4 v241, v[106:109], s[10:11] offset:16
	v_mfma_f32_16x16x32_bf16 v[30:33], v[196:199], v[172:175], v[30:33]
	ds_read_b128 v[164:167], v232 offset:6144
	s_add_u32 m0, s8, 0xc000
	v_mfma_f32_16x16x32_bf16 v[34:37], v[184:187], v[176:179], v[34:37]
	global_load_lds_dwordx4 v200, s[4:5]
	s_add_u32 m0, s8, 0xc400
	v_mfma_f32_16x16x32_bf16 v[38:41], v[188:191], v[176:179], v[38:41]
	global_load_lds_dwordx4 v201, s[4:5]
	v_mul_f32_e32 v114, s12, v114
	s_add_u32 m0, s8, 0xc800
	v_mfma_f32_16x16x32_bf16 v[42:45], v[192:195], v[176:179], v[42:45]
	global_load_lds_dwordx4 v202, s[4:5]
	s_add_u32 m0, s8, 0xcc00
	v_mfma_f32_16x16x32_bf16 v[46:49], v[196:199], v[176:179], v[46:49]
	global_load_lds_dwordx4 v203, s[4:5]
	v_mul_f32_e32 v115, s12, v115
	s_add_u32 m0, s9, 0xc000
	v_mfma_f32_16x16x32_bf16 v[50:53], v[184:187], v[180:183], v[50:53]
	global_load_lds_dwordx4 v204, s[6:7]
	s_add_u32 m0, s9, 0xc400
	v_mfma_f32_16x16x32_bf16 v[54:57], v[188:191], v[180:183], v[54:57]
	global_load_lds_dwordx4 v205, s[6:7]
	v_mul_f32_e32 v116, s12, v116
	v_mfma_f32_16x16x32_bf16 v[58:61], v[192:195], v[180:183], v[58:61]
	s_add_u32 s4, s4, 0x80
	s_addc_u32 s5, s5, 0
	v_mfma_f32_16x16x32_bf16 v[62:65], v[196:199], v[180:183], v[62:65]
	s_add_u32 s6, s6, 0x80
	s_addc_u32 s7, s7, 0
	v_mul_f32_e32 v117, s12, v117
	s_waitcnt lgkmcnt(0)
	v_mfma_f32_16x16x32_bf16 v[2:5], v[152:155], v[136:139], v[2:5]
	ds_read_b128 v[168:171], v229 offset:0
	v_mfma_f32_16x16x32_bf16 v[6:9], v[156:159], v[136:139], v[6:9]
	ds_read_b128 v[172:175], v229 offset:2048
	v_mul_f32_e32 v118, s12, v118
	v_mfma_f32_16x16x32_bf16 v[10:13], v[160:163], v[136:139], v[10:13]
	ds_read_b128 v[176:179], v229 offset:4096
	v_mul_f32_e32 v119, s12, v119
	v_mfma_f32_16x16x32_bf16 v[14:17], v[164:167], v[136:139], v[14:17]
	ds_read_b128 v[180:183], v229 offset:6144
	v_mul_f32_e32 v120, s12, v120
	v_mfma_f32_16x16x32_bf16 v[18:21], v[152:155], v[140:143], v[18:21]
	ds_read_b128 v[184:187], v235 offset:0
	v_mfma_f32_16x16x32_bf16 v[22:25], v[156:159], v[140:143], v[22:25]
	ds_read_b128 v[188:191], v235 offset:2048
	v_mul_f32_e32 v121, s12, v121
	v_mfma_f32_16x16x32_bf16 v[26:29], v[160:163], v[140:143], v[26:29]
	ds_read_b128 v[192:195], v235 offset:4096
	v_exp_f32_e32 v114, v114
	v_mfma_f32_16x16x32_bf16 v[30:33], v[164:167], v[140:143], v[30:33]
	ds_read_b128 v[196:199], v235 offset:6144
	v_exp_f32_e32 v115, v115
	v_mfma_f32_16x16x32_bf16 v[34:37], v[152:155], v[144:147], v[34:37]
	v_mfma_f32_16x16x32_bf16 v[38:41], v[156:159], v[144:147], v[38:41]
	v_exp_f32_e32 v116, v116
	v_mfma_f32_16x16x32_bf16 v[42:45], v[160:163], v[144:147], v[42:45]
	v_exp_f32_e32 v117, v117
	v_mfma_f32_16x16x32_bf16 v[46:49], v[164:167], v[144:147], v[46:49]
	v_exp_f32_e32 v118, v118
	v_mfma_f32_16x16x32_bf16 v[50:53], v[152:155], v[148:151], v[50:53]
	v_mfma_f32_16x16x32_bf16 v[54:57], v[156:159], v[148:151], v[54:57]
	v_exp_f32_e32 v119, v119
	v_mfma_f32_16x16x32_bf16 v[58:61], v[160:163], v[148:151], v[58:61]
	v_exp_f32_e32 v120, v120
	v_mfma_f32_16x16x32_bf16 v[62:65], v[164:167], v[148:151], v[62:65]
	v_exp_f32_e32 v121, v121
	s_waitcnt vmcnt(7) lgkmcnt(0)
	s_barrier
	v_mfma_f32_16x16x32_bf16 v[2:5], v[184:187], v[168:171], v[2:5]
	ds_read_b128 v[136:139], v218 offset:0
	v_mfma_f32_16x16x32_bf16 v[6:9], v[188:191], v[168:171], v[6:9]
	ds_read_b128 v[140:143], v218 offset:2048
	v_mfma_f32_16x16x32_bf16 v[10:13], v[192:195], v[168:171], v[10:13]
	ds_read_b128 v[144:147], v218 offset:4096
	v_add_f32_e32 v114, 1.0, v114
	v_mfma_f32_16x16x32_bf16 v[14:17], v[196:199], v[168:171], v[14:17]
	ds_read_b128 v[148:151], v218 offset:6144
	v_mfma_f32_16x16x32_bf16 v[18:21], v[184:187], v[172:175], v[18:21]
	ds_read_b128 v[152:155], v230 offset:0
	v_add_f32_e32 v115, 1.0, v115
	v_mfma_f32_16x16x32_bf16 v[22:25], v[188:191], v[172:175], v[22:25]
	ds_read_b128 v[156:159], v230 offset:2048
	v_mfma_f32_16x16x32_bf16 v[26:29], v[192:195], v[172:175], v[26:29]
	ds_read_b128 v[160:163], v230 offset:4096
	v_add_f32_e32 v116, 1.0, v116
	v_mfma_f32_16x16x32_bf16 v[30:33], v[196:199], v[172:175], v[30:33]
	ds_read_b128 v[164:167], v230 offset:6144
	s_add_u32 m0, s8, 0x18000
	v_mfma_f32_16x16x32_bf16 v[34:37], v[184:187], v[176:179], v[34:37]
	global_load_lds_dwordx4 v200, s[4:5]
	s_add_u32 m0, s8, 0x18400
	v_mfma_f32_16x16x32_bf16 v[38:41], v[188:191], v[176:179], v[38:41]
	global_load_lds_dwordx4 v201, s[4:5]
	v_add_f32_e32 v117, 1.0, v117
	s_add_u32 m0, s8, 0x18800
	v_mfma_f32_16x16x32_bf16 v[42:45], v[192:195], v[176:179], v[42:45]
	global_load_lds_dwordx4 v202, s[4:5]
	s_add_u32 m0, s8, 0x18c00
	v_mfma_f32_16x16x32_bf16 v[46:49], v[196:199], v[176:179], v[46:49]
	global_load_lds_dwordx4 v203, s[4:5]
	v_add_f32_e32 v118, 1.0, v118
	s_add_u32 m0, s9, 0x18000
	v_mfma_f32_16x16x32_bf16 v[50:53], v[184:187], v[180:183], v[50:53]
	global_load_lds_dwordx4 v204, s[6:7]
	s_add_u32 m0, s9, 0x18400
	v_mfma_f32_16x16x32_bf16 v[54:57], v[188:191], v[180:183], v[54:57]
	global_load_lds_dwordx4 v205, s[6:7]
	v_add_f32_e32 v119, 1.0, v119
	v_mfma_f32_16x16x32_bf16 v[58:61], v[192:195], v[180:183], v[58:61]
	s_sub_u32 s4, s4, 0x780
	s_subb_u32 s5, s5, 0
	v_mfma_f32_16x16x32_bf16 v[62:65], v[196:199], v[180:183], v[62:65]
	s_add_u32 s6, s6, 0x3f880
	s_addc_u32 s7, s7, 0
	v_add_f32_e32 v120, 1.0, v120
	s_waitcnt lgkmcnt(0)
	v_mfma_f32_16x16x32_bf16 v[2:5], v[152:155], v[136:139], v[2:5]
	ds_read_b128 v[168:171], v225 offset:0
	v_mfma_f32_16x16x32_bf16 v[6:9], v[156:159], v[136:139], v[6:9]
	ds_read_b128 v[172:175], v225 offset:2048
	v_add_f32_e32 v121, 1.0, v121
	v_mfma_f32_16x16x32_bf16 v[10:13], v[160:163], v[136:139], v[10:13]
	ds_read_b128 v[176:179], v225 offset:4096
	v_rcp_f32_e32 v114, v114
	v_mfma_f32_16x16x32_bf16 v[14:17], v[164:167], v[136:139], v[14:17]
	ds_read_b128 v[180:183], v225 offset:6144
	v_rcp_f32_e32 v115, v115
	v_mfma_f32_16x16x32_bf16 v[18:21], v[152:155], v[140:143], v[18:21]
	ds_read_b128 v[184:187], v233 offset:0
	v_mfma_f32_16x16x32_bf16 v[22:25], v[156:159], v[140:143], v[22:25]
	ds_read_b128 v[188:191], v233 offset:2048
	v_rcp_f32_e32 v116, v116
	v_mfma_f32_16x16x32_bf16 v[26:29], v[160:163], v[140:143], v[26:29]
	ds_read_b128 v[192:195], v233 offset:4096
	v_rcp_f32_e32 v117, v117
	v_mfma_f32_16x16x32_bf16 v[30:33], v[164:167], v[140:143], v[30:33]
	ds_read_b128 v[196:199], v233 offset:6144
	v_rcp_f32_e32 v118, v118
	v_mfma_f32_16x16x32_bf16 v[34:37], v[152:155], v[144:147], v[34:37]
	v_mfma_f32_16x16x32_bf16 v[38:41], v[156:159], v[144:147], v[38:41]
	v_rcp_f32_e32 v119, v119
	v_mfma_f32_16x16x32_bf16 v[42:45], v[160:163], v[144:147], v[42:45]
	v_rcp_f32_e32 v120, v120
	v_mfma_f32_16x16x32_bf16 v[46:49], v[164:167], v[144:147], v[46:49]
	v_rcp_f32_e32 v121, v121
	v_mfma_f32_16x16x32_bf16 v[50:53], v[152:155], v[148:151], v[50:53]
	v_mfma_f32_16x16x32_bf16 v[54:57], v[156:159], v[148:151], v[54:57]
	v_cvt_pk_bf16_f32 v114, v114, v115
	v_mfma_f32_16x16x32_bf16 v[58:61], v[160:163], v[148:151], v[58:61]
	v_cvt_pk_bf16_f32 v115, v116, v117
	v_mfma_f32_16x16x32_bf16 v[62:65], v[164:167], v[148:151], v[62:65]
	v_cvt_pk_bf16_f32 v116, v118, v119
	s_waitcnt vmcnt(6) lgkmcnt(0)
	s_barrier
	v_mfma_f32_16x16x32_bf16 v[2:5], v[184:187], v[168:171], v[2:5]
	ds_read_b128 v[136:139], v219 offset:0
	v_mfma_f32_16x16x32_bf16 v[6:9], v[188:191], v[168:171], v[6:9]
	ds_read_b128 v[140:143], v219 offset:2048
	v_mfma_f32_16x16x32_bf16 v[10:13], v[192:195], v[168:171], v[10:13]
	ds_read_b128 v[144:147], v219 offset:4096
	v_cvt_pk_bf16_f32 v117, v120, v121
	v_mfma_f32_16x16x32_bf16 v[14:17], v[196:199], v[168:171], v[14:17]
	ds_read_b128 v[148:151], v219 offset:6144
	v_mfma_f32_16x16x32_bf16 v[18:21], v[184:187], v[172:175], v[18:21]
	ds_read_b128 v[152:155], v231 offset:0
	global_store_dwordx4 v241, v[114:117], s[10:11] offset:2048
	v_mfma_f32_16x16x32_bf16 v[22:25], v[188:191], v[172:175], v[22:25]
	ds_read_b128 v[156:159], v231 offset:2048
	v_mfma_f32_16x16x32_bf16 v[26:29], v[192:195], v[172:175], v[26:29]
	ds_read_b128 v[160:163], v231 offset:4096
	v_mul_f32_e32 v122, s12, v122
	v_mfma_f32_16x16x32_bf16 v[30:33], v[196:199], v[172:175], v[30:33]
	ds_read_b128 v[164:167], v231 offset:6144
	s_mov_b32 m0, s8
	v_mfma_f32_16x16x32_bf16 v[34:37], v[184:187], v[176:179], v[34:37]
	global_load_lds_dwordx4 v200, s[4:5]
	s_add_u32 m0, s8, 0x400
	v_mfma_f32_16x16x32_bf16 v[38:41], v[188:191], v[176:179], v[38:41]
	global_load_lds_dwordx4 v201, s[4:5]
	v_mul_f32_e32 v123, s12, v123
	s_add_u32 m0, s8, 0x800
	v_mfma_f32_16x16x32_bf16 v[42:45], v[192:195], v[176:179], v[42:45]
	global_load_lds_dwordx4 v202, s[4:5]
	s_add_u32 m0, s8, 0xc00
	v_mfma_f32_16x16x32_bf16 v[46:49], v[196:199], v[176:179], v[46:49]
	global_load_lds_dwordx4 v203, s[4:5]
	v_mul_f32_e32 v124, s12, v124
	s_mov_b32 m0, s9
	v_mfma_f32_16x16x32_bf16 v[50:53], v[184:187], v[180:183], v[50:53]
	global_load_lds_dwordx4 v204, s[6:7]
	s_add_u32 m0, s9, 0x400
	v_mfma_f32_16x16x32_bf16 v[54:57], v[188:191], v[180:183], v[54:57]
	global_load_lds_dwordx4 v205, s[6:7]
	v_mul_f32_e32 v125, s12, v125
	v_mfma_f32_16x16x32_bf16 v[58:61], v[192:195], v[180:183], v[58:61]
	s_add_u32 s4, s4, 0x80
	s_addc_u32 s5, s5, 0
	v_mfma_f32_16x16x32_bf16 v[62:65], v[196:199], v[180:183], v[62:65]
	s_add_u32 s6, s6, 0x80
	s_addc_u32 s7, s7, 0
	v_mul_f32_e32 v126, s12, v126
	s_waitcnt lgkmcnt(0)
	v_mfma_f32_16x16x32_bf16 v[2:5], v[152:155], v[136:139], v[2:5]
	ds_read_b128 v[168:171], v228 offset:0
	v_mfma_f32_16x16x32_bf16 v[6:9], v[156:159], v[136:139], v[6:9]
	ds_read_b128 v[172:175], v228 offset:2048
	v_mul_f32_e32 v127, s12, v127
	v_mfma_f32_16x16x32_bf16 v[10:13], v[160:163], v[136:139], v[10:13]
	ds_read_b128 v[176:179], v228 offset:4096
	v_mul_f32_e32 v128, s12, v128
	v_mfma_f32_16x16x32_bf16 v[14:17], v[164:167], v[136:139], v[14:17]
	ds_read_b128 v[180:183], v228 offset:6144
	v_mul_f32_e32 v129, s12, v129
	v_mfma_f32_16x16x32_bf16 v[18:21], v[152:155], v[140:143], v[18:21]
	ds_read_b128 v[184:187], v234 offset:0
	v_mfma_f32_16x16x32_bf16 v[22:25], v[156:159], v[140:143], v[22:25]
	ds_read_b128 v[188:191], v234 offset:2048
	v_exp_f32_e32 v122, v122
	v_mfma_f32_16x16x32_bf16 v[26:29], v[160:163], v[140:143], v[26:29]
	ds_read_b128 v[192:195], v234 offset:4096
	v_exp_f32_e32 v123, v123
	v_mfma_f32_16x16x32_bf16 v[30:33], v[164:167], v[140:143], v[30:33]
	ds_read_b128 v[196:199], v234 offset:6144
	v_exp_f32_e32 v124, v124
	v_mfma_f32_16x16x32_bf16 v[34:37], v[152:155], v[144:147], v[34:37]
	v_mfma_f32_16x16x32_bf16 v[38:41], v[156:159], v[144:147], v[38:41]
	v_exp_f32_e32 v125, v125
	v_mfma_f32_16x16x32_bf16 v[42:45], v[160:163], v[144:147], v[42:45]
	v_exp_f32_e32 v126, v126
	v_mfma_f32_16x16x32_bf16 v[46:49], v[164:167], v[144:147], v[46:49]
	v_exp_f32_e32 v127, v127
	v_mfma_f32_16x16x32_bf16 v[50:53], v[152:155], v[148:151], v[50:53]
	v_mfma_f32_16x16x32_bf16 v[54:57], v[156:159], v[148:151], v[54:57]
	v_exp_f32_e32 v128, v128
	v_mfma_f32_16x16x32_bf16 v[58:61], v[160:163], v[148:151], v[58:61]
	v_exp_f32_e32 v129, v129
	v_mfma_f32_16x16x32_bf16 v[62:65], v[164:167], v[148:151], v[62:65]
	v_add_f32_e32 v122, 1.0, v122
	s_waitcnt vmcnt(7) lgkmcnt(0)
	s_barrier
	v_mfma_f32_16x16x32_bf16 v[2:5], v[184:187], v[168:171], v[2:5]
	ds_read_b128 v[136:139], v224 offset:0
	v_mfma_f32_16x16x32_bf16 v[6:9], v[188:191], v[168:171], v[6:9]
	ds_read_b128 v[140:143], v224 offset:2048
	v_mfma_f32_16x16x32_bf16 v[10:13], v[192:195], v[168:171], v[10:13]
	ds_read_b128 v[144:147], v224 offset:4096
	v_add_f32_e32 v123, 1.0, v123
	v_mfma_f32_16x16x32_bf16 v[14:17], v[196:199], v[168:171], v[14:17]
	ds_read_b128 v[148:151], v224 offset:6144
	v_mfma_f32_16x16x32_bf16 v[18:21], v[184:187], v[172:175], v[18:21]
	ds_read_b128 v[152:155], v232 offset:0
	v_add_f32_e32 v124, 1.0, v124
	v_mfma_f32_16x16x32_bf16 v[22:25], v[188:191], v[172:175], v[22:25]
	ds_read_b128 v[156:159], v232 offset:2048
	v_mfma_f32_16x16x32_bf16 v[26:29], v[192:195], v[172:175], v[26:29]
	ds_read_b128 v[160:163], v232 offset:4096
	v_add_f32_e32 v125, 1.0, v125
	v_mfma_f32_16x16x32_bf16 v[30:33], v[196:199], v[172:175], v[30:33]
	ds_read_b128 v[164:167], v232 offset:6144
	s_add_u32 m0, s8, 0xc000
	v_mfma_f32_16x16x32_bf16 v[34:37], v[184:187], v[176:179], v[34:37]
	global_load_lds_dwordx4 v200, s[4:5]
	s_add_u32 m0, s8, 0xc400
	v_mfma_f32_16x16x32_bf16 v[38:41], v[188:191], v[176:179], v[38:41]
	global_load_lds_dwordx4 v201, s[4:5]
	v_add_f32_e32 v126, 1.0, v126
	s_add_u32 m0, s8, 0xc800
	v_mfma_f32_16x16x32_bf16 v[42:45], v[192:195], v[176:179], v[42:45]
	global_load_lds_dwordx4 v202, s[4:5]
	s_add_u32 m0, s8, 0xcc00
	v_mfma_f32_16x16x32_bf16 v[46:49], v[196:199], v[176:179], v[46:49]
	global_load_lds_dwordx4 v203, s[4:5]
	v_add_f32_e32 v127, 1.0, v127
	s_add_u32 m0, s9, 0xc000
	v_mfma_f32_16x16x32_bf16 v[50:53], v[184:187], v[180:183], v[50:53]
	global_load_lds_dwordx4 v204, s[6:7]
	s_add_u32 m0, s9, 0xc400
	v_mfma_f32_16x16x32_bf16 v[54:57], v[188:191], v[180:183], v[54:57]
	global_load_lds_dwordx4 v205, s[6:7]
	v_add_f32_e32 v128, 1.0, v128
	v_mfma_f32_16x16x32_bf16 v[58:61], v[192:195], v[180:183], v[58:61]
	s_add_u32 s4, s4, 0x80
	s_addc_u32 s5, s5, 0
	v_mfma_f32_16x16x32_bf16 v[62:65], v[196:199], v[180:183], v[62:65]
	s_add_u32 s6, s6, 0x80
	s_addc_u32 s7, s7, 0
	v_add_f32_e32 v129, 1.0, v129
	s_waitcnt lgkmcnt(0)
	v_mfma_f32_16x16x32_bf16 v[2:5], v[152:155], v[136:139], v[2:5]
	ds_read_b128 v[168:171], v229 offset:0
	v_mfma_f32_16x16x32_bf16 v[6:9], v[156:159], v[136:139], v[6:9]
	ds_read_b128 v[172:175], v229 offset:2048
	v_rcp_f32_e32 v122, v122
	v_mfma_f32_16x16x32_bf16 v[10:13], v[160:163], v[136:139], v[10:13]
	ds_read_b128 v[176:179], v229 offset:4096
	v_rcp_f32_e32 v123, v123
	v_mfma_f32_16x16x32_bf16 v[14:17], v[164:167], v[136:139], v[14:17]
	ds_read_b128 v[180:183], v229 offset:6144
	v_rcp_f32_e32 v124, v124
	v_mfma_f32_16x16x32_bf16 v[18:21], v[152:155], v[140:143], v[18:21]
	ds_read_b128 v[184:187], v235 offset:0
	v_mfma_f32_16x16x32_bf16 v[22:25], v[156:159], v[140:143], v[22:25]
	ds_read_b128 v[188:191], v235 offset:2048
	v_rcp_f32_e32 v125, v125
	v_mfma_f32_16x16x32_bf16 v[26:29], v[160:163], v[140:143], v[26:29]
	ds_read_b128 v[192:195], v235 offset:4096
	v_rcp_f32_e32 v126, v126
	v_mfma_f32_16x16x32_bf16 v[30:33], v[164:167], v[140:143], v[30:33]
	ds_read_b128 v[196:199], v235 offset:6144
	v_rcp_f32_e32 v127, v127
	v_mfma_f32_16x16x32_bf16 v[34:37], v[152:155], v[144:147], v[34:37]
	v_mfma_f32_16x16x32_bf16 v[38:41], v[156:159], v[144:147], v[38:41]
	v_rcp_f32_e32 v128, v128
	v_mfma_f32_16x16x32_bf16 v[42:45], v[160:163], v[144:147], v[42:45]
	v_rcp_f32_e32 v129, v129
	v_mfma_f32_16x16x32_bf16 v[46:49], v[164:167], v[144:147], v[46:49]
	v_cvt_pk_bf16_f32 v122, v122, v123
	v_mfma_f32_16x16x32_bf16 v[50:53], v[152:155], v[148:151], v[50:53]
	v_mfma_f32_16x16x32_bf16 v[54:57], v[156:159], v[148:151], v[54:57]
	v_cvt_pk_bf16_f32 v123, v124, v125
	v_mfma_f32_16x16x32_bf16 v[58:61], v[160:163], v[148:151], v[58:61]
	v_cvt_pk_bf16_f32 v124, v126, v127
	v_mfma_f32_16x16x32_bf16 v[62:65], v[164:167], v[148:151], v[62:65]
	v_cvt_pk_bf16_f32 v125, v128, v129
	s_waitcnt vmcnt(6) lgkmcnt(0)
	s_barrier
	v_mfma_f32_16x16x32_bf16 v[2:5], v[184:187], v[168:171], v[2:5]
	ds_read_b128 v[136:139], v218 offset:0
	v_mfma_f32_16x16x32_bf16 v[6:9], v[188:191], v[168:171], v[6:9]
	ds_read_b128 v[140:143], v218 offset:2048
	v_mfma_f32_16x16x32_bf16 v[10:13], v[192:195], v[168:171], v[10:13]
	ds_read_b128 v[144:147], v218 offset:4096
	v_mfma_f32_16x16x32_bf16 v[14:17], v[196:199], v[168:171], v[14:17]
	ds_read_b128 v[148:151], v218 offset:6144
	v_mfma_f32_16x16x32_bf16 v[18:21], v[184:187], v[172:175], v[18:21]
	ds_read_b128 v[152:155], v230 offset:0
	v_mfma_f32_16x16x32_bf16 v[22:25], v[188:191], v[172:175], v[22:25]
	ds_read_b128 v[156:159], v230 offset:2048
	v_mfma_f32_16x16x32_bf16 v[26:29], v[192:195], v[172:175], v[26:29]
	ds_read_b128 v[160:163], v230 offset:4096
	v_mfma_f32_16x16x32_bf16 v[30:33], v[196:199], v[172:175], v[30:33]
	ds_read_b128 v[164:167], v230 offset:6144
	s_add_u32 m0, s8, 0x18000
	v_mfma_f32_16x16x32_bf16 v[34:37], v[184:187], v[176:179], v[34:37]
	global_load_lds_dwordx4 v200, s[4:5]
	s_add_u32 m0, s8, 0x18400
	v_mfma_f32_16x16x32_bf16 v[38:41], v[188:191], v[176:179], v[38:41]
	global_load_lds_dwordx4 v201, s[4:5]
	s_add_u32 m0, s8, 0x18800
	v_mfma_f32_16x16x32_bf16 v[42:45], v[192:195], v[176:179], v[42:45]
	global_load_lds_dwordx4 v202, s[4:5]
	s_add_u32 m0, s8, 0x18c00
	v_mfma_f32_16x16x32_bf16 v[46:49], v[196:199], v[176:179], v[46:49]
	global_load_lds_dwordx4 v203, s[4:5]
	s_add_u32 m0, s9, 0x18000
	v_mfma_f32_16x16x32_bf16 v[50:53], v[184:187], v[180:183], v[50:53]
	global_load_lds_dwordx4 v204, s[6:7]
	s_add_u32 m0, s9, 0x18400
	v_mfma_f32_16x16x32_bf16 v[54:57], v[188:191], v[180:183], v[54:57]
	global_load_lds_dwordx4 v205, s[6:7]
	v_mfma_f32_16x16x32_bf16 v[58:61], v[192:195], v[180:183], v[58:61]
	s_add_u32 s4, s4, 0x80
	s_addc_u32 s5, s5, 0
	v_mfma_f32_16x16x32_bf16 v[62:65], v[196:199], v[180:183], v[62:65]
	s_add_u32 s6, s6, 0x80
	s_addc_u32 s7, s7, 0
	global_store_dwordx4 v241, v[122:125], s[10:11] offset:2064
	s_waitcnt lgkmcnt(0)
	v_mfma_f32_16x16x32_bf16 v[66:69], v[152:155], v[136:139], 0
	ds_read_b128 v[168:171], v225 offset:0
	v_mfma_f32_16x16x32_bf16 v[70:73], v[156:159], v[136:139], 0
	ds_read_b128 v[172:175], v225 offset:2048
	s_add_u32 s10, s28, s13
	s_addc_u32 s11, s29, 0
	v_mfma_f32_16x16x32_bf16 v[74:77], v[160:163], v[136:139], 0
	ds_read_b128 v[176:179], v225 offset:4096
	s_add_u32 s13, s13, 0x10000
	v_mfma_f32_16x16x32_bf16 v[78:81], v[164:167], v[136:139], 0
	ds_read_b128 v[180:183], v225 offset:6144
	v_mul_f32_e32 v2, s12, v2
	v_mfma_f32_16x16x32_bf16 v[82:85], v[152:155], v[140:143], 0
	ds_read_b128 v[184:187], v233 offset:0
	v_mfma_f32_16x16x32_bf16 v[86:89], v[156:159], v[140:143], 0
	ds_read_b128 v[188:191], v233 offset:2048
	v_mul_f32_e32 v3, s12, v3
	v_mfma_f32_16x16x32_bf16 v[90:93], v[160:163], v[140:143], 0
	ds_read_b128 v[192:195], v233 offset:4096
	v_mul_f32_e32 v4, s12, v4
	v_mfma_f32_16x16x32_bf16 v[94:97], v[164:167], v[140:143], 0
	ds_read_b128 v[196:199], v233 offset:6144
	v_mul_f32_e32 v5, s12, v5
	v_mfma_f32_16x16x32_bf16 v[98:101], v[152:155], v[144:147], 0
	v_mfma_f32_16x16x32_bf16 v[102:105], v[156:159], v[144:147], 0
	v_mul_f32_e32 v6, s12, v6
	v_mfma_f32_16x16x32_bf16 v[106:109], v[160:163], v[144:147], 0
	v_mul_f32_e32 v7, s12, v7
	v_mfma_f32_16x16x32_bf16 v[110:113], v[164:167], v[144:147], 0
	v_mul_f32_e32 v8, s12, v8
	v_mfma_f32_16x16x32_bf16 v[114:117], v[152:155], v[148:151], 0
	v_mfma_f32_16x16x32_bf16 v[118:121], v[156:159], v[148:151], 0
	v_mul_f32_e32 v9, s12, v9
	v_mfma_f32_16x16x32_bf16 v[122:125], v[160:163], v[148:151], 0
	v_exp_f32_e32 v2, v2
	v_mfma_f32_16x16x32_bf16 v[126:129], v[164:167], v[148:151], 0
	v_exp_f32_e32 v3, v3
	s_waitcnt vmcnt(7) lgkmcnt(0)
	s_barrier
	v_mfma_f32_16x16x32_bf16 v[66:69], v[184:187], v[168:171], v[66:69]
	ds_read_b128 v[136:139], v219 offset:0
	v_mfma_f32_16x16x32_bf16 v[70:73], v[188:191], v[168:171], v[70:73]
	ds_read_b128 v[140:143], v219 offset:2048
	v_mfma_f32_16x16x32_bf16 v[74:77], v[192:195], v[168:171], v[74:77]
	ds_read_b128 v[144:147], v219 offset:4096
	v_exp_f32_e32 v4, v4
	v_mfma_f32_16x16x32_bf16 v[78:81], v[196:199], v[168:171], v[78:81]
	ds_read_b128 v[148:151], v219 offset:6144
	v_mfma_f32_16x16x32_bf16 v[82:85], v[184:187], v[172:175], v[82:85]
	ds_read_b128 v[152:155], v231 offset:0
	v_exp_f32_e32 v5, v5
	v_mfma_f32_16x16x32_bf16 v[86:89], v[188:191], v[172:175], v[86:89]
	ds_read_b128 v[156:159], v231 offset:2048
	v_mfma_f32_16x16x32_bf16 v[90:93], v[192:195], v[172:175], v[90:93]
	ds_read_b128 v[160:163], v231 offset:4096
	v_exp_f32_e32 v6, v6
	v_mfma_f32_16x16x32_bf16 v[94:97], v[196:199], v[172:175], v[94:97]
	ds_read_b128 v[164:167], v231 offset:6144
	s_mov_b32 m0, s8
	v_mfma_f32_16x16x32_bf16 v[98:101], v[184:187], v[176:179], v[98:101]
	global_load_lds_dwordx4 v200, s[4:5]
	s_add_u32 m0, s8, 0x400
	v_mfma_f32_16x16x32_bf16 v[102:105], v[188:191], v[176:179], v[102:105]
	global_load_lds_dwordx4 v201, s[4:5]
	v_exp_f32_e32 v7, v7
	s_add_u32 m0, s8, 0x800
	v_mfma_f32_16x16x32_bf16 v[106:109], v[192:195], v[176:179], v[106:109]
	global_load_lds_dwordx4 v202, s[4:5]
	s_add_u32 m0, s8, 0xc00
	v_mfma_f32_16x16x32_bf16 v[110:113], v[196:199], v[176:179], v[110:113]
	global_load_lds_dwordx4 v203, s[4:5]
	v_exp_f32_e32 v8, v8
	s_mov_b32 m0, s9
	v_mfma_f32_16x16x32_bf16 v[114:117], v[184:187], v[180:183], v[114:117]
	global_load_lds_dwordx4 v204, s[6:7]
	s_add_u32 m0, s9, 0x400
	v_mfma_f32_16x16x32_bf16 v[118:121], v[188:191], v[180:183], v[118:121]
	global_load_lds_dwordx4 v205, s[6:7]
	v_exp_f32_e32 v9, v9
	v_mfma_f32_16x16x32_bf16 v[122:125], v[192:195], v[180:183], v[122:125]
	s_add_u32 s4, s4, 0x80
	s_addc_u32 s5, s5, 0
	v_mfma_f32_16x16x32_bf16 v[126:129], v[196:199], v[180:183], v[126:129]
	s_add_u32 s6, s6, 0x80
	s_addc_u32 s7, s7, 0
	v_add_f32_e32 v2, 1.0, v2
	s_waitcnt lgkmcnt(0)
	v_mfma_f32_16x16x32_bf16 v[66:69], v[152:155], v[136:139], v[66:69]
	ds_read_b128 v[168:171], v228 offset:0
	v_mfma_f32_16x16x32_bf16 v[70:73], v[156:159], v[136:139], v[70:73]
	ds_read_b128 v[172:175], v228 offset:2048
	v_add_f32_e32 v3, 1.0, v3
	v_mfma_f32_16x16x32_bf16 v[74:77], v[160:163], v[136:139], v[74:77]
	ds_read_b128 v[176:179], v228 offset:4096
	v_add_f32_e32 v4, 1.0, v4
	v_mfma_f32_16x16x32_bf16 v[78:81], v[164:167], v[136:139], v[78:81]
	ds_read_b128 v[180:183], v228 offset:6144
	v_add_f32_e32 v5, 1.0, v5
	v_mfma_f32_16x16x32_bf16 v[82:85], v[152:155], v[140:143], v[82:85]
	ds_read_b128 v[184:187], v234 offset:0
	v_mfma_f32_16x16x32_bf16 v[86:89], v[156:159], v[140:143], v[86:89]
	ds_read_b128 v[188:191], v234 offset:2048
	v_add_f32_e32 v6, 1.0, v6
	v_mfma_f32_16x16x32_bf16 v[90:93], v[160:163], v[140:143], v[90:93]
	ds_read_b128 v[192:195], v234 offset:4096
	v_add_f32_e32 v7, 1.0, v7
	v_mfma_f32_16x16x32_bf16 v[94:97], v[164:167], v[140:143], v[94:97]
	ds_read_b128 v[196:199], v234 offset:6144
	v_add_f32_e32 v8, 1.0, v8
	v_mfma_f32_16x16x32_bf16 v[98:101], v[152:155], v[144:147], v[98:101]
	v_mfma_f32_16x16x32_bf16 v[102:105], v[156:159], v[144:147], v[102:105]
	v_add_f32_e32 v9, 1.0, v9
	v_mfma_f32_16x16x32_bf16 v[106:109], v[160:163], v[144:147], v[106:109]
	v_rcp_f32_e32 v2, v2
	v_mfma_f32_16x16x32_bf16 v[110:113], v[164:167], v[144:147], v[110:113]
	v_rcp_f32_e32 v3, v3
	v_mfma_f32_16x16x32_bf16 v[114:117], v[152:155], v[148:151], v[114:117]
	v_mfma_f32_16x16x32_bf16 v[118:121], v[156:159], v[148:151], v[118:121]
	v_rcp_f32_e32 v4, v4
	v_mfma_f32_16x16x32_bf16 v[122:125], v[160:163], v[148:151], v[122:125]
	v_rcp_f32_e32 v5, v5
	v_mfma_f32_16x16x32_bf16 v[126:129], v[164:167], v[148:151], v[126:129]
	v_rcp_f32_e32 v6, v6
	s_waitcnt vmcnt(7) lgkmcnt(0)
	s_barrier
	v_mfma_f32_16x16x32_bf16 v[66:69], v[184:187], v[168:171], v[66:69]
	ds_read_b128 v[136:139], v224 offset:0
	v_mfma_f32_16x16x32_bf16 v[70:73], v[188:191], v[168:171], v[70:73]
	ds_read_b128 v[140:143], v224 offset:2048
	v_mfma_f32_16x16x32_bf16 v[74:77], v[192:195], v[168:171], v[74:77]
	ds_read_b128 v[144:147], v224 offset:4096
	v_rcp_f32_e32 v7, v7
	v_mfma_f32_16x16x32_bf16 v[78:81], v[196:199], v[168:171], v[78:81]
	ds_read_b128 v[148:151], v224 offset:6144
	v_mfma_f32_16x16x32_bf16 v[82:85], v[184:187], v[172:175], v[82:85]
	ds_read_b128 v[152:155], v232 offset:0
	v_rcp_f32_e32 v8, v8
	v_mfma_f32_16x16x32_bf16 v[86:89], v[188:191], v[172:175], v[86:89]
	ds_read_b128 v[156:159], v232 offset:2048
	v_mfma_f32_16x16x32_bf16 v[90:93], v[192:195], v[172:175], v[90:93]
	ds_read_b128 v[160:163], v232 offset:4096
	v_rcp_f32_e32 v9, v9
	v_mfma_f32_16x16x32_bf16 v[94:97], v[196:199], v[172:175], v[94:97]
	ds_read_b128 v[164:167], v232 offset:6144
	s_add_u32 m0, s8, 0xc000
	v_mfma_f32_16x16x32_bf16 v[98:101], v[184:187], v[176:179], v[98:101]
	global_load_lds_dwordx4 v200, s[4:5]
	s_add_u32 m0, s8, 0xc400
	v_mfma_f32_16x16x32_bf16 v[102:105], v[188:191], v[176:179], v[102:105]
	global_load_lds_dwordx4 v201, s[4:5]
	v_cvt_pk_bf16_f32 v2, v2, v3
	s_add_u32 m0, s8, 0xc800
	v_mfma_f32_16x16x32_bf16 v[106:109], v[192:195], v[176:179], v[106:109]
	global_load_lds_dwordx4 v202, s[4:5]
	s_add_u32 m0, s8, 0xcc00
	v_mfma_f32_16x16x32_bf16 v[110:113], v[196:199], v[176:179], v[110:113]
	global_load_lds_dwordx4 v203, s[4:5]
	v_cvt_pk_bf16_f32 v3, v4, v5
	s_add_u32 m0, s9, 0xc000
	v_mfma_f32_16x16x32_bf16 v[114:117], v[184:187], v[180:183], v[114:117]
	global_load_lds_dwordx4 v204, s[6:7]
	s_add_u32 m0, s9, 0xc400
	v_mfma_f32_16x16x32_bf16 v[118:121], v[188:191], v[180:183], v[118:121]
	global_load_lds_dwordx4 v205, s[6:7]
	v_cvt_pk_bf16_f32 v4, v6, v7
	v_mfma_f32_16x16x32_bf16 v[122:125], v[192:195], v[180:183], v[122:125]
	s_add_u32 s4, s4, 0x80
	s_addc_u32 s5, s5, 0
	v_mfma_f32_16x16x32_bf16 v[126:129], v[196:199], v[180:183], v[126:129]
	s_add_u32 s6, s6, 0x80
	s_addc_u32 s7, s7, 0
	v_cvt_pk_bf16_f32 v5, v8, v9
	s_waitcnt lgkmcnt(0)
	v_mfma_f32_16x16x32_bf16 v[66:69], v[152:155], v[136:139], v[66:69]
	ds_read_b128 v[168:171], v229 offset:0
	v_mfma_f32_16x16x32_bf16 v[70:73], v[156:159], v[136:139], v[70:73]
	ds_read_b128 v[172:175], v229 offset:2048
	global_store_dwordx4 v240, v[2:5], s[10:11] offset:0
	v_mfma_f32_16x16x32_bf16 v[74:77], v[160:163], v[136:139], v[74:77]
	ds_read_b128 v[176:179], v229 offset:4096
	v_mul_f32_e32 v10, s12, v10
	v_mfma_f32_16x16x32_bf16 v[78:81], v[164:167], v[136:139], v[78:81]
	ds_read_b128 v[180:183], v229 offset:6144
	v_mul_f32_e32 v11, s12, v11
	v_mfma_f32_16x16x32_bf16 v[82:85], v[152:155], v[140:143], v[82:85]
	ds_read_b128 v[184:187], v235 offset:0
	v_mfma_f32_16x16x32_bf16 v[86:89], v[156:159], v[140:143], v[86:89]
	ds_read_b128 v[188:191], v235 offset:2048
	v_mul_f32_e32 v12, s12, v12
	v_mfma_f32_16x16x32_bf16 v[90:93], v[160:163], v[140:143], v[90:93]
	ds_read_b128 v[192:195], v235 offset:4096
	v_mul_f32_e32 v13, s12, v13
	v_mfma_f32_16x16x32_bf16 v[94:97], v[164:167], v[140:143], v[94:97]
	ds_read_b128 v[196:199], v235 offset:6144
	v_mul_f32_e32 v14, s12, v14
	v_mfma_f32_16x16x32_bf16 v[98:101], v[152:155], v[144:147], v[98:101]
	v_mfma_f32_16x16x32_bf16 v[102:105], v[156:159], v[144:147], v[102:105]
	v_mul_f32_e32 v15, s12, v15
	v_mfma_f32_16x16x32_bf16 v[106:109], v[160:163], v[144:147], v[106:109]
	v_mul_f32_e32 v16, s12, v16
	v_mfma_f32_16x16x32_bf16 v[110:113], v[164:167], v[144:147], v[110:113]
	v_mul_f32_e32 v17, s12, v17
	v_mfma_f32_16x16x32_bf16 v[114:117], v[152:155], v[148:151], v[114:117]
	v_mfma_f32_16x16x32_bf16 v[118:121], v[156:159], v[148:151], v[118:121]
	v_exp_f32_e32 v10, v10
	v_mfma_f32_16x16x32_bf16 v[122:125], v[160:163], v[148:151], v[122:125]
	v_exp_f32_e32 v11, v11
	v_mfma_f32_16x16x32_bf16 v[126:129], v[164:167], v[148:151], v[126:129]
	v_exp_f32_e32 v12, v12
	s_waitcnt vmcnt(7) lgkmcnt(0)
	s_barrier
	v_mfma_f32_16x16x32_bf16 v[66:69], v[184:187], v[168:171], v[66:69]
	ds_read_b128 v[136:139], v218 offset:0
	v_mfma_f32_16x16x32_bf16 v[70:73], v[188:191], v[168:171], v[70:73]
	ds_read_b128 v[140:143], v218 offset:2048
	v_mfma_f32_16x16x32_bf16 v[74:77], v[192:195], v[168:171], v[74:77]
	ds_read_b128 v[144:147], v218 offset:4096
	v_exp_f32_e32 v13, v13
	v_mfma_f32_16x16x32_bf16 v[78:81], v[196:199], v[168:171], v[78:81]
	ds_read_b128 v[148:151], v218 offset:6144
	v_mfma_f32_16x16x32_bf16 v[82:85], v[184:187], v[172:175], v[82:85]
	ds_read_b128 v[152:155], v230 offset:0
	v_exp_f32_e32 v14, v14
	v_mfma_f32_16x16x32_bf16 v[86:89], v[188:191], v[172:175], v[86:89]
	ds_read_b128 v[156:159], v230 offset:2048
	v_mfma_f32_16x16x32_bf16 v[90:93], v[192:195], v[172:175], v[90:93]
	ds_read_b128 v[160:163], v230 offset:4096
	v_exp_f32_e32 v15, v15
	v_mfma_f32_16x16x32_bf16 v[94:97], v[196:199], v[172:175], v[94:97]
	ds_read_b128 v[164:167], v230 offset:6144
	s_add_u32 m0, s8, 0x18000
	v_mfma_f32_16x16x32_bf16 v[98:101], v[184:187], v[176:179], v[98:101]
	global_load_lds_dwordx4 v200, s[4:5]
	s_add_u32 m0, s8, 0x18400
	v_mfma_f32_16x16x32_bf16 v[102:105], v[188:191], v[176:179], v[102:105]
	global_load_lds_dwordx4 v201, s[4:5]
	v_exp_f32_e32 v16, v16
	s_add_u32 m0, s8, 0x18800
	v_mfma_f32_16x16x32_bf16 v[106:109], v[192:195], v[176:179], v[106:109]
	global_load_lds_dwordx4 v202, s[4:5]
	s_add_u32 m0, s8, 0x18c00
	v_mfma_f32_16x16x32_bf16 v[110:113], v[196:199], v[176:179], v[110:113]
	global_load_lds_dwordx4 v203, s[4:5]
	v_exp_f32_e32 v17, v17
	s_add_u32 m0, s9, 0x18000
	v_mfma_f32_16x16x32_bf16 v[114:117], v[184:187], v[180:183], v[114:117]
	global_load_lds_dwordx4 v204, s[6:7]
	s_add_u32 m0, s9, 0x18400
	v_mfma_f32_16x16x32_bf16 v[118:121], v[188:191], v[180:183], v[118:121]
	global_load_lds_dwordx4 v205, s[6:7]
	v_add_f32_e32 v10, 1.0, v10
	v_mfma_f32_16x16x32_bf16 v[122:125], v[192:195], v[180:183], v[122:125]
	s_add_u32 s4, s4, 0x80
	s_addc_u32 s5, s5, 0
	v_mfma_f32_16x16x32_bf16 v[126:129], v[196:199], v[180:183], v[126:129]
	s_add_u32 s6, s6, 0x80
	s_addc_u32 s7, s7, 0
	v_add_f32_e32 v11, 1.0, v11
	s_waitcnt lgkmcnt(0)
	v_mfma_f32_16x16x32_bf16 v[66:69], v[152:155], v[136:139], v[66:69]
	ds_read_b128 v[168:171], v225 offset:0
	v_mfma_f32_16x16x32_bf16 v[70:73], v[156:159], v[136:139], v[70:73]
	ds_read_b128 v[172:175], v225 offset:2048
	v_add_f32_e32 v12, 1.0, v12
	v_mfma_f32_16x16x32_bf16 v[74:77], v[160:163], v[136:139], v[74:77]
	ds_read_b128 v[176:179], v225 offset:4096
	v_add_f32_e32 v13, 1.0, v13
	v_mfma_f32_16x16x32_bf16 v[78:81], v[164:167], v[136:139], v[78:81]
	ds_read_b128 v[180:183], v225 offset:6144
	v_add_f32_e32 v14, 1.0, v14
	v_mfma_f32_16x16x32_bf16 v[82:85], v[152:155], v[140:143], v[82:85]
	ds_read_b128 v[184:187], v233 offset:0
	v_mfma_f32_16x16x32_bf16 v[86:89], v[156:159], v[140:143], v[86:89]
	ds_read_b128 v[188:191], v233 offset:2048
	v_add_f32_e32 v15, 1.0, v15
	v_mfma_f32_16x16x32_bf16 v[90:93], v[160:163], v[140:143], v[90:93]
	ds_read_b128 v[192:195], v233 offset:4096
	v_add_f32_e32 v16, 1.0, v16
	v_mfma_f32_16x16x32_bf16 v[94:97], v[164:167], v[140:143], v[94:97]
	ds_read_b128 v[196:199], v233 offset:6144
	v_add_f32_e32 v17, 1.0, v17
	v_mfma_f32_16x16x32_bf16 v[98:101], v[152:155], v[144:147], v[98:101]
	v_mfma_f32_16x16x32_bf16 v[102:105], v[156:159], v[144:147], v[102:105]
	v_rcp_f32_e32 v10, v10
	v_mfma_f32_16x16x32_bf16 v[106:109], v[160:163], v[144:147], v[106:109]
	v_rcp_f32_e32 v11, v11
	v_mfma_f32_16x16x32_bf16 v[110:113], v[164:167], v[144:147], v[110:113]
	v_rcp_f32_e32 v12, v12
	v_mfma_f32_16x16x32_bf16 v[114:117], v[152:155], v[148:151], v[114:117]
	v_mfma_f32_16x16x32_bf16 v[118:121], v[156:159], v[148:151], v[118:121]
	v_rcp_f32_e32 v13, v13
	v_mfma_f32_16x16x32_bf16 v[122:125], v[160:163], v[148:151], v[122:125]
	v_rcp_f32_e32 v14, v14
	v_mfma_f32_16x16x32_bf16 v[126:129], v[164:167], v[148:151], v[126:129]
	v_rcp_f32_e32 v15, v15
	s_waitcnt vmcnt(7) lgkmcnt(0)
	s_barrier
	v_mfma_f32_16x16x32_bf16 v[66:69], v[184:187], v[168:171], v[66:69]
	ds_read_b128 v[136:139], v219 offset:0
	v_mfma_f32_16x16x32_bf16 v[70:73], v[188:191], v[168:171], v[70:73]
	ds_read_b128 v[140:143], v219 offset:2048
	v_mfma_f32_16x16x32_bf16 v[74:77], v[192:195], v[168:171], v[74:77]
	ds_read_b128 v[144:147], v219 offset:4096
	v_rcp_f32_e32 v16, v16
	v_mfma_f32_16x16x32_bf16 v[78:81], v[196:199], v[168:171], v[78:81]
	ds_read_b128 v[148:151], v219 offset:6144
	v_mfma_f32_16x16x32_bf16 v[82:85], v[184:187], v[172:175], v[82:85]
	ds_read_b128 v[152:155], v231 offset:0
	v_rcp_f32_e32 v17, v17
	v_mfma_f32_16x16x32_bf16 v[86:89], v[188:191], v[172:175], v[86:89]
	ds_read_b128 v[156:159], v231 offset:2048
	v_mfma_f32_16x16x32_bf16 v[90:93], v[192:195], v[172:175], v[90:93]
	ds_read_b128 v[160:163], v231 offset:4096
	v_cvt_pk_bf16_f32 v10, v10, v11
	v_mfma_f32_16x16x32_bf16 v[94:97], v[196:199], v[172:175], v[94:97]
	ds_read_b128 v[164:167], v231 offset:6144
	s_mov_b32 m0, s8
	v_mfma_f32_16x16x32_bf16 v[98:101], v[184:187], v[176:179], v[98:101]
	global_load_lds_dwordx4 v200, s[4:5]
	s_add_u32 m0, s8, 0x400
	v_mfma_f32_16x16x32_bf16 v[102:105], v[188:191], v[176:179], v[102:105]
	global_load_lds_dwordx4 v201, s[4:5]
	v_cvt_pk_bf16_f32 v11, v12, v13
	s_add_u32 m0, s8, 0x800
	v_mfma_f32_16x16x32_bf16 v[106:109], v[192:195], v[176:179], v[106:109]
	global_load_lds_dwordx4 v202, s[4:5]
	s_add_u32 m0, s8, 0xc00
	v_mfma_f32_16x16x32_bf16 v[110:113], v[196:199], v[176:179], v[110:113]
	global_load_lds_dwordx4 v203, s[4:5]
	v_cvt_pk_bf16_f32 v12, v14, v15
	s_mov_b32 m0, s9
	v_mfma_f32_16x16x32_bf16 v[114:117], v[184:187], v[180:183], v[114:117]
	global_load_lds_dwordx4 v204, s[6:7]
	s_add_u32 m0, s9, 0x400
	v_mfma_f32_16x16x32_bf16 v[118:121], v[188:191], v[180:183], v[118:121]
	global_load_lds_dwordx4 v205, s[6:7]
	v_cvt_pk_bf16_f32 v13, v16, v17
	v_mfma_f32_16x16x32_bf16 v[122:125], v[192:195], v[180:183], v[122:125]
	s_add_u32 s4, s4, 0x80
	s_addc_u32 s5, s5, 0
	v_mfma_f32_16x16x32_bf16 v[126:129], v[196:199], v[180:183], v[126:129]
	s_add_u32 s6, s6, 0x80
	s_addc_u32 s7, s7, 0
	global_store_dwordx4 v240, v[10:13], s[10:11] offset:16
	s_waitcnt lgkmcnt(0)
	v_mfma_f32_16x16x32_bf16 v[66:69], v[152:155], v[136:139], v[66:69]
	ds_read_b128 v[168:171], v228 offset:0
	v_mfma_f32_16x16x32_bf16 v[70:73], v[156:159], v[136:139], v[70:73]
	ds_read_b128 v[172:175], v228 offset:2048
	v_mul_f32_e32 v18, s12, v18
	v_mfma_f32_16x16x32_bf16 v[74:77], v[160:163], v[136:139], v[74:77]
	ds_read_b128 v[176:179], v228 offset:4096
	v_mul_f32_e32 v19, s12, v19
	v_mfma_f32_16x16x32_bf16 v[78:81], v[164:167], v[136:139], v[78:81]
	ds_read_b128 v[180:183], v228 offset:6144
	v_mul_f32_e32 v20, s12, v20
	v_mfma_f32_16x16x32_bf16 v[82:85], v[152:155], v[140:143], v[82:85]
	ds_read_b128 v[184:187], v234 offset:0
	v_mfma_f32_16x16x32_bf16 v[86:89], v[156:159], v[140:143], v[86:89]
	ds_read_b128 v[188:191], v234 offset:2048
	v_mul_f32_e32 v21, s12, v21
	v_mfma_f32_16x16x32_bf16 v[90:93], v[160:163], v[140:143], v[90:93]
	ds_read_b128 v[192:195], v234 offset:4096
	v_mul_f32_e32 v22, s12, v22
	v_mfma_f32_16x16x32_bf16 v[94:97], v[164:167], v[140:143], v[94:97]
	ds_read_b128 v[196:199], v234 offset:6144
	v_mul_f32_e32 v23, s12, v23
	v_mfma_f32_16x16x32_bf16 v[98:101], v[152:155], v[144:147], v[98:101]
	v_mfma_f32_16x16x32_bf16 v[102:105], v[156:159], v[144:147], v[102:105]
	v_mul_f32_e32 v24, s12, v24
	v_mfma_f32_16x16x32_bf16 v[106:109], v[160:163], v[144:147], v[106:109]
	v_mul_f32_e32 v25, s12, v25
	v_mfma_f32_16x16x32_bf16 v[110:113], v[164:167], v[144:147], v[110:113]
	v_exp_f32_e32 v18, v18
	v_mfma_f32_16x16x32_bf16 v[114:117], v[152:155], v[148:151], v[114:117]
	v_mfma_f32_16x16x32_bf16 v[118:121], v[156:159], v[148:151], v[118:121]
	v_exp_f32_e32 v19, v19
	v_mfma_f32_16x16x32_bf16 v[122:125], v[160:163], v[148:151], v[122:125]
	v_exp_f32_e32 v20, v20
	v_mfma_f32_16x16x32_bf16 v[126:129], v[164:167], v[148:151], v[126:129]
	v_exp_f32_e32 v21, v21
	s_waitcnt vmcnt(7) lgkmcnt(0)
	s_barrier
	v_mfma_f32_16x16x32_bf16 v[66:69], v[184:187], v[168:171], v[66:69]
	ds_read_b128 v[136:139], v224 offset:0
	v_mfma_f32_16x16x32_bf16 v[70:73], v[188:191], v[168:171], v[70:73]
	ds_read_b128 v[140:143], v224 offset:2048
	v_mfma_f32_16x16x32_bf16 v[74:77], v[192:195], v[168:171], v[74:77]
	ds_read_b128 v[144:147], v224 offset:4096
	v_exp_f32_e32 v22, v22
	v_mfma_f32_16x16x32_bf16 v[78:81], v[196:199], v[168:171], v[78:81]
	ds_read_b128 v[148:151], v224 offset:6144
	v_mfma_f32_16x16x32_bf16 v[82:85], v[184:187], v[172:175], v[82:85]
	ds_read_b128 v[152:155], v232 offset:0
	v_exp_f32_e32 v23, v23
	v_mfma_f32_16x16x32_bf16 v[86:89], v[188:191], v[172:175], v[86:89]
	ds_read_b128 v[156:159], v232 offset:2048
	v_mfma_f32_16x16x32_bf16 v[90:93], v[192:195], v[172:175], v[90:93]
	ds_read_b128 v[160:163], v232 offset:4096
	v_exp_f32_e32 v24, v24
	v_mfma_f32_16x16x32_bf16 v[94:97], v[196:199], v[172:175], v[94:97]
	ds_read_b128 v[164:167], v232 offset:6144
	s_add_u32 m0, s8, 0xc000
	v_mfma_f32_16x16x32_bf16 v[98:101], v[184:187], v[176:179], v[98:101]
	global_load_lds_dwordx4 v200, s[4:5]
	s_add_u32 m0, s8, 0xc400
	v_mfma_f32_16x16x32_bf16 v[102:105], v[188:191], v[176:179], v[102:105]
	global_load_lds_dwordx4 v201, s[4:5]
	v_exp_f32_e32 v25, v25
	s_add_u32 m0, s8, 0xc800
	v_mfma_f32_16x16x32_bf16 v[106:109], v[192:195], v[176:179], v[106:109]
	global_load_lds_dwordx4 v202, s[4:5]
	s_add_u32 m0, s8, 0xcc00
	v_mfma_f32_16x16x32_bf16 v[110:113], v[196:199], v[176:179], v[110:113]
	global_load_lds_dwordx4 v203, s[4:5]
	v_add_f32_e32 v18, 1.0, v18
	s_add_u32 m0, s9, 0xc000
	v_mfma_f32_16x16x32_bf16 v[114:117], v[184:187], v[180:183], v[114:117]
	global_load_lds_dwordx4 v204, s[6:7]
	s_add_u32 m0, s9, 0xc400
	v_mfma_f32_16x16x32_bf16 v[118:121], v[188:191], v[180:183], v[118:121]
	global_load_lds_dwordx4 v205, s[6:7]
	v_add_f32_e32 v19, 1.0, v19
	v_mfma_f32_16x16x32_bf16 v[122:125], v[192:195], v[180:183], v[122:125]
	s_add_u32 s4, s4, 0x80
	s_addc_u32 s5, s5, 0
	v_mfma_f32_16x16x32_bf16 v[126:129], v[196:199], v[180:183], v[126:129]
	s_add_u32 s6, s6, 0x80
	s_addc_u32 s7, s7, 0
	v_add_f32_e32 v20, 1.0, v20
	s_waitcnt lgkmcnt(0)
	v_mfma_f32_16x16x32_bf16 v[66:69], v[152:155], v[136:139], v[66:69]
	ds_read_b128 v[168:171], v229 offset:0
	v_mfma_f32_16x16x32_bf16 v[70:73], v[156:159], v[136:139], v[70:73]
	ds_read_b128 v[172:175], v229 offset:2048
	v_add_f32_e32 v21, 1.0, v21
	v_mfma_f32_16x16x32_bf16 v[74:77], v[160:163], v[136:139], v[74:77]
	ds_read_b128 v[176:179], v229 offset:4096
	v_add_f32_e32 v22, 1.0, v22
	v_mfma_f32_16x16x32_bf16 v[78:81], v[164:167], v[136:139], v[78:81]
	ds_read_b128 v[180:183], v229 offset:6144
	v_add_f32_e32 v23, 1.0, v23
	v_mfma_f32_16x16x32_bf16 v[82:85], v[152:155], v[140:143], v[82:85]
	ds_read_b128 v[184:187], v235 offset:0
	v_mfma_f32_16x16x32_bf16 v[86:89], v[156:159], v[140:143], v[86:89]
	ds_read_b128 v[188:191], v235 offset:2048
	v_add_f32_e32 v24, 1.0, v24
	v_mfma_f32_16x16x32_bf16 v[90:93], v[160:163], v[140:143], v[90:93]
	ds_read_b128 v[192:195], v235 offset:4096
	v_add_f32_e32 v25, 1.0, v25
	v_mfma_f32_16x16x32_bf16 v[94:97], v[164:167], v[140:143], v[94:97]
	ds_read_b128 v[196:199], v235 offset:6144
	v_rcp_f32_e32 v18, v18
	v_mfma_f32_16x16x32_bf16 v[98:101], v[152:155], v[144:147], v[98:101]
	v_mfma_f32_16x16x32_bf16 v[102:105], v[156:159], v[144:147], v[102:105]
	v_rcp_f32_e32 v19, v19
	v_mfma_f32_16x16x32_bf16 v[106:109], v[160:163], v[144:147], v[106:109]
	v_rcp_f32_e32 v20, v20
	v_mfma_f32_16x16x32_bf16 v[110:113], v[164:167], v[144:147], v[110:113]
	v_rcp_f32_e32 v21, v21
	v_mfma_f32_16x16x32_bf16 v[114:117], v[152:155], v[148:151], v[114:117]
	v_mfma_f32_16x16x32_bf16 v[118:121], v[156:159], v[148:151], v[118:121]
	v_rcp_f32_e32 v22, v22
	v_mfma_f32_16x16x32_bf16 v[122:125], v[160:163], v[148:151], v[122:125]
	v_rcp_f32_e32 v23, v23
	v_mfma_f32_16x16x32_bf16 v[126:129], v[164:167], v[148:151], v[126:129]
	v_rcp_f32_e32 v24, v24
	s_waitcnt vmcnt(7) lgkmcnt(0)
	s_barrier
	v_mfma_f32_16x16x32_bf16 v[66:69], v[184:187], v[168:171], v[66:69]
	ds_read_b128 v[136:139], v218 offset:0
	v_mfma_f32_16x16x32_bf16 v[70:73], v[188:191], v[168:171], v[70:73]
	ds_read_b128 v[140:143], v218 offset:2048
	v_mfma_f32_16x16x32_bf16 v[74:77], v[192:195], v[168:171], v[74:77]
	ds_read_b128 v[144:147], v218 offset:4096
	v_rcp_f32_e32 v25, v25
	v_mfma_f32_16x16x32_bf16 v[78:81], v[196:199], v[168:171], v[78:81]
	ds_read_b128 v[148:151], v218 offset:6144
	v_mfma_f32_16x16x32_bf16 v[82:85], v[184:187], v[172:175], v[82:85]
	ds_read_b128 v[152:155], v230 offset:0
	v_cvt_pk_bf16_f32 v18, v18, v19
	v_mfma_f32_16x16x32_bf16 v[86:89], v[188:191], v[172:175], v[86:89]
	ds_read_b128 v[156:159], v230 offset:2048
	v_mfma_f32_16x16x32_bf16 v[90:93], v[192:195], v[172:175], v[90:93]
	ds_read_b128 v[160:163], v230 offset:4096
	v_cvt_pk_bf16_f32 v19, v20, v21
	v_mfma_f32_16x16x32_bf16 v[94:97], v[196:199], v[172:175], v[94:97]
	ds_read_b128 v[164:167], v230 offset:6144
	s_add_u32 m0, s8, 0x18000
	v_mfma_f32_16x16x32_bf16 v[98:101], v[184:187], v[176:179], v[98:101]
	global_load_lds_dwordx4 v200, s[4:5]
	s_add_u32 m0, s8, 0x18400
	v_mfma_f32_16x16x32_bf16 v[102:105], v[188:191], v[176:179], v[102:105]
	global_load_lds_dwordx4 v201, s[4:5]
	v_cvt_pk_bf16_f32 v20, v22, v23
	s_add_u32 m0, s8, 0x18800
	v_mfma_f32_16x16x32_bf16 v[106:109], v[192:195], v[176:179], v[106:109]
	global_load_lds_dwordx4 v202, s[4:5]
	s_add_u32 m0, s8, 0x18c00
	v_mfma_f32_16x16x32_bf16 v[110:113], v[196:199], v[176:179], v[110:113]
	global_load_lds_dwordx4 v203, s[4:5]
	v_cvt_pk_bf16_f32 v21, v24, v25
	s_add_u32 m0, s9, 0x18000
	v_mfma_f32_16x16x32_bf16 v[114:117], v[184:187], v[180:183], v[114:117]
	global_load_lds_dwordx4 v204, s[6:7]
	s_add_u32 m0, s9, 0x18400
	v_mfma_f32_16x16x32_bf16 v[118:121], v[188:191], v[180:183], v[118:121]
	global_load_lds_dwordx4 v205, s[6:7]
	global_store_dwordx4 v240, v[18:21], s[10:11] offset:2048
	v_mfma_f32_16x16x32_bf16 v[122:125], v[192:195], v[180:183], v[122:125]
	s_add_u32 s4, s4, 0x80
	s_addc_u32 s5, s5, 0
	v_mfma_f32_16x16x32_bf16 v[126:129], v[196:199], v[180:183], v[126:129]
	s_add_u32 s6, s6, 0x80
	s_addc_u32 s7, s7, 0
	v_mul_f32_e32 v26, s12, v26
	s_waitcnt lgkmcnt(0)
	v_mfma_f32_16x16x32_bf16 v[66:69], v[152:155], v[136:139], v[66:69]
	ds_read_b128 v[168:171], v225 offset:0
	v_mfma_f32_16x16x32_bf16 v[70:73], v[156:159], v[136:139], v[70:73]
	ds_read_b128 v[172:175], v225 offset:2048
	v_mul_f32_e32 v27, s12, v27
	v_mfma_f32_16x16x32_bf16 v[74:77], v[160:163], v[136:139], v[74:77]
	ds_read_b128 v[176:179], v225 offset:4096
	v_mul_f32_e32 v28, s12, v28
	v_mfma_f32_16x16x32_bf16 v[78:81], v[164:167], v[136:139], v[78:81]
	ds_read_b128 v[180:183], v225 offset:6144
	v_mul_f32_e32 v29, s12, v29
	v_mfma_f32_16x16x32_bf16 v[82:85], v[152:155], v[140:143], v[82:85]
	ds_read_b128 v[184:187], v233 offset:0
	v_mfma_f32_16x16x32_bf16 v[86:89], v[156:159], v[140:143], v[86:89]
	ds_read_b128 v[188:191], v233 offset:2048
	v_mul_f32_e32 v30, s12, v30
	v_mfma_f32_16x16x32_bf16 v[90:93], v[160:163], v[140:143], v[90:93]
	ds_read_b128 v[192:195], v233 offset:4096
	v_mul_f32_e32 v31, s12, v31
	v_mfma_f32_16x16x32_bf16 v[94:97], v[164:167], v[140:143], v[94:97]
	ds_read_b128 v[196:199], v233 offset:6144
	v_mul_f32_e32 v32, s12, v32
	v_mfma_f32_16x16x32_bf16 v[98:101], v[152:155], v[144:147], v[98:101]
	v_mfma_f32_16x16x32_bf16 v[102:105], v[156:159], v[144:147], v[102:105]
	v_mul_f32_e32 v33, s12, v33
	v_mfma_f32_16x16x32_bf16 v[106:109], v[160:163], v[144:147], v[106:109]
	v_exp_f32_e32 v26, v26
	v_mfma_f32_16x16x32_bf16 v[110:113], v[164:167], v[144:147], v[110:113]
	v_exp_f32_e32 v27, v27
	v_mfma_f32_16x16x32_bf16 v[114:117], v[152:155], v[148:151], v[114:117]
	v_mfma_f32_16x16x32_bf16 v[118:121], v[156:159], v[148:151], v[118:121]
	v_exp_f32_e32 v28, v28
	v_mfma_f32_16x16x32_bf16 v[122:125], v[160:163], v[148:151], v[122:125]
	v_exp_f32_e32 v29, v29
	v_mfma_f32_16x16x32_bf16 v[126:129], v[164:167], v[148:151], v[126:129]
	v_exp_f32_e32 v30, v30
	s_waitcnt vmcnt(7) lgkmcnt(0)
	s_barrier
	v_mfma_f32_16x16x32_bf16 v[66:69], v[184:187], v[168:171], v[66:69]
	ds_read_b128 v[136:139], v219 offset:0
	v_mfma_f32_16x16x32_bf16 v[70:73], v[188:191], v[168:171], v[70:73]
	ds_read_b128 v[140:143], v219 offset:2048
	v_mfma_f32_16x16x32_bf16 v[74:77], v[192:195], v[168:171], v[74:77]
	ds_read_b128 v[144:147], v219 offset:4096
	v_exp_f32_e32 v31, v31
	v_mfma_f32_16x16x32_bf16 v[78:81], v[196:199], v[168:171], v[78:81]
	ds_read_b128 v[148:151], v219 offset:6144
	v_mfma_f32_16x16x32_bf16 v[82:85], v[184:187], v[172:175], v[82:85]
	ds_read_b128 v[152:155], v231 offset:0
	v_exp_f32_e32 v32, v32
	v_mfma_f32_16x16x32_bf16 v[86:89], v[188:191], v[172:175], v[86:89]
	ds_read_b128 v[156:159], v231 offset:2048
	v_mfma_f32_16x16x32_bf16 v[90:93], v[192:195], v[172:175], v[90:93]
	ds_read_b128 v[160:163], v231 offset:4096
	v_exp_f32_e32 v33, v33
	v_mfma_f32_16x16x32_bf16 v[94:97], v[196:199], v[172:175], v[94:97]
	ds_read_b128 v[164:167], v231 offset:6144
	s_mov_b32 m0, s8
	v_mfma_f32_16x16x32_bf16 v[98:101], v[184:187], v[176:179], v[98:101]
	global_load_lds_dwordx4 v200, s[4:5]
	s_add_u32 m0, s8, 0x400
	v_mfma_f32_16x16x32_bf16 v[102:105], v[188:191], v[176:179], v[102:105]
	global_load_lds_dwordx4 v201, s[4:5]
	v_add_f32_e32 v26, 1.0, v26
	s_add_u32 m0, s8, 0x800
	v_mfma_f32_16x16x32_bf16 v[106:109], v[192:195], v[176:179], v[106:109]
	global_load_lds_dwordx4 v202, s[4:5]
	s_add_u32 m0, s8, 0xc00
	v_mfma_f32_16x16x32_bf16 v[110:113], v[196:199], v[176:179], v[110:113]
	global_load_lds_dwordx4 v203, s[4:5]
	v_add_f32_e32 v27, 1.0, v27
	s_mov_b32 m0, s9
	v_mfma_f32_16x16x32_bf16 v[114:117], v[184:187], v[180:183], v[114:117]
	global_load_lds_dwordx4 v204, s[6:7]
	s_add_u32 m0, s9, 0x400
	v_mfma_f32_16x16x32_bf16 v[118:121], v[188:191], v[180:183], v[118:121]
	global_load_lds_dwordx4 v205, s[6:7]
	v_add_f32_e32 v28, 1.0, v28
	v_mfma_f32_16x16x32_bf16 v[122:125], v[192:195], v[180:183], v[122:125]
	s_add_u32 s4, s4, 0x80
	s_addc_u32 s5, s5, 0
	v_mfma_f32_16x16x32_bf16 v[126:129], v[196:199], v[180:183], v[126:129]
	s_add_u32 s6, s6, 0x80
	s_addc_u32 s7, s7, 0
	v_add_f32_e32 v29, 1.0, v29
	s_waitcnt lgkmcnt(0)
	v_mfma_f32_16x16x32_bf16 v[66:69], v[152:155], v[136:139], v[66:69]
	ds_read_b128 v[168:171], v228 offset:0
	v_mfma_f32_16x16x32_bf16 v[70:73], v[156:159], v[136:139], v[70:73]
	ds_read_b128 v[172:175], v228 offset:2048
	v_add_f32_e32 v30, 1.0, v30
	v_mfma_f32_16x16x32_bf16 v[74:77], v[160:163], v[136:139], v[74:77]
	ds_read_b128 v[176:179], v228 offset:4096
	v_add_f32_e32 v31, 1.0, v31
	v_mfma_f32_16x16x32_bf16 v[78:81], v[164:167], v[136:139], v[78:81]
	ds_read_b128 v[180:183], v228 offset:6144
	v_add_f32_e32 v32, 1.0, v32
	v_mfma_f32_16x16x32_bf16 v[82:85], v[152:155], v[140:143], v[82:85]
	ds_read_b128 v[184:187], v234 offset:0
	v_mfma_f32_16x16x32_bf16 v[86:89], v[156:159], v[140:143], v[86:89]
	ds_read_b128 v[188:191], v234 offset:2048
	v_add_f32_e32 v33, 1.0, v33
	v_mfma_f32_16x16x32_bf16 v[90:93], v[160:163], v[140:143], v[90:93]
	ds_read_b128 v[192:195], v234 offset:4096
	v_rcp_f32_e32 v26, v26
	v_mfma_f32_16x16x32_bf16 v[94:97], v[164:167], v[140:143], v[94:97]
	ds_read_b128 v[196:199], v234 offset:6144
	v_rcp_f32_e32 v27, v27
	v_mfma_f32_16x16x32_bf16 v[98:101], v[152:155], v[144:147], v[98:101]
	v_mfma_f32_16x16x32_bf16 v[102:105], v[156:159], v[144:147], v[102:105]
	v_rcp_f32_e32 v28, v28
	v_mfma_f32_16x16x32_bf16 v[106:109], v[160:163], v[144:147], v[106:109]
	v_rcp_f32_e32 v29, v29
	v_mfma_f32_16x16x32_bf16 v[110:113], v[164:167], v[144:147], v[110:113]
	v_rcp_f32_e32 v30, v30
	v_mfma_f32_16x16x32_bf16 v[114:117], v[152:155], v[148:151], v[114:117]
	v_mfma_f32_16x16x32_bf16 v[118:121], v[156:159], v[148:151], v[118:121]
	v_rcp_f32_e32 v31, v31
	v_mfma_f32_16x16x32_bf16 v[122:125], v[160:163], v[148:151], v[122:125]
	v_rcp_f32_e32 v32, v32
	v_mfma_f32_16x16x32_bf16 v[126:129], v[164:167], v[148:151], v[126:129]
	v_rcp_f32_e32 v33, v33
	s_waitcnt vmcnt(7) lgkmcnt(0)
	s_barrier
	v_mfma_f32_16x16x32_bf16 v[66:69], v[184:187], v[168:171], v[66:69]
	ds_read_b128 v[136:139], v224 offset:0
	v_mfma_f32_16x16x32_bf16 v[70:73], v[188:191], v[168:171], v[70:73]
	ds_read_b128 v[140:143], v224 offset:2048
	v_mfma_f32_16x16x32_bf16 v[74:77], v[192:195], v[168:171], v[74:77]
	ds_read_b128 v[144:147], v224 offset:4096
	v_cvt_pk_bf16_f32 v26, v26, v27
	v_mfma_f32_16x16x32_bf16 v[78:81], v[196:199], v[168:171], v[78:81]
	ds_read_b128 v[148:151], v224 offset:6144
	v_mfma_f32_16x16x32_bf16 v[82:85], v[184:187], v[172:175], v[82:85]
	ds_read_b128 v[152:155], v232 offset:0
	v_cvt_pk_bf16_f32 v27, v28, v29
	v_mfma_f32_16x16x32_bf16 v[86:89], v[188:191], v[172:175], v[86:89]
	ds_read_b128 v[156:159], v232 offset:2048
	v_mfma_f32_16x16x32_bf16 v[90:93], v[192:195], v[172:175], v[90:93]
	ds_read_b128 v[160:163], v232 offset:4096
	v_cvt_pk_bf16_f32 v28, v30, v31
	v_mfma_f32_16x16x32_bf16 v[94:97], v[196:199], v[172:175], v[94:97]
	ds_read_b128 v[164:167], v232 offset:6144
	s_add_u32 m0, s8, 0xc000
	v_mfma_f32_16x16x32_bf16 v[98:101], v[184:187], v[176:179], v[98:101]
	global_load_lds_dwordx4 v200, s[4:5]
	s_add_u32 m0, s8, 0xc400
	v_mfma_f32_16x16x32_bf16 v[102:105], v[188:191], v[176:179], v[102:105]
	global_load_lds_dwordx4 v201, s[4:5]
	v_cvt_pk_bf16_f32 v29, v32, v33
	s_add_u32 m0, s8, 0xc800
	v_mfma_f32_16x16x32_bf16 v[106:109], v[192:195], v[176:179], v[106:109]
	global_load_lds_dwordx4 v202, s[4:5]
	s_add_u32 m0, s8, 0xcc00
	v_mfma_f32_16x16x32_bf16 v[110:113], v[196:199], v[176:179], v[110:113]
	global_load_lds_dwordx4 v203, s[4:5]
	global_store_dwordx4 v240, v[26:29], s[10:11] offset:2064
	s_add_u32 m0, s9, 0xc000
	v_mfma_f32_16x16x32_bf16 v[114:117], v[184:187], v[180:183], v[114:117]
	global_load_lds_dwordx4 v204, s[6:7]
	s_add_u32 m0, s9, 0xc400
	v_mfma_f32_16x16x32_bf16 v[118:121], v[188:191], v[180:183], v[118:121]
	global_load_lds_dwordx4 v205, s[6:7]
	v_mul_f32_e32 v34, s12, v34
	v_mfma_f32_16x16x32_bf16 v[122:125], v[192:195], v[180:183], v[122:125]
	s_add_u32 s4, s4, 0x80
	s_addc_u32 s5, s5, 0
	v_mfma_f32_16x16x32_bf16 v[126:129], v[196:199], v[180:183], v[126:129]
	s_add_u32 s6, s6, 0x80
	s_addc_u32 s7, s7, 0
	v_mul_f32_e32 v35, s12, v35
	s_waitcnt lgkmcnt(0)
	v_mfma_f32_16x16x32_bf16 v[66:69], v[152:155], v[136:139], v[66:69]
	ds_read_b128 v[168:171], v229 offset:0
	v_mfma_f32_16x16x32_bf16 v[70:73], v[156:159], v[136:139], v[70:73]
	ds_read_b128 v[172:175], v229 offset:2048
	v_mul_f32_e32 v36, s12, v36
	v_mfma_f32_16x16x32_bf16 v[74:77], v[160:163], v[136:139], v[74:77]
	ds_read_b128 v[176:179], v229 offset:4096
	v_mul_f32_e32 v37, s12, v37
	v_mfma_f32_16x16x32_bf16 v[78:81], v[164:167], v[136:139], v[78:81]
	ds_read_b128 v[180:183], v229 offset:6144
	v_mul_f32_e32 v38, s12, v38
	v_mfma_f32_16x16x32_bf16 v[82:85], v[152:155], v[140:143], v[82:85]
	ds_read_b128 v[184:187], v235 offset:0
	v_mfma_f32_16x16x32_bf16 v[86:89], v[156:159], v[140:143], v[86:89]
	ds_read_b128 v[188:191], v235 offset:2048
	v_mul_f32_e32 v39, s12, v39
	v_mfma_f32_16x16x32_bf16 v[90:93], v[160:163], v[140:143], v[90:93]
	ds_read_b128 v[192:195], v235 offset:4096
	v_mul_f32_e32 v40, s12, v40
	v_mfma_f32_16x16x32_bf16 v[94:97], v[164:167], v[140:143], v[94:97]
	ds_read_b128 v[196:199], v235 offset:6144
	v_mul_f32_e32 v41, s12, v41
	v_mfma_f32_16x16x32_bf16 v[98:101], v[152:155], v[144:147], v[98:101]
	v_mfma_f32_16x16x32_bf16 v[102:105], v[156:159], v[144:147], v[102:105]
	v_exp_f32_e32 v34, v34
	v_mfma_f32_16x16x32_bf16 v[106:109], v[160:163], v[144:147], v[106:109]
	v_exp_f32_e32 v35, v35
	v_mfma_f32_16x16x32_bf16 v[110:113], v[164:167], v[144:147], v[110:113]
	v_exp_f32_e32 v36, v36
	v_mfma_f32_16x16x32_bf16 v[114:117], v[152:155], v[148:151], v[114:117]
	v_mfma_f32_16x16x32_bf16 v[118:121], v[156:159], v[148:151], v[118:121]
	v_exp_f32_e32 v37, v37
	v_mfma_f32_16x16x32_bf16 v[122:125], v[160:163], v[148:151], v[122:125]
	v_exp_f32_e32 v38, v38
	v_mfma_f32_16x16x32_bf16 v[126:129], v[164:167], v[148:151], v[126:129]
	v_exp_f32_e32 v39, v39
	s_waitcnt vmcnt(7) lgkmcnt(0)
	s_barrier
	v_mfma_f32_16x16x32_bf16 v[66:69], v[184:187], v[168:171], v[66:69]
	ds_read_b128 v[136:139], v218 offset:0
	v_mfma_f32_16x16x32_bf16 v[70:73], v[188:191], v[168:171], v[70:73]
	ds_read_b128 v[140:143], v218 offset:2048
	v_mfma_f32_16x16x32_bf16 v[74:77], v[192:195], v[168:171], v[74:77]
	ds_read_b128 v[144:147], v218 offset:4096
	v_exp_f32_e32 v40, v40
	v_mfma_f32_16x16x32_bf16 v[78:81], v[196:199], v[168:171], v[78:81]
	ds_read_b128 v[148:151], v218 offset:6144
	v_mfma_f32_16x16x32_bf16 v[82:85], v[184:187], v[172:175], v[82:85]
	ds_read_b128 v[152:155], v230 offset:0
	v_exp_f32_e32 v41, v41
	v_mfma_f32_16x16x32_bf16 v[86:89], v[188:191], v[172:175], v[86:89]
	ds_read_b128 v[156:159], v230 offset:2048
	v_mfma_f32_16x16x32_bf16 v[90:93], v[192:195], v[172:175], v[90:93]
	ds_read_b128 v[160:163], v230 offset:4096
	v_add_f32_e32 v34, 1.0, v34
	v_mfma_f32_16x16x32_bf16 v[94:97], v[196:199], v[172:175], v[94:97]
	ds_read_b128 v[164:167], v230 offset:6144
	s_add_u32 m0, s8, 0x18000
	v_mfma_f32_16x16x32_bf16 v[98:101], v[184:187], v[176:179], v[98:101]
	global_load_lds_dwordx4 v200, s[4:5]
	s_add_u32 m0, s8, 0x18400
	v_mfma_f32_16x16x32_bf16 v[102:105], v[188:191], v[176:179], v[102:105]
	global_load_lds_dwordx4 v201, s[4:5]
	v_add_f32_e32 v35, 1.0, v35
	s_add_u32 m0, s8, 0x18800
	v_mfma_f32_16x16x32_bf16 v[106:109], v[192:195], v[176:179], v[106:109]
	global_load_lds_dwordx4 v202, s[4:5]
	s_add_u32 m0, s8, 0x18c00
	v_mfma_f32_16x16x32_bf16 v[110:113], v[196:199], v[176:179], v[110:113]
	global_load_lds_dwordx4 v203, s[4:5]
	v_add_f32_e32 v36, 1.0, v36
	s_add_u32 m0, s9, 0x18000
	v_mfma_f32_16x16x32_bf16 v[114:117], v[184:187], v[180:183], v[114:117]
	global_load_lds_dwordx4 v204, s[6:7]
	s_add_u32 m0, s9, 0x18400
	v_mfma_f32_16x16x32_bf16 v[118:121], v[188:191], v[180:183], v[118:121]
	global_load_lds_dwordx4 v205, s[6:7]
	v_add_f32_e32 v37, 1.0, v37
	v_mfma_f32_16x16x32_bf16 v[122:125], v[192:195], v[180:183], v[122:125]
	s_add_u32 s4, s4, 0x80
	s_addc_u32 s5, s5, 0
	v_mfma_f32_16x16x32_bf16 v[126:129], v[196:199], v[180:183], v[126:129]
	s_add_u32 s6, s6, 0x80
	s_addc_u32 s7, s7, 0
	v_add_f32_e32 v38, 1.0, v38
	s_waitcnt lgkmcnt(0)
	v_mfma_f32_16x16x32_bf16 v[66:69], v[152:155], v[136:139], v[66:69]
	ds_read_b128 v[168:171], v225 offset:0
	v_mfma_f32_16x16x32_bf16 v[70:73], v[156:159], v[136:139], v[70:73]
	ds_read_b128 v[172:175], v225 offset:2048
	v_add_f32_e32 v39, 1.0, v39
	v_mfma_f32_16x16x32_bf16 v[74:77], v[160:163], v[136:139], v[74:77]
	ds_read_b128 v[176:179], v225 offset:4096
	v_add_f32_e32 v40, 1.0, v40
	v_mfma_f32_16x16x32_bf16 v[78:81], v[164:167], v[136:139], v[78:81]
	ds_read_b128 v[180:183], v225 offset:6144
	v_add_f32_e32 v41, 1.0, v41
	v_mfma_f32_16x16x32_bf16 v[82:85], v[152:155], v[140:143], v[82:85]
	ds_read_b128 v[184:187], v233 offset:0
	v_mfma_f32_16x16x32_bf16 v[86:89], v[156:159], v[140:143], v[86:89]
	ds_read_b128 v[188:191], v233 offset:2048
	v_rcp_f32_e32 v34, v34
	v_mfma_f32_16x16x32_bf16 v[90:93], v[160:163], v[140:143], v[90:93]
	ds_read_b128 v[192:195], v233 offset:4096
	v_rcp_f32_e32 v35, v35
	v_mfma_f32_16x16x32_bf16 v[94:97], v[164:167], v[140:143], v[94:97]
	ds_read_b128 v[196:199], v233 offset:6144
	v_rcp_f32_e32 v36, v36
	v_mfma_f32_16x16x32_bf16 v[98:101], v[152:155], v[144:147], v[98:101]
	v_mfma_f32_16x16x32_bf16 v[102:105], v[156:159], v[144:147], v[102:105]
	v_rcp_f32_e32 v37, v37
	v_mfma_f32_16x16x32_bf16 v[106:109], v[160:163], v[144:147], v[106:109]
	v_rcp_f32_e32 v38, v38
	v_mfma_f32_16x16x32_bf16 v[110:113], v[164:167], v[144:147], v[110:113]
	v_rcp_f32_e32 v39, v39
	v_mfma_f32_16x16x32_bf16 v[114:117], v[152:155], v[148:151], v[114:117]
	v_mfma_f32_16x16x32_bf16 v[118:121], v[156:159], v[148:151], v[118:121]
	v_rcp_f32_e32 v40, v40
	v_mfma_f32_16x16x32_bf16 v[122:125], v[160:163], v[148:151], v[122:125]
	v_rcp_f32_e32 v41, v41
	v_mfma_f32_16x16x32_bf16 v[126:129], v[164:167], v[148:151], v[126:129]
	v_cvt_pk_bf16_f32 v34, v34, v35
	s_waitcnt vmcnt(6) lgkmcnt(0)
	s_barrier
	v_mfma_f32_16x16x32_bf16 v[66:69], v[184:187], v[168:171], v[66:69]
	ds_read_b128 v[136:139], v219 offset:0
	v_mfma_f32_16x16x32_bf16 v[70:73], v[188:191], v[168:171], v[70:73]
	ds_read_b128 v[140:143], v219 offset:2048
	v_mfma_f32_16x16x32_bf16 v[74:77], v[192:195], v[168:171], v[74:77]
	ds_read_b128 v[144:147], v219 offset:4096
	v_cvt_pk_bf16_f32 v35, v36, v37
	v_mfma_f32_16x16x32_bf16 v[78:81], v[196:199], v[168:171], v[78:81]
	ds_read_b128 v[148:151], v219 offset:6144
	v_mfma_f32_16x16x32_bf16 v[82:85], v[184:187], v[172:175], v[82:85]
	ds_read_b128 v[152:155], v231 offset:0
	v_cvt_pk_bf16_f32 v36, v38, v39
	v_mfma_f32_16x16x32_bf16 v[86:89], v[188:191], v[172:175], v[86:89]
	ds_read_b128 v[156:159], v231 offset:2048
	v_mfma_f32_16x16x32_bf16 v[90:93], v[192:195], v[172:175], v[90:93]
	ds_read_b128 v[160:163], v231 offset:4096
	v_cvt_pk_bf16_f32 v37, v40, v41
	v_mfma_f32_16x16x32_bf16 v[94:97], v[196:199], v[172:175], v[94:97]
	ds_read_b128 v[164:167], v231 offset:6144
	s_mov_b32 m0, s8
	v_mfma_f32_16x16x32_bf16 v[98:101], v[184:187], v[176:179], v[98:101]
	global_load_lds_dwordx4 v200, s[4:5]
	s_add_u32 m0, s8, 0x400
	v_mfma_f32_16x16x32_bf16 v[102:105], v[188:191], v[176:179], v[102:105]
	global_load_lds_dwordx4 v201, s[4:5]
	global_store_dwordx4 v241, v[34:37], s[10:11] offset:0
	s_add_u32 m0, s8, 0x800
	v_mfma_f32_16x16x32_bf16 v[106:109], v[192:195], v[176:179], v[106:109]
	global_load_lds_dwordx4 v202, s[4:5]
	s_add_u32 m0, s8, 0xc00
	v_mfma_f32_16x16x32_bf16 v[110:113], v[196:199], v[176:179], v[110:113]
	global_load_lds_dwordx4 v203, s[4:5]
	v_mul_f32_e32 v42, s12, v42
	s_mov_b32 m0, s9
	v_mfma_f32_16x16x32_bf16 v[114:117], v[184:187], v[180:183], v[114:117]
	global_load_lds_dwordx4 v204, s[6:7]
	s_add_u32 m0, s9, 0x400
	v_mfma_f32_16x16x32_bf16 v[118:121], v[188:191], v[180:183], v[118:121]
	global_load_lds_dwordx4 v205, s[6:7]
	v_mul_f32_e32 v43, s12, v43
	v_mfma_f32_16x16x32_bf16 v[122:125], v[192:195], v[180:183], v[122:125]
	s_add_u32 s4, s4, 0x80
	s_addc_u32 s5, s5, 0
	v_mfma_f32_16x16x32_bf16 v[126:129], v[196:199], v[180:183], v[126:129]
	s_add_u32 s6, s6, 0x80
	s_addc_u32 s7, s7, 0
	v_mul_f32_e32 v44, s12, v44
	s_waitcnt lgkmcnt(0)
	v_mfma_f32_16x16x32_bf16 v[66:69], v[152:155], v[136:139], v[66:69]
	ds_read_b128 v[168:171], v228 offset:0
	v_mfma_f32_16x16x32_bf16 v[70:73], v[156:159], v[136:139], v[70:73]
	ds_read_b128 v[172:175], v228 offset:2048
	v_mul_f32_e32 v45, s12, v45
	v_mfma_f32_16x16x32_bf16 v[74:77], v[160:163], v[136:139], v[74:77]
	ds_read_b128 v[176:179], v228 offset:4096
	v_mul_f32_e32 v46, s12, v46
	v_mfma_f32_16x16x32_bf16 v[78:81], v[164:167], v[136:139], v[78:81]
	ds_read_b128 v[180:183], v228 offset:6144
	v_mul_f32_e32 v47, s12, v47
	v_mfma_f32_16x16x32_bf16 v[82:85], v[152:155], v[140:143], v[82:85]
	ds_read_b128 v[184:187], v234 offset:0
	v_mfma_f32_16x16x32_bf16 v[86:89], v[156:159], v[140:143], v[86:89]
	ds_read_b128 v[188:191], v234 offset:2048
	v_mul_f32_e32 v48, s12, v48
	v_mfma_f32_16x16x32_bf16 v[90:93], v[160:163], v[140:143], v[90:93]
	ds_read_b128 v[192:195], v234 offset:4096
	v_mul_f32_e32 v49, s12, v49
	v_mfma_f32_16x16x32_bf16 v[94:97], v[164:167], v[140:143], v[94:97]
	ds_read_b128 v[196:199], v234 offset:6144
	v_exp_f32_e32 v42, v42
	v_mfma_f32_16x16x32_bf16 v[98:101], v[152:155], v[144:147], v[98:101]
	v_mfma_f32_16x16x32_bf16 v[102:105], v[156:159], v[144:147], v[102:105]
	v_exp_f32_e32 v43, v43
	v_mfma_f32_16x16x32_bf16 v[106:109], v[160:163], v[144:147], v[106:109]
	v_exp_f32_e32 v44, v44
	v_mfma_f32_16x16x32_bf16 v[110:113], v[164:167], v[144:147], v[110:113]
	v_exp_f32_e32 v45, v45
	v_mfma_f32_16x16x32_bf16 v[114:117], v[152:155], v[148:151], v[114:117]
	v_mfma_f32_16x16x32_bf16 v[118:121], v[156:159], v[148:151], v[118:121]
	v_exp_f32_e32 v46, v46
	v_mfma_f32_16x16x32_bf16 v[122:125], v[160:163], v[148:151], v[122:125]
	v_exp_f32_e32 v47, v47
	v_mfma_f32_16x16x32_bf16 v[126:129], v[164:167], v[148:151], v[126:129]
	v_exp_f32_e32 v48, v48
	s_waitcnt vmcnt(7) lgkmcnt(0)
	s_barrier
	v_mfma_f32_16x16x32_bf16 v[66:69], v[184:187], v[168:171], v[66:69]
	ds_read_b128 v[136:139], v224 offset:0
	v_mfma_f32_16x16x32_bf16 v[70:73], v[188:191], v[168:171], v[70:73]
	ds_read_b128 v[140:143], v224 offset:2048
	v_mfma_f32_16x16x32_bf16 v[74:77], v[192:195], v[168:171], v[74:77]
	ds_read_b128 v[144:147], v224 offset:4096
	v_exp_f32_e32 v49, v49
	v_mfma_f32_16x16x32_bf16 v[78:81], v[196:199], v[168:171], v[78:81]
	ds_read_b128 v[148:151], v224 offset:6144
	v_mfma_f32_16x16x32_bf16 v[82:85], v[184:187], v[172:175], v[82:85]
	ds_read_b128 v[152:155], v232 offset:0
	v_add_f32_e32 v42, 1.0, v42
	v_mfma_f32_16x16x32_bf16 v[86:89], v[188:191], v[172:175], v[86:89]
	ds_read_b128 v[156:159], v232 offset:2048
	v_mfma_f32_16x16x32_bf16 v[90:93], v[192:195], v[172:175], v[90:93]
	ds_read_b128 v[160:163], v232 offset:4096
	v_add_f32_e32 v43, 1.0, v43
	v_mfma_f32_16x16x32_bf16 v[94:97], v[196:199], v[172:175], v[94:97]
	ds_read_b128 v[164:167], v232 offset:6144
	s_add_u32 m0, s8, 0xc000
	v_mfma_f32_16x16x32_bf16 v[98:101], v[184:187], v[176:179], v[98:101]
	global_load_lds_dwordx4 v200, s[4:5]
	s_add_u32 m0, s8, 0xc400
	v_mfma_f32_16x16x32_bf16 v[102:105], v[188:191], v[176:179], v[102:105]
	global_load_lds_dwordx4 v201, s[4:5]
	v_add_f32_e32 v44, 1.0, v44
	s_add_u32 m0, s8, 0xc800
	v_mfma_f32_16x16x32_bf16 v[106:109], v[192:195], v[176:179], v[106:109]
	global_load_lds_dwordx4 v202, s[4:5]
	s_add_u32 m0, s8, 0xcc00
	v_mfma_f32_16x16x32_bf16 v[110:113], v[196:199], v[176:179], v[110:113]
	global_load_lds_dwordx4 v203, s[4:5]
	v_add_f32_e32 v45, 1.0, v45
	s_add_u32 m0, s9, 0xc000
	v_mfma_f32_16x16x32_bf16 v[114:117], v[184:187], v[180:183], v[114:117]
	global_load_lds_dwordx4 v204, s[6:7]
	s_add_u32 m0, s9, 0xc400
	v_mfma_f32_16x16x32_bf16 v[118:121], v[188:191], v[180:183], v[118:121]
	global_load_lds_dwordx4 v205, s[6:7]
	v_add_f32_e32 v46, 1.0, v46
	v_mfma_f32_16x16x32_bf16 v[122:125], v[192:195], v[180:183], v[122:125]
	s_add_u32 s4, s4, 0x80
	s_addc_u32 s5, s5, 0
	v_mfma_f32_16x16x32_bf16 v[126:129], v[196:199], v[180:183], v[126:129]
	s_add_u32 s6, s6, 0x80
	s_addc_u32 s7, s7, 0
	v_add_f32_e32 v47, 1.0, v47
	s_waitcnt lgkmcnt(0)
	v_mfma_f32_16x16x32_bf16 v[66:69], v[152:155], v[136:139], v[66:69]
	ds_read_b128 v[168:171], v229 offset:0
	v_mfma_f32_16x16x32_bf16 v[70:73], v[156:159], v[136:139], v[70:73]
	ds_read_b128 v[172:175], v229 offset:2048
	v_add_f32_e32 v48, 1.0, v48
	v_mfma_f32_16x16x32_bf16 v[74:77], v[160:163], v[136:139], v[74:77]
	ds_read_b128 v[176:179], v229 offset:4096
	v_add_f32_e32 v49, 1.0, v49
	v_mfma_f32_16x16x32_bf16 v[78:81], v[164:167], v[136:139], v[78:81]
	ds_read_b128 v[180:183], v229 offset:6144
	v_rcp_f32_e32 v42, v42
	v_mfma_f32_16x16x32_bf16 v[82:85], v[152:155], v[140:143], v[82:85]
	ds_read_b128 v[184:187], v235 offset:0
	v_mfma_f32_16x16x32_bf16 v[86:89], v[156:159], v[140:143], v[86:89]
	ds_read_b128 v[188:191], v235 offset:2048
	v_rcp_f32_e32 v43, v43
	v_mfma_f32_16x16x32_bf16 v[90:93], v[160:163], v[140:143], v[90:93]
	ds_read_b128 v[192:195], v235 offset:4096
	v_rcp_f32_e32 v44, v44
	v_mfma_f32_16x16x32_bf16 v[94:97], v[164:167], v[140:143], v[94:97]
	ds_read_b128 v[196:199], v235 offset:6144
	v_rcp_f32_e32 v45, v45
	v_mfma_f32_16x16x32_bf16 v[98:101], v[152:155], v[144:147], v[98:101]
	v_mfma_f32_16x16x32_bf16 v[102:105], v[156:159], v[144:147], v[102:105]
	v_rcp_f32_e32 v46, v46
	v_mfma_f32_16x16x32_bf16 v[106:109], v[160:163], v[144:147], v[106:109]
	v_rcp_f32_e32 v47, v47
	v_mfma_f32_16x16x32_bf16 v[110:113], v[164:167], v[144:147], v[110:113]
	v_rcp_f32_e32 v48, v48
	v_mfma_f32_16x16x32_bf16 v[114:117], v[152:155], v[148:151], v[114:117]
	v_mfma_f32_16x16x32_bf16 v[118:121], v[156:159], v[148:151], v[118:121]
	v_rcp_f32_e32 v49, v49
	v_mfma_f32_16x16x32_bf16 v[122:125], v[160:163], v[148:151], v[122:125]
	v_cvt_pk_bf16_f32 v42, v42, v43
	v_mfma_f32_16x16x32_bf16 v[126:129], v[164:167], v[148:151], v[126:129]
	v_cvt_pk_bf16_f32 v43, v44, v45
	s_waitcnt vmcnt(6) lgkmcnt(0)
	s_barrier
	v_mfma_f32_16x16x32_bf16 v[66:69], v[184:187], v[168:171], v[66:69]
	ds_read_b128 v[136:139], v218 offset:0
	v_mfma_f32_16x16x32_bf16 v[70:73], v[188:191], v[168:171], v[70:73]
	ds_read_b128 v[140:143], v218 offset:2048
	v_mfma_f32_16x16x32_bf16 v[74:77], v[192:195], v[168:171], v[74:77]
	ds_read_b128 v[144:147], v218 offset:4096
	v_cvt_pk_bf16_f32 v44, v46, v47
	v_mfma_f32_16x16x32_bf16 v[78:81], v[196:199], v[168:171], v[78:81]
	ds_read_b128 v[148:151], v218 offset:6144
	v_mfma_f32_16x16x32_bf16 v[82:85], v[184:187], v[172:175], v[82:85]
	ds_read_b128 v[152:155], v230 offset:0
	v_cvt_pk_bf16_f32 v45, v48, v49
	v_mfma_f32_16x16x32_bf16 v[86:89], v[188:191], v[172:175], v[86:89]
	ds_read_b128 v[156:159], v230 offset:2048
	v_mfma_f32_16x16x32_bf16 v[90:93], v[192:195], v[172:175], v[90:93]
	ds_read_b128 v[160:163], v230 offset:4096
	global_store_dwordx4 v241, v[42:45], s[10:11] offset:16
	v_mfma_f32_16x16x32_bf16 v[94:97], v[196:199], v[172:175], v[94:97]
	ds_read_b128 v[164:167], v230 offset:6144
	s_add_u32 m0, s8, 0x18000
	v_mfma_f32_16x16x32_bf16 v[98:101], v[184:187], v[176:179], v[98:101]
	global_load_lds_dwordx4 v200, s[4:5]
	s_add_u32 m0, s8, 0x18400
	v_mfma_f32_16x16x32_bf16 v[102:105], v[188:191], v[176:179], v[102:105]
	global_load_lds_dwordx4 v201, s[4:5]
	v_mul_f32_e32 v50, s12, v50
	s_add_u32 m0, s8, 0x18800
	v_mfma_f32_16x16x32_bf16 v[106:109], v[192:195], v[176:179], v[106:109]
	global_load_lds_dwordx4 v202, s[4:5]
	s_add_u32 m0, s8, 0x18c00
	v_mfma_f32_16x16x32_bf16 v[110:113], v[196:199], v[176:179], v[110:113]
	global_load_lds_dwordx4 v203, s[4:5]
	v_mul_f32_e32 v51, s12, v51
	s_add_u32 m0, s9, 0x18000
	v_mfma_f32_16x16x32_bf16 v[114:117], v[184:187], v[180:183], v[114:117]
	global_load_lds_dwordx4 v204, s[6:7]
	s_add_u32 m0, s9, 0x18400
	v_mfma_f32_16x16x32_bf16 v[118:121], v[188:191], v[180:183], v[118:121]
	global_load_lds_dwordx4 v205, s[6:7]
	v_mul_f32_e32 v52, s12, v52
	v_mfma_f32_16x16x32_bf16 v[122:125], v[192:195], v[180:183], v[122:125]
	s_add_u32 s4, s4, 0x80
	s_addc_u32 s5, s5, 0
	v_mfma_f32_16x16x32_bf16 v[126:129], v[196:199], v[180:183], v[126:129]
	s_add_u32 s6, s6, 0x80
	s_addc_u32 s7, s7, 0
	v_mul_f32_e32 v53, s12, v53
	s_waitcnt lgkmcnt(0)
	v_mfma_f32_16x16x32_bf16 v[66:69], v[152:155], v[136:139], v[66:69]
	ds_read_b128 v[168:171], v225 offset:0
	v_mfma_f32_16x16x32_bf16 v[70:73], v[156:159], v[136:139], v[70:73]
	ds_read_b128 v[172:175], v225 offset:2048
	v_mul_f32_e32 v54, s12, v54
	v_mfma_f32_16x16x32_bf16 v[74:77], v[160:163], v[136:139], v[74:77]
	ds_read_b128 v[176:179], v225 offset:4096
	v_mul_f32_e32 v55, s12, v55
	v_mfma_f32_16x16x32_bf16 v[78:81], v[164:167], v[136:139], v[78:81]
	ds_read_b128 v[180:183], v225 offset:6144
	v_mul_f32_e32 v56, s12, v56
	v_mfma_f32_16x16x32_bf16 v[82:85], v[152:155], v[140:143], v[82:85]
	ds_read_b128 v[184:187], v233 offset:0
	v_mfma_f32_16x16x32_bf16 v[86:89], v[156:159], v[140:143], v[86:89]
	ds_read_b128 v[188:191], v233 offset:2048
	v_mul_f32_e32 v57, s12, v57
	v_mfma_f32_16x16x32_bf16 v[90:93], v[160:163], v[140:143], v[90:93]
	ds_read_b128 v[192:195], v233 offset:4096
	v_exp_f32_e32 v50, v50
	v_mfma_f32_16x16x32_bf16 v[94:97], v[164:167], v[140:143], v[94:97]
	ds_read_b128 v[196:199], v233 offset:6144
	v_exp_f32_e32 v51, v51
	v_mfma_f32_16x16x32_bf16 v[98:101], v[152:155], v[144:147], v[98:101]
	v_mfma_f32_16x16x32_bf16 v[102:105], v[156:159], v[144:147], v[102:105]
	v_exp_f32_e32 v52, v52
	v_mfma_f32_16x16x32_bf16 v[106:109], v[160:163], v[144:147], v[106:109]
	v_exp_f32_e32 v53, v53
	v_mfma_f32_16x16x32_bf16 v[110:113], v[164:167], v[144:147], v[110:113]
	v_exp_f32_e32 v54, v54
	v_mfma_f32_16x16x32_bf16 v[114:117], v[152:155], v[148:151], v[114:117]
	v_mfma_f32_16x16x32_bf16 v[118:121], v[156:159], v[148:151], v[118:121]
	v_exp_f32_e32 v55, v55
	v_mfma_f32_16x16x32_bf16 v[122:125], v[160:163], v[148:151], v[122:125]
	v_exp_f32_e32 v56, v56
	v_mfma_f32_16x16x32_bf16 v[126:129], v[164:167], v[148:151], v[126:129]
	v_exp_f32_e32 v57, v57
	s_waitcnt vmcnt(7) lgkmcnt(0)
	s_barrier
	v_mfma_f32_16x16x32_bf16 v[66:69], v[184:187], v[168:171], v[66:69]
	ds_read_b128 v[136:139], v219 offset:0
	v_mfma_f32_16x16x32_bf16 v[70:73], v[188:191], v[168:171], v[70:73]
	ds_read_b128 v[140:143], v219 offset:2048
	v_mfma_f32_16x16x32_bf16 v[74:77], v[192:195], v[168:171], v[74:77]
	ds_read_b128 v[144:147], v219 offset:4096
	v_add_f32_e32 v50, 1.0, v50
	v_mfma_f32_16x16x32_bf16 v[78:81], v[196:199], v[168:171], v[78:81]
	ds_read_b128 v[148:151], v219 offset:6144
	v_mfma_f32_16x16x32_bf16 v[82:85], v[184:187], v[172:175], v[82:85]
	ds_read_b128 v[152:155], v231 offset:0
	v_add_f32_e32 v51, 1.0, v51
	v_mfma_f32_16x16x32_bf16 v[86:89], v[188:191], v[172:175], v[86:89]
	ds_read_b128 v[156:159], v231 offset:2048
	v_mfma_f32_16x16x32_bf16 v[90:93], v[192:195], v[172:175], v[90:93]
	ds_read_b128 v[160:163], v231 offset:4096
	v_add_f32_e32 v52, 1.0, v52
	v_mfma_f32_16x16x32_bf16 v[94:97], v[196:199], v[172:175], v[94:97]
	ds_read_b128 v[164:167], v231 offset:6144
	s_mov_b32 m0, s8
	v_mfma_f32_16x16x32_bf16 v[98:101], v[184:187], v[176:179], v[98:101]
	global_load_lds_dwordx4 v200, s[4:5]
	s_add_u32 m0, s8, 0x400
	v_mfma_f32_16x16x32_bf16 v[102:105], v[188:191], v[176:179], v[102:105]
	global_load_lds_dwordx4 v201, s[4:5]
	v_add_f32_e32 v53, 1.0, v53
	s_add_u32 m0, s8, 0x800
	v_mfma_f32_16x16x32_bf16 v[106:109], v[192:195], v[176:179], v[106:109]
	global_load_lds_dwordx4 v202, s[4:5]
	s_add_u32 m0, s8, 0xc00
	v_mfma_f32_16x16x32_bf16 v[110:113], v[196:199], v[176:179], v[110:113]
	global_load_lds_dwordx4 v203, s[4:5]
	v_add_f32_e32 v54, 1.0, v54
	s_mov_b32 m0, s9
	v_mfma_f32_16x16x32_bf16 v[114:117], v[184:187], v[180:183], v[114:117]
	global_load_lds_dwordx4 v204, s[6:7]
	s_add_u32 m0, s9, 0x400
	v_mfma_f32_16x16x32_bf16 v[118:121], v[188:191], v[180:183], v[118:121]
	global_load_lds_dwordx4 v205, s[6:7]
	v_add_f32_e32 v55, 1.0, v55
	v_mfma_f32_16x16x32_bf16 v[122:125], v[192:195], v[180:183], v[122:125]
	s_sub_u32 s4, s4, 0x780
	s_subb_u32 s5, s5, 0
	v_mfma_f32_16x16x32_bf16 v[126:129], v[196:199], v[180:183], v[126:129]
	s_add_u32 s6, s6, 0x3f880
	s_addc_u32 s7, s7, 0
	v_add_f32_e32 v56, 1.0, v56
	s_waitcnt lgkmcnt(0)
	v_mfma_f32_16x16x32_bf16 v[66:69], v[152:155], v[136:139], v[66:69]
	ds_read_b128 v[168:171], v228 offset:0
	v_mfma_f32_16x16x32_bf16 v[70:73], v[156:159], v[136:139], v[70:73]
	ds_read_b128 v[172:175], v228 offset:2048
	v_add_f32_e32 v57, 1.0, v57
	v_mfma_f32_16x16x32_bf16 v[74:77], v[160:163], v[136:139], v[74:77]
	ds_read_b128 v[176:179], v228 offset:4096
	v_rcp_f32_e32 v50, v50
	v_mfma_f32_16x16x32_bf16 v[78:81], v[164:167], v[136:139], v[78:81]
	ds_read_b128 v[180:183], v228 offset:6144
	v_rcp_f32_e32 v51, v51
	v_mfma_f32_16x16x32_bf16 v[82:85], v[152:155], v[140:143], v[82:85]
	ds_read_b128 v[184:187], v234 offset:0
	v_mfma_f32_16x16x32_bf16 v[86:89], v[156:159], v[140:143], v[86:89]
	ds_read_b128 v[188:191], v234 offset:2048
	v_rcp_f32_e32 v52, v52
	v_mfma_f32_16x16x32_bf16 v[90:93], v[160:163], v[140:143], v[90:93]
	ds_read_b128 v[192:195], v234 offset:4096
	v_rcp_f32_e32 v53, v53
	v_mfma_f32_16x16x32_bf16 v[94:97], v[164:167], v[140:143], v[94:97]
	ds_read_b128 v[196:199], v234 offset:6144
	v_rcp_f32_e32 v54, v54
	v_mfma_f32_16x16x32_bf16 v[98:101], v[152:155], v[144:147], v[98:101]
	v_mfma_f32_16x16x32_bf16 v[102:105], v[156:159], v[144:147], v[102:105]
	v_rcp_f32_e32 v55, v55
	v_mfma_f32_16x16x32_bf16 v[106:109], v[160:163], v[144:147], v[106:109]
	v_rcp_f32_e32 v56, v56
	v_mfma_f32_16x16x32_bf16 v[110:113], v[164:167], v[144:147], v[110:113]
	v_rcp_f32_e32 v57, v57
	v_mfma_f32_16x16x32_bf16 v[114:117], v[152:155], v[148:151], v[114:117]
	v_mfma_f32_16x16x32_bf16 v[118:121], v[156:159], v[148:151], v[118:121]
	v_cvt_pk_bf16_f32 v50, v50, v51
	v_mfma_f32_16x16x32_bf16 v[122:125], v[160:163], v[148:151], v[122:125]
	v_cvt_pk_bf16_f32 v51, v52, v53
	v_mfma_f32_16x16x32_bf16 v[126:129], v[164:167], v[148:151], v[126:129]
	v_cvt_pk_bf16_f32 v52, v54, v55
	s_waitcnt vmcnt(6) lgkmcnt(0)
	s_barrier
	v_mfma_f32_16x16x32_bf16 v[66:69], v[184:187], v[168:171], v[66:69]
	ds_read_b128 v[136:139], v224 offset:0
	v_mfma_f32_16x16x32_bf16 v[70:73], v[188:191], v[168:171], v[70:73]
	ds_read_b128 v[140:143], v224 offset:2048
	v_mfma_f32_16x16x32_bf16 v[74:77], v[192:195], v[168:171], v[74:77]
	ds_read_b128 v[144:147], v224 offset:4096
	v_cvt_pk_bf16_f32 v53, v56, v57
	v_mfma_f32_16x16x32_bf16 v[78:81], v[196:199], v[168:171], v[78:81]
	ds_read_b128 v[148:151], v224 offset:6144
	v_mfma_f32_16x16x32_bf16 v[82:85], v[184:187], v[172:175], v[82:85]
	ds_read_b128 v[152:155], v232 offset:0
	global_store_dwordx4 v241, v[50:53], s[10:11] offset:2048
	v_mfma_f32_16x16x32_bf16 v[86:89], v[188:191], v[172:175], v[86:89]
	ds_read_b128 v[156:159], v232 offset:2048
	v_mfma_f32_16x16x32_bf16 v[90:93], v[192:195], v[172:175], v[90:93]
	ds_read_b128 v[160:163], v232 offset:4096
	v_mul_f32_e32 v58, s12, v58
	v_mfma_f32_16x16x32_bf16 v[94:97], v[196:199], v[172:175], v[94:97]
	ds_read_b128 v[164:167], v232 offset:6144
	v_mfma_f32_16x16x32_bf16 v[98:101], v[184:187], v[176:179], v[98:101]
	v_mfma_f32_16x16x32_bf16 v[102:105], v[188:191], v[176:179], v[102:105]
	v_mul_f32_e32 v59, s12, v59
	v_mfma_f32_16x16x32_bf16 v[106:109], v[192:195], v[176:179], v[106:109]
	v_mfma_f32_16x16x32_bf16 v[110:113], v[196:199], v[176:179], v[110:113]
	v_mul_f32_e32 v60, s12, v60
	v_mfma_f32_16x16x32_bf16 v[114:117], v[184:187], v[180:183], v[114:117]
	v_mfma_f32_16x16x32_bf16 v[118:121], v[188:191], v[180:183], v[118:121]
	v_mul_f32_e32 v61, s12, v61
	v_mfma_f32_16x16x32_bf16 v[122:125], v[192:195], v[180:183], v[122:125]
	v_mfma_f32_16x16x32_bf16 v[126:129], v[196:199], v[180:183], v[126:129]
	v_mul_f32_e32 v62, s12, v62
	s_waitcnt lgkmcnt(0)
	v_mfma_f32_16x16x32_bf16 v[66:69], v[152:155], v[136:139], v[66:69]
	ds_read_b128 v[168:171], v229 offset:0
	v_mfma_f32_16x16x32_bf16 v[70:73], v[156:159], v[136:139], v[70:73]
	ds_read_b128 v[172:175], v229 offset:2048
	v_mul_f32_e32 v63, s12, v63
	v_mfma_f32_16x16x32_bf16 v[74:77], v[160:163], v[136:139], v[74:77]
	ds_read_b128 v[176:179], v229 offset:4096
	v_mul_f32_e32 v64, s12, v64
	v_mfma_f32_16x16x32_bf16 v[78:81], v[164:167], v[136:139], v[78:81]
	ds_read_b128 v[180:183], v229 offset:6144
	v_mul_f32_e32 v65, s12, v65
	v_mfma_f32_16x16x32_bf16 v[82:85], v[152:155], v[140:143], v[82:85]
	ds_read_b128 v[184:187], v235 offset:0
	v_mfma_f32_16x16x32_bf16 v[86:89], v[156:159], v[140:143], v[86:89]
	ds_read_b128 v[188:191], v235 offset:2048
	v_exp_f32_e32 v58, v58
	v_mfma_f32_16x16x32_bf16 v[90:93], v[160:163], v[140:143], v[90:93]
	ds_read_b128 v[192:195], v235 offset:4096
	v_exp_f32_e32 v59, v59
	v_mfma_f32_16x16x32_bf16 v[94:97], v[164:167], v[140:143], v[94:97]
	ds_read_b128 v[196:199], v235 offset:6144
	v_exp_f32_e32 v60, v60
	v_mfma_f32_16x16x32_bf16 v[98:101], v[152:155], v[144:147], v[98:101]
	v_mfma_f32_16x16x32_bf16 v[102:105], v[156:159], v[144:147], v[102:105]
	v_exp_f32_e32 v61, v61
	v_mfma_f32_16x16x32_bf16 v[106:109], v[160:163], v[144:147], v[106:109]
	v_exp_f32_e32 v62, v62
	v_mfma_f32_16x16x32_bf16 v[110:113], v[164:167], v[144:147], v[110:113]
	v_exp_f32_e32 v63, v63
	v_mfma_f32_16x16x32_bf16 v[114:117], v[152:155], v[148:151], v[114:117]
	v_mfma_f32_16x16x32_bf16 v[118:121], v[156:159], v[148:151], v[118:121]
	v_exp_f32_e32 v64, v64
	v_mfma_f32_16x16x32_bf16 v[122:125], v[160:163], v[148:151], v[122:125]
	v_exp_f32_e32 v65, v65
	v_mfma_f32_16x16x32_bf16 v[126:129], v[164:167], v[148:151], v[126:129]
	v_add_f32_e32 v58, 1.0, v58
	s_waitcnt vmcnt(1) lgkmcnt(0)
	s_barrier
	v_mfma_f32_16x16x32_bf16 v[66:69], v[184:187], v[168:171], v[66:69]
	ds_read_b128 v[136:139], v218 offset:0
	v_mfma_f32_16x16x32_bf16 v[70:73], v[188:191], v[168:171], v[70:73]
	ds_read_b128 v[140:143], v218 offset:2048
	v_mfma_f32_16x16x32_bf16 v[74:77], v[192:195], v[168:171], v[74:77]
	ds_read_b128 v[144:147], v218 offset:4096
	v_add_f32_e32 v59, 1.0, v59
	v_mfma_f32_16x16x32_bf16 v[78:81], v[196:199], v[168:171], v[78:81]
	ds_read_b128 v[148:151], v218 offset:6144
	v_mfma_f32_16x16x32_bf16 v[82:85], v[184:187], v[172:175], v[82:85]
	ds_read_b128 v[152:155], v230 offset:0
	v_add_f32_e32 v60, 1.0, v60
	v_mfma_f32_16x16x32_bf16 v[86:89], v[188:191], v[172:175], v[86:89]
	ds_read_b128 v[156:159], v230 offset:2048
	v_mfma_f32_16x16x32_bf16 v[90:93], v[192:195], v[172:175], v[90:93]
	ds_read_b128 v[160:163], v230 offset:4096
	v_add_f32_e32 v61, 1.0, v61
	v_mfma_f32_16x16x32_bf16 v[94:97], v[196:199], v[172:175], v[94:97]
	ds_read_b128 v[164:167], v230 offset:6144
	v_mfma_f32_16x16x32_bf16 v[98:101], v[184:187], v[176:179], v[98:101]
	v_mfma_f32_16x16x32_bf16 v[102:105], v[188:191], v[176:179], v[102:105]
	v_add_f32_e32 v62, 1.0, v62
	v_mfma_f32_16x16x32_bf16 v[106:109], v[192:195], v[176:179], v[106:109]
	v_mfma_f32_16x16x32_bf16 v[110:113], v[196:199], v[176:179], v[110:113]
	v_add_f32_e32 v63, 1.0, v63
	v_mfma_f32_16x16x32_bf16 v[114:117], v[184:187], v[180:183], v[114:117]
	v_mfma_f32_16x16x32_bf16 v[118:121], v[188:191], v[180:183], v[118:121]
	v_add_f32_e32 v64, 1.0, v64
	v_mfma_f32_16x16x32_bf16 v[122:125], v[192:195], v[180:183], v[122:125]
	v_mfma_f32_16x16x32_bf16 v[126:129], v[196:199], v[180:183], v[126:129]
	v_add_f32_e32 v65, 1.0, v65
	s_waitcnt lgkmcnt(0)
	v_mfma_f32_16x16x32_bf16 v[66:69], v[152:155], v[136:139], v[66:69]
	ds_read_b128 v[168:171], v225 offset:0
	v_mfma_f32_16x16x32_bf16 v[70:73], v[156:159], v[136:139], v[70:73]
	ds_read_b128 v[172:175], v225 offset:2048
	v_rcp_f32_e32 v58, v58
	v_mfma_f32_16x16x32_bf16 v[74:77], v[160:163], v[136:139], v[74:77]
	ds_read_b128 v[176:179], v225 offset:4096
	v_rcp_f32_e32 v59, v59
	v_mfma_f32_16x16x32_bf16 v[78:81], v[164:167], v[136:139], v[78:81]
	ds_read_b128 v[180:183], v225 offset:6144
	v_rcp_f32_e32 v60, v60
	v_mfma_f32_16x16x32_bf16 v[82:85], v[152:155], v[140:143], v[82:85]
	ds_read_b128 v[184:187], v233 offset:0
	v_mfma_f32_16x16x32_bf16 v[86:89], v[156:159], v[140:143], v[86:89]
	ds_read_b128 v[188:191], v233 offset:2048
	v_rcp_f32_e32 v61, v61
	v_mfma_f32_16x16x32_bf16 v[90:93], v[160:163], v[140:143], v[90:93]
	ds_read_b128 v[192:195], v233 offset:4096
	v_rcp_f32_e32 v62, v62
	v_mfma_f32_16x16x32_bf16 v[94:97], v[164:167], v[140:143], v[94:97]
	ds_read_b128 v[196:199], v233 offset:6144
	v_rcp_f32_e32 v63, v63
	v_mfma_f32_16x16x32_bf16 v[98:101], v[152:155], v[144:147], v[98:101]
	v_mfma_f32_16x16x32_bf16 v[102:105], v[156:159], v[144:147], v[102:105]
	v_rcp_f32_e32 v64, v64
	v_mfma_f32_16x16x32_bf16 v[106:109], v[160:163], v[144:147], v[106:109]
	v_rcp_f32_e32 v65, v65
	v_mfma_f32_16x16x32_bf16 v[110:113], v[164:167], v[144:147], v[110:113]
	v_cvt_pk_bf16_f32 v58, v58, v59
	v_mfma_f32_16x16x32_bf16 v[114:117], v[152:155], v[148:151], v[114:117]
	v_mfma_f32_16x16x32_bf16 v[118:121], v[156:159], v[148:151], v[118:121]
	v_cvt_pk_bf16_f32 v59, v60, v61
	v_mfma_f32_16x16x32_bf16 v[122:125], v[160:163], v[148:151], v[122:125]
	v_cvt_pk_bf16_f32 v60, v62, v63
	v_mfma_f32_16x16x32_bf16 v[126:129], v[164:167], v[148:151], v[126:129]
	v_cvt_pk_bf16_f32 v61, v64, v65
	s_waitcnt lgkmcnt(0)
	v_mfma_f32_16x16x32_bf16 v[66:69], v[184:187], v[168:171], v[66:69]
	v_mfma_f32_16x16x32_bf16 v[70:73], v[188:191], v[168:171], v[70:73]
	v_mfma_f32_16x16x32_bf16 v[74:77], v[192:195], v[168:171], v[74:77]
	v_mfma_f32_16x16x32_bf16 v[78:81], v[196:199], v[168:171], v[78:81]
	v_mfma_f32_16x16x32_bf16 v[82:85], v[184:187], v[172:175], v[82:85]
	v_mfma_f32_16x16x32_bf16 v[86:89], v[188:191], v[172:175], v[86:89]
	v_mfma_f32_16x16x32_bf16 v[90:93], v[192:195], v[172:175], v[90:93]
	v_mfma_f32_16x16x32_bf16 v[94:97], v[196:199], v[172:175], v[94:97]
	v_mfma_f32_16x16x32_bf16 v[98:101], v[184:187], v[176:179], v[98:101]
	v_mfma_f32_16x16x32_bf16 v[102:105], v[188:191], v[176:179], v[102:105]
	v_mfma_f32_16x16x32_bf16 v[106:109], v[192:195], v[176:179], v[106:109]
	v_mfma_f32_16x16x32_bf16 v[110:113], v[196:199], v[176:179], v[110:113]
	v_mfma_f32_16x16x32_bf16 v[114:117], v[184:187], v[180:183], v[114:117]
	v_mfma_f32_16x16x32_bf16 v[118:121], v[188:191], v[180:183], v[118:121]
	v_mfma_f32_16x16x32_bf16 v[122:125], v[192:195], v[180:183], v[122:125]
	v_mfma_f32_16x16x32_bf16 v[126:129], v[196:199], v[180:183], v[126:129]
	global_store_dwordx4 v241, v[58:61], s[10:11] offset:2064
	s_add_u32 s10, s28, s13
	s_addc_u32 s11, s29, 0
	s_add_u32 s13, s13, 0x10000
	v_mul_f32_e32 v66, s12, v66
	v_mul_f32_e32 v67, s12, v67
	v_mul_f32_e32 v68, s12, v68
	v_mul_f32_e32 v69, s12, v69
	v_mul_f32_e32 v70, s12, v70
	v_mul_f32_e32 v71, s12, v71
	v_mul_f32_e32 v72, s12, v72
	v_mul_f32_e32 v73, s12, v73
	v_exp_f32_e32 v66, v66
	v_exp_f32_e32 v67, v67
	v_exp_f32_e32 v68, v68
	v_exp_f32_e32 v69, v69
	v_exp_f32_e32 v70, v70
	v_exp_f32_e32 v71, v71
	v_exp_f32_e32 v72, v72
	v_exp_f32_e32 v73, v73
	v_add_f32_e32 v66, 1.0, v66
	v_add_f32_e32 v67, 1.0, v67
	v_add_f32_e32 v68, 1.0, v68
	v_add_f32_e32 v69, 1.0, v69
	v_add_f32_e32 v70, 1.0, v70
	v_add_f32_e32 v71, 1.0, v71
	v_add_f32_e32 v72, 1.0, v72
	v_add_f32_e32 v73, 1.0, v73
	v_rcp_f32_e32 v66, v66
	v_rcp_f32_e32 v67, v67
	v_rcp_f32_e32 v68, v68
	v_rcp_f32_e32 v69, v69
	v_rcp_f32_e32 v70, v70
	v_rcp_f32_e32 v71, v71
	v_rcp_f32_e32 v72, v72
	v_rcp_f32_e32 v73, v73
	v_cvt_pk_bf16_f32 v66, v66, v67
	v_cvt_pk_bf16_f32 v67, v68, v69
	v_cvt_pk_bf16_f32 v68, v70, v71
	v_cvt_pk_bf16_f32 v69, v72, v73
	global_store_dwordx4 v240, v[66:69], s[10:11] offset:0
	v_mul_f32_e32 v74, s12, v74
	v_mul_f32_e32 v75, s12, v75
	v_mul_f32_e32 v76, s12, v76
	v_mul_f32_e32 v77, s12, v77
	v_mul_f32_e32 v78, s12, v78
	v_mul_f32_e32 v79, s12, v79
	v_mul_f32_e32 v80, s12, v80
	v_mul_f32_e32 v81, s12, v81
	v_exp_f32_e32 v74, v74
	v_exp_f32_e32 v75, v75
	v_exp_f32_e32 v76, v76
	v_exp_f32_e32 v77, v77
	v_exp_f32_e32 v78, v78
	v_exp_f32_e32 v79, v79
	v_exp_f32_e32 v80, v80
	v_exp_f32_e32 v81, v81
	v_add_f32_e32 v74, 1.0, v74
	v_add_f32_e32 v75, 1.0, v75
	v_add_f32_e32 v76, 1.0, v76
	v_add_f32_e32 v77, 1.0, v77
	v_add_f32_e32 v78, 1.0, v78
	v_add_f32_e32 v79, 1.0, v79
	v_add_f32_e32 v80, 1.0, v80
	v_add_f32_e32 v81, 1.0, v81
	v_rcp_f32_e32 v74, v74
	v_rcp_f32_e32 v75, v75
	v_rcp_f32_e32 v76, v76
	v_rcp_f32_e32 v77, v77
	v_rcp_f32_e32 v78, v78
	v_rcp_f32_e32 v79, v79
	v_rcp_f32_e32 v80, v80
	v_rcp_f32_e32 v81, v81
	v_cvt_pk_bf16_f32 v74, v74, v75
	v_cvt_pk_bf16_f32 v75, v76, v77
	v_cvt_pk_bf16_f32 v76, v78, v79
	v_cvt_pk_bf16_f32 v77, v80, v81
	global_store_dwordx4 v240, v[74:77], s[10:11] offset:16
	v_mul_f32_e32 v82, s12, v82
	v_mul_f32_e32 v83, s12, v83
	v_mul_f32_e32 v84, s12, v84
	v_mul_f32_e32 v85, s12, v85
	v_mul_f32_e32 v86, s12, v86
	v_mul_f32_e32 v87, s12, v87
	v_mul_f32_e32 v88, s12, v88
	v_mul_f32_e32 v89, s12, v89
	v_exp_f32_e32 v82, v82
	v_exp_f32_e32 v83, v83
	v_exp_f32_e32 v84, v84
	v_exp_f32_e32 v85, v85
	v_exp_f32_e32 v86, v86
	v_exp_f32_e32 v87, v87
	v_exp_f32_e32 v88, v88
	v_exp_f32_e32 v89, v89
	v_add_f32_e32 v82, 1.0, v82
	v_add_f32_e32 v83, 1.0, v83
	v_add_f32_e32 v84, 1.0, v84
	v_add_f32_e32 v85, 1.0, v85
	v_add_f32_e32 v86, 1.0, v86
	v_add_f32_e32 v87, 1.0, v87
	v_add_f32_e32 v88, 1.0, v88
	v_add_f32_e32 v89, 1.0, v89
	v_rcp_f32_e32 v82, v82
	v_rcp_f32_e32 v83, v83
	v_rcp_f32_e32 v84, v84
	v_rcp_f32_e32 v85, v85
	v_rcp_f32_e32 v86, v86
	v_rcp_f32_e32 v87, v87
	v_rcp_f32_e32 v88, v88
	v_rcp_f32_e32 v89, v89
	v_cvt_pk_bf16_f32 v82, v82, v83
	v_cvt_pk_bf16_f32 v83, v84, v85
	v_cvt_pk_bf16_f32 v84, v86, v87
	v_cvt_pk_bf16_f32 v85, v88, v89
	global_store_dwordx4 v240, v[82:85], s[10:11] offset:2048
	v_mul_f32_e32 v90, s12, v90
	v_mul_f32_e32 v91, s12, v91
	v_mul_f32_e32 v92, s12, v92
	v_mul_f32_e32 v93, s12, v93
	v_mul_f32_e32 v94, s12, v94
	v_mul_f32_e32 v95, s12, v95
	v_mul_f32_e32 v96, s12, v96
	v_mul_f32_e32 v97, s12, v97
	v_exp_f32_e32 v90, v90
	v_exp_f32_e32 v91, v91
	v_exp_f32_e32 v92, v92
	v_exp_f32_e32 v93, v93
	v_exp_f32_e32 v94, v94
	v_exp_f32_e32 v95, v95
	v_exp_f32_e32 v96, v96
	v_exp_f32_e32 v97, v97
	v_add_f32_e32 v90, 1.0, v90
	v_add_f32_e32 v91, 1.0, v91
	v_add_f32_e32 v92, 1.0, v92
	v_add_f32_e32 v93, 1.0, v93
	v_add_f32_e32 v94, 1.0, v94
	v_add_f32_e32 v95, 1.0, v95
	v_add_f32_e32 v96, 1.0, v96
	v_add_f32_e32 v97, 1.0, v97
	v_rcp_f32_e32 v90, v90
	v_rcp_f32_e32 v91, v91
	v_rcp_f32_e32 v92, v92
	v_rcp_f32_e32 v93, v93
	v_rcp_f32_e32 v94, v94
	v_rcp_f32_e32 v95, v95
	v_rcp_f32_e32 v96, v96
	v_rcp_f32_e32 v97, v97
	v_cvt_pk_bf16_f32 v90, v90, v91
	v_cvt_pk_bf16_f32 v91, v92, v93
	v_cvt_pk_bf16_f32 v92, v94, v95
	v_cvt_pk_bf16_f32 v93, v96, v97
	global_store_dwordx4 v240, v[90:93], s[10:11] offset:2064
	v_mul_f32_e32 v98, s12, v98
	v_mul_f32_e32 v99, s12, v99
	v_mul_f32_e32 v100, s12, v100
	v_mul_f32_e32 v101, s12, v101
	v_mul_f32_e32 v102, s12, v102
	v_mul_f32_e32 v103, s12, v103
	v_mul_f32_e32 v104, s12, v104
	v_mul_f32_e32 v105, s12, v105
	v_exp_f32_e32 v98, v98
	v_exp_f32_e32 v99, v99
	v_exp_f32_e32 v100, v100
	v_exp_f32_e32 v101, v101
	v_exp_f32_e32 v102, v102
	v_exp_f32_e32 v103, v103
	v_exp_f32_e32 v104, v104
	v_exp_f32_e32 v105, v105
	v_add_f32_e32 v98, 1.0, v98
	v_add_f32_e32 v99, 1.0, v99
	v_add_f32_e32 v100, 1.0, v100
	v_add_f32_e32 v101, 1.0, v101
	v_add_f32_e32 v102, 1.0, v102
	v_add_f32_e32 v103, 1.0, v103
	v_add_f32_e32 v104, 1.0, v104
	v_add_f32_e32 v105, 1.0, v105
	v_rcp_f32_e32 v98, v98
	v_rcp_f32_e32 v99, v99
	v_rcp_f32_e32 v100, v100
	v_rcp_f32_e32 v101, v101
	v_rcp_f32_e32 v102, v102
	v_rcp_f32_e32 v103, v103
	v_rcp_f32_e32 v104, v104
	v_rcp_f32_e32 v105, v105
	v_cvt_pk_bf16_f32 v98, v98, v99
	v_cvt_pk_bf16_f32 v99, v100, v101
	v_cvt_pk_bf16_f32 v100, v102, v103
	v_cvt_pk_bf16_f32 v101, v104, v105
	global_store_dwordx4 v241, v[98:101], s[10:11] offset:0
	v_mul_f32_e32 v106, s12, v106
	v_mul_f32_e32 v107, s12, v107
	v_mul_f32_e32 v108, s12, v108
	v_mul_f32_e32 v109, s12, v109
	v_mul_f32_e32 v110, s12, v110
	v_mul_f32_e32 v111, s12, v111
	v_mul_f32_e32 v112, s12, v112
	v_mul_f32_e32 v113, s12, v113
	v_exp_f32_e32 v106, v106
	v_exp_f32_e32 v107, v107
	v_exp_f32_e32 v108, v108
	v_exp_f32_e32 v109, v109
	v_exp_f32_e32 v110, v110
	v_exp_f32_e32 v111, v111
	v_exp_f32_e32 v112, v112
	v_exp_f32_e32 v113, v113
	v_add_f32_e32 v106, 1.0, v106
	v_add_f32_e32 v107, 1.0, v107
	v_add_f32_e32 v108, 1.0, v108
	v_add_f32_e32 v109, 1.0, v109
	v_add_f32_e32 v110, 1.0, v110
	v_add_f32_e32 v111, 1.0, v111
	v_add_f32_e32 v112, 1.0, v112
	v_add_f32_e32 v113, 1.0, v113
	v_rcp_f32_e32 v106, v106
	v_rcp_f32_e32 v107, v107
	v_rcp_f32_e32 v108, v108
	v_rcp_f32_e32 v109, v109
	v_rcp_f32_e32 v110, v110
	v_rcp_f32_e32 v111, v111
	v_rcp_f32_e32 v112, v112
	v_rcp_f32_e32 v113, v113
	v_cvt_pk_bf16_f32 v106, v106, v107
	v_cvt_pk_bf16_f32 v107, v108, v109
	v_cvt_pk_bf16_f32 v108, v110, v111
	v_cvt_pk_bf16_f32 v109, v112, v113
	global_store_dwordx4 v241, v[106:109], s[10:11] offset:16
	v_mul_f32_e32 v114, s12, v114
	v_mul_f32_e32 v115, s12, v115
	v_mul_f32_e32 v116, s12, v116
	v_mul_f32_e32 v117, s12, v117
	v_mul_f32_e32 v118, s12, v118
	v_mul_f32_e32 v119, s12, v119
	v_mul_f32_e32 v120, s12, v120
	v_mul_f32_e32 v121, s12, v121
	v_exp_f32_e32 v114, v114
	v_exp_f32_e32 v115, v115
	v_exp_f32_e32 v116, v116
	v_exp_f32_e32 v117, v117
	v_exp_f32_e32 v118, v118
	v_exp_f32_e32 v119, v119
	v_exp_f32_e32 v120, v120
	v_exp_f32_e32 v121, v121
	v_add_f32_e32 v114, 1.0, v114
	v_add_f32_e32 v115, 1.0, v115
	v_add_f32_e32 v116, 1.0, v116
	v_add_f32_e32 v117, 1.0, v117
	v_add_f32_e32 v118, 1.0, v118
	v_add_f32_e32 v119, 1.0, v119
	v_add_f32_e32 v120, 1.0, v120
	v_add_f32_e32 v121, 1.0, v121
	v_rcp_f32_e32 v114, v114
	v_rcp_f32_e32 v115, v115
	v_rcp_f32_e32 v116, v116
	v_rcp_f32_e32 v117, v117
	v_rcp_f32_e32 v118, v118
	v_rcp_f32_e32 v119, v119
	v_rcp_f32_e32 v120, v120
	v_rcp_f32_e32 v121, v121
	v_cvt_pk_bf16_f32 v114, v114, v115
	v_cvt_pk_bf16_f32 v115, v116, v117
	v_cvt_pk_bf16_f32 v116, v118, v119
	v_cvt_pk_bf16_f32 v117, v120, v121
	global_store_dwordx4 v241, v[114:117], s[10:11] offset:2048
	v_mul_f32_e32 v122, s12, v122
	v_mul_f32_e32 v123, s12, v123
	v_mul_f32_e32 v124, s12, v124
	v_mul_f32_e32 v125, s12, v125
	v_mul_f32_e32 v126, s12, v126
	v_mul_f32_e32 v127, s12, v127
	v_mul_f32_e32 v128, s12, v128
	v_mul_f32_e32 v129, s12, v129
	v_exp_f32_e32 v122, v122
	v_exp_f32_e32 v123, v123
	v_exp_f32_e32 v124, v124
	v_exp_f32_e32 v125, v125
	v_exp_f32_e32 v126, v126
	v_exp_f32_e32 v127, v127
	v_exp_f32_e32 v128, v128
	v_exp_f32_e32 v129, v129
	v_add_f32_e32 v122, 1.0, v122
	v_add_f32_e32 v123, 1.0, v123
	v_add_f32_e32 v124, 1.0, v124
	v_add_f32_e32 v125, 1.0, v125
	v_add_f32_e32 v126, 1.0, v126
	v_add_f32_e32 v127, 1.0, v127
	v_add_f32_e32 v128, 1.0, v128
	v_add_f32_e32 v129, 1.0, v129
	v_rcp_f32_e32 v122, v122
	v_rcp_f32_e32 v123, v123
	v_rcp_f32_e32 v124, v124
	v_rcp_f32_e32 v125, v125
	v_rcp_f32_e32 v126, v126
	v_rcp_f32_e32 v127, v127
	v_rcp_f32_e32 v128, v128
	v_rcp_f32_e32 v129, v129
	v_cvt_pk_bf16_f32 v122, v122, v123
	v_cvt_pk_bf16_f32 v123, v124, v125
	v_cvt_pk_bf16_f32 v124, v126, v127
	v_cvt_pk_bf16_f32 v125, v128, v129
	global_store_dwordx4 v241, v[122:125], s[10:11] offset:2064
	s_waitcnt vmcnt(0)
	s_barrier
	v_mov_b32_e32 v236, s20
	v_mov_b32_e32 v237, s21
	v_mov_b32_e32 v238, 0x200f0
	ds_write_b64 v238, v[236:237]
	s_waitcnt vmcnt(0)
	v_readlane_b32 s60, v254, 32
	v_readlane_b32 s58, v254, 46
	s_mov_b32 s64, s44
	s_mov_b32 s72, s67
	s_cmpk_gt_u32 s50, 0xff
	v_readlane_b32 s61, v254, 33
	v_readlane_b32 s59, v254, 47
	s_movk_i32 s73, 0xf0
	v_readlane_b32 s79, v254, 50

.LBB0_880:
	s_andn2_b64 vcc, exec, s[0:1]
	s_cbranch_vccnz .LBB0_891
	s_lshl_b32 s96, s80, 20
	s_mov_b64 s[4:5], s[96:97]
	s_mov_b32 s13, s2
	v_mov_b32_e32 v205, 0x200f0
	ds_read_b64 v[250:251], v205
	v_and_b32_e32 v198, 63, v0
	v_lshrrev_b32_e32 v199, 6, v0
	v_lshrrev_b32_e32 v200, 3, v198
	v_lshrrev_b32_e32 v201, 4, v198
	s_nop 0
	v_readfirstlane_b32 s0, v199
	v_add_u32_e32 v132, 0, v201
	v_xor_b32_e32 v132, v132, v198
	v_and_b32_e32 v132, 7, v132
	v_lshlrev_b32_e32 v132, 4, v132
	v_lshl_add_u32 v130, v199, 5, v200
	v_add_u32_e32 v130, 0, v130
	v_mul_u32_u24_e32 v130, 0x800, v130
	v_add_u32_e32 v132, v132, v130
	v_add_u32_e32 v133, 4, v201
	v_xor_b32_e32 v133, v133, v198
	v_and_b32_e32 v133, 7, v133
	v_lshlrev_b32_e32 v133, 4, v133
	v_lshl_add_u32 v130, v199, 5, v200
	v_add_u32_e32 v130, 8, v130
	v_mul_u32_u24_e32 v130, 0x800, v130
	v_add_u32_e32 v133, v133, v130
	v_add_u32_e32 v134, 8, v201
	v_xor_b32_e32 v134, v134, v198
	v_and_b32_e32 v134, 7, v134
	v_lshlrev_b32_e32 v134, 4, v134
	v_lshl_add_u32 v130, v199, 5, v200
	v_add_u32_e32 v130, 16, v130
	v_mul_u32_u24_e32 v130, 0x800, v130
	v_add_u32_e32 v134, v134, v130
	v_add_u32_e32 v135, 12, v201
	v_xor_b32_e32 v135, v135, v198
	v_and_b32_e32 v135, 7, v135
	v_lshlrev_b32_e32 v135, 4, v135
	v_lshl_add_u32 v130, v199, 5, v200
	v_add_u32_e32 v130, 24, v130
	v_mul_u32_u24_e32 v130, 0x800, v130
	v_add_u32_e32 v135, v135, v130
	v_add_u32_e32 v136, 0, v201
	v_xor_b32_e32 v136, v136, v198
	v_and_b32_e32 v136, 7, v136
	v_lshlrev_b32_e32 v136, 4, v136
	v_lshl_add_u32 v130, v199, 4, v200
	v_add_u32_e32 v130, 0, v130
	v_mul_u32_u24_e32 v130, 0x200, v130
	v_add_u32_e32 v136, v136, v130
	v_add_u32_e32 v137, 4, v201
	v_xor_b32_e32 v137, v137, v198
	v_and_b32_e32 v137, 7, v137
	v_lshlrev_b32_e32 v137, 4, v137
	v_lshl_add_u32 v130, v199, 4, v200
	v_add_u32_e32 v130, 8, v130
	v_mul_u32_u24_e32 v130, 0x200, v130
	v_add_u32_e32 v137, v137, v130
	v_and_b32_e32 v200, 15, v198
	v_lshrrev_b32_e32 v130, 1, v200
	v_xor_b32_e32 v130, v130, v201
	v_lshlrev_b32_e32 v130, 4, v130
	v_lshrrev_b32_e32 v198, 1, v199
	v_lshl_add_u32 v198, v198, 6, v200
	v_lshl_add_u32 v198, v198, 7, v130
	v_and_b32_e32 v199, 1, v199
	v_lshl_add_u32 v199, v199, 6, v200
	v_lshl_add_u32 v199, v199, 7, v130
	v_add_u32_e32 v138, 0x100, v198
	v_xor_b32_e32 v141, 64, v138
	v_add_u32_e32 v144, 0x8100, v199
	v_xor_b32_e32 v147, 64, v144
	v_add_u32_e32 v139, 0xc100, v198
	v_xor_b32_e32 v142, 64, v139
	v_add_u32_e32 v145, 0x14100, v199
	v_xor_b32_e32 v196, 64, v145
	v_add_u32_e32 v140, 0x18100, v198
	v_xor_b32_e32 v143, 64, v140
	v_add_u32_e32 v146, 0x20100, v199
	v_xor_b32_e32 v197, 64, v146
	s_lshl_b32 s1, s0, 12
	s_add_u32 s10, s1, 0x100
	s_lshl_b32 s1, s0, 11
	s_add_u32 s11, s1, 0x8100
	v_mov_b32_e32 v2, 0
	v_mov_b32_e32 v3, 0
	v_mov_b32_e32 v4, 0
	v_mov_b32_e32 v5, 0
	v_mov_b32_e32 v6, 0
	v_mov_b32_e32 v7, 0
	v_mov_b32_e32 v8, 0
	v_mov_b32_e32 v9, 0
	v_mov_b32_e32 v10, 0
	v_mov_b32_e32 v11, 0
	v_mov_b32_e32 v12, 0
	v_mov_b32_e32 v13, 0
	v_mov_b32_e32 v14, 0
	v_mov_b32_e32 v15, 0
	v_mov_b32_e32 v16, 0
	v_mov_b32_e32 v17, 0
	v_mov_b32_e32 v18, 0
	v_mov_b32_e32 v19, 0
	v_mov_b32_e32 v20, 0
	v_mov_b32_e32 v21, 0
	v_mov_b32_e32 v22, 0
	v_mov_b32_e32 v23, 0
	v_mov_b32_e32 v24, 0
	v_mov_b32_e32 v25, 0
	v_mov_b32_e32 v26, 0
	v_mov_b32_e32 v27, 0
	v_mov_b32_e32 v28, 0
	v_mov_b32_e32 v29, 0
	v_mov_b32_e32 v30, 0
	v_mov_b32_e32 v31, 0
	v_mov_b32_e32 v32, 0
	v_mov_b32_e32 v33, 0
	v_mov_b32_e32 v34, 0
	v_mov_b32_e32 v35, 0
	v_mov_b32_e32 v36, 0
	v_mov_b32_e32 v37, 0
	v_mov_b32_e32 v38, 0
	v_mov_b32_e32 v39, 0
	v_mov_b32_e32 v40, 0
	v_mov_b32_e32 v41, 0
	v_mov_b32_e32 v42, 0
	v_mov_b32_e32 v43, 0
	v_mov_b32_e32 v44, 0
	v_mov_b32_e32 v45, 0
	v_mov_b32_e32 v46, 0
	v_mov_b32_e32 v47, 0
	v_mov_b32_e32 v48, 0
	v_mov_b32_e32 v49, 0
	v_mov_b32_e32 v50, 0
	v_mov_b32_e32 v51, 0
	v_mov_b32_e32 v52, 0
	v_mov_b32_e32 v53, 0
	v_mov_b32_e32 v54, 0
	v_mov_b32_e32 v55, 0
	v_mov_b32_e32 v56, 0
	v_mov_b32_e32 v57, 0
	v_mov_b32_e32 v58, 0
	v_mov_b32_e32 v59, 0
	v_mov_b32_e32 v60, 0
	v_mov_b32_e32 v61, 0
	v_mov_b32_e32 v62, 0
	v_mov_b32_e32 v63, 0
	v_mov_b32_e32 v64, 0
	v_mov_b32_e32 v65, 0
	s_waitcnt lgkmcnt(0)
	s_barrier
	v_and_b32_e32 v198, 63, v0
	v_lshrrev_b32_e32 v199, 6, v0
	v_and_b32_e32 v200, 15, v198
	v_lshrrev_b32_e32 v201, 4, v198
	v_lshlrev_b32_e32 v202, 13, v199
	v_lshl_add_u32 v202, v200, 7, v202
	v_lshl_add_u32 v202, v201, 5, v202
	v_add_u32_e32 v203, 0x1000, v202
	v_lshrrev_b32_e32 v130, 1, v199
	v_lshl_add_u32 v130, v130, 6, v200
	v_lshlrev_b32_e32 v204, 11, v130
	v_and_b32_e32 v130, 1, v199
	v_lshl_add_u32 v204, v130, 7, v204
	v_lshl_add_u32 v204, v201, 3, v204
.Lc2_unit:
	s_cmpk_lt_i32 s13, 0x100
	s_cbranch_scc0 .Lc2_exit
	v_mov_b32_e32 v66, 0
	v_mov_b32_e32 v67, 0
	v_mov_b32_e32 v68, 0
	v_mov_b32_e32 v69, 0
	v_mov_b32_e32 v70, 0
	v_mov_b32_e32 v71, 0
	v_mov_b32_e32 v72, 0
	v_mov_b32_e32 v73, 0
	v_mov_b32_e32 v74, 0
	v_mov_b32_e32 v75, 0
	v_mov_b32_e32 v76, 0
	v_mov_b32_e32 v77, 0
	v_mov_b32_e32 v78, 0
	v_mov_b32_e32 v79, 0
	v_mov_b32_e32 v80, 0
	v_mov_b32_e32 v81, 0
	v_mov_b32_e32 v82, 0
	v_mov_b32_e32 v83, 0
	v_mov_b32_e32 v84, 0
	v_mov_b32_e32 v85, 0
	v_mov_b32_e32 v86, 0
	v_mov_b32_e32 v87, 0
	v_mov_b32_e32 v88, 0
	v_mov_b32_e32 v89, 0
	v_mov_b32_e32 v90, 0
	v_mov_b32_e32 v91, 0
	v_mov_b32_e32 v92, 0
	v_mov_b32_e32 v93, 0
	v_mov_b32_e32 v94, 0
	v_mov_b32_e32 v95, 0
	v_mov_b32_e32 v96, 0
	v_mov_b32_e32 v97, 0
	v_mov_b32_e32 v98, 0
	v_mov_b32_e32 v99, 0
	v_mov_b32_e32 v100, 0
	v_mov_b32_e32 v101, 0
	v_mov_b32_e32 v102, 0
	v_mov_b32_e32 v103, 0
	v_mov_b32_e32 v104, 0
	v_mov_b32_e32 v105, 0
	v_mov_b32_e32 v106, 0
	v_mov_b32_e32 v107, 0
	v_mov_b32_e32 v108, 0
	v_mov_b32_e32 v109, 0
	v_mov_b32_e32 v110, 0
	v_mov_b32_e32 v111, 0
	v_mov_b32_e32 v112, 0
	v_mov_b32_e32 v113, 0
	v_mov_b32_e32 v114, 0
	v_mov_b32_e32 v115, 0
	v_mov_b32_e32 v116, 0
	v_mov_b32_e32 v117, 0
	v_mov_b32_e32 v118, 0
	v_mov_b32_e32 v119, 0
	v_mov_b32_e32 v120, 0
	v_mov_b32_e32 v121, 0
	v_mov_b32_e32 v122, 0
	v_mov_b32_e32 v123, 0
	v_mov_b32_e32 v124, 0
	v_mov_b32_e32 v125, 0
	v_mov_b32_e32 v126, 0
	v_mov_b32_e32 v127, 0
	v_mov_b32_e32 v128, 0
	v_mov_b32_e32 v129, 0
	s_and_b32 s0, s13, 31
	s_lshr_b32 s1, s13, 5
	v_readlane_b32 s6, v253, 55
	v_readlane_b32 s7, v253, 56
	s_lshl_b32 s20, s0, 19
	s_nop 0
	s_add_u32 s6, s6, s20
	s_addc_u32 s7, s7, 0
	v_readlane_b32 s8, v254, 2
	v_readlane_b32 s9, v254, 3
	s_lshl_b32 s20, s80, 21
	s_lshl_b32 s21, s1, 16
	s_add_u32 s20, s20, s21
	s_add_u32 s8, s8, s20
	s_addc_u32 s9, s9, 0
	s_lshl_b32 s20, s0, 3
	s_add_u32 s20, s20, s1
	s_lshl_b32 s20, s20, 16
	s_add_u32 s14, s28, s20
	s_addc_u32 s15, s29, 0
	s_mov_b32 m0, s10
	s_nop 0
	global_load_lds_dwordx4 v132, s[6:7]
	s_add_u32 m0, s10, 0x400
	s_nop 0
	global_load_lds_dwordx4 v133, s[6:7]
	s_add_u32 m0, s10, 0x800
	s_nop 0
	global_load_lds_dwordx4 v134, s[6:7]
	s_add_u32 m0, s10, 0xc00
	s_nop 0
	global_load_lds_dwordx4 v135, s[6:7]
	s_mov_b32 m0, s11
	s_nop 0
	global_load_lds_dwordx4 v136, s[8:9]
	s_add_u32 m0, s11, 0x400
	s_nop 0
	global_load_lds_dwordx4 v137, s[8:9]
	s_add_u32 s6, s6, 0x80
	s_addc_u32 s7, s7, 0
	s_add_u32 s8, s8, 0x80
	s_addc_u32 s9, s9, 0
	s_add_u32 m0, s10, 0xc000
	s_nop 0
	global_load_lds_dwordx4 v132, s[6:7]
	s_add_u32 m0, s10, 0xc400
	s_nop 0
	global_load_lds_dwordx4 v133, s[6:7]
	s_add_u32 m0, s10, 0xc800
	s_nop 0
	global_load_lds_dwordx4 v134, s[6:7]
	s_add_u32 m0, s10, 0xcc00
	s_nop 0
	global_load_lds_dwordx4 v135, s[6:7]
	s_add_u32 m0, s11, 0xc000
	s_nop 0
	global_load_lds_dwordx4 v136, s[8:9]
	s_add_u32 m0, s11, 0xc400
	s_nop 0
	global_load_lds_dwordx4 v137, s[8:9]
	s_add_u32 s6, s6, 0x80
	s_addc_u32 s7, s7, 0
	s_add_u32 s8, s8, 0x80
	s_addc_u32 s9, s9, 0
	s_add_u32 s20, s14, 0x1000000
	s_addc_u32 s21, s15, 0
	global_load_dword v244, v202, s[14:15] offset:0
	global_load_dword v244, v202, s[14:15] offset:2048
	global_load_dword v244, v203, s[14:15] offset:0
	global_load_dword v244, v203, s[14:15] offset:2048
	s_waitcnt vmcnt(10)
	s_barrier
	ds_read_b128 v[148:151], v138 offset:0
	ds_read_b128 v[152:155], v138 offset:2048
	ds_read_b128 v[156:159], v138 offset:4096
	ds_read_b128 v[160:163], v138 offset:6144
	ds_read_b128 v[164:167], v144 offset:0
	ds_read_b128 v[168:171], v144 offset:2048
	ds_read_b128 v[172:175], v144 offset:4096
	ds_read_b128 v[176:179], v144 offset:6144
	ds_read_b128 v[180:183], v141 offset:0
	ds_read_b128 v[184:187], v141 offset:2048
	ds_read_b128 v[188:191], v141 offset:4096
	ds_read_b128 v[192:195], v141 offset:6144
	ds_read_b128 v[228:231], v147 offset:0
	ds_read_b128 v[232:235], v147 offset:2048
	ds_read_b128 v[236:239], v147 offset:4096
	ds_read_b128 v[240:243], v147 offset:6144
	s_waitcnt lgkmcnt(8)
	v_mfma_f32_16x16x32_bf16 v[2:5], v[164:167], v[148:151], v[2:5]
	s_add_u32 m0, s10, 0x18000
	v_mfma_f32_16x16x32_bf16 v[6:9], v[168:171], v[148:151], v[6:9]
	global_load_lds_dwordx4 v132, s[6:7]
	v_mfma_f32_16x16x32_bf16 v[10:13], v[172:175], v[148:151], v[10:13]
	s_add_u32 m0, s10, 0x18400
	v_mfma_f32_16x16x32_bf16 v[14:17], v[176:179], v[148:151], v[14:17]
	global_load_lds_dwordx4 v133, s[6:7]
	v_mfma_f32_16x16x32_bf16 v[18:21], v[164:167], v[152:155], v[18:21]
	s_add_u32 m0, s10, 0x18800
	v_mfma_f32_16x16x32_bf16 v[22:25], v[168:171], v[152:155], v[22:25]
	global_load_lds_dwordx4 v134, s[6:7]
	v_mfma_f32_16x16x32_bf16 v[26:29], v[172:175], v[152:155], v[26:29]
	s_add_u32 m0, s10, 0x18c00
	v_mfma_f32_16x16x32_bf16 v[30:33], v[176:179], v[152:155], v[30:33]
	global_load_lds_dwordx4 v135, s[6:7]
	v_mfma_f32_16x16x32_bf16 v[34:37], v[164:167], v[156:159], v[34:37]
	s_add_u32 m0, s11, 0x18000
	v_mfma_f32_16x16x32_bf16 v[38:41], v[168:171], v[156:159], v[38:41]
	global_load_lds_dwordx4 v136, s[8:9]
	v_mfma_f32_16x16x32_bf16 v[42:45], v[172:175], v[156:159], v[42:45]
	s_add_u32 m0, s11, 0x18400
	v_mfma_f32_16x16x32_bf16 v[46:49], v[176:179], v[156:159], v[46:49]
	global_load_lds_dwordx4 v137, s[8:9]
	v_mfma_f32_16x16x32_bf16 v[50:53], v[164:167], v[160:163], v[50:53]
	v_mfma_f32_16x16x32_bf16 v[54:57], v[168:171], v[160:163], v[54:57]
	v_mfma_f32_16x16x32_bf16 v[58:61], v[172:175], v[160:163], v[58:61]
	v_mfma_f32_16x16x32_bf16 v[62:65], v[176:179], v[160:163], v[62:65]
	s_waitcnt lgkmcnt(0)
	v_mfma_f32_16x16x32_bf16 v[2:5], v[228:231], v[180:183], v[2:5]
	v_mfma_f32_16x16x32_bf16 v[6:9], v[232:235], v[180:183], v[6:9]
	v_mfma_f32_16x16x32_bf16 v[10:13], v[236:239], v[180:183], v[10:13]
	v_mfma_f32_16x16x32_bf16 v[14:17], v[240:243], v[180:183], v[14:17]
	v_mfma_f32_16x16x32_bf16 v[18:21], v[228:231], v[184:187], v[18:21]
	v_mfma_f32_16x16x32_bf16 v[22:25], v[232:235], v[184:187], v[22:25]
	v_mfma_f32_16x16x32_bf16 v[26:29], v[236:239], v[184:187], v[26:29]
	v_mfma_f32_16x16x32_bf16 v[30:33], v[240:243], v[184:187], v[30:33]
	v_mfma_f32_16x16x32_bf16 v[34:37], v[228:231], v[188:191], v[34:37]
	v_mfma_f32_16x16x32_bf16 v[38:41], v[232:235], v[188:191], v[38:41]
	v_mfma_f32_16x16x32_bf16 v[42:45], v[236:239], v[188:191], v[42:45]
	v_mfma_f32_16x16x32_bf16 v[46:49], v[240:243], v[188:191], v[46:49]
	v_mfma_f32_16x16x32_bf16 v[50:53], v[228:231], v[192:195], v[50:53]
	v_mfma_f32_16x16x32_bf16 v[54:57], v[232:235], v[192:195], v[54:57]
	v_mfma_f32_16x16x32_bf16 v[58:61], v[236:239], v[192:195], v[58:61]
	v_mfma_f32_16x16x32_bf16 v[62:65], v[240:243], v[192:195], v[62:65]
	s_add_u32 s6, s6, 0x80
	s_addc_u32 s7, s7, 0
	s_add_u32 s8, s8, 0x80
	s_addc_u32 s9, s9, 0
	global_load_dword v244, v202, s[20:21] offset:0
	s_waitcnt vmcnt(11)
	s_barrier
	ds_read_b128 v[148:151], v139 offset:0
	ds_read_b128 v[152:155], v139 offset:2048
	ds_read_b128 v[156:159], v139 offset:4096
	ds_read_b128 v[160:163], v139 offset:6144
	ds_read_b128 v[164:167], v145 offset:0
	ds_read_b128 v[168:171], v145 offset:2048
	ds_read_b128 v[172:175], v145 offset:4096
	ds_read_b128 v[176:179], v145 offset:6144
	ds_read_b128 v[180:183], v142 offset:0
	ds_read_b128 v[184:187], v142 offset:2048
	ds_read_b128 v[188:191], v142 offset:4096
	ds_read_b128 v[192:195], v142 offset:6144
	ds_read_b128 v[228:231], v196 offset:0
	ds_read_b128 v[232:235], v196 offset:2048
	ds_read_b128 v[236:239], v196 offset:4096
	ds_read_b128 v[240:243], v196 offset:6144
	s_waitcnt lgkmcnt(8)
	v_mfma_f32_16x16x32_bf16 v[2:5], v[164:167], v[148:151], v[2:5]
	s_mov_b32 m0, s10
	v_mfma_f32_16x16x32_bf16 v[6:9], v[168:171], v[148:151], v[6:9]
	global_load_lds_dwordx4 v132, s[6:7]
	v_mfma_f32_16x16x32_bf16 v[10:13], v[172:175], v[148:151], v[10:13]
	s_add_u32 m0, s10, 0x400
	v_mfma_f32_16x16x32_bf16 v[14:17], v[176:179], v[148:151], v[14:17]
	global_load_lds_dwordx4 v133, s[6:7]
	v_mfma_f32_16x16x32_bf16 v[18:21], v[164:167], v[152:155], v[18:21]
	s_add_u32 m0, s10, 0x800
	v_mfma_f32_16x16x32_bf16 v[22:25], v[168:171], v[152:155], v[22:25]
	global_load_lds_dwordx4 v134, s[6:7]
	v_mfma_f32_16x16x32_bf16 v[26:29], v[172:175], v[152:155], v[26:29]
	s_add_u32 m0, s10, 0xc00
	v_mfma_f32_16x16x32_bf16 v[30:33], v[176:179], v[152:155], v[30:33]
	global_load_lds_dwordx4 v135, s[6:7]
	v_mfma_f32_16x16x32_bf16 v[34:37], v[164:167], v[156:159], v[34:37]
	s_mov_b32 m0, s11
	v_mfma_f32_16x16x32_bf16 v[38:41], v[168:171], v[156:159], v[38:41]
	global_load_lds_dwordx4 v136, s[8:9]
	v_mfma_f32_16x16x32_bf16 v[42:45], v[172:175], v[156:159], v[42:45]
	s_add_u32 m0, s11, 0x400
	v_mfma_f32_16x16x32_bf16 v[46:49], v[176:179], v[156:159], v[46:49]
	global_load_lds_dwordx4 v137, s[8:9]
	v_mfma_f32_16x16x32_bf16 v[50:53], v[164:167], v[160:163], v[50:53]
	v_mfma_f32_16x16x32_bf16 v[54:57], v[168:171], v[160:163], v[54:57]
	v_mfma_f32_16x16x32_bf16 v[58:61], v[172:175], v[160:163], v[58:61]
	v_mfma_f32_16x16x32_bf16 v[62:65], v[176:179], v[160:163], v[62:65]
	s_waitcnt lgkmcnt(0)
	v_mfma_f32_16x16x32_bf16 v[2:5], v[228:231], v[180:183], v[2:5]
	v_mfma_f32_16x16x32_bf16 v[6:9], v[232:235], v[180:183], v[6:9]
	v_mfma_f32_16x16x32_bf16 v[10:13], v[236:239], v[180:183], v[10:13]
	v_mfma_f32_16x16x32_bf16 v[14:17], v[240:243], v[180:183], v[14:17]
	v_mfma_f32_16x16x32_bf16 v[18:21], v[228:231], v[184:187], v[18:21]
	v_mfma_f32_16x16x32_bf16 v[22:25], v[232:235], v[184:187], v[22:25]
	v_mfma_f32_16x16x32_bf16 v[26:29], v[236:239], v[184:187], v[26:29]
	v_mfma_f32_16x16x32_bf16 v[30:33], v[240:243], v[184:187], v[30:33]
	v_mfma_f32_16x16x32_bf16 v[34:37], v[228:231], v[188:191], v[34:37]
	v_mfma_f32_16x16x32_bf16 v[38:41], v[232:235], v[188:191], v[38:41]
	v_mfma_f32_16x16x32_bf16 v[42:45], v[236:239], v[188:191], v[42:45]
	v_mfma_f32_16x16x32_bf16 v[46:49], v[240:243], v[188:191], v[46:49]
	v_mfma_f32_16x16x32_bf16 v[50:53], v[228:231], v[192:195], v[50:53]
	v_mfma_f32_16x16x32_bf16 v[54:57], v[232:235], v[192:195], v[54:57]
	v_mfma_f32_16x16x32_bf16 v[58:61], v[236:239], v[192:195], v[58:61]
	v_mfma_f32_16x16x32_bf16 v[62:65], v[240:243], v[192:195], v[62:65]
	s_add_u32 s6, s6, 0x80
	s_addc_u32 s7, s7, 0
	s_add_u32 s8, s8, 0x7fe80
	s_addc_u32 s9, s9, 0
	global_load_dword v244, v202, s[20:21] offset:2048
	s_waitcnt vmcnt(8)
	s_barrier
	ds_read_b128 v[148:151], v140 offset:0
	ds_read_b128 v[152:155], v140 offset:2048
	ds_read_b128 v[156:159], v140 offset:4096
	ds_read_b128 v[160:163], v140 offset:6144
	ds_read_b128 v[164:167], v146 offset:0
	ds_read_b128 v[168:171], v146 offset:2048
	ds_read_b128 v[172:175], v146 offset:4096
	ds_read_b128 v[176:179], v146 offset:6144
	ds_read_b128 v[180:183], v143 offset:0
	ds_read_b128 v[184:187], v143 offset:2048
	ds_read_b128 v[188:191], v143 offset:4096
	ds_read_b128 v[192:195], v143 offset:6144
	ds_read_b128 v[228:231], v197 offset:0
	ds_read_b128 v[232:235], v197 offset:2048
	ds_read_b128 v[236:239], v197 offset:4096
	ds_read_b128 v[240:243], v197 offset:6144
	s_waitcnt lgkmcnt(8)
	v_mfma_f32_16x16x32_bf16 v[2:5], v[164:167], v[148:151], v[2:5]
	s_add_u32 m0, s10, 0xc000
	v_mfma_f32_16x16x32_bf16 v[6:9], v[168:171], v[148:151], v[6:9]
	global_load_lds_dwordx4 v132, s[6:7]
	v_mfma_f32_16x16x32_bf16 v[10:13], v[172:175], v[148:151], v[10:13]
	s_add_u32 m0, s10, 0xc400
	v_mfma_f32_16x16x32_bf16 v[14:17], v[176:179], v[148:151], v[14:17]
	global_load_lds_dwordx4 v133, s[6:7]
	v_mfma_f32_16x16x32_bf16 v[18:21], v[164:167], v[152:155], v[18:21]
	s_add_u32 m0, s10, 0xc800
	v_mfma_f32_16x16x32_bf16 v[22:25], v[168:171], v[152:155], v[22:25]
	global_load_lds_dwordx4 v134, s[6:7]
	v_mfma_f32_16x16x32_bf16 v[26:29], v[172:175], v[152:155], v[26:29]
	s_add_u32 m0, s10, 0xcc00
	v_mfma_f32_16x16x32_bf16 v[30:33], v[176:179], v[152:155], v[30:33]
	global_load_lds_dwordx4 v135, s[6:7]
	v_mfma_f32_16x16x32_bf16 v[34:37], v[164:167], v[156:159], v[34:37]
	s_add_u32 m0, s11, 0xc000
	v_mfma_f32_16x16x32_bf16 v[38:41], v[168:171], v[156:159], v[38:41]
	global_load_lds_dwordx4 v136, s[8:9]
	v_mfma_f32_16x16x32_bf16 v[42:45], v[172:175], v[156:159], v[42:45]
	s_add_u32 m0, s11, 0xc400
	v_mfma_f32_16x16x32_bf16 v[46:49], v[176:179], v[156:159], v[46:49]
	global_load_lds_dwordx4 v137, s[8:9]
	v_mfma_f32_16x16x32_bf16 v[50:53], v[164:167], v[160:163], v[50:53]
	v_mfma_f32_16x16x32_bf16 v[54:57], v[168:171], v[160:163], v[54:57]
	v_mfma_f32_16x16x32_bf16 v[58:61], v[172:175], v[160:163], v[58:61]
	v_mfma_f32_16x16x32_bf16 v[62:65], v[176:179], v[160:163], v[62:65]
	s_waitcnt lgkmcnt(0)
	v_mfma_f32_16x16x32_bf16 v[2:5], v[228:231], v[180:183], v[2:5]
	v_mfma_f32_16x16x32_bf16 v[6:9], v[232:235], v[180:183], v[6:9]
	v_mfma_f32_16x16x32_bf16 v[10:13], v[236:239], v[180:183], v[10:13]
	v_mfma_f32_16x16x32_bf16 v[14:17], v[240:243], v[180:183], v[14:17]
	v_mfma_f32_16x16x32_bf16 v[18:21], v[228:231], v[184:187], v[18:21]
	v_mfma_f32_16x16x32_bf16 v[22:25], v[232:235], v[184:187], v[22:25]
	v_mfma_f32_16x16x32_bf16 v[26:29], v[236:239], v[184:187], v[26:29]
	v_mfma_f32_16x16x32_bf16 v[30:33], v[240:243], v[184:187], v[30:33]
	v_mfma_f32_16x16x32_bf16 v[34:37], v[228:231], v[188:191], v[34:37]
	v_mfma_f32_16x16x32_bf16 v[38:41], v[232:235], v[188:191], v[38:41]
	v_mfma_f32_16x16x32_bf16 v[42:45], v[236:239], v[188:191], v[42:45]
	v_mfma_f32_16x16x32_bf16 v[46:49], v[240:243], v[188:191], v[46:49]
	v_mfma_f32_16x16x32_bf16 v[50:53], v[228:231], v[192:195], v[50:53]
	v_mfma_f32_16x16x32_bf16 v[54:57], v[232:235], v[192:195], v[54:57]
	v_mfma_f32_16x16x32_bf16 v[58:61], v[236:239], v[192:195], v[58:61]
	v_mfma_f32_16x16x32_bf16 v[62:65], v[240:243], v[192:195], v[62:65]
	s_add_u32 s6, s6, 0x80
	s_addc_u32 s7, s7, 0
	s_add_u32 s8, s8, 0x80
	s_addc_u32 s9, s9, 0
	global_load_dword v244, v203, s[20:21] offset:0
	s_waitcnt vmcnt(8)
	s_barrier
	ds_read_b128 v[148:151], v138 offset:0
	ds_read_b128 v[152:155], v138 offset:2048
	ds_read_b128 v[156:159], v138 offset:4096
	ds_read_b128 v[160:163], v138 offset:6144
	ds_read_b128 v[164:167], v144 offset:0
	ds_read_b128 v[168:171], v144 offset:2048
	ds_read_b128 v[172:175], v144 offset:4096
	ds_read_b128 v[176:179], v144 offset:6144
	ds_read_b128 v[180:183], v141 offset:0
	ds_read_b128 v[184:187], v141 offset:2048
	ds_read_b128 v[188:191], v141 offset:4096
	ds_read_b128 v[192:195], v141 offset:6144
	ds_read_b128 v[228:231], v147 offset:0
	ds_read_b128 v[232:235], v147 offset:2048
	ds_read_b128 v[236:239], v147 offset:4096
	ds_read_b128 v[240:243], v147 offset:6144
	s_waitcnt lgkmcnt(8)
	v_mfma_f32_16x16x32_bf16 v[2:5], v[164:167], v[148:151], v[2:5]
	v_mfma_f32_16x16x32_bf16 v[6:9], v[168:171], v[148:151], v[6:9]
	v_mfma_f32_16x16x32_bf16 v[10:13], v[172:175], v[148:151], v[10:13]
	v_mfma_f32_16x16x32_bf16 v[14:17], v[176:179], v[148:151], v[14:17]
	v_mfma_f32_16x16x32_bf16 v[18:21], v[164:167], v[152:155], v[18:21]
	v_mfma_f32_16x16x32_bf16 v[22:25], v[168:171], v[152:155], v[22:25]
	v_mfma_f32_16x16x32_bf16 v[26:29], v[172:175], v[152:155], v[26:29]
	v_mfma_f32_16x16x32_bf16 v[30:33], v[176:179], v[152:155], v[30:33]
	v_mfma_f32_16x16x32_bf16 v[34:37], v[164:167], v[156:159], v[34:37]
	v_mfma_f32_16x16x32_bf16 v[38:41], v[168:171], v[156:159], v[38:41]
	v_mfma_f32_16x16x32_bf16 v[42:45], v[172:175], v[156:159], v[42:45]
	v_mfma_f32_16x16x32_bf16 v[46:49], v[176:179], v[156:159], v[46:49]
	v_mfma_f32_16x16x32_bf16 v[50:53], v[164:167], v[160:163], v[50:53]
	v_mfma_f32_16x16x32_bf16 v[54:57], v[168:171], v[160:163], v[54:57]
	v_mfma_f32_16x16x32_bf16 v[58:61], v[172:175], v[160:163], v[58:61]
	v_mfma_f32_16x16x32_bf16 v[62:65], v[176:179], v[160:163], v[62:65]
	global_load_dwordx4 v[148:151], v202, s[14:15] offset:0
	global_load_dwordx4 v[152:155], v202, s[14:15] offset:16
	global_load_dwordx4 v[156:159], v202, s[14:15] offset:2048
	global_load_dwordx4 v[160:163], v202, s[14:15] offset:2064
	global_load_dwordx4 v[164:167], v203, s[14:15] offset:0
	global_load_dwordx4 v[168:171], v203, s[14:15] offset:16
	global_load_dwordx4 v[172:175], v203, s[14:15] offset:2048
	global_load_dwordx4 v[176:179], v203, s[14:15] offset:2064
	s_waitcnt lgkmcnt(0)
	v_mfma_f32_16x16x32_bf16 v[2:5], v[228:231], v[180:183], v[2:5]
	s_add_u32 m0, s10, 0x18000
	v_mfma_f32_16x16x32_bf16 v[6:9], v[232:235], v[180:183], v[6:9]
	global_load_lds_dwordx4 v132, s[6:7]
	v_mfma_f32_16x16x32_bf16 v[10:13], v[236:239], v[180:183], v[10:13]
	s_add_u32 m0, s10, 0x18400
	v_mfma_f32_16x16x32_bf16 v[14:17], v[240:243], v[180:183], v[14:17]
	global_load_lds_dwordx4 v133, s[6:7]
	v_mfma_f32_16x16x32_bf16 v[18:21], v[228:231], v[184:187], v[18:21]
	s_add_u32 m0, s10, 0x18800
	v_mfma_f32_16x16x32_bf16 v[22:25], v[232:235], v[184:187], v[22:25]
	global_load_lds_dwordx4 v134, s[6:7]
	v_mfma_f32_16x16x32_bf16 v[26:29], v[236:239], v[184:187], v[26:29]
	s_add_u32 m0, s10, 0x18c00
	v_mfma_f32_16x16x32_bf16 v[30:33], v[240:243], v[184:187], v[30:33]
	global_load_lds_dwordx4 v135, s[6:7]
	v_mfma_f32_16x16x32_bf16 v[34:37], v[228:231], v[188:191], v[34:37]
	s_add_u32 m0, s11, 0x18000
	v_mfma_f32_16x16x32_bf16 v[38:41], v[232:235], v[188:191], v[38:41]
	global_load_lds_dwordx4 v136, s[8:9]
	v_mfma_f32_16x16x32_bf16 v[42:45], v[236:239], v[188:191], v[42:45]
	s_add_u32 m0, s11, 0x18400
	v_mfma_f32_16x16x32_bf16 v[46:49], v[240:243], v[188:191], v[46:49]
	global_load_lds_dwordx4 v137, s[8:9]
	v_mfma_f32_16x16x32_bf16 v[50:53], v[228:231], v[192:195], v[50:53]
	v_mfma_f32_16x16x32_bf16 v[54:57], v[232:235], v[192:195], v[54:57]
	v_mfma_f32_16x16x32_bf16 v[58:61], v[236:239], v[192:195], v[58:61]
	v_mfma_f32_16x16x32_bf16 v[62:65], v[240:243], v[192:195], v[62:65]
	s_add_u32 s6, s6, 0x80
	s_addc_u32 s7, s7, 0
	s_add_u32 s8, s8, 0x80
	s_addc_u32 s9, s9, 0
	s_add_u32 s14, s14, 0x1000000
	s_addc_u32 s15, s15, 0
	global_load_dword v244, v203, s[20:21] offset:2048
	s_add_u32 s20, s20, 0x1000000
	s_addc_u32 s21, s21, 0
	s_nop 7
	s_nop 3
	s_waitcnt vmcnt(7)
	v_lshlrev_b32_e32 v246, 16, v148
	v_and_b32_e32 v247, 0xffff0000, v148
	v_pk_fma_f32 v[66:67], v[2:3], v[246:247], v[66:67]
	v_lshlrev_b32_e32 v248, 16, v149
	v_and_b32_e32 v249, 0xffff0000, v149
	v_pk_fma_f32 v[68:69], v[4:5], v[248:249], v[68:69]
	v_lshlrev_b32_e32 v246, 16, v150
	v_and_b32_e32 v247, 0xffff0000, v150
	v_pk_fma_f32 v[70:71], v[6:7], v[246:247], v[70:71]
	v_lshlrev_b32_e32 v248, 16, v151
	v_and_b32_e32 v249, 0xffff0000, v151
	v_pk_fma_f32 v[72:73], v[8:9], v[248:249], v[72:73]
	v_lshlrev_b32_e32 v246, 16, v152
	v_and_b32_e32 v247, 0xffff0000, v152
	v_pk_fma_f32 v[74:75], v[10:11], v[246:247], v[74:75]
	v_lshlrev_b32_e32 v248, 16, v153
	v_and_b32_e32 v249, 0xffff0000, v153
	v_pk_fma_f32 v[76:77], v[12:13], v[248:249], v[76:77]
	v_lshlrev_b32_e32 v246, 16, v154
	v_and_b32_e32 v247, 0xffff0000, v154
	v_pk_fma_f32 v[78:79], v[14:15], v[246:247], v[78:79]
	v_lshlrev_b32_e32 v248, 16, v155
	v_and_b32_e32 v249, 0xffff0000, v155
	v_pk_fma_f32 v[80:81], v[16:17], v[248:249], v[80:81]
	v_lshlrev_b32_e32 v246, 16, v156
	v_and_b32_e32 v247, 0xffff0000, v156
	v_pk_fma_f32 v[82:83], v[18:19], v[246:247], v[82:83]
	v_lshlrev_b32_e32 v248, 16, v157
	v_and_b32_e32 v249, 0xffff0000, v157
	v_pk_fma_f32 v[84:85], v[20:21], v[248:249], v[84:85]
	v_lshlrev_b32_e32 v246, 16, v158
	v_and_b32_e32 v247, 0xffff0000, v158
	v_pk_fma_f32 v[86:87], v[22:23], v[246:247], v[86:87]
	v_lshlrev_b32_e32 v248, 16, v159
	v_and_b32_e32 v249, 0xffff0000, v159
	v_pk_fma_f32 v[88:89], v[24:25], v[248:249], v[88:89]
	v_lshlrev_b32_e32 v246, 16, v160
	v_and_b32_e32 v247, 0xffff0000, v160
	v_pk_fma_f32 v[90:91], v[26:27], v[246:247], v[90:91]
	v_lshlrev_b32_e32 v248, 16, v161
	v_and_b32_e32 v249, 0xffff0000, v161
	v_pk_fma_f32 v[92:93], v[28:29], v[248:249], v[92:93]
	v_lshlrev_b32_e32 v246, 16, v162
	v_and_b32_e32 v247, 0xffff0000, v162
	v_pk_fma_f32 v[94:95], v[30:31], v[246:247], v[94:95]
	v_lshlrev_b32_e32 v248, 16, v163
	v_and_b32_e32 v249, 0xffff0000, v163
	v_pk_fma_f32 v[96:97], v[32:33], v[248:249], v[96:97]
	v_lshlrev_b32_e32 v246, 16, v164
	v_and_b32_e32 v247, 0xffff0000, v164
	v_pk_fma_f32 v[98:99], v[34:35], v[246:247], v[98:99]
	v_lshlrev_b32_e32 v248, 16, v165
	v_and_b32_e32 v249, 0xffff0000, v165
	v_pk_fma_f32 v[100:101], v[36:37], v[248:249], v[100:101]
	v_lshlrev_b32_e32 v246, 16, v166
	v_and_b32_e32 v247, 0xffff0000, v166
	v_pk_fma_f32 v[102:103], v[38:39], v[246:247], v[102:103]
	v_lshlrev_b32_e32 v248, 16, v167
	v_and_b32_e32 v249, 0xffff0000, v167
	v_pk_fma_f32 v[104:105], v[40:41], v[248:249], v[104:105]
	v_lshlrev_b32_e32 v246, 16, v168
	v_and_b32_e32 v247, 0xffff0000, v168
	v_pk_fma_f32 v[106:107], v[42:43], v[246:247], v[106:107]
	v_lshlrev_b32_e32 v248, 16, v169
	v_and_b32_e32 v249, 0xffff0000, v169
	v_pk_fma_f32 v[108:109], v[44:45], v[248:249], v[108:109]
	v_lshlrev_b32_e32 v246, 16, v170
	v_and_b32_e32 v247, 0xffff0000, v170
	v_pk_fma_f32 v[110:111], v[46:47], v[246:247], v[110:111]
	v_lshlrev_b32_e32 v248, 16, v171
	v_and_b32_e32 v249, 0xffff0000, v171
	v_pk_fma_f32 v[112:113], v[48:49], v[248:249], v[112:113]
	v_lshlrev_b32_e32 v246, 16, v172
	v_and_b32_e32 v247, 0xffff0000, v172
	v_pk_fma_f32 v[114:115], v[50:51], v[246:247], v[114:115]
	v_lshlrev_b32_e32 v248, 16, v173
	v_and_b32_e32 v249, 0xffff0000, v173
	v_pk_fma_f32 v[116:117], v[52:53], v[248:249], v[116:117]
	v_lshlrev_b32_e32 v246, 16, v174
	v_and_b32_e32 v247, 0xffff0000, v174
	v_pk_fma_f32 v[118:119], v[54:55], v[246:247], v[118:119]
	v_lshlrev_b32_e32 v248, 16, v175
	v_and_b32_e32 v249, 0xffff0000, v175
	v_pk_fma_f32 v[120:121], v[56:57], v[248:249], v[120:121]
	v_lshlrev_b32_e32 v246, 16, v176
	v_and_b32_e32 v247, 0xffff0000, v176
	v_pk_fma_f32 v[122:123], v[58:59], v[246:247], v[122:123]
	v_lshlrev_b32_e32 v248, 16, v177
	v_and_b32_e32 v249, 0xffff0000, v177
	v_pk_fma_f32 v[124:125], v[60:61], v[248:249], v[124:125]
	v_lshlrev_b32_e32 v246, 16, v178
	v_and_b32_e32 v247, 0xffff0000, v178
	v_pk_fma_f32 v[126:127], v[62:63], v[246:247], v[126:127]
	v_lshlrev_b32_e32 v248, 16, v179
	v_and_b32_e32 v249, 0xffff0000, v179
	v_pk_fma_f32 v[128:129], v[64:65], v[248:249], v[128:129]
	v_mov_b32_e32 v2, 0
	v_mov_b32_e32 v3, 0
	v_mov_b32_e32 v4, 0
	v_mov_b32_e32 v5, 0
	v_mov_b32_e32 v6, 0
	v_mov_b32_e32 v7, 0
	v_mov_b32_e32 v8, 0
	v_mov_b32_e32 v9, 0
	v_mov_b32_e32 v10, 0
	v_mov_b32_e32 v11, 0
	v_mov_b32_e32 v12, 0
	v_mov_b32_e32 v13, 0
	v_mov_b32_e32 v14, 0
	v_mov_b32_e32 v15, 0
	v_mov_b32_e32 v16, 0
	v_mov_b32_e32 v17, 0
	v_mov_b32_e32 v18, 0
	v_mov_b32_e32 v19, 0
	v_mov_b32_e32 v20, 0
	v_mov_b32_e32 v21, 0
	v_mov_b32_e32 v22, 0
	v_mov_b32_e32 v23, 0
	v_mov_b32_e32 v24, 0
	v_mov_b32_e32 v25, 0
	v_mov_b32_e32 v26, 0
	v_mov_b32_e32 v27, 0
	v_mov_b32_e32 v28, 0
	v_mov_b32_e32 v29, 0
	v_mov_b32_e32 v30, 0
	v_mov_b32_e32 v31, 0
	v_mov_b32_e32 v32, 0
	v_mov_b32_e32 v33, 0
	v_mov_b32_e32 v34, 0
	v_mov_b32_e32 v35, 0
	v_mov_b32_e32 v36, 0
	v_mov_b32_e32 v37, 0
	v_mov_b32_e32 v38, 0
	v_mov_b32_e32 v39, 0
	v_mov_b32_e32 v40, 0
	v_mov_b32_e32 v41, 0
	v_mov_b32_e32 v42, 0
	v_mov_b32_e32 v43, 0
	v_mov_b32_e32 v44, 0
	v_mov_b32_e32 v45, 0
	v_mov_b32_e32 v46, 0
	v_mov_b32_e32 v47, 0
	v_mov_b32_e32 v48, 0
	v_mov_b32_e32 v49, 0
	v_mov_b32_e32 v50, 0
	v_mov_b32_e32 v51, 0
	v_mov_b32_e32 v52, 0
	v_mov_b32_e32 v53, 0
	v_mov_b32_e32 v54, 0
	v_mov_b32_e32 v55, 0
	v_mov_b32_e32 v56, 0
	v_mov_b32_e32 v57, 0
	v_mov_b32_e32 v58, 0
	v_mov_b32_e32 v59, 0
	v_mov_b32_e32 v60, 0
	v_mov_b32_e32 v61, 0
	v_mov_b32_e32 v62, 0
	v_mov_b32_e32 v63, 0
	v_mov_b32_e32 v64, 0
	v_mov_b32_e32 v65, 0
	s_waitcnt vmcnt(16)
	s_barrier
	ds_read_b128 v[148:151], v139 offset:0
	ds_read_b128 v[152:155], v139 offset:2048
	ds_read_b128 v[156:159], v139 offset:4096
	ds_read_b128 v[160:163], v139 offset:6144
	ds_read_b128 v[164:167], v145 offset:0
	ds_read_b128 v[168:171], v145 offset:2048
	ds_read_b128 v[172:175], v145 offset:4096
	ds_read_b128 v[176:179], v145 offset:6144
	ds_read_b128 v[180:183], v142 offset:0
	ds_read_b128 v[184:187], v142 offset:2048
	ds_read_b128 v[188:191], v142 offset:4096
	ds_read_b128 v[192:195], v142 offset:6144
	ds_read_b128 v[228:231], v196 offset:0
	ds_read_b128 v[232:235], v196 offset:2048
	ds_read_b128 v[236:239], v196 offset:4096
	ds_read_b128 v[240:243], v196 offset:6144
	s_waitcnt lgkmcnt(8)
	v_mfma_f32_16x16x32_bf16 v[2:5], v[164:167], v[148:151], v[2:5]
	s_mov_b32 m0, s10
	v_mfma_f32_16x16x32_bf16 v[6:9], v[168:171], v[148:151], v[6:9]
	global_load_lds_dwordx4 v132, s[6:7]
	v_mfma_f32_16x16x32_bf16 v[10:13], v[172:175], v[148:151], v[10:13]
	s_add_u32 m0, s10, 0x400
	v_mfma_f32_16x16x32_bf16 v[14:17], v[176:179], v[148:151], v[14:17]
	global_load_lds_dwordx4 v133, s[6:7]
	v_mfma_f32_16x16x32_bf16 v[18:21], v[164:167], v[152:155], v[18:21]
	s_add_u32 m0, s10, 0x800
	v_mfma_f32_16x16x32_bf16 v[22:25], v[168:171], v[152:155], v[22:25]
	global_load_lds_dwordx4 v134, s[6:7]
	v_mfma_f32_16x16x32_bf16 v[26:29], v[172:175], v[152:155], v[26:29]
	s_add_u32 m0, s10, 0xc00
	v_mfma_f32_16x16x32_bf16 v[30:33], v[176:179], v[152:155], v[30:33]
	global_load_lds_dwordx4 v135, s[6:7]
	v_mfma_f32_16x16x32_bf16 v[34:37], v[164:167], v[156:159], v[34:37]
	s_mov_b32 m0, s11
	v_mfma_f32_16x16x32_bf16 v[38:41], v[168:171], v[156:159], v[38:41]
	global_load_lds_dwordx4 v136, s[8:9]
	v_mfma_f32_16x16x32_bf16 v[42:45], v[172:175], v[156:159], v[42:45]
	s_add_u32 m0, s11, 0x400
	v_mfma_f32_16x16x32_bf16 v[46:49], v[176:179], v[156:159], v[46:49]
	global_load_lds_dwordx4 v137, s[8:9]
	v_mfma_f32_16x16x32_bf16 v[50:53], v[164:167], v[160:163], v[50:53]
	v_mfma_f32_16x16x32_bf16 v[54:57], v[168:171], v[160:163], v[54:57]
	v_mfma_f32_16x16x32_bf16 v[58:61], v[172:175], v[160:163], v[58:61]
	v_mfma_f32_16x16x32_bf16 v[62:65], v[176:179], v[160:163], v[62:65]
	s_waitcnt lgkmcnt(0)
	v_mfma_f32_16x16x32_bf16 v[2:5], v[228:231], v[180:183], v[2:5]
	v_mfma_f32_16x16x32_bf16 v[6:9], v[232:235], v[180:183], v[6:9]
	v_mfma_f32_16x16x32_bf16 v[10:13], v[236:239], v[180:183], v[10:13]
	v_mfma_f32_16x16x32_bf16 v[14:17], v[240:243], v[180:183], v[14:17]
	v_mfma_f32_16x16x32_bf16 v[18:21], v[228:231], v[184:187], v[18:21]
	v_mfma_f32_16x16x32_bf16 v[22:25], v[232:235], v[184:187], v[22:25]
	v_mfma_f32_16x16x32_bf16 v[26:29], v[236:239], v[184:187], v[26:29]
	v_mfma_f32_16x16x32_bf16 v[30:33], v[240:243], v[184:187], v[30:33]
	v_mfma_f32_16x16x32_bf16 v[34:37], v[228:231], v[188:191], v[34:37]
	v_mfma_f32_16x16x32_bf16 v[38:41], v[232:235], v[188:191], v[38:41]
	v_mfma_f32_16x16x32_bf16 v[42:45], v[236:239], v[188:191], v[42:45]
	v_mfma_f32_16x16x32_bf16 v[46:49], v[240:243], v[188:191], v[46:49]
	v_mfma_f32_16x16x32_bf16 v[50:53], v[228:231], v[192:195], v[50:53]
	v_mfma_f32_16x16x32_bf16 v[54:57], v[232:235], v[192:195], v[54:57]
	v_mfma_f32_16x16x32_bf16 v[58:61], v[236:239], v[192:195], v[58:61]
	v_mfma_f32_16x16x32_bf16 v[62:65], v[240:243], v[192:195], v[62:65]
	s_add_u32 s6, s6, 0x80
	s_addc_u32 s7, s7, 0
	s_add_u32 s8, s8, 0x80
	s_addc_u32 s9, s9, 0
	global_load_dword v244, v202, s[20:21] offset:0
	s_waitcnt vmcnt(8)
	s_barrier
	ds_read_b128 v[148:151], v140 offset:0
	ds_read_b128 v[152:155], v140 offset:2048
	ds_read_b128 v[156:159], v140 offset:4096
	ds_read_b128 v[160:163], v140 offset:6144
	ds_read_b128 v[164:167], v146 offset:0
	ds_read_b128 v[168:171], v146 offset:2048
	ds_read_b128 v[172:175], v146 offset:4096
	ds_read_b128 v[176:179], v146 offset:6144
	ds_read_b128 v[180:183], v143 offset:0
	ds_read_b128 v[184:187], v143 offset:2048
	ds_read_b128 v[188:191], v143 offset:4096
	ds_read_b128 v[192:195], v143 offset:6144
	ds_read_b128 v[228:231], v197 offset:0
	ds_read_b128 v[232:235], v197 offset:2048
	ds_read_b128 v[236:239], v197 offset:4096
	ds_read_b128 v[240:243], v197 offset:6144
	s_waitcnt lgkmcnt(8)
	v_mfma_f32_16x16x32_bf16 v[2:5], v[164:167], v[148:151], v[2:5]
	s_add_u32 m0, s10, 0xc000
	v_mfma_f32_16x16x32_bf16 v[6:9], v[168:171], v[148:151], v[6:9]
	global_load_lds_dwordx4 v132, s[6:7]
	v_mfma_f32_16x16x32_bf16 v[10:13], v[172:175], v[148:151], v[10:13]
	s_add_u32 m0, s10, 0xc400
	v_mfma_f32_16x16x32_bf16 v[14:17], v[176:179], v[148:151], v[14:17]
	global_load_lds_dwordx4 v133, s[6:7]
	v_mfma_f32_16x16x32_bf16 v[18:21], v[164:167], v[152:155], v[18:21]
	s_add_u32 m0, s10, 0xc800
	v_mfma_f32_16x16x32_bf16 v[22:25], v[168:171], v[152:155], v[22:25]
	global_load_lds_dwordx4 v134, s[6:7]
	v_mfma_f32_16x16x32_bf16 v[26:29], v[172:175], v[152:155], v[26:29]
	s_add_u32 m0, s10, 0xcc00
	v_mfma_f32_16x16x32_bf16 v[30:33], v[176:179], v[152:155], v[30:33]
	global_load_lds_dwordx4 v135, s[6:7]
	v_mfma_f32_16x16x32_bf16 v[34:37], v[164:167], v[156:159], v[34:37]
	s_add_u32 m0, s11, 0xc000
	v_mfma_f32_16x16x32_bf16 v[38:41], v[168:171], v[156:159], v[38:41]
	global_load_lds_dwordx4 v136, s[8:9]
	v_mfma_f32_16x16x32_bf16 v[42:45], v[172:175], v[156:159], v[42:45]
	s_add_u32 m0, s11, 0xc400
	v_mfma_f32_16x16x32_bf16 v[46:49], v[176:179], v[156:159], v[46:49]
	global_load_lds_dwordx4 v137, s[8:9]
	v_mfma_f32_16x16x32_bf16 v[50:53], v[164:167], v[160:163], v[50:53]
	v_mfma_f32_16x16x32_bf16 v[54:57], v[168:171], v[160:163], v[54:57]
	v_mfma_f32_16x16x32_bf16 v[58:61], v[172:175], v[160:163], v[58:61]
	v_mfma_f32_16x16x32_bf16 v[62:65], v[176:179], v[160:163], v[62:65]
	s_waitcnt lgkmcnt(0)
	v_mfma_f32_16x16x32_bf16 v[2:5], v[228:231], v[180:183], v[2:5]
	v_mfma_f32_16x16x32_bf16 v[6:9], v[232:235], v[180:183], v[6:9]
	v_mfma_f32_16x16x32_bf16 v[10:13], v[236:239], v[180:183], v[10:13]
	v_mfma_f32_16x16x32_bf16 v[14:17], v[240:243], v[180:183], v[14:17]
	v_mfma_f32_16x16x32_bf16 v[18:21], v[228:231], v[184:187], v[18:21]
	v_mfma_f32_16x16x32_bf16 v[22:25], v[232:235], v[184:187], v[22:25]
	v_mfma_f32_16x16x32_bf16 v[26:29], v[236:239], v[184:187], v[26:29]
	v_mfma_f32_16x16x32_bf16 v[30:33], v[240:243], v[184:187], v[30:33]
	v_mfma_f32_16x16x32_bf16 v[34:37], v[228:231], v[188:191], v[34:37]
	v_mfma_f32_16x16x32_bf16 v[38:41], v[232:235], v[188:191], v[38:41]
	v_mfma_f32_16x16x32_bf16 v[42:45], v[236:239], v[188:191], v[42:45]
	v_mfma_f32_16x16x32_bf16 v[46:49], v[240:243], v[188:191], v[46:49]
	v_mfma_f32_16x16x32_bf16 v[50:53], v[228:231], v[192:195], v[50:53]
	v_mfma_f32_16x16x32_bf16 v[54:57], v[232:235], v[192:195], v[54:57]
	v_mfma_f32_16x16x32_bf16 v[58:61], v[236:239], v[192:195], v[58:61]
	v_mfma_f32_16x16x32_bf16 v[62:65], v[240:243], v[192:195], v[62:65]
	s_add_u32 s6, s6, 0x80
	s_addc_u32 s7, s7, 0
	s_add_u32 s8, s8, 0x7fe80
	s_addc_u32 s9, s9, 0
	global_load_dword v244, v202, s[20:21] offset:2048
	s_waitcnt vmcnt(8)
	s_barrier
	ds_read_b128 v[148:151], v138 offset:0
	ds_read_b128 v[152:155], v138 offset:2048
	ds_read_b128 v[156:159], v138 offset:4096
	ds_read_b128 v[160:163], v138 offset:6144
	ds_read_b128 v[164:167], v144 offset:0
	ds_read_b128 v[168:171], v144 offset:2048
	ds_read_b128 v[172:175], v144 offset:4096
	ds_read_b128 v[176:179], v144 offset:6144
	ds_read_b128 v[180:183], v141 offset:0
	ds_read_b128 v[184:187], v141 offset:2048
	ds_read_b128 v[188:191], v141 offset:4096
	ds_read_b128 v[192:195], v141 offset:6144
	ds_read_b128 v[228:231], v147 offset:0
	ds_read_b128 v[232:235], v147 offset:2048
	ds_read_b128 v[236:239], v147 offset:4096
	ds_read_b128 v[240:243], v147 offset:6144
	s_waitcnt lgkmcnt(8)
	v_mfma_f32_16x16x32_bf16 v[2:5], v[164:167], v[148:151], v[2:5]
	s_add_u32 m0, s10, 0x18000
	v_mfma_f32_16x16x32_bf16 v[6:9], v[168:171], v[148:151], v[6:9]
	global_load_lds_dwordx4 v132, s[6:7]
	v_mfma_f32_16x16x32_bf16 v[10:13], v[172:175], v[148:151], v[10:13]
	s_add_u32 m0, s10, 0x18400
	v_mfma_f32_16x16x32_bf16 v[14:17], v[176:179], v[148:151], v[14:17]
	global_load_lds_dwordx4 v133, s[6:7]
	v_mfma_f32_16x16x32_bf16 v[18:21], v[164:167], v[152:155], v[18:21]
	s_add_u32 m0, s10, 0x18800
	v_mfma_f32_16x16x32_bf16 v[22:25], v[168:171], v[152:155], v[22:25]
	global_load_lds_dwordx4 v134, s[6:7]
	v_mfma_f32_16x16x32_bf16 v[26:29], v[172:175], v[152:155], v[26:29]
	s_add_u32 m0, s10, 0x18c00
	v_mfma_f32_16x16x32_bf16 v[30:33], v[176:179], v[152:155], v[30:33]
	global_load_lds_dwordx4 v135, s[6:7]
	v_mfma_f32_16x16x32_bf16 v[34:37], v[164:167], v[156:159], v[34:37]
	s_add_u32 m0, s11, 0x18000
	v_mfma_f32_16x16x32_bf16 v[38:41], v[168:171], v[156:159], v[38:41]
	global_load_lds_dwordx4 v136, s[8:9]
	v_mfma_f32_16x16x32_bf16 v[42:45], v[172:175], v[156:159], v[42:45]
	s_add_u32 m0, s11, 0x18400
	v_mfma_f32_16x16x32_bf16 v[46:49], v[176:179], v[156:159], v[46:49]
	global_load_lds_dwordx4 v137, s[8:9]
	v_mfma_f32_16x16x32_bf16 v[50:53], v[164:167], v[160:163], v[50:53]
	v_mfma_f32_16x16x32_bf16 v[54:57], v[168:171], v[160:163], v[54:57]
	v_mfma_f32_16x16x32_bf16 v[58:61], v[172:175], v[160:163], v[58:61]
	v_mfma_f32_16x16x32_bf16 v[62:65], v[176:179], v[160:163], v[62:65]
	s_waitcnt lgkmcnt(0)
	v_mfma_f32_16x16x32_bf16 v[2:5], v[228:231], v[180:183], v[2:5]
	v_mfma_f32_16x16x32_bf16 v[6:9], v[232:235], v[180:183], v[6:9]
	v_mfma_f32_16x16x32_bf16 v[10:13], v[236:239], v[180:183], v[10:13]
	v_mfma_f32_16x16x32_bf16 v[14:17], v[240:243], v[180:183], v[14:17]
	v_mfma_f32_16x16x32_bf16 v[18:21], v[228:231], v[184:187], v[18:21]
	v_mfma_f32_16x16x32_bf16 v[22:25], v[232:235], v[184:187], v[22:25]
	v_mfma_f32_16x16x32_bf16 v[26:29], v[236:239], v[184:187], v[26:29]
	v_mfma_f32_16x16x32_bf16 v[30:33], v[240:243], v[184:187], v[30:33]
	v_mfma_f32_16x16x32_bf16 v[34:37], v[228:231], v[188:191], v[34:37]
	v_mfma_f32_16x16x32_bf16 v[38:41], v[232:235], v[188:191], v[38:41]
	v_mfma_f32_16x16x32_bf16 v[42:45], v[236:239], v[188:191], v[42:45]
	v_mfma_f32_16x16x32_bf16 v[46:49], v[240:243], v[188:191], v[46:49]
	v_mfma_f32_16x16x32_bf16 v[50:53], v[228:231], v[192:195], v[50:53]
	v_mfma_f32_16x16x32_bf16 v[54:57], v[232:235], v[192:195], v[54:57]
	v_mfma_f32_16x16x32_bf16 v[58:61], v[236:239], v[192:195], v[58:61]
	v_mfma_f32_16x16x32_bf16 v[62:65], v[240:243], v[192:195], v[62:65]
	s_add_u32 s6, s6, 0x80
	s_addc_u32 s7, s7, 0
	s_add_u32 s8, s8, 0x80
	s_addc_u32 s9, s9, 0
	global_load_dword v244, v203, s[20:21] offset:0
	s_waitcnt vmcnt(8)
	s_barrier
	ds_read_b128 v[148:151], v139 offset:0
	ds_read_b128 v[152:155], v139 offset:2048
	ds_read_b128 v[156:159], v139 offset:4096
	ds_read_b128 v[160:163], v139 offset:6144
	ds_read_b128 v[164:167], v145 offset:0
	ds_read_b128 v[168:171], v145 offset:2048
	ds_read_b128 v[172:175], v145 offset:4096
	ds_read_b128 v[176:179], v145 offset:6144
	ds_read_b128 v[180:183], v142 offset:0
	ds_read_b128 v[184:187], v142 offset:2048
	ds_read_b128 v[188:191], v142 offset:4096
	ds_read_b128 v[192:195], v142 offset:6144
	ds_read_b128 v[228:231], v196 offset:0
	ds_read_b128 v[232:235], v196 offset:2048
	ds_read_b128 v[236:239], v196 offset:4096
	ds_read_b128 v[240:243], v196 offset:6144
	s_waitcnt lgkmcnt(8)
	v_mfma_f32_16x16x32_bf16 v[2:5], v[164:167], v[148:151], v[2:5]
	v_mfma_f32_16x16x32_bf16 v[6:9], v[168:171], v[148:151], v[6:9]
	v_mfma_f32_16x16x32_bf16 v[10:13], v[172:175], v[148:151], v[10:13]
	v_mfma_f32_16x16x32_bf16 v[14:17], v[176:179], v[148:151], v[14:17]
	v_mfma_f32_16x16x32_bf16 v[18:21], v[164:167], v[152:155], v[18:21]
	v_mfma_f32_16x16x32_bf16 v[22:25], v[168:171], v[152:155], v[22:25]
	v_mfma_f32_16x16x32_bf16 v[26:29], v[172:175], v[152:155], v[26:29]
	v_mfma_f32_16x16x32_bf16 v[30:33], v[176:179], v[152:155], v[30:33]
	v_mfma_f32_16x16x32_bf16 v[34:37], v[164:167], v[156:159], v[34:37]
	v_mfma_f32_16x16x32_bf16 v[38:41], v[168:171], v[156:159], v[38:41]
	v_mfma_f32_16x16x32_bf16 v[42:45], v[172:175], v[156:159], v[42:45]
	v_mfma_f32_16x16x32_bf16 v[46:49], v[176:179], v[156:159], v[46:49]
	v_mfma_f32_16x16x32_bf16 v[50:53], v[164:167], v[160:163], v[50:53]
	v_mfma_f32_16x16x32_bf16 v[54:57], v[168:171], v[160:163], v[54:57]
	v_mfma_f32_16x16x32_bf16 v[58:61], v[172:175], v[160:163], v[58:61]
	v_mfma_f32_16x16x32_bf16 v[62:65], v[176:179], v[160:163], v[62:65]
	global_load_dwordx4 v[148:151], v202, s[14:15] offset:0
	global_load_dwordx4 v[152:155], v202, s[14:15] offset:16
	global_load_dwordx4 v[156:159], v202, s[14:15] offset:2048
	global_load_dwordx4 v[160:163], v202, s[14:15] offset:2064
	global_load_dwordx4 v[164:167], v203, s[14:15] offset:0
	global_load_dwordx4 v[168:171], v203, s[14:15] offset:16
	global_load_dwordx4 v[172:175], v203, s[14:15] offset:2048
	global_load_dwordx4 v[176:179], v203, s[14:15] offset:2064
	s_waitcnt lgkmcnt(0)
	v_mfma_f32_16x16x32_bf16 v[2:5], v[228:231], v[180:183], v[2:5]
	s_mov_b32 m0, s10
	v_mfma_f32_16x16x32_bf16 v[6:9], v[232:235], v[180:183], v[6:9]
	global_load_lds_dwordx4 v132, s[6:7]
	v_mfma_f32_16x16x32_bf16 v[10:13], v[236:239], v[180:183], v[10:13]
	s_add_u32 m0, s10, 0x400
	v_mfma_f32_16x16x32_bf16 v[14:17], v[240:243], v[180:183], v[14:17]
	global_load_lds_dwordx4 v133, s[6:7]
	v_mfma_f32_16x16x32_bf16 v[18:21], v[228:231], v[184:187], v[18:21]
	s_add_u32 m0, s10, 0x800
	v_mfma_f32_16x16x32_bf16 v[22:25], v[232:235], v[184:187], v[22:25]
	global_load_lds_dwordx4 v134, s[6:7]
	v_mfma_f32_16x16x32_bf16 v[26:29], v[236:239], v[184:187], v[26:29]
	s_add_u32 m0, s10, 0xc00
	v_mfma_f32_16x16x32_bf16 v[30:33], v[240:243], v[184:187], v[30:33]
	global_load_lds_dwordx4 v135, s[6:7]
	v_mfma_f32_16x16x32_bf16 v[34:37], v[228:231], v[188:191], v[34:37]
	s_mov_b32 m0, s11
	v_mfma_f32_16x16x32_bf16 v[38:41], v[232:235], v[188:191], v[38:41]
	global_load_lds_dwordx4 v136, s[8:9]
	v_mfma_f32_16x16x32_bf16 v[42:45], v[236:239], v[188:191], v[42:45]
	s_add_u32 m0, s11, 0x400
	v_mfma_f32_16x16x32_bf16 v[46:49], v[240:243], v[188:191], v[46:49]
	global_load_lds_dwordx4 v137, s[8:9]
	v_mfma_f32_16x16x32_bf16 v[50:53], v[228:231], v[192:195], v[50:53]
	v_mfma_f32_16x16x32_bf16 v[54:57], v[232:235], v[192:195], v[54:57]
	v_mfma_f32_16x16x32_bf16 v[58:61], v[236:239], v[192:195], v[58:61]
	v_mfma_f32_16x16x32_bf16 v[62:65], v[240:243], v[192:195], v[62:65]
	s_add_u32 s6, s6, 0x80
	s_addc_u32 s7, s7, 0
	s_add_u32 s8, s8, 0x80
	s_addc_u32 s9, s9, 0
	s_add_u32 s14, s14, 0x1000000
	s_addc_u32 s15, s15, 0
	global_load_dword v244, v203, s[20:21] offset:2048
	s_add_u32 s20, s20, 0x1000000
	s_addc_u32 s21, s21, 0
	s_nop 7
	s_nop 3
	s_waitcnt vmcnt(7)
	v_lshlrev_b32_e32 v246, 16, v148
	v_and_b32_e32 v247, 0xffff0000, v148
	v_pk_fma_f32 v[66:67], v[2:3], v[246:247], v[66:67]
	v_lshlrev_b32_e32 v248, 16, v149
	v_and_b32_e32 v249, 0xffff0000, v149
	v_pk_fma_f32 v[68:69], v[4:5], v[248:249], v[68:69]
	v_lshlrev_b32_e32 v246, 16, v150
	v_and_b32_e32 v247, 0xffff0000, v150
	v_pk_fma_f32 v[70:71], v[6:7], v[246:247], v[70:71]
	v_lshlrev_b32_e32 v248, 16, v151
	v_and_b32_e32 v249, 0xffff0000, v151
	v_pk_fma_f32 v[72:73], v[8:9], v[248:249], v[72:73]
	v_lshlrev_b32_e32 v246, 16, v152
	v_and_b32_e32 v247, 0xffff0000, v152
	v_pk_fma_f32 v[74:75], v[10:11], v[246:247], v[74:75]
	v_lshlrev_b32_e32 v248, 16, v153
	v_and_b32_e32 v249, 0xffff0000, v153
	v_pk_fma_f32 v[76:77], v[12:13], v[248:249], v[76:77]
	v_lshlrev_b32_e32 v246, 16, v154
	v_and_b32_e32 v247, 0xffff0000, v154
	v_pk_fma_f32 v[78:79], v[14:15], v[246:247], v[78:79]
	v_lshlrev_b32_e32 v248, 16, v155
	v_and_b32_e32 v249, 0xffff0000, v155
	v_pk_fma_f32 v[80:81], v[16:17], v[248:249], v[80:81]
	v_lshlrev_b32_e32 v246, 16, v156
	v_and_b32_e32 v247, 0xffff0000, v156
	v_pk_fma_f32 v[82:83], v[18:19], v[246:247], v[82:83]
	v_lshlrev_b32_e32 v248, 16, v157
	v_and_b32_e32 v249, 0xffff0000, v157
	v_pk_fma_f32 v[84:85], v[20:21], v[248:249], v[84:85]
	v_lshlrev_b32_e32 v246, 16, v158
	v_and_b32_e32 v247, 0xffff0000, v158
	v_pk_fma_f32 v[86:87], v[22:23], v[246:247], v[86:87]
	v_lshlrev_b32_e32 v248, 16, v159
	v_and_b32_e32 v249, 0xffff0000, v159
	v_pk_fma_f32 v[88:89], v[24:25], v[248:249], v[88:89]
	v_lshlrev_b32_e32 v246, 16, v160
	v_and_b32_e32 v247, 0xffff0000, v160
	v_pk_fma_f32 v[90:91], v[26:27], v[246:247], v[90:91]
	v_lshlrev_b32_e32 v248, 16, v161
	v_and_b32_e32 v249, 0xffff0000, v161
	v_pk_fma_f32 v[92:93], v[28:29], v[248:249], v[92:93]
	v_lshlrev_b32_e32 v246, 16, v162
	v_and_b32_e32 v247, 0xffff0000, v162
	v_pk_fma_f32 v[94:95], v[30:31], v[246:247], v[94:95]
	v_lshlrev_b32_e32 v248, 16, v163
	v_and_b32_e32 v249, 0xffff0000, v163
	v_pk_fma_f32 v[96:97], v[32:33], v[248:249], v[96:97]
	v_lshlrev_b32_e32 v246, 16, v164
	v_and_b32_e32 v247, 0xffff0000, v164
	v_pk_fma_f32 v[98:99], v[34:35], v[246:247], v[98:99]
	v_lshlrev_b32_e32 v248, 16, v165
	v_and_b32_e32 v249, 0xffff0000, v165
	v_pk_fma_f32 v[100:101], v[36:37], v[248:249], v[100:101]
	v_lshlrev_b32_e32 v246, 16, v166
	v_and_b32_e32 v247, 0xffff0000, v166
	v_pk_fma_f32 v[102:103], v[38:39], v[246:247], v[102:103]
	v_lshlrev_b32_e32 v248, 16, v167
	v_and_b32_e32 v249, 0xffff0000, v167
	v_pk_fma_f32 v[104:105], v[40:41], v[248:249], v[104:105]
	v_lshlrev_b32_e32 v246, 16, v168
	v_and_b32_e32 v247, 0xffff0000, v168
	v_pk_fma_f32 v[106:107], v[42:43], v[246:247], v[106:107]
	v_lshlrev_b32_e32 v248, 16, v169
	v_and_b32_e32 v249, 0xffff0000, v169
	v_pk_fma_f32 v[108:109], v[44:45], v[248:249], v[108:109]
	v_lshlrev_b32_e32 v246, 16, v170
	v_and_b32_e32 v247, 0xffff0000, v170
	v_pk_fma_f32 v[110:111], v[46:47], v[246:247], v[110:111]
	v_lshlrev_b32_e32 v248, 16, v171
	v_and_b32_e32 v249, 0xffff0000, v171
	v_pk_fma_f32 v[112:113], v[48:49], v[248:249], v[112:113]
	v_lshlrev_b32_e32 v246, 16, v172
	v_and_b32_e32 v247, 0xffff0000, v172
	v_pk_fma_f32 v[114:115], v[50:51], v[246:247], v[114:115]
	v_lshlrev_b32_e32 v248, 16, v173
	v_and_b32_e32 v249, 0xffff0000, v173
	v_pk_fma_f32 v[116:117], v[52:53], v[248:249], v[116:117]
	v_lshlrev_b32_e32 v246, 16, v174
	v_and_b32_e32 v247, 0xffff0000, v174
	v_pk_fma_f32 v[118:119], v[54:55], v[246:247], v[118:119]
	v_lshlrev_b32_e32 v248, 16, v175
	v_and_b32_e32 v249, 0xffff0000, v175
	v_pk_fma_f32 v[120:121], v[56:57], v[248:249], v[120:121]
	v_lshlrev_b32_e32 v246, 16, v176
	v_and_b32_e32 v247, 0xffff0000, v176
	v_pk_fma_f32 v[122:123], v[58:59], v[246:247], v[122:123]
	v_lshlrev_b32_e32 v248, 16, v177
	v_and_b32_e32 v249, 0xffff0000, v177
	v_pk_fma_f32 v[124:125], v[60:61], v[248:249], v[124:125]
	v_lshlrev_b32_e32 v246, 16, v178
	v_and_b32_e32 v247, 0xffff0000, v178
	v_pk_fma_f32 v[126:127], v[62:63], v[246:247], v[126:127]
	v_lshlrev_b32_e32 v248, 16, v179
	v_and_b32_e32 v249, 0xffff0000, v179
	v_pk_fma_f32 v[128:129], v[64:65], v[248:249], v[128:129]
	v_mov_b32_e32 v2, 0
	v_mov_b32_e32 v3, 0
	v_mov_b32_e32 v4, 0
	v_mov_b32_e32 v5, 0
	v_mov_b32_e32 v6, 0
	v_mov_b32_e32 v7, 0
	v_mov_b32_e32 v8, 0
	v_mov_b32_e32 v9, 0
	v_mov_b32_e32 v10, 0
	v_mov_b32_e32 v11, 0
	v_mov_b32_e32 v12, 0
	v_mov_b32_e32 v13, 0
	v_mov_b32_e32 v14, 0
	v_mov_b32_e32 v15, 0
	v_mov_b32_e32 v16, 0
	v_mov_b32_e32 v17, 0
	v_mov_b32_e32 v18, 0
	v_mov_b32_e32 v19, 0
	v_mov_b32_e32 v20, 0
	v_mov_b32_e32 v21, 0
	v_mov_b32_e32 v22, 0
	v_mov_b32_e32 v23, 0
	v_mov_b32_e32 v24, 0
	v_mov_b32_e32 v25, 0
	v_mov_b32_e32 v26, 0
	v_mov_b32_e32 v27, 0
	v_mov_b32_e32 v28, 0
	v_mov_b32_e32 v29, 0
	v_mov_b32_e32 v30, 0
	v_mov_b32_e32 v31, 0
	v_mov_b32_e32 v32, 0
	v_mov_b32_e32 v33, 0
	v_mov_b32_e32 v34, 0
	v_mov_b32_e32 v35, 0
	v_mov_b32_e32 v36, 0
	v_mov_b32_e32 v37, 0
	v_mov_b32_e32 v38, 0
	v_mov_b32_e32 v39, 0
	v_mov_b32_e32 v40, 0
	v_mov_b32_e32 v41, 0
	v_mov_b32_e32 v42, 0
	v_mov_b32_e32 v43, 0
	v_mov_b32_e32 v44, 0
	v_mov_b32_e32 v45, 0
	v_mov_b32_e32 v46, 0
	v_mov_b32_e32 v47, 0
	v_mov_b32_e32 v48, 0
	v_mov_b32_e32 v49, 0
	v_mov_b32_e32 v50, 0
	v_mov_b32_e32 v51, 0
	v_mov_b32_e32 v52, 0
	v_mov_b32_e32 v53, 0
	v_mov_b32_e32 v54, 0
	v_mov_b32_e32 v55, 0
	v_mov_b32_e32 v56, 0
	v_mov_b32_e32 v57, 0
	v_mov_b32_e32 v58, 0
	v_mov_b32_e32 v59, 0
	v_mov_b32_e32 v60, 0
	v_mov_b32_e32 v61, 0
	v_mov_b32_e32 v62, 0
	v_mov_b32_e32 v63, 0
	v_mov_b32_e32 v64, 0
	v_mov_b32_e32 v65, 0
	s_waitcnt vmcnt(16)
	s_barrier
	ds_read_b128 v[148:151], v140 offset:0
	ds_read_b128 v[152:155], v140 offset:2048
	ds_read_b128 v[156:159], v140 offset:4096
	ds_read_b128 v[160:163], v140 offset:6144
	ds_read_b128 v[164:167], v146 offset:0
	ds_read_b128 v[168:171], v146 offset:2048
	ds_read_b128 v[172:175], v146 offset:4096
	ds_read_b128 v[176:179], v146 offset:6144
	ds_read_b128 v[180:183], v143 offset:0
	ds_read_b128 v[184:187], v143 offset:2048
	ds_read_b128 v[188:191], v143 offset:4096
	ds_read_b128 v[192:195], v143 offset:6144
	ds_read_b128 v[228:231], v197 offset:0
	ds_read_b128 v[232:235], v197 offset:2048
	ds_read_b128 v[236:239], v197 offset:4096
	ds_read_b128 v[240:243], v197 offset:6144
	s_waitcnt lgkmcnt(8)
	v_mfma_f32_16x16x32_bf16 v[2:5], v[164:167], v[148:151], v[2:5]
	s_add_u32 m0, s10, 0xc000
	v_mfma_f32_16x16x32_bf16 v[6:9], v[168:171], v[148:151], v[6:9]
	global_load_lds_dwordx4 v132, s[6:7]
	v_mfma_f32_16x16x32_bf16 v[10:13], v[172:175], v[148:151], v[10:13]
	s_add_u32 m0, s10, 0xc400
	v_mfma_f32_16x16x32_bf16 v[14:17], v[176:179], v[148:151], v[14:17]
	global_load_lds_dwordx4 v133, s[6:7]
	v_mfma_f32_16x16x32_bf16 v[18:21], v[164:167], v[152:155], v[18:21]
	s_add_u32 m0, s10, 0xc800
	v_mfma_f32_16x16x32_bf16 v[22:25], v[168:171], v[152:155], v[22:25]
	global_load_lds_dwordx4 v134, s[6:7]
	v_mfma_f32_16x16x32_bf16 v[26:29], v[172:175], v[152:155], v[26:29]
	s_add_u32 m0, s10, 0xcc00
	v_mfma_f32_16x16x32_bf16 v[30:33], v[176:179], v[152:155], v[30:33]
	global_load_lds_dwordx4 v135, s[6:7]
	v_mfma_f32_16x16x32_bf16 v[34:37], v[164:167], v[156:159], v[34:37]
	s_add_u32 m0, s11, 0xc000
	v_mfma_f32_16x16x32_bf16 v[38:41], v[168:171], v[156:159], v[38:41]
	global_load_lds_dwordx4 v136, s[8:9]
	v_mfma_f32_16x16x32_bf16 v[42:45], v[172:175], v[156:159], v[42:45]
	s_add_u32 m0, s11, 0xc400
	v_mfma_f32_16x16x32_bf16 v[46:49], v[176:179], v[156:159], v[46:49]
	global_load_lds_dwordx4 v137, s[8:9]
	v_mfma_f32_16x16x32_bf16 v[50:53], v[164:167], v[160:163], v[50:53]
	v_mfma_f32_16x16x32_bf16 v[54:57], v[168:171], v[160:163], v[54:57]
	v_mfma_f32_16x16x32_bf16 v[58:61], v[172:175], v[160:163], v[58:61]
	v_mfma_f32_16x16x32_bf16 v[62:65], v[176:179], v[160:163], v[62:65]
	s_waitcnt lgkmcnt(0)
	v_mfma_f32_16x16x32_bf16 v[2:5], v[228:231], v[180:183], v[2:5]
	v_mfma_f32_16x16x32_bf16 v[6:9], v[232:235], v[180:183], v[6:9]
	v_mfma_f32_16x16x32_bf16 v[10:13], v[236:239], v[180:183], v[10:13]
	v_mfma_f32_16x16x32_bf16 v[14:17], v[240:243], v[180:183], v[14:17]
	v_mfma_f32_16x16x32_bf16 v[18:21], v[228:231], v[184:187], v[18:21]
	v_mfma_f32_16x16x32_bf16 v[22:25], v[232:235], v[184:187], v[22:25]
	v_mfma_f32_16x16x32_bf16 v[26:29], v[236:239], v[184:187], v[26:29]
	v_mfma_f32_16x16x32_bf16 v[30:33], v[240:243], v[184:187], v[30:33]
	v_mfma_f32_16x16x32_bf16 v[34:37], v[228:231], v[188:191], v[34:37]
	v_mfma_f32_16x16x32_bf16 v[38:41], v[232:235], v[188:191], v[38:41]
	v_mfma_f32_16x16x32_bf16 v[42:45], v[236:239], v[188:191], v[42:45]
	v_mfma_f32_16x16x32_bf16 v[46:49], v[240:243], v[188:191], v[46:49]
	v_mfma_f32_16x16x32_bf16 v[50:53], v[228:231], v[192:195], v[50:53]
	v_mfma_f32_16x16x32_bf16 v[54:57], v[232:235], v[192:195], v[54:57]
	v_mfma_f32_16x16x32_bf16 v[58:61], v[236:239], v[192:195], v[58:61]
	v_mfma_f32_16x16x32_bf16 v[62:65], v[240:243], v[192:195], v[62:65]
	s_add_u32 s6, s6, 0x80
	s_addc_u32 s7, s7, 0
	s_add_u32 s8, s8, 0x80
	s_addc_u32 s9, s9, 0
	global_load_dword v244, v202, s[20:21] offset:0
	s_waitcnt vmcnt(8)
	s_barrier
	ds_read_b128 v[148:151], v138 offset:0
	ds_read_b128 v[152:155], v138 offset:2048
	ds_read_b128 v[156:159], v138 offset:4096
	ds_read_b128 v[160:163], v138 offset:6144
	ds_read_b128 v[164:167], v144 offset:0
	ds_read_b128 v[168:171], v144 offset:2048
	ds_read_b128 v[172:175], v144 offset:4096
	ds_read_b128 v[176:179], v144 offset:6144
	ds_read_b128 v[180:183], v141 offset:0
	ds_read_b128 v[184:187], v141 offset:2048
	ds_read_b128 v[188:191], v141 offset:4096
	ds_read_b128 v[192:195], v141 offset:6144
	ds_read_b128 v[228:231], v147 offset:0
	ds_read_b128 v[232:235], v147 offset:2048
	ds_read_b128 v[236:239], v147 offset:4096
	ds_read_b128 v[240:243], v147 offset:6144
	s_waitcnt lgkmcnt(8)
	v_mfma_f32_16x16x32_bf16 v[2:5], v[164:167], v[148:151], v[2:5]
	s_add_u32 m0, s10, 0x18000
	v_mfma_f32_16x16x32_bf16 v[6:9], v[168:171], v[148:151], v[6:9]
	global_load_lds_dwordx4 v132, s[6:7]
	v_mfma_f32_16x16x32_bf16 v[10:13], v[172:175], v[148:151], v[10:13]
	s_add_u32 m0, s10, 0x18400
	v_mfma_f32_16x16x32_bf16 v[14:17], v[176:179], v[148:151], v[14:17]
	global_load_lds_dwordx4 v133, s[6:7]
	v_mfma_f32_16x16x32_bf16 v[18:21], v[164:167], v[152:155], v[18:21]
	s_add_u32 m0, s10, 0x18800
	v_mfma_f32_16x16x32_bf16 v[22:25], v[168:171], v[152:155], v[22:25]
	global_load_lds_dwordx4 v134, s[6:7]
	v_mfma_f32_16x16x32_bf16 v[26:29], v[172:175], v[152:155], v[26:29]
	s_add_u32 m0, s10, 0x18c00
	v_mfma_f32_16x16x32_bf16 v[30:33], v[176:179], v[152:155], v[30:33]
	global_load_lds_dwordx4 v135, s[6:7]
	v_mfma_f32_16x16x32_bf16 v[34:37], v[164:167], v[156:159], v[34:37]
	s_add_u32 m0, s11, 0x18000
	v_mfma_f32_16x16x32_bf16 v[38:41], v[168:171], v[156:159], v[38:41]
	global_load_lds_dwordx4 v136, s[8:9]
	v_mfma_f32_16x16x32_bf16 v[42:45], v[172:175], v[156:159], v[42:45]
	s_add_u32 m0, s11, 0x18400
	v_mfma_f32_16x16x32_bf16 v[46:49], v[176:179], v[156:159], v[46:49]
	global_load_lds_dwordx4 v137, s[8:9]
	v_mfma_f32_16x16x32_bf16 v[50:53], v[164:167], v[160:163], v[50:53]
	v_mfma_f32_16x16x32_bf16 v[54:57], v[168:171], v[160:163], v[54:57]
	v_mfma_f32_16x16x32_bf16 v[58:61], v[172:175], v[160:163], v[58:61]
	v_mfma_f32_16x16x32_bf16 v[62:65], v[176:179], v[160:163], v[62:65]
	s_waitcnt lgkmcnt(0)
	v_mfma_f32_16x16x32_bf16 v[2:5], v[228:231], v[180:183], v[2:5]
	v_mfma_f32_16x16x32_bf16 v[6:9], v[232:235], v[180:183], v[6:9]
	v_mfma_f32_16x16x32_bf16 v[10:13], v[236:239], v[180:183], v[10:13]
	v_mfma_f32_16x16x32_bf16 v[14:17], v[240:243], v[180:183], v[14:17]
	v_mfma_f32_16x16x32_bf16 v[18:21], v[228:231], v[184:187], v[18:21]
	v_mfma_f32_16x16x32_bf16 v[22:25], v[232:235], v[184:187], v[22:25]
	v_mfma_f32_16x16x32_bf16 v[26:29], v[236:239], v[184:187], v[26:29]
	v_mfma_f32_16x16x32_bf16 v[30:33], v[240:243], v[184:187], v[30:33]
	v_mfma_f32_16x16x32_bf16 v[34:37], v[228:231], v[188:191], v[34:37]
	v_mfma_f32_16x16x32_bf16 v[38:41], v[232:235], v[188:191], v[38:41]
	v_mfma_f32_16x16x32_bf16 v[42:45], v[236:239], v[188:191], v[42:45]
	v_mfma_f32_16x16x32_bf16 v[46:49], v[240:243], v[188:191], v[46:49]
	v_mfma_f32_16x16x32_bf16 v[50:53], v[228:231], v[192:195], v[50:53]
	v_mfma_f32_16x16x32_bf16 v[54:57], v[232:235], v[192:195], v[54:57]
	v_mfma_f32_16x16x32_bf16 v[58:61], v[236:239], v[192:195], v[58:61]
	v_mfma_f32_16x16x32_bf16 v[62:65], v[240:243], v[192:195], v[62:65]
	s_add_u32 s6, s6, 0x80
	s_addc_u32 s7, s7, 0
	s_add_u32 s8, s8, 0x7fe80
	s_addc_u32 s9, s9, 0
	global_load_dword v244, v202, s[20:21] offset:2048
	s_waitcnt vmcnt(8)
	s_barrier
	ds_read_b128 v[148:151], v139 offset:0
	ds_read_b128 v[152:155], v139 offset:2048
	ds_read_b128 v[156:159], v139 offset:4096
	ds_read_b128 v[160:163], v139 offset:6144
	ds_read_b128 v[164:167], v145 offset:0
	ds_read_b128 v[168:171], v145 offset:2048
	ds_read_b128 v[172:175], v145 offset:4096
	ds_read_b128 v[176:179], v145 offset:6144
	ds_read_b128 v[180:183], v142 offset:0
	ds_read_b128 v[184:187], v142 offset:2048
	ds_read_b128 v[188:191], v142 offset:4096
	ds_read_b128 v[192:195], v142 offset:6144
	ds_read_b128 v[228:231], v196 offset:0
	ds_read_b128 v[232:235], v196 offset:2048
	ds_read_b128 v[236:239], v196 offset:4096
	ds_read_b128 v[240:243], v196 offset:6144
	s_waitcnt lgkmcnt(8)
	v_mfma_f32_16x16x32_bf16 v[2:5], v[164:167], v[148:151], v[2:5]
	s_mov_b32 m0, s10
	v_mfma_f32_16x16x32_bf16 v[6:9], v[168:171], v[148:151], v[6:9]
	global_load_lds_dwordx4 v132, s[6:7]
	v_mfma_f32_16x16x32_bf16 v[10:13], v[172:175], v[148:151], v[10:13]
	s_add_u32 m0, s10, 0x400
	v_mfma_f32_16x16x32_bf16 v[14:17], v[176:179], v[148:151], v[14:17]
	global_load_lds_dwordx4 v133, s[6:7]
	v_mfma_f32_16x16x32_bf16 v[18:21], v[164:167], v[152:155], v[18:21]
	s_add_u32 m0, s10, 0x800
	v_mfma_f32_16x16x32_bf16 v[22:25], v[168:171], v[152:155], v[22:25]
	global_load_lds_dwordx4 v134, s[6:7]
	v_mfma_f32_16x16x32_bf16 v[26:29], v[172:175], v[152:155], v[26:29]
	s_add_u32 m0, s10, 0xc00
	v_mfma_f32_16x16x32_bf16 v[30:33], v[176:179], v[152:155], v[30:33]
	global_load_lds_dwordx4 v135, s[6:7]
	v_mfma_f32_16x16x32_bf16 v[34:37], v[164:167], v[156:159], v[34:37]
	s_mov_b32 m0, s11
	v_mfma_f32_16x16x32_bf16 v[38:41], v[168:171], v[156:159], v[38:41]
	global_load_lds_dwordx4 v136, s[8:9]
	v_mfma_f32_16x16x32_bf16 v[42:45], v[172:175], v[156:159], v[42:45]
	s_add_u32 m0, s11, 0x400
	v_mfma_f32_16x16x32_bf16 v[46:49], v[176:179], v[156:159], v[46:49]
	global_load_lds_dwordx4 v137, s[8:9]
	v_mfma_f32_16x16x32_bf16 v[50:53], v[164:167], v[160:163], v[50:53]
	v_mfma_f32_16x16x32_bf16 v[54:57], v[168:171], v[160:163], v[54:57]
	v_mfma_f32_16x16x32_bf16 v[58:61], v[172:175], v[160:163], v[58:61]
	v_mfma_f32_16x16x32_bf16 v[62:65], v[176:179], v[160:163], v[62:65]
	s_waitcnt lgkmcnt(0)
	v_mfma_f32_16x16x32_bf16 v[2:5], v[228:231], v[180:183], v[2:5]
	v_mfma_f32_16x16x32_bf16 v[6:9], v[232:235], v[180:183], v[6:9]
	v_mfma_f32_16x16x32_bf16 v[10:13], v[236:239], v[180:183], v[10:13]
	v_mfma_f32_16x16x32_bf16 v[14:17], v[240:243], v[180:183], v[14:17]
	v_mfma_f32_16x16x32_bf16 v[18:21], v[228:231], v[184:187], v[18:21]
	v_mfma_f32_16x16x32_bf16 v[22:25], v[232:235], v[184:187], v[22:25]
	v_mfma_f32_16x16x32_bf16 v[26:29], v[236:239], v[184:187], v[26:29]
	v_mfma_f32_16x16x32_bf16 v[30:33], v[240:243], v[184:187], v[30:33]
	v_mfma_f32_16x16x32_bf16 v[34:37], v[228:231], v[188:191], v[34:37]
	v_mfma_f32_16x16x32_bf16 v[38:41], v[232:235], v[188:191], v[38:41]
	v_mfma_f32_16x16x32_bf16 v[42:45], v[236:239], v[188:191], v[42:45]
	v_mfma_f32_16x16x32_bf16 v[46:49], v[240:243], v[188:191], v[46:49]
	v_mfma_f32_16x16x32_bf16 v[50:53], v[228:231], v[192:195], v[50:53]
	v_mfma_f32_16x16x32_bf16 v[54:57], v[232:235], v[192:195], v[54:57]
	v_mfma_f32_16x16x32_bf16 v[58:61], v[236:239], v[192:195], v[58:61]
	v_mfma_f32_16x16x32_bf16 v[62:65], v[240:243], v[192:195], v[62:65]
	s_add_u32 s6, s6, 0x80
	s_addc_u32 s7, s7, 0
	s_add_u32 s8, s8, 0x80
	s_addc_u32 s9, s9, 0
	global_load_dword v244, v203, s[20:21] offset:0
	s_waitcnt vmcnt(8)
	s_barrier
	ds_read_b128 v[148:151], v140 offset:0
	ds_read_b128 v[152:155], v140 offset:2048
	ds_read_b128 v[156:159], v140 offset:4096
	ds_read_b128 v[160:163], v140 offset:6144
	ds_read_b128 v[164:167], v146 offset:0
	ds_read_b128 v[168:171], v146 offset:2048
	ds_read_b128 v[172:175], v146 offset:4096
	ds_read_b128 v[176:179], v146 offset:6144
	ds_read_b128 v[180:183], v143 offset:0
	ds_read_b128 v[184:187], v143 offset:2048
	ds_read_b128 v[188:191], v143 offset:4096
	ds_read_b128 v[192:195], v143 offset:6144
	ds_read_b128 v[228:231], v197 offset:0
	ds_read_b128 v[232:235], v197 offset:2048
	ds_read_b128 v[236:239], v197 offset:4096
	ds_read_b128 v[240:243], v197 offset:6144
	s_waitcnt lgkmcnt(8)
	v_mfma_f32_16x16x32_bf16 v[2:5], v[164:167], v[148:151], v[2:5]
	v_mfma_f32_16x16x32_bf16 v[6:9], v[168:171], v[148:151], v[6:9]
	v_mfma_f32_16x16x32_bf16 v[10:13], v[172:175], v[148:151], v[10:13]
	v_mfma_f32_16x16x32_bf16 v[14:17], v[176:179], v[148:151], v[14:17]
	v_mfma_f32_16x16x32_bf16 v[18:21], v[164:167], v[152:155], v[18:21]
	v_mfma_f32_16x16x32_bf16 v[22:25], v[168:171], v[152:155], v[22:25]
	v_mfma_f32_16x16x32_bf16 v[26:29], v[172:175], v[152:155], v[26:29]
	v_mfma_f32_16x16x32_bf16 v[30:33], v[176:179], v[152:155], v[30:33]
	v_mfma_f32_16x16x32_bf16 v[34:37], v[164:167], v[156:159], v[34:37]
	v_mfma_f32_16x16x32_bf16 v[38:41], v[168:171], v[156:159], v[38:41]
	v_mfma_f32_16x16x32_bf16 v[42:45], v[172:175], v[156:159], v[42:45]
	v_mfma_f32_16x16x32_bf16 v[46:49], v[176:179], v[156:159], v[46:49]
	v_mfma_f32_16x16x32_bf16 v[50:53], v[164:167], v[160:163], v[50:53]
	v_mfma_f32_16x16x32_bf16 v[54:57], v[168:171], v[160:163], v[54:57]
	v_mfma_f32_16x16x32_bf16 v[58:61], v[172:175], v[160:163], v[58:61]
	v_mfma_f32_16x16x32_bf16 v[62:65], v[176:179], v[160:163], v[62:65]
	global_load_dwordx4 v[148:151], v202, s[14:15] offset:0
	global_load_dwordx4 v[152:155], v202, s[14:15] offset:16
	global_load_dwordx4 v[156:159], v202, s[14:15] offset:2048
	global_load_dwordx4 v[160:163], v202, s[14:15] offset:2064
	global_load_dwordx4 v[164:167], v203, s[14:15] offset:0
	global_load_dwordx4 v[168:171], v203, s[14:15] offset:16
	global_load_dwordx4 v[172:175], v203, s[14:15] offset:2048
	global_load_dwordx4 v[176:179], v203, s[14:15] offset:2064
	s_waitcnt lgkmcnt(0)
	v_mfma_f32_16x16x32_bf16 v[2:5], v[228:231], v[180:183], v[2:5]
	s_add_u32 m0, s10, 0xc000
	v_mfma_f32_16x16x32_bf16 v[6:9], v[232:235], v[180:183], v[6:9]
	global_load_lds_dwordx4 v132, s[6:7]
	v_mfma_f32_16x16x32_bf16 v[10:13], v[236:239], v[180:183], v[10:13]
	s_add_u32 m0, s10, 0xc400
	v_mfma_f32_16x16x32_bf16 v[14:17], v[240:243], v[180:183], v[14:17]
	global_load_lds_dwordx4 v133, s[6:7]
	v_mfma_f32_16x16x32_bf16 v[18:21], v[228:231], v[184:187], v[18:21]
	s_add_u32 m0, s10, 0xc800
	v_mfma_f32_16x16x32_bf16 v[22:25], v[232:235], v[184:187], v[22:25]
	global_load_lds_dwordx4 v134, s[6:7]
	v_mfma_f32_16x16x32_bf16 v[26:29], v[236:239], v[184:187], v[26:29]
	s_add_u32 m0, s10, 0xcc00
	v_mfma_f32_16x16x32_bf16 v[30:33], v[240:243], v[184:187], v[30:33]
	global_load_lds_dwordx4 v135, s[6:7]
	v_mfma_f32_16x16x32_bf16 v[34:37], v[228:231], v[188:191], v[34:37]
	s_add_u32 m0, s11, 0xc000
	v_mfma_f32_16x16x32_bf16 v[38:41], v[232:235], v[188:191], v[38:41]
	global_load_lds_dwordx4 v136, s[8:9]
	v_mfma_f32_16x16x32_bf16 v[42:45], v[236:239], v[188:191], v[42:45]
	s_add_u32 m0, s11, 0xc400
	v_mfma_f32_16x16x32_bf16 v[46:49], v[240:243], v[188:191], v[46:49]
	global_load_lds_dwordx4 v137, s[8:9]
	v_mfma_f32_16x16x32_bf16 v[50:53], v[228:231], v[192:195], v[50:53]
	v_mfma_f32_16x16x32_bf16 v[54:57], v[232:235], v[192:195], v[54:57]
	v_mfma_f32_16x16x32_bf16 v[58:61], v[236:239], v[192:195], v[58:61]
	v_mfma_f32_16x16x32_bf16 v[62:65], v[240:243], v[192:195], v[62:65]
	s_add_u32 s6, s6, 0x80
	s_addc_u32 s7, s7, 0
	s_add_u32 s8, s8, 0x80
	s_addc_u32 s9, s9, 0
	s_add_u32 s14, s14, 0x1000000
	s_addc_u32 s15, s15, 0
	global_load_dword v244, v203, s[20:21] offset:2048
	s_add_u32 s20, s20, 0x1000000
	s_addc_u32 s21, s21, 0
	s_nop 7
	s_nop 3
	s_waitcnt vmcnt(7)
	v_lshlrev_b32_e32 v246, 16, v148
	v_and_b32_e32 v247, 0xffff0000, v148
	v_pk_fma_f32 v[66:67], v[2:3], v[246:247], v[66:67]
	v_lshlrev_b32_e32 v248, 16, v149
	v_and_b32_e32 v249, 0xffff0000, v149
	v_pk_fma_f32 v[68:69], v[4:5], v[248:249], v[68:69]
	v_lshlrev_b32_e32 v246, 16, v150
	v_and_b32_e32 v247, 0xffff0000, v150
	v_pk_fma_f32 v[70:71], v[6:7], v[246:247], v[70:71]
	v_lshlrev_b32_e32 v248, 16, v151
	v_and_b32_e32 v249, 0xffff0000, v151
	v_pk_fma_f32 v[72:73], v[8:9], v[248:249], v[72:73]
	v_lshlrev_b32_e32 v246, 16, v152
	v_and_b32_e32 v247, 0xffff0000, v152
	v_pk_fma_f32 v[74:75], v[10:11], v[246:247], v[74:75]
	v_lshlrev_b32_e32 v248, 16, v153
	v_and_b32_e32 v249, 0xffff0000, v153
	v_pk_fma_f32 v[76:77], v[12:13], v[248:249], v[76:77]
	v_lshlrev_b32_e32 v246, 16, v154
	v_and_b32_e32 v247, 0xffff0000, v154
	v_pk_fma_f32 v[78:79], v[14:15], v[246:247], v[78:79]
	v_lshlrev_b32_e32 v248, 16, v155
	v_and_b32_e32 v249, 0xffff0000, v155
	v_pk_fma_f32 v[80:81], v[16:17], v[248:249], v[80:81]
	v_lshlrev_b32_e32 v246, 16, v156
	v_and_b32_e32 v247, 0xffff0000, v156
	v_pk_fma_f32 v[82:83], v[18:19], v[246:247], v[82:83]
	v_lshlrev_b32_e32 v248, 16, v157
	v_and_b32_e32 v249, 0xffff0000, v157
	v_pk_fma_f32 v[84:85], v[20:21], v[248:249], v[84:85]
	v_lshlrev_b32_e32 v246, 16, v158
	v_and_b32_e32 v247, 0xffff0000, v158
	v_pk_fma_f32 v[86:87], v[22:23], v[246:247], v[86:87]
	v_lshlrev_b32_e32 v248, 16, v159
	v_and_b32_e32 v249, 0xffff0000, v159
	v_pk_fma_f32 v[88:89], v[24:25], v[248:249], v[88:89]
	v_lshlrev_b32_e32 v246, 16, v160
	v_and_b32_e32 v247, 0xffff0000, v160
	v_pk_fma_f32 v[90:91], v[26:27], v[246:247], v[90:91]
	v_lshlrev_b32_e32 v248, 16, v161
	v_and_b32_e32 v249, 0xffff0000, v161
	v_pk_fma_f32 v[92:93], v[28:29], v[248:249], v[92:93]
	v_lshlrev_b32_e32 v246, 16, v162
	v_and_b32_e32 v247, 0xffff0000, v162
	v_pk_fma_f32 v[94:95], v[30:31], v[246:247], v[94:95]
	v_lshlrev_b32_e32 v248, 16, v163
	v_and_b32_e32 v249, 0xffff0000, v163
	v_pk_fma_f32 v[96:97], v[32:33], v[248:249], v[96:97]
	v_lshlrev_b32_e32 v246, 16, v164
	v_and_b32_e32 v247, 0xffff0000, v164
	v_pk_fma_f32 v[98:99], v[34:35], v[246:247], v[98:99]
	v_lshlrev_b32_e32 v248, 16, v165
	v_and_b32_e32 v249, 0xffff0000, v165
	v_pk_fma_f32 v[100:101], v[36:37], v[248:249], v[100:101]
	v_lshlrev_b32_e32 v246, 16, v166
	v_and_b32_e32 v247, 0xffff0000, v166
	v_pk_fma_f32 v[102:103], v[38:39], v[246:247], v[102:103]
	v_lshlrev_b32_e32 v248, 16, v167
	v_and_b32_e32 v249, 0xffff0000, v167
	v_pk_fma_f32 v[104:105], v[40:41], v[248:249], v[104:105]
	v_lshlrev_b32_e32 v246, 16, v168
	v_and_b32_e32 v247, 0xffff0000, v168
	v_pk_fma_f32 v[106:107], v[42:43], v[246:247], v[106:107]
	v_lshlrev_b32_e32 v248, 16, v169
	v_and_b32_e32 v249, 0xffff0000, v169
	v_pk_fma_f32 v[108:109], v[44:45], v[248:249], v[108:109]
	v_lshlrev_b32_e32 v246, 16, v170
	v_and_b32_e32 v247, 0xffff0000, v170
	v_pk_fma_f32 v[110:111], v[46:47], v[246:247], v[110:111]
	v_lshlrev_b32_e32 v248, 16, v171
	v_and_b32_e32 v249, 0xffff0000, v171
	v_pk_fma_f32 v[112:113], v[48:49], v[248:249], v[112:113]
	v_lshlrev_b32_e32 v246, 16, v172
	v_and_b32_e32 v247, 0xffff0000, v172
	v_pk_fma_f32 v[114:115], v[50:51], v[246:247], v[114:115]
	v_lshlrev_b32_e32 v248, 16, v173
	v_and_b32_e32 v249, 0xffff0000, v173
	v_pk_fma_f32 v[116:117], v[52:53], v[248:249], v[116:117]
	v_lshlrev_b32_e32 v246, 16, v174
	v_and_b32_e32 v247, 0xffff0000, v174
	v_pk_fma_f32 v[118:119], v[54:55], v[246:247], v[118:119]
	v_lshlrev_b32_e32 v248, 16, v175
	v_and_b32_e32 v249, 0xffff0000, v175
	v_pk_fma_f32 v[120:121], v[56:57], v[248:249], v[120:121]
	v_lshlrev_b32_e32 v246, 16, v176
	v_and_b32_e32 v247, 0xffff0000, v176
	v_pk_fma_f32 v[122:123], v[58:59], v[246:247], v[122:123]
	v_lshlrev_b32_e32 v248, 16, v177
	v_and_b32_e32 v249, 0xffff0000, v177
	v_pk_fma_f32 v[124:125], v[60:61], v[248:249], v[124:125]
	v_lshlrev_b32_e32 v246, 16, v178
	v_and_b32_e32 v247, 0xffff0000, v178
	v_pk_fma_f32 v[126:127], v[62:63], v[246:247], v[126:127]
	v_lshlrev_b32_e32 v248, 16, v179
	v_and_b32_e32 v249, 0xffff0000, v179
	v_pk_fma_f32 v[128:129], v[64:65], v[248:249], v[128:129]
	v_mov_b32_e32 v2, 0
	v_mov_b32_e32 v3, 0
	v_mov_b32_e32 v4, 0
	v_mov_b32_e32 v5, 0
	v_mov_b32_e32 v6, 0
	v_mov_b32_e32 v7, 0
	v_mov_b32_e32 v8, 0
	v_mov_b32_e32 v9, 0
	v_mov_b32_e32 v10, 0
	v_mov_b32_e32 v11, 0
	v_mov_b32_e32 v12, 0
	v_mov_b32_e32 v13, 0
	v_mov_b32_e32 v14, 0
	v_mov_b32_e32 v15, 0
	v_mov_b32_e32 v16, 0
	v_mov_b32_e32 v17, 0
	v_mov_b32_e32 v18, 0
	v_mov_b32_e32 v19, 0
	v_mov_b32_e32 v20, 0
	v_mov_b32_e32 v21, 0
	v_mov_b32_e32 v22, 0
	v_mov_b32_e32 v23, 0
	v_mov_b32_e32 v24, 0
	v_mov_b32_e32 v25, 0
	v_mov_b32_e32 v26, 0
	v_mov_b32_e32 v27, 0
	v_mov_b32_e32 v28, 0
	v_mov_b32_e32 v29, 0
	v_mov_b32_e32 v30, 0
	v_mov_b32_e32 v31, 0
	v_mov_b32_e32 v32, 0
	v_mov_b32_e32 v33, 0
	v_mov_b32_e32 v34, 0
	v_mov_b32_e32 v35, 0
	v_mov_b32_e32 v36, 0
	v_mov_b32_e32 v37, 0
	v_mov_b32_e32 v38, 0
	v_mov_b32_e32 v39, 0
	v_mov_b32_e32 v40, 0
	v_mov_b32_e32 v41, 0
	v_mov_b32_e32 v42, 0
	v_mov_b32_e32 v43, 0
	v_mov_b32_e32 v44, 0
	v_mov_b32_e32 v45, 0
	v_mov_b32_e32 v46, 0
	v_mov_b32_e32 v47, 0
	v_mov_b32_e32 v48, 0
	v_mov_b32_e32 v49, 0
	v_mov_b32_e32 v50, 0
	v_mov_b32_e32 v51, 0
	v_mov_b32_e32 v52, 0
	v_mov_b32_e32 v53, 0
	v_mov_b32_e32 v54, 0
	v_mov_b32_e32 v55, 0
	v_mov_b32_e32 v56, 0
	v_mov_b32_e32 v57, 0
	v_mov_b32_e32 v58, 0
	v_mov_b32_e32 v59, 0
	v_mov_b32_e32 v60, 0
	v_mov_b32_e32 v61, 0
	v_mov_b32_e32 v62, 0
	v_mov_b32_e32 v63, 0
	v_mov_b32_e32 v64, 0
	v_mov_b32_e32 v65, 0
	s_waitcnt vmcnt(16)
	s_barrier
	ds_read_b128 v[148:151], v138 offset:0
	ds_read_b128 v[152:155], v138 offset:2048
	ds_read_b128 v[156:159], v138 offset:4096
	ds_read_b128 v[160:163], v138 offset:6144
	ds_read_b128 v[164:167], v144 offset:0
	ds_read_b128 v[168:171], v144 offset:2048
	ds_read_b128 v[172:175], v144 offset:4096
	ds_read_b128 v[176:179], v144 offset:6144
	ds_read_b128 v[180:183], v141 offset:0
	ds_read_b128 v[184:187], v141 offset:2048
	ds_read_b128 v[188:191], v141 offset:4096
	ds_read_b128 v[192:195], v141 offset:6144
	ds_read_b128 v[228:231], v147 offset:0
	ds_read_b128 v[232:235], v147 offset:2048
	ds_read_b128 v[236:239], v147 offset:4096
	ds_read_b128 v[240:243], v147 offset:6144
	s_waitcnt lgkmcnt(8)
	v_mfma_f32_16x16x32_bf16 v[2:5], v[164:167], v[148:151], v[2:5]
	s_add_u32 m0, s10, 0x18000
	v_mfma_f32_16x16x32_bf16 v[6:9], v[168:171], v[148:151], v[6:9]
	global_load_lds_dwordx4 v132, s[6:7]
	v_mfma_f32_16x16x32_bf16 v[10:13], v[172:175], v[148:151], v[10:13]
	s_add_u32 m0, s10, 0x18400
	v_mfma_f32_16x16x32_bf16 v[14:17], v[176:179], v[148:151], v[14:17]
	global_load_lds_dwordx4 v133, s[6:7]
	v_mfma_f32_16x16x32_bf16 v[18:21], v[164:167], v[152:155], v[18:21]
	s_add_u32 m0, s10, 0x18800
	v_mfma_f32_16x16x32_bf16 v[22:25], v[168:171], v[152:155], v[22:25]
	global_load_lds_dwordx4 v134, s[6:7]
	v_mfma_f32_16x16x32_bf16 v[26:29], v[172:175], v[152:155], v[26:29]
	s_add_u32 m0, s10, 0x18c00
	v_mfma_f32_16x16x32_bf16 v[30:33], v[176:179], v[152:155], v[30:33]
	global_load_lds_dwordx4 v135, s[6:7]
	v_mfma_f32_16x16x32_bf16 v[34:37], v[164:167], v[156:159], v[34:37]
	s_add_u32 m0, s11, 0x18000
	v_mfma_f32_16x16x32_bf16 v[38:41], v[168:171], v[156:159], v[38:41]
	global_load_lds_dwordx4 v136, s[8:9]
	v_mfma_f32_16x16x32_bf16 v[42:45], v[172:175], v[156:159], v[42:45]
	s_add_u32 m0, s11, 0x18400
	v_mfma_f32_16x16x32_bf16 v[46:49], v[176:179], v[156:159], v[46:49]
	global_load_lds_dwordx4 v137, s[8:9]
	v_mfma_f32_16x16x32_bf16 v[50:53], v[164:167], v[160:163], v[50:53]
	v_mfma_f32_16x16x32_bf16 v[54:57], v[168:171], v[160:163], v[54:57]
	v_mfma_f32_16x16x32_bf16 v[58:61], v[172:175], v[160:163], v[58:61]
	v_mfma_f32_16x16x32_bf16 v[62:65], v[176:179], v[160:163], v[62:65]
	s_waitcnt lgkmcnt(0)
	v_mfma_f32_16x16x32_bf16 v[2:5], v[228:231], v[180:183], v[2:5]
	v_mfma_f32_16x16x32_bf16 v[6:9], v[232:235], v[180:183], v[6:9]
	v_mfma_f32_16x16x32_bf16 v[10:13], v[236:239], v[180:183], v[10:13]
	v_mfma_f32_16x16x32_bf16 v[14:17], v[240:243], v[180:183], v[14:17]
	v_mfma_f32_16x16x32_bf16 v[18:21], v[228:231], v[184:187], v[18:21]
	v_mfma_f32_16x16x32_bf16 v[22:25], v[232:235], v[184:187], v[22:25]
	v_mfma_f32_16x16x32_bf16 v[26:29], v[236:239], v[184:187], v[26:29]
	v_mfma_f32_16x16x32_bf16 v[30:33], v[240:243], v[184:187], v[30:33]
	v_mfma_f32_16x16x32_bf16 v[34:37], v[228:231], v[188:191], v[34:37]
	v_mfma_f32_16x16x32_bf16 v[38:41], v[232:235], v[188:191], v[38:41]
	v_mfma_f32_16x16x32_bf16 v[42:45], v[236:239], v[188:191], v[42:45]
	v_mfma_f32_16x16x32_bf16 v[46:49], v[240:243], v[188:191], v[46:49]
	v_mfma_f32_16x16x32_bf16 v[50:53], v[228:231], v[192:195], v[50:53]
	v_mfma_f32_16x16x32_bf16 v[54:57], v[232:235], v[192:195], v[54:57]
	v_mfma_f32_16x16x32_bf16 v[58:61], v[236:239], v[192:195], v[58:61]
	v_mfma_f32_16x16x32_bf16 v[62:65], v[240:243], v[192:195], v[62:65]
	s_add_u32 s6, s6, 0x80
	s_addc_u32 s7, s7, 0
	s_add_u32 s8, s8, 0x80
	s_addc_u32 s9, s9, 0
	s_waitcnt vmcnt(7)
	s_barrier
	ds_read_b128 v[148:151], v139 offset:0
	ds_read_b128 v[152:155], v139 offset:2048
	ds_read_b128 v[156:159], v139 offset:4096
	ds_read_b128 v[160:163], v139 offset:6144
	ds_read_b128 v[164:167], v145 offset:0
	ds_read_b128 v[168:171], v145 offset:2048
	ds_read_b128 v[172:175], v145 offset:4096
	ds_read_b128 v[176:179], v145 offset:6144
	ds_read_b128 v[180:183], v142 offset:0
	ds_read_b128 v[184:187], v142 offset:2048
	ds_read_b128 v[188:191], v142 offset:4096
	ds_read_b128 v[192:195], v142 offset:6144
	ds_read_b128 v[228:231], v196 offset:0
	ds_read_b128 v[232:235], v196 offset:2048
	ds_read_b128 v[236:239], v196 offset:4096
	ds_read_b128 v[240:243], v196 offset:6144
	s_waitcnt lgkmcnt(8)
	v_mfma_f32_16x16x32_bf16 v[2:5], v[164:167], v[148:151], v[2:5]
	s_mov_b32 m0, s10
	v_mfma_f32_16x16x32_bf16 v[6:9], v[168:171], v[148:151], v[6:9]
	global_load_lds_dwordx4 v132, s[6:7]
	v_mfma_f32_16x16x32_bf16 v[10:13], v[172:175], v[148:151], v[10:13]
	s_add_u32 m0, s10, 0x400
	v_mfma_f32_16x16x32_bf16 v[14:17], v[176:179], v[148:151], v[14:17]
	global_load_lds_dwordx4 v133, s[6:7]
	v_mfma_f32_16x16x32_bf16 v[18:21], v[164:167], v[152:155], v[18:21]
	s_add_u32 m0, s10, 0x800
	v_mfma_f32_16x16x32_bf16 v[22:25], v[168:171], v[152:155], v[22:25]
	global_load_lds_dwordx4 v134, s[6:7]
	v_mfma_f32_16x16x32_bf16 v[26:29], v[172:175], v[152:155], v[26:29]
	s_add_u32 m0, s10, 0xc00
	v_mfma_f32_16x16x32_bf16 v[30:33], v[176:179], v[152:155], v[30:33]
	global_load_lds_dwordx4 v135, s[6:7]
	v_mfma_f32_16x16x32_bf16 v[34:37], v[164:167], v[156:159], v[34:37]
	s_mov_b32 m0, s11
	v_mfma_f32_16x16x32_bf16 v[38:41], v[168:171], v[156:159], v[38:41]
	global_load_lds_dwordx4 v136, s[8:9]
	v_mfma_f32_16x16x32_bf16 v[42:45], v[172:175], v[156:159], v[42:45]
	s_add_u32 m0, s11, 0x400
	v_mfma_f32_16x16x32_bf16 v[46:49], v[176:179], v[156:159], v[46:49]
	global_load_lds_dwordx4 v137, s[8:9]
	v_mfma_f32_16x16x32_bf16 v[50:53], v[164:167], v[160:163], v[50:53]
	v_mfma_f32_16x16x32_bf16 v[54:57], v[168:171], v[160:163], v[54:57]
	v_mfma_f32_16x16x32_bf16 v[58:61], v[172:175], v[160:163], v[58:61]
	v_mfma_f32_16x16x32_bf16 v[62:65], v[176:179], v[160:163], v[62:65]
	s_waitcnt lgkmcnt(0)
	v_mfma_f32_16x16x32_bf16 v[2:5], v[228:231], v[180:183], v[2:5]
	v_mfma_f32_16x16x32_bf16 v[6:9], v[232:235], v[180:183], v[6:9]
	v_mfma_f32_16x16x32_bf16 v[10:13], v[236:239], v[180:183], v[10:13]
	v_mfma_f32_16x16x32_bf16 v[14:17], v[240:243], v[180:183], v[14:17]
	v_mfma_f32_16x16x32_bf16 v[18:21], v[228:231], v[184:187], v[18:21]
	v_mfma_f32_16x16x32_bf16 v[22:25], v[232:235], v[184:187], v[22:25]
	v_mfma_f32_16x16x32_bf16 v[26:29], v[236:239], v[184:187], v[26:29]
	v_mfma_f32_16x16x32_bf16 v[30:33], v[240:243], v[184:187], v[30:33]
	v_mfma_f32_16x16x32_bf16 v[34:37], v[228:231], v[188:191], v[34:37]
	v_mfma_f32_16x16x32_bf16 v[38:41], v[232:235], v[188:191], v[38:41]
	v_mfma_f32_16x16x32_bf16 v[42:45], v[236:239], v[188:191], v[42:45]
	v_mfma_f32_16x16x32_bf16 v[46:49], v[240:243], v[188:191], v[46:49]
	v_mfma_f32_16x16x32_bf16 v[50:53], v[228:231], v[192:195], v[50:53]
	v_mfma_f32_16x16x32_bf16 v[54:57], v[232:235], v[192:195], v[54:57]
	v_mfma_f32_16x16x32_bf16 v[58:61], v[236:239], v[192:195], v[58:61]
	v_mfma_f32_16x16x32_bf16 v[62:65], v[240:243], v[192:195], v[62:65]
	s_add_u32 s6, s6, 0x80
	s_addc_u32 s7, s7, 0
	s_add_u32 s8, s8, 0x7fe80
	s_addc_u32 s9, s9, 0
	s_waitcnt vmcnt(6)
	s_barrier
	ds_read_b128 v[148:151], v140 offset:0
	ds_read_b128 v[152:155], v140 offset:2048
	ds_read_b128 v[156:159], v140 offset:4096
	ds_read_b128 v[160:163], v140 offset:6144
	ds_read_b128 v[164:167], v146 offset:0
	ds_read_b128 v[168:171], v146 offset:2048
	ds_read_b128 v[172:175], v146 offset:4096
	ds_read_b128 v[176:179], v146 offset:6144
	ds_read_b128 v[180:183], v143 offset:0
	ds_read_b128 v[184:187], v143 offset:2048
	ds_read_b128 v[188:191], v143 offset:4096
	ds_read_b128 v[192:195], v143 offset:6144
	ds_read_b128 v[228:231], v197 offset:0
	ds_read_b128 v[232:235], v197 offset:2048
	ds_read_b128 v[236:239], v197 offset:4096
	ds_read_b128 v[240:243], v197 offset:6144
	s_waitcnt lgkmcnt(8)
	v_mfma_f32_16x16x32_bf16 v[2:5], v[164:167], v[148:151], v[2:5]
	v_mfma_f32_16x16x32_bf16 v[6:9], v[168:171], v[148:151], v[6:9]
	v_mfma_f32_16x16x32_bf16 v[10:13], v[172:175], v[148:151], v[10:13]
	v_mfma_f32_16x16x32_bf16 v[14:17], v[176:179], v[148:151], v[14:17]
	v_mfma_f32_16x16x32_bf16 v[18:21], v[164:167], v[152:155], v[18:21]
	v_mfma_f32_16x16x32_bf16 v[22:25], v[168:171], v[152:155], v[22:25]
	v_mfma_f32_16x16x32_bf16 v[26:29], v[172:175], v[152:155], v[26:29]
	v_mfma_f32_16x16x32_bf16 v[30:33], v[176:179], v[152:155], v[30:33]
	v_mfma_f32_16x16x32_bf16 v[34:37], v[164:167], v[156:159], v[34:37]
	v_mfma_f32_16x16x32_bf16 v[38:41], v[168:171], v[156:159], v[38:41]
	v_mfma_f32_16x16x32_bf16 v[42:45], v[172:175], v[156:159], v[42:45]
	v_mfma_f32_16x16x32_bf16 v[46:49], v[176:179], v[156:159], v[46:49]
	v_mfma_f32_16x16x32_bf16 v[50:53], v[164:167], v[160:163], v[50:53]
	v_mfma_f32_16x16x32_bf16 v[54:57], v[168:171], v[160:163], v[54:57]
	v_mfma_f32_16x16x32_bf16 v[58:61], v[172:175], v[160:163], v[58:61]
	v_mfma_f32_16x16x32_bf16 v[62:65], v[176:179], v[160:163], v[62:65]
	s_waitcnt lgkmcnt(0)
	v_mfma_f32_16x16x32_bf16 v[2:5], v[228:231], v[180:183], v[2:5]
	v_mfma_f32_16x16x32_bf16 v[6:9], v[232:235], v[180:183], v[6:9]
	v_mfma_f32_16x16x32_bf16 v[10:13], v[236:239], v[180:183], v[10:13]
	v_mfma_f32_16x16x32_bf16 v[14:17], v[240:243], v[180:183], v[14:17]
	v_mfma_f32_16x16x32_bf16 v[18:21], v[228:231], v[184:187], v[18:21]
	v_mfma_f32_16x16x32_bf16 v[22:25], v[232:235], v[184:187], v[22:25]
	v_mfma_f32_16x16x32_bf16 v[26:29], v[236:239], v[184:187], v[26:29]
	v_mfma_f32_16x16x32_bf16 v[30:33], v[240:243], v[184:187], v[30:33]
	v_mfma_f32_16x16x32_bf16 v[34:37], v[228:231], v[188:191], v[34:37]
	v_mfma_f32_16x16x32_bf16 v[38:41], v[232:235], v[188:191], v[38:41]
	v_mfma_f32_16x16x32_bf16 v[42:45], v[236:239], v[188:191], v[42:45]
	v_mfma_f32_16x16x32_bf16 v[46:49], v[240:243], v[188:191], v[46:49]
	v_mfma_f32_16x16x32_bf16 v[50:53], v[228:231], v[192:195], v[50:53]
	v_mfma_f32_16x16x32_bf16 v[54:57], v[232:235], v[192:195], v[54:57]
	v_mfma_f32_16x16x32_bf16 v[58:61], v[236:239], v[192:195], v[58:61]
	v_mfma_f32_16x16x32_bf16 v[62:65], v[240:243], v[192:195], v[62:65]
	s_waitcnt vmcnt(0)
	s_barrier
	ds_read_b128 v[148:151], v138 offset:0
	ds_read_b128 v[152:155], v138 offset:2048
	ds_read_b128 v[156:159], v138 offset:4096
	ds_read_b128 v[160:163], v138 offset:6144
	ds_read_b128 v[164:167], v144 offset:0
	ds_read_b128 v[168:171], v144 offset:2048
	ds_read_b128 v[172:175], v144 offset:4096
	ds_read_b128 v[176:179], v144 offset:6144
	ds_read_b128 v[180:183], v141 offset:0
	ds_read_b128 v[184:187], v141 offset:2048
	ds_read_b128 v[188:191], v141 offset:4096
	ds_read_b128 v[192:195], v141 offset:6144
	ds_read_b128 v[228:231], v147 offset:0
	ds_read_b128 v[232:235], v147 offset:2048
	ds_read_b128 v[236:239], v147 offset:4096
	ds_read_b128 v[240:243], v147 offset:6144
	s_waitcnt lgkmcnt(8)
	v_mfma_f32_16x16x32_bf16 v[2:5], v[164:167], v[148:151], v[2:5]
	v_mfma_f32_16x16x32_bf16 v[6:9], v[168:171], v[148:151], v[6:9]
	v_mfma_f32_16x16x32_bf16 v[10:13], v[172:175], v[148:151], v[10:13]
	v_mfma_f32_16x16x32_bf16 v[14:17], v[176:179], v[148:151], v[14:17]
	v_mfma_f32_16x16x32_bf16 v[18:21], v[164:167], v[152:155], v[18:21]
	v_mfma_f32_16x16x32_bf16 v[22:25], v[168:171], v[152:155], v[22:25]
	v_mfma_f32_16x16x32_bf16 v[26:29], v[172:175], v[152:155], v[26:29]
	v_mfma_f32_16x16x32_bf16 v[30:33], v[176:179], v[152:155], v[30:33]
	v_mfma_f32_16x16x32_bf16 v[34:37], v[164:167], v[156:159], v[34:37]
	v_mfma_f32_16x16x32_bf16 v[38:41], v[168:171], v[156:159], v[38:41]
	v_mfma_f32_16x16x32_bf16 v[42:45], v[172:175], v[156:159], v[42:45]
	v_mfma_f32_16x16x32_bf16 v[46:49], v[176:179], v[156:159], v[46:49]
	v_mfma_f32_16x16x32_bf16 v[50:53], v[164:167], v[160:163], v[50:53]
	v_mfma_f32_16x16x32_bf16 v[54:57], v[168:171], v[160:163], v[54:57]
	v_mfma_f32_16x16x32_bf16 v[58:61], v[172:175], v[160:163], v[58:61]
	v_mfma_f32_16x16x32_bf16 v[62:65], v[176:179], v[160:163], v[62:65]
	global_load_dwordx4 v[148:151], v202, s[14:15] offset:0
	global_load_dwordx4 v[152:155], v202, s[14:15] offset:16
	global_load_dwordx4 v[156:159], v202, s[14:15] offset:2048
	global_load_dwordx4 v[160:163], v202, s[14:15] offset:2064
	global_load_dwordx4 v[164:167], v203, s[14:15] offset:0
	global_load_dwordx4 v[168:171], v203, s[14:15] offset:16
	global_load_dwordx4 v[172:175], v203, s[14:15] offset:2048
	global_load_dwordx4 v[176:179], v203, s[14:15] offset:2064
	s_waitcnt lgkmcnt(0)
	v_mfma_f32_16x16x32_bf16 v[2:5], v[228:231], v[180:183], v[2:5]
	v_mfma_f32_16x16x32_bf16 v[6:9], v[232:235], v[180:183], v[6:9]
	v_mfma_f32_16x16x32_bf16 v[10:13], v[236:239], v[180:183], v[10:13]
	v_mfma_f32_16x16x32_bf16 v[14:17], v[240:243], v[180:183], v[14:17]
	v_mfma_f32_16x16x32_bf16 v[18:21], v[228:231], v[184:187], v[18:21]
	v_mfma_f32_16x16x32_bf16 v[22:25], v[232:235], v[184:187], v[22:25]
	v_mfma_f32_16x16x32_bf16 v[26:29], v[236:239], v[184:187], v[26:29]
	v_mfma_f32_16x16x32_bf16 v[30:33], v[240:243], v[184:187], v[30:33]
	v_mfma_f32_16x16x32_bf16 v[34:37], v[228:231], v[188:191], v[34:37]
	v_mfma_f32_16x16x32_bf16 v[38:41], v[232:235], v[188:191], v[38:41]
	v_mfma_f32_16x16x32_bf16 v[42:45], v[236:239], v[188:191], v[42:45]
	v_mfma_f32_16x16x32_bf16 v[46:49], v[240:243], v[188:191], v[46:49]
	v_mfma_f32_16x16x32_bf16 v[50:53], v[228:231], v[192:195], v[50:53]
	v_mfma_f32_16x16x32_bf16 v[54:57], v[232:235], v[192:195], v[54:57]
	v_mfma_f32_16x16x32_bf16 v[58:61], v[236:239], v[192:195], v[58:61]
	v_mfma_f32_16x16x32_bf16 v[62:65], v[240:243], v[192:195], v[62:65]
	s_add_u32 s14, s14, 0x1000000
	s_addc_u32 s15, s15, 0
	s_nop 7
	s_nop 3
	s_waitcnt vmcnt(0)
	v_lshlrev_b32_e32 v246, 16, v148
	v_and_b32_e32 v247, 0xffff0000, v148
	v_pk_fma_f32 v[66:67], v[2:3], v[246:247], v[66:67]
	v_lshlrev_b32_e32 v248, 16, v149
	v_and_b32_e32 v249, 0xffff0000, v149
	v_pk_fma_f32 v[68:69], v[4:5], v[248:249], v[68:69]
	v_lshlrev_b32_e32 v246, 16, v150
	v_and_b32_e32 v247, 0xffff0000, v150
	v_pk_fma_f32 v[70:71], v[6:7], v[246:247], v[70:71]
	v_lshlrev_b32_e32 v248, 16, v151
	v_and_b32_e32 v249, 0xffff0000, v151
	v_pk_fma_f32 v[72:73], v[8:9], v[248:249], v[72:73]
	v_lshlrev_b32_e32 v246, 16, v152
	v_and_b32_e32 v247, 0xffff0000, v152
	v_pk_fma_f32 v[74:75], v[10:11], v[246:247], v[74:75]
	v_lshlrev_b32_e32 v248, 16, v153
	v_and_b32_e32 v249, 0xffff0000, v153
	v_pk_fma_f32 v[76:77], v[12:13], v[248:249], v[76:77]
	v_lshlrev_b32_e32 v246, 16, v154
	v_and_b32_e32 v247, 0xffff0000, v154
	v_pk_fma_f32 v[78:79], v[14:15], v[246:247], v[78:79]
	v_lshlrev_b32_e32 v248, 16, v155
	v_and_b32_e32 v249, 0xffff0000, v155
	v_pk_fma_f32 v[80:81], v[16:17], v[248:249], v[80:81]
	v_lshlrev_b32_e32 v246, 16, v156
	v_and_b32_e32 v247, 0xffff0000, v156
	v_pk_fma_f32 v[82:83], v[18:19], v[246:247], v[82:83]
	v_lshlrev_b32_e32 v248, 16, v157
	v_and_b32_e32 v249, 0xffff0000, v157
	v_pk_fma_f32 v[84:85], v[20:21], v[248:249], v[84:85]
	v_lshlrev_b32_e32 v246, 16, v158
	v_and_b32_e32 v247, 0xffff0000, v158
	v_pk_fma_f32 v[86:87], v[22:23], v[246:247], v[86:87]
	v_lshlrev_b32_e32 v248, 16, v159
	v_and_b32_e32 v249, 0xffff0000, v159
	v_pk_fma_f32 v[88:89], v[24:25], v[248:249], v[88:89]
	v_lshlrev_b32_e32 v246, 16, v160
	v_and_b32_e32 v247, 0xffff0000, v160
	v_pk_fma_f32 v[90:91], v[26:27], v[246:247], v[90:91]
	v_lshlrev_b32_e32 v248, 16, v161
	v_and_b32_e32 v249, 0xffff0000, v161
	v_pk_fma_f32 v[92:93], v[28:29], v[248:249], v[92:93]
	v_lshlrev_b32_e32 v246, 16, v162
	v_and_b32_e32 v247, 0xffff0000, v162
	v_pk_fma_f32 v[94:95], v[30:31], v[246:247], v[94:95]
	v_lshlrev_b32_e32 v248, 16, v163
	v_and_b32_e32 v249, 0xffff0000, v163
	v_pk_fma_f32 v[96:97], v[32:33], v[248:249], v[96:97]
	v_lshlrev_b32_e32 v246, 16, v164
	v_and_b32_e32 v247, 0xffff0000, v164
	v_pk_fma_f32 v[98:99], v[34:35], v[246:247], v[98:99]
	v_lshlrev_b32_e32 v248, 16, v165
	v_and_b32_e32 v249, 0xffff0000, v165
	v_pk_fma_f32 v[100:101], v[36:37], v[248:249], v[100:101]
	v_lshlrev_b32_e32 v246, 16, v166
	v_and_b32_e32 v247, 0xffff0000, v166
	v_pk_fma_f32 v[102:103], v[38:39], v[246:247], v[102:103]
	v_lshlrev_b32_e32 v248, 16, v167
	v_and_b32_e32 v249, 0xffff0000, v167
	v_pk_fma_f32 v[104:105], v[40:41], v[248:249], v[104:105]
	v_lshlrev_b32_e32 v246, 16, v168
	v_and_b32_e32 v247, 0xffff0000, v168
	v_pk_fma_f32 v[106:107], v[42:43], v[246:247], v[106:107]
	v_lshlrev_b32_e32 v248, 16, v169
	v_and_b32_e32 v249, 0xffff0000, v169
	v_pk_fma_f32 v[108:109], v[44:45], v[248:249], v[108:109]
	v_lshlrev_b32_e32 v246, 16, v170
	v_and_b32_e32 v247, 0xffff0000, v170
	v_pk_fma_f32 v[110:111], v[46:47], v[246:247], v[110:111]
	v_lshlrev_b32_e32 v248, 16, v171
	v_and_b32_e32 v249, 0xffff0000, v171
	v_pk_fma_f32 v[112:113], v[48:49], v[248:249], v[112:113]
	v_lshlrev_b32_e32 v246, 16, v172
	v_and_b32_e32 v247, 0xffff0000, v172
	v_pk_fma_f32 v[114:115], v[50:51], v[246:247], v[114:115]
	v_lshlrev_b32_e32 v248, 16, v173
	v_and_b32_e32 v249, 0xffff0000, v173
	v_pk_fma_f32 v[116:117], v[52:53], v[248:249], v[116:117]
	v_lshlrev_b32_e32 v246, 16, v174
	v_and_b32_e32 v247, 0xffff0000, v174
	v_pk_fma_f32 v[118:119], v[54:55], v[246:247], v[118:119]
	v_lshlrev_b32_e32 v248, 16, v175
	v_and_b32_e32 v249, 0xffff0000, v175
	v_pk_fma_f32 v[120:121], v[56:57], v[248:249], v[120:121]
	v_lshlrev_b32_e32 v246, 16, v176
	v_and_b32_e32 v247, 0xffff0000, v176
	v_pk_fma_f32 v[122:123], v[58:59], v[246:247], v[122:123]
	v_lshlrev_b32_e32 v248, 16, v177
	v_and_b32_e32 v249, 0xffff0000, v177
	v_pk_fma_f32 v[124:125], v[60:61], v[248:249], v[124:125]
	v_lshlrev_b32_e32 v246, 16, v178
	v_and_b32_e32 v247, 0xffff0000, v178
	v_pk_fma_f32 v[126:127], v[62:63], v[246:247], v[126:127]
	v_lshlrev_b32_e32 v248, 16, v179
	v_and_b32_e32 v249, 0xffff0000, v179
	v_pk_fma_f32 v[128:129], v[64:65], v[248:249], v[128:129]
	v_readlane_b32 s20, v253, 28
	v_readlane_b32 s21, v253, 29
	s_and_b32 s0, s13, 31
	s_lshr_b32 s1, s13, 5
	s_lshl_b32 s22, s0, 19
	s_lshl_b32 s1, s1, 8
	s_add_u32 s22, s22, s1
	s_add_u32 s20, s20, s22
	s_addc_u32 s21, s21, 0
	v_mov_b32_e32 v246, v204
	v_cvt_pk_bf16_f32 v66, v66, v67
	v_cvt_pk_bf16_f32 v67, v68, v69
	global_store_dwordx2 v246, v[66:67], s[20:21] offset:0 sc1
	v_cvt_pk_bf16_f32 v70, v70, v71
	v_cvt_pk_bf16_f32 v71, v72, v73
	global_store_dwordx2 v246, v[70:71], s[20:21] offset:32 sc1
	v_cvt_pk_bf16_f32 v74, v74, v75
	v_cvt_pk_bf16_f32 v75, v76, v77
	global_store_dwordx2 v246, v[74:75], s[20:21] offset:64 sc1
	v_cvt_pk_bf16_f32 v78, v78, v79
	v_cvt_pk_bf16_f32 v79, v80, v81
	global_store_dwordx2 v246, v[78:79], s[20:21] offset:96 sc1
	v_add_u32_e32 v246, 0x8000, v246
	v_cvt_pk_bf16_f32 v82, v82, v83
	v_cvt_pk_bf16_f32 v83, v84, v85
	global_store_dwordx2 v246, v[82:83], s[20:21] offset:0 sc1
	v_cvt_pk_bf16_f32 v86, v86, v87
	v_cvt_pk_bf16_f32 v87, v88, v89
	global_store_dwordx2 v246, v[86:87], s[20:21] offset:32 sc1
	v_cvt_pk_bf16_f32 v90, v90, v91
	v_cvt_pk_bf16_f32 v91, v92, v93
	global_store_dwordx2 v246, v[90:91], s[20:21] offset:64 sc1
	v_cvt_pk_bf16_f32 v94, v94, v95
	v_cvt_pk_bf16_f32 v95, v96, v97
	global_store_dwordx2 v246, v[94:95], s[20:21] offset:96 sc1
	v_add_u32_e32 v246, 0x8000, v246
	v_cvt_pk_bf16_f32 v98, v98, v99
	v_cvt_pk_bf16_f32 v99, v100, v101
	global_store_dwordx2 v246, v[98:99], s[20:21] offset:0 sc1
	v_cvt_pk_bf16_f32 v102, v102, v103
	v_cvt_pk_bf16_f32 v103, v104, v105
	global_store_dwordx2 v246, v[102:103], s[20:21] offset:32 sc1
	v_cvt_pk_bf16_f32 v106, v106, v107
	v_cvt_pk_bf16_f32 v107, v108, v109
	global_store_dwordx2 v246, v[106:107], s[20:21] offset:64 sc1
	v_cvt_pk_bf16_f32 v110, v110, v111
	v_cvt_pk_bf16_f32 v111, v112, v113
	global_store_dwordx2 v246, v[110:111], s[20:21] offset:96 sc1
	v_add_u32_e32 v246, 0x8000, v246
	v_cvt_pk_bf16_f32 v114, v114, v115
	v_cvt_pk_bf16_f32 v115, v116, v117
	global_store_dwordx2 v246, v[114:115], s[20:21] offset:0 sc1
	v_cvt_pk_bf16_f32 v118, v118, v119
	v_cvt_pk_bf16_f32 v119, v120, v121
	global_store_dwordx2 v246, v[118:119], s[20:21] offset:32 sc1
	v_cvt_pk_bf16_f32 v122, v122, v123
	v_cvt_pk_bf16_f32 v123, v124, v125
	global_store_dwordx2 v246, v[122:123], s[20:21] offset:64 sc1
	v_cvt_pk_bf16_f32 v126, v126, v127
	v_cvt_pk_bf16_f32 v127, v128, v129
	global_store_dwordx2 v246, v[126:127], s[20:21] offset:96 sc1
	s_waitcnt vmcnt(0)
	s_barrier
	v_cmp_eq_u32_e32 vcc, 0, v0
	s_and_saveexec_b64 s[20:21], vcc
	s_cbranch_execz .Lc2_noarr
	s_lshl_b32 s1, s80, 5
	s_add_u32 s1, s1, 64
	s_add_u32 s1, s1, s0
	s_lshl_b32 s1, s1, 8
	v_readlane_b32 s0, v254, 4
	v_readlane_b32 s22, v254, 5
	s_nop 3
	s_add_u32 s0, s0, s1
	s_addc_u32 s1, s22, 0
	v_mov_b32_e32 v247, 1
	s_nop 3
	global_atomic_add v131, v247, s[0:1]
.Lc2_noarr:
	s_or_b64 exec, exec, s[20:21]
	ds_write_b64 v205, v[250:251]
	s_add_i32 s13, s13, s65
	v_mov_b32_e32 v2, 0
	v_mov_b32_e32 v3, 0
	v_mov_b32_e32 v4, 0
	v_mov_b32_e32 v5, 0
	v_mov_b32_e32 v6, 0
	v_mov_b32_e32 v7, 0
	v_mov_b32_e32 v8, 0
	v_mov_b32_e32 v9, 0
	v_mov_b32_e32 v10, 0
	v_mov_b32_e32 v11, 0
	v_mov_b32_e32 v12, 0
	v_mov_b32_e32 v13, 0
	v_mov_b32_e32 v14, 0
	v_mov_b32_e32 v15, 0
	v_mov_b32_e32 v16, 0
	v_mov_b32_e32 v17, 0
	v_mov_b32_e32 v18, 0
	v_mov_b32_e32 v19, 0
	v_mov_b32_e32 v20, 0
	v_mov_b32_e32 v21, 0
	v_mov_b32_e32 v22, 0
	v_mov_b32_e32 v23, 0
	v_mov_b32_e32 v24, 0
	v_mov_b32_e32 v25, 0
	v_mov_b32_e32 v26, 0
	v_mov_b32_e32 v27, 0
	v_mov_b32_e32 v28, 0
	v_mov_b32_e32 v29, 0
	v_mov_b32_e32 v30, 0
	v_mov_b32_e32 v31, 0
	v_mov_b32_e32 v32, 0
	v_mov_b32_e32 v33, 0
	v_mov_b32_e32 v34, 0
	v_mov_b32_e32 v35, 0
	v_mov_b32_e32 v36, 0
	v_mov_b32_e32 v37, 0
	v_mov_b32_e32 v38, 0
	v_mov_b32_e32 v39, 0
	v_mov_b32_e32 v40, 0
	v_mov_b32_e32 v41, 0
	v_mov_b32_e32 v42, 0
	v_mov_b32_e32 v43, 0
	v_mov_b32_e32 v44, 0
	v_mov_b32_e32 v45, 0
	v_mov_b32_e32 v46, 0
	v_mov_b32_e32 v47, 0
	v_mov_b32_e32 v48, 0
	v_mov_b32_e32 v49, 0
	v_mov_b32_e32 v50, 0
	v_mov_b32_e32 v51, 0
	v_mov_b32_e32 v52, 0
	v_mov_b32_e32 v53, 0
	v_mov_b32_e32 v54, 0
	v_mov_b32_e32 v55, 0
	v_mov_b32_e32 v56, 0
	v_mov_b32_e32 v57, 0
	v_mov_b32_e32 v58, 0
	v_mov_b32_e32 v59, 0
	v_mov_b32_e32 v60, 0
	v_mov_b32_e32 v61, 0
	v_mov_b32_e32 v62, 0
	v_mov_b32_e32 v63, 0
	v_mov_b32_e32 v64, 0
	v_mov_b32_e32 v65, 0
	s_branch .Lc2_unit
.Lc2_exit:
.LBB0_890:
	v_readlane_b32 s79, v254, 50
